# v11 + GEMM K-loop A-fragment tail split: every phase issues 6 ds_read_b128 (last two A quads read one phase early into spare registers), counted vmcnt(8) retire in odd phases
# speedup vs baseline: 1.0250x; 1.0025x over previous
.LBB0_116:
	s_ashr_i32 s9, s8, 31
	s_lshl_b64 s[12:13], s[8:9], 18
	s_add_u32 s12, s24, s12
	s_addc_u32 s13, s25, s13
	s_and_b64 s[14:15], s[22:23], exec
	s_cselect_b32 s9, s13, s19
	s_cselect_b32 s41, s12, s18
	s_ashr_i32 s7, s6, 31
	s_lshl_b64 s[14:15], s[6:7], 18
	s_add_u32 s14, s28, s14
	s_addc_u32 s15, s29, s15
	s_and_b64 s[22:23], s[22:23], exec
	s_cselect_b32 s7, s15, s21
	s_cselect_b32 s42, s14, s20
	s_add_u32 s18, s18, 0x20080
	s_addc_u32 s19, s19, 0
	s_add_u32 s43, s20, 0x100
	v_mov_b32_e32 v0, 0
	s_addc_u32 s44, s21, 0
	s_mov_b32 s45, -2
	v_mov_b32_e32 v1, v0
	v_mov_b32_e32 v2, v0
	v_mov_b32_e32 v3, v0
	v_mov_b32_e32 v4, v0
	v_mov_b32_e32 v5, v0
	v_mov_b32_e32 v6, v0
	v_mov_b32_e32 v7, v0
	v_mov_b32_e32 v16, v0
	v_mov_b32_e32 v17, v0
	v_mov_b32_e32 v18, v0
	v_mov_b32_e32 v19, v0
	v_mov_b32_e32 v20, v0
	v_mov_b32_e32 v21, v0
	v_mov_b32_e32 v22, v0
	v_mov_b32_e32 v23, v0
	v_mov_b32_e32 v32, v0
	v_mov_b32_e32 v33, v0
	v_mov_b32_e32 v34, v0
	v_mov_b32_e32 v35, v0
	v_mov_b32_e32 v36, v0
	v_mov_b32_e32 v37, v0
	v_mov_b32_e32 v38, v0
	v_mov_b32_e32 v39, v0
	v_mov_b32_e32 v48, v0
	v_mov_b32_e32 v49, v0
	v_mov_b32_e32 v50, v0
	v_mov_b32_e32 v51, v0
	v_mov_b32_e32 v52, v0
	v_mov_b32_e32 v53, v0
	v_mov_b32_e32 v54, v0
	v_mov_b32_e32 v55, v0
	v_mov_b32_e32 v8, v0
	v_mov_b32_e32 v9, v0
	v_mov_b32_e32 v10, v0
	v_mov_b32_e32 v11, v0
	v_mov_b32_e32 v12, v0
	v_mov_b32_e32 v13, v0
	v_mov_b32_e32 v14, v0
	v_mov_b32_e32 v15, v0
	v_mov_b32_e32 v24, v0
	v_mov_b32_e32 v25, v0
	v_mov_b32_e32 v26, v0
	v_mov_b32_e32 v27, v0
	v_mov_b32_e32 v28, v0
	v_mov_b32_e32 v29, v0
	v_mov_b32_e32 v30, v0
	v_mov_b32_e32 v31, v0
	v_mov_b32_e32 v40, v0
	v_mov_b32_e32 v41, v0
	v_mov_b32_e32 v42, v0
	v_mov_b32_e32 v43, v0
	v_mov_b32_e32 v44, v0
	v_mov_b32_e32 v45, v0
	v_mov_b32_e32 v46, v0
	v_mov_b32_e32 v47, v0
	v_mov_b32_e32 v56, v0
	v_mov_b32_e32 v57, v0
	v_mov_b32_e32 v58, v0
	v_mov_b32_e32 v59, v0
	v_mov_b32_e32 v60, v0
	v_mov_b32_e32 v61, v0
	v_mov_b32_e32 v62, v0
	v_mov_b32_e32 v63, v0
	v_mov_b32_e32 v64, v0
	v_mov_b32_e32 v65, v0
	v_mov_b32_e32 v66, v0
	v_mov_b32_e32 v67, v0
	v_mov_b32_e32 v68, v0
	v_mov_b32_e32 v69, v0
	v_mov_b32_e32 v70, v0
	v_mov_b32_e32 v71, v0
	v_mov_b32_e32 v80, v0
	v_mov_b32_e32 v81, v0
	v_mov_b32_e32 v82, v0
	v_mov_b32_e32 v83, v0
	v_mov_b32_e32 v84, v0
	v_mov_b32_e32 v85, v0
	v_mov_b32_e32 v86, v0
	v_mov_b32_e32 v87, v0
	v_mov_b32_e32 v96, v0
	v_mov_b32_e32 v97, v0
	v_mov_b32_e32 v98, v0
	v_mov_b32_e32 v99, v0
	v_mov_b32_e32 v100, v0
	v_mov_b32_e32 v101, v0
	v_mov_b32_e32 v102, v0
	v_mov_b32_e32 v103, v0
	v_mov_b32_e32 v112, v0
	v_mov_b32_e32 v113, v0
	v_mov_b32_e32 v114, v0
	v_mov_b32_e32 v115, v0
	v_mov_b32_e32 v116, v0
	v_mov_b32_e32 v117, v0
	v_mov_b32_e32 v118, v0
	v_mov_b32_e32 v119, v0
	v_mov_b32_e32 v72, v0
	v_mov_b32_e32 v73, v0
	v_mov_b32_e32 v74, v0
	v_mov_b32_e32 v75, v0
	v_mov_b32_e32 v76, v0
	v_mov_b32_e32 v77, v0
	v_mov_b32_e32 v78, v0
	v_mov_b32_e32 v79, v0
	v_mov_b32_e32 v88, v0
	v_mov_b32_e32 v89, v0
	v_mov_b32_e32 v90, v0
	v_mov_b32_e32 v91, v0
	v_mov_b32_e32 v92, v0
	v_mov_b32_e32 v93, v0
	v_mov_b32_e32 v94, v0
	v_mov_b32_e32 v95, v0
	v_mov_b32_e32 v104, v0
	v_mov_b32_e32 v105, v0
	v_mov_b32_e32 v106, v0
	v_mov_b32_e32 v107, v0
	v_mov_b32_e32 v108, v0
	v_mov_b32_e32 v109, v0
	v_mov_b32_e32 v110, v0
	v_mov_b32_e32 v111, v0
	v_mov_b32_e32 v120, v0
	v_mov_b32_e32 v121, v0
	v_mov_b32_e32 v122, v0
	v_mov_b32_e32 v123, v0
	v_mov_b32_e32 v124, v0
	v_mov_b32_e32 v125, v0
	v_mov_b32_e32 v126, v0
	v_mov_b32_e32 v127, v0
	s_mov_b64 s[50:51], 0x80
	v_add_u32_e32 v156, 0x10000, v142
	ds_read_b128 v[144:147], v156
	ds_read_b128 v[148:151], v156 offset:1024
	ds_read_b128 v[152:155], v156 offset:2048
	ds_read_b128 v[156:159], v156 offset:3072
	ds_read_b128 v[248:251], v143 offset:6144
	ds_read_b128 v[252:255], v143 offset:7168
.LBB0_117:
	s_add_u32 s20, s18, 0xfffe0080
	s_addc_u32 s21, s19, -1
	s_add_i32 s46, 0, 0x10000
	v_add_u32_e32 v138, s46, v142
	s_cmp_eq_u32 s45, 4
	s_cselect_b32 s23, s9, s21
	s_cselect_b32 s22, s41, s20
	s_cselect_b32 s21, s7, s44
	s_cselect_b32 s20, s42, s43
	v_lshl_add_u64 v[138:139], s[18:19], 0, v[134:135]
	s_add_i32 m0, s17, 0xc000
	ds_read_b128 v[160:163], v143
	ds_read_b128 v[164:167], v143 offset:1024
	ds_read_b128 v[168:171], v143 offset:2048
	ds_read_b128 v[172:175], v143 offset:3072
	ds_read_b128 v[176:179], v143 offset:4096
	ds_read_b128 v[180:183], v143 offset:5120
	global_load_lds_dwordx4 v[138:139], off
	v_lshl_add_u64 v[138:139], s[18:19], 0, v[136:137]
	s_add_i32 m0, s17, 0xe000
	s_nop 0
	global_load_lds_dwordx4 v[138:139], off
	s_waitcnt lgkmcnt(8)
	s_setprio 1
	s_waitcnt vmcnt(8)
	s_barrier
	s_waitcnt lgkmcnt(0)
	v_mfma_f32_16x16x32_bf16 v[124:127], v[144:147], v[160:163], v[124:127]
	v_mfma_f32_16x16x32_bf16 v[120:123], v[152:155], v[160:163], v[120:123]
	v_mfma_f32_16x16x32_bf16 v[108:111], v[144:147], v[168:171], v[108:111]
	v_mfma_f32_16x16x32_bf16 v[104:107], v[152:155], v[168:171], v[104:107]
	v_mfma_f32_16x16x32_bf16 v[92:95], v[144:147], v[176:179], v[92:95]
	v_mfma_f32_16x16x32_bf16 v[88:91], v[152:155], v[176:179], v[88:91]
	v_mfma_f32_16x16x32_bf16 v[76:79], v[144:147], v[248:251], v[76:79]
	v_mfma_f32_16x16x32_bf16 v[72:75], v[152:155], v[248:251], v[72:75]
	v_mfma_f32_16x16x32_bf16 v[124:127], v[148:151], v[164:167], v[124:127]
	v_mfma_f32_16x16x32_bf16 v[120:123], v[156:159], v[164:167], v[120:123]
	v_mfma_f32_16x16x32_bf16 v[108:111], v[148:151], v[172:175], v[108:111]
	v_mfma_f32_16x16x32_bf16 v[104:107], v[156:159], v[172:175], v[104:107]
	v_mfma_f32_16x16x32_bf16 v[92:95], v[148:151], v[180:183], v[92:95]
	v_mfma_f32_16x16x32_bf16 v[88:91], v[156:159], v[180:183], v[88:91]
	v_mfma_f32_16x16x32_bf16 v[76:79], v[148:151], v[252:255], v[76:79]
	v_mfma_f32_16x16x32_bf16 v[72:75], v[156:159], v[252:255], v[72:75]
	s_barrier
	s_setprio 0
	ds_read_b128 v[188:191], v143 offset:22528
	ds_read_b128 v[192:195], v143 offset:23552
	s_add_i32 s48, 0, 0x14000
	v_add_u32_e32 v138, s48, v142
	s_add_i32 s46, s46, s30
	ds_read_b128 v[202:205], v138
	ds_read_b128 v[206:209], v138 offset:1024
	ds_read_b128 v[210:213], v138 offset:2048
	ds_read_b128 v[214:217], v138 offset:3072
	v_lshl_add_u64 v[138:139], s[20:21], 0, v[184:185]
	s_mov_b32 m0, s46
	v_lshl_add_u64 v[196:197], s[20:21], 0, v[128:129]
	global_load_lds_dwordx4 v[138:139], off
	s_add_i32 m0, s46, 0x2000
	s_nop 0
	global_load_lds_dwordx4 v[196:197], off
	s_setprio 1
	s_barrier
	s_waitcnt lgkmcnt(0)
	v_mfma_f32_16x16x32_bf16 v[116:119], v[202:205], v[160:163], v[116:119]
	v_mfma_f32_16x16x32_bf16 v[112:115], v[210:213], v[160:163], v[112:115]
	v_mfma_f32_16x16x32_bf16 v[100:103], v[202:205], v[168:171], v[100:103]
	v_mfma_f32_16x16x32_bf16 v[96:99], v[210:213], v[168:171], v[96:99]
	v_mfma_f32_16x16x32_bf16 v[84:87], v[202:205], v[176:179], v[84:87]
	v_mfma_f32_16x16x32_bf16 v[80:83], v[210:213], v[176:179], v[80:83]
	v_mfma_f32_16x16x32_bf16 v[68:71], v[202:205], v[248:251], v[68:71]
	v_mfma_f32_16x16x32_bf16 v[64:67], v[210:213], v[248:251], v[64:67]
	v_mfma_f32_16x16x32_bf16 v[116:119], v[206:209], v[164:167], v[116:119]
	v_mfma_f32_16x16x32_bf16 v[112:115], v[214:217], v[164:167], v[112:115]
	v_mfma_f32_16x16x32_bf16 v[100:103], v[206:209], v[172:175], v[100:103]
	v_mfma_f32_16x16x32_bf16 v[96:99], v[214:217], v[172:175], v[96:99]
	v_mfma_f32_16x16x32_bf16 v[84:87], v[206:209], v[180:183], v[84:87]
	v_mfma_f32_16x16x32_bf16 v[80:83], v[214:217], v[180:183], v[80:83]
	v_mfma_f32_16x16x32_bf16 v[68:71], v[206:209], v[252:255], v[68:71]
	v_mfma_f32_16x16x32_bf16 v[64:67], v[214:217], v[252:255], v[64:67]
	s_barrier
	s_setprio 0
	s_mov_b32 m0, s17
	v_lshl_add_u64 v[218:219], s[22:23], 0, v[132:133]
	ds_read_b128 v[160:163], v143 offset:16384
	ds_read_b128 v[164:167], v143 offset:17408
	ds_read_b128 v[168:171], v143 offset:18432
	ds_read_b128 v[172:175], v143 offset:19456
	ds_read_b128 v[176:179], v143 offset:20480
	ds_read_b128 v[180:183], v143 offset:21504
	global_load_lds_dwordx4 v[218:219], off
	v_lshl_add_u64 v[220:221], s[22:23], 0, v[130:131]
	s_mov_b32 m0, s31
	s_nop 0
	global_load_lds_dwordx4 v[220:221], off
	s_setprio 1
	s_waitcnt vmcnt(8)
	s_barrier
	s_waitcnt lgkmcnt(0)
	v_mfma_f32_16x16x32_bf16 v[60:63], v[144:147], v[160:163], v[60:63]
	v_mfma_f32_16x16x32_bf16 v[56:59], v[152:155], v[160:163], v[56:59]
	v_mfma_f32_16x16x32_bf16 v[44:47], v[144:147], v[168:171], v[44:47]
	v_mfma_f32_16x16x32_bf16 v[40:43], v[152:155], v[168:171], v[40:43]
	v_mfma_f32_16x16x32_bf16 v[28:31], v[144:147], v[176:179], v[28:31]
	v_mfma_f32_16x16x32_bf16 v[24:27], v[152:155], v[176:179], v[24:27]
	v_mfma_f32_16x16x32_bf16 v[12:15], v[144:147], v[188:191], v[12:15]
	v_mfma_f32_16x16x32_bf16 v[8:11], v[152:155], v[188:191], v[8:11]
	v_mfma_f32_16x16x32_bf16 v[60:63], v[148:151], v[164:167], v[60:63]
	v_mfma_f32_16x16x32_bf16 v[56:59], v[156:159], v[164:167], v[56:59]
	v_mfma_f32_16x16x32_bf16 v[44:47], v[148:151], v[172:175], v[44:47]
	v_mfma_f32_16x16x32_bf16 v[40:43], v[156:159], v[172:175], v[40:43]
	v_mfma_f32_16x16x32_bf16 v[28:31], v[148:151], v[180:183], v[28:31]
	v_mfma_f32_16x16x32_bf16 v[24:27], v[156:159], v[180:183], v[24:27]
	v_mfma_f32_16x16x32_bf16 v[12:15], v[148:151], v[192:195], v[12:15]
	v_mfma_f32_16x16x32_bf16 v[8:11], v[156:159], v[192:195], v[8:11]
	s_barrier
	s_setprio 0
	v_add_u32_e32 v156, 0x18000, v142
	ds_read_b128 v[144:147], v156
	ds_read_b128 v[148:151], v156 offset:1024
	ds_read_b128 v[152:155], v156 offset:2048
	ds_read_b128 v[156:159], v156 offset:3072
	ds_read_b128 v[248:251], v143 offset:38912
	ds_read_b128 v[252:255], v143 offset:39936
	s_add_u32 s46, s20, 0x20000
	s_addc_u32 s47, s21, 0
	s_add_i32 s48, s48, s30
	v_lshl_add_u64 v[246:247], s[46:47], 0, v[184:185]
	s_mov_b32 m0, s48
	s_nop 0
	global_load_lds_dwordx4 v[246:247], off
	v_lshl_add_u64 v[246:247], s[46:47], 0, v[128:129]
	s_add_i32 m0, s48, 0x2000
	s_nop 0
	global_load_lds_dwordx4 v[246:247], off
	s_waitcnt vmcnt(6)
	s_setprio 1
	s_barrier
	v_mfma_f32_16x16x32_bf16 v[52:55], v[202:205], v[160:163], v[52:55]
	v_mfma_f32_16x16x32_bf16 v[48:51], v[210:213], v[160:163], v[48:51]
	v_mfma_f32_16x16x32_bf16 v[36:39], v[202:205], v[168:171], v[36:39]
	v_mfma_f32_16x16x32_bf16 v[32:35], v[210:213], v[168:171], v[32:35]
	v_mfma_f32_16x16x32_bf16 v[20:23], v[202:205], v[176:179], v[20:23]
	v_mfma_f32_16x16x32_bf16 v[16:19], v[210:213], v[176:179], v[16:19]
	v_mfma_f32_16x16x32_bf16 v[4:7], v[202:205], v[188:191], v[4:7]
	v_mfma_f32_16x16x32_bf16 v[0:3], v[210:213], v[188:191], v[0:3]
	v_mfma_f32_16x16x32_bf16 v[52:55], v[206:209], v[164:167], v[52:55]
	v_mfma_f32_16x16x32_bf16 v[48:51], v[214:217], v[164:167], v[48:51]
	v_mfma_f32_16x16x32_bf16 v[36:39], v[206:209], v[172:175], v[36:39]
	v_mfma_f32_16x16x32_bf16 v[32:35], v[214:217], v[172:175], v[32:35]
	v_mfma_f32_16x16x32_bf16 v[20:23], v[206:209], v[180:183], v[20:23]
	v_mfma_f32_16x16x32_bf16 v[16:19], v[214:217], v[180:183], v[16:19]
	v_mfma_f32_16x16x32_bf16 v[4:7], v[206:209], v[192:195], v[4:7]
	v_mfma_f32_16x16x32_bf16 v[0:3], v[214:217], v[192:195], v[0:3]
	s_barrier
	s_setprio 0
	s_add_i32 s46, 0, 0x18000
	s_add_u32 s22, s22, 0x20000
	s_addc_u32 s23, s23, 0
	s_mov_b32 m0, s33
	v_lshl_add_u64 v[202:203], s[22:23], 0, v[132:133]
	ds_read_b128 v[160:163], v143 offset:32768
	ds_read_b128 v[164:167], v143 offset:33792
	ds_read_b128 v[168:171], v143 offset:34816
	ds_read_b128 v[172:175], v143 offset:35840
	ds_read_b128 v[176:179], v143 offset:36864
	ds_read_b128 v[180:183], v143 offset:37888
	global_load_lds_dwordx4 v[202:203], off
	v_lshl_add_u64 v[202:203], s[22:23], 0, v[130:131]
	s_mov_b32 m0, s34
	s_nop 0
	global_load_lds_dwordx4 v[202:203], off
	s_waitcnt lgkmcnt(8)
	s_setprio 1
	s_waitcnt vmcnt(8)
	s_barrier
	s_waitcnt lgkmcnt(0)
	v_mfma_f32_16x16x32_bf16 v[124:127], v[144:147], v[160:163], v[124:127]
	v_mfma_f32_16x16x32_bf16 v[120:123], v[152:155], v[160:163], v[120:123]
	v_mfma_f32_16x16x32_bf16 v[108:111], v[144:147], v[168:171], v[108:111]
	v_mfma_f32_16x16x32_bf16 v[104:107], v[152:155], v[168:171], v[104:107]
	v_mfma_f32_16x16x32_bf16 v[92:95], v[144:147], v[176:179], v[92:95]
	v_mfma_f32_16x16x32_bf16 v[88:91], v[152:155], v[176:179], v[88:91]
	v_mfma_f32_16x16x32_bf16 v[76:79], v[144:147], v[248:251], v[76:79]
	v_mfma_f32_16x16x32_bf16 v[72:75], v[152:155], v[248:251], v[72:75]
	v_mfma_f32_16x16x32_bf16 v[124:127], v[148:151], v[164:167], v[124:127]
	v_mfma_f32_16x16x32_bf16 v[120:123], v[156:159], v[164:167], v[120:123]
	v_mfma_f32_16x16x32_bf16 v[108:111], v[148:151], v[172:175], v[108:111]
	v_mfma_f32_16x16x32_bf16 v[104:107], v[156:159], v[172:175], v[104:107]
	v_mfma_f32_16x16x32_bf16 v[92:95], v[148:151], v[180:183], v[92:95]
	v_mfma_f32_16x16x32_bf16 v[88:91], v[156:159], v[180:183], v[88:91]
	v_mfma_f32_16x16x32_bf16 v[76:79], v[148:151], v[252:255], v[76:79]
	v_mfma_f32_16x16x32_bf16 v[72:75], v[156:159], v[252:255], v[72:75]
	s_barrier
	s_setprio 0
	ds_read_b128 v[188:191], v143 offset:55296
	ds_read_b128 v[192:195], v143 offset:56320
	s_add_i32 s22, 0, 0x1c000
	s_add_i32 s23, s46, s30
	v_add_u32_e32 v187, s22, v142
	v_lshl_add_u64 v[138:139], v[138:139], 0, s[50:51]
	s_mov_b32 m0, s23
	ds_read_b128 v[202:205], v187
	ds_read_b128 v[206:209], v187 offset:1024
	ds_read_b128 v[210:213], v187 offset:2048
	ds_read_b128 v[214:217], v187 offset:3072
	global_load_lds_dwordx4 v[138:139], off
	v_lshl_add_u64 v[138:139], v[196:197], 0, s[50:51]
	s_add_i32 m0, s23, 0x2000
	s_nop 0
	global_load_lds_dwordx4 v[138:139], off
	s_setprio 1
	s_barrier
	s_waitcnt lgkmcnt(0)
	v_mfma_f32_16x16x32_bf16 v[116:119], v[202:205], v[160:163], v[116:119]
	v_mfma_f32_16x16x32_bf16 v[112:115], v[210:213], v[160:163], v[112:115]
	v_mfma_f32_16x16x32_bf16 v[100:103], v[202:205], v[168:171], v[100:103]
	v_mfma_f32_16x16x32_bf16 v[96:99], v[210:213], v[168:171], v[96:99]
	v_mfma_f32_16x16x32_bf16 v[84:87], v[202:205], v[176:179], v[84:87]
	v_mfma_f32_16x16x32_bf16 v[80:83], v[210:213], v[176:179], v[80:83]
	v_mfma_f32_16x16x32_bf16 v[68:71], v[202:205], v[248:251], v[68:71]
	v_mfma_f32_16x16x32_bf16 v[64:67], v[210:213], v[248:251], v[64:67]
	v_mfma_f32_16x16x32_bf16 v[116:119], v[206:209], v[164:167], v[116:119]
	v_mfma_f32_16x16x32_bf16 v[112:115], v[214:217], v[164:167], v[112:115]
	v_mfma_f32_16x16x32_bf16 v[100:103], v[206:209], v[172:175], v[100:103]
	v_mfma_f32_16x16x32_bf16 v[96:99], v[214:217], v[172:175], v[96:99]
	v_mfma_f32_16x16x32_bf16 v[84:87], v[206:209], v[180:183], v[84:87]
	v_mfma_f32_16x16x32_bf16 v[80:83], v[214:217], v[180:183], v[80:83]
	v_mfma_f32_16x16x32_bf16 v[68:71], v[206:209], v[252:255], v[68:71]
	v_mfma_f32_16x16x32_bf16 v[64:67], v[214:217], v[252:255], v[64:67]
	s_barrier
	s_setprio 0
	s_mov_b32 m0, s37
	v_lshl_add_u64 v[138:139], v[218:219], 0, s[50:51]
	ds_read_b128 v[160:163], v143 offset:49152
	ds_read_b128 v[164:167], v143 offset:50176
	ds_read_b128 v[168:171], v143 offset:51200
	ds_read_b128 v[172:175], v143 offset:52224
	ds_read_b128 v[176:179], v143 offset:53248
	ds_read_b128 v[180:183], v143 offset:54272
	global_load_lds_dwordx4 v[138:139], off
	v_lshl_add_u64 v[138:139], v[220:221], 0, s[50:51]
	s_mov_b32 m0, s38
	s_nop 0
	global_load_lds_dwordx4 v[138:139], off
	s_setprio 1
	s_waitcnt vmcnt(8)
	s_barrier
	s_waitcnt lgkmcnt(0)
	v_mfma_f32_16x16x32_bf16 v[60:63], v[144:147], v[160:163], v[60:63]
	v_mfma_f32_16x16x32_bf16 v[56:59], v[152:155], v[160:163], v[56:59]
	v_mfma_f32_16x16x32_bf16 v[44:47], v[144:147], v[168:171], v[44:47]
	v_mfma_f32_16x16x32_bf16 v[40:43], v[152:155], v[168:171], v[40:43]
	v_mfma_f32_16x16x32_bf16 v[28:31], v[144:147], v[176:179], v[28:31]
	v_mfma_f32_16x16x32_bf16 v[24:27], v[152:155], v[176:179], v[24:27]
	v_mfma_f32_16x16x32_bf16 v[12:15], v[144:147], v[188:191], v[12:15]
	v_mfma_f32_16x16x32_bf16 v[8:11], v[152:155], v[188:191], v[8:11]
	v_mfma_f32_16x16x32_bf16 v[60:63], v[148:151], v[164:167], v[60:63]
	v_mfma_f32_16x16x32_bf16 v[56:59], v[156:159], v[164:167], v[56:59]
	v_mfma_f32_16x16x32_bf16 v[44:47], v[148:151], v[172:175], v[44:47]
	v_mfma_f32_16x16x32_bf16 v[40:43], v[156:159], v[172:175], v[40:43]
	v_mfma_f32_16x16x32_bf16 v[28:31], v[148:151], v[180:183], v[28:31]
	v_mfma_f32_16x16x32_bf16 v[24:27], v[156:159], v[180:183], v[24:27]
	v_mfma_f32_16x16x32_bf16 v[12:15], v[148:151], v[192:195], v[12:15]
	v_mfma_f32_16x16x32_bf16 v[8:11], v[156:159], v[192:195], v[8:11]
	s_barrier
	s_setprio 0
	v_add_u32_e32 v156, 0x10000, v142
	ds_read_b128 v[144:147], v156
	ds_read_b128 v[148:151], v156 offset:1024
	ds_read_b128 v[152:155], v156 offset:2048
	ds_read_b128 v[156:159], v156 offset:3072
	ds_read_b128 v[248:251], v143 offset:6144
	ds_read_b128 v[252:255], v143 offset:7168
	s_add_u32 s20, s20, 0x20080
	s_addc_u32 s21, s21, 0
	s_add_i32 s22, s22, s30
	v_lshl_add_u64 v[138:139], s[20:21], 0, v[184:185]
	s_mov_b32 m0, s22
	s_nop 0
	global_load_lds_dwordx4 v[138:139], off
	v_lshl_add_u64 v[138:139], s[20:21], 0, v[128:129]
	s_add_i32 m0, s22, 0x2000
	s_nop 0
	global_load_lds_dwordx4 v[138:139], off
	s_waitcnt vmcnt(6)
	s_setprio 1
	s_barrier
	v_mfma_f32_16x16x32_bf16 v[52:55], v[202:205], v[160:163], v[52:55]
	v_mfma_f32_16x16x32_bf16 v[48:51], v[210:213], v[160:163], v[48:51]
	v_mfma_f32_16x16x32_bf16 v[36:39], v[202:205], v[168:171], v[36:39]
	v_mfma_f32_16x16x32_bf16 v[32:35], v[210:213], v[168:171], v[32:35]
	v_mfma_f32_16x16x32_bf16 v[20:23], v[202:205], v[176:179], v[20:23]
	v_mfma_f32_16x16x32_bf16 v[16:19], v[210:213], v[176:179], v[16:19]
	v_mfma_f32_16x16x32_bf16 v[4:7], v[202:205], v[188:191], v[4:7]
	v_mfma_f32_16x16x32_bf16 v[0:3], v[210:213], v[188:191], v[0:3]
	v_mfma_f32_16x16x32_bf16 v[52:55], v[206:209], v[164:167], v[52:55]
	v_mfma_f32_16x16x32_bf16 v[48:51], v[214:217], v[164:167], v[48:51]
	v_mfma_f32_16x16x32_bf16 v[36:39], v[206:209], v[172:175], v[36:39]
	v_mfma_f32_16x16x32_bf16 v[32:35], v[214:217], v[172:175], v[32:35]
	v_mfma_f32_16x16x32_bf16 v[20:23], v[206:209], v[180:183], v[20:23]
	v_mfma_f32_16x16x32_bf16 v[16:19], v[214:217], v[180:183], v[16:19]
	v_mfma_f32_16x16x32_bf16 v[4:7], v[206:209], v[192:195], v[4:7]
	v_mfma_f32_16x16x32_bf16 v[0:3], v[214:217], v[192:195], v[0:3]
	s_barrier
	s_setprio 0
	s_add_i32 s45, s45, 2
	s_add_u32 s18, s18, 0x100
	s_addc_u32 s19, s19, 0
	s_add_u32 s43, s43, 0x100
	s_addc_u32 s44, s44, 0
	s_cmp_gt_u32 s45, 5
	s_cbranch_scc0 .LBB0_117
	s_waitcnt lgkmcnt(0)
	v_mov_b32_e32 v138, v140
	v_mov_b32_e32 v139, v141
	s_lshl_b32 s7, s16, 8
	s_add_i32 s7, s7, s35
	v_add_u32_e32 v138, s7, v138
	s_lshl_b32 s7, s40, 8
	s_or_b32 s7, s7, s36
	v_lshl_add_u32 v152, v139, 3, s7
	v_ashrrev_i32_e32 v139, 31, v138
	v_lshlrev_b64 v[144:145], 5, v[138:139]
	v_lshl_add_u64 v[148:149], s[4:5], 0, v[144:145]
	global_load_dwordx4 v[144:147], v[148:149], off offset:16
	s_nop 0
	global_load_dwordx4 v[148:151], v[148:149], off
	v_ashrrev_i32_e32 v153, 31, v152
	s_mov_b32 s40, s6
	s_mov_b32 s16, s8
	s_mov_b64 s[20:21], s[14:15]
	s_mov_b64 s[18:19], s[12:13]
	s_waitcnt vmcnt(0)
	v_add_f32_e32 v148, v148, v149
	v_add_f32_e32 v148, v150, v148
	v_add_f32_e32 v148, v151, v148
	v_add_f32_e32 v144, v144, v148
	v_add_f32_e32 v144, v145, v144
	v_add_f32_e32 v144, v146, v144
	v_add_f32_e32 v144, v147, v144
	v_add_f32_e32 v144, 0x3a0637bd, v144
	v_mul_f32_e32 v144, 0x3b000000, v144
	v_cmp_gt_f32_e32 vcc, s67, v144
	v_mul_f32_e32 v145, 0x4b800000, v144
	s_nop 0
	v_cndmask_b32_e32 v144, v144, v145, vcc
	v_rsq_f32_e32 v144, v144
	s_nop 0
	v_mul_f32_e32 v145, 0x45800000, v144
	v_cndmask_b32_e32 v144, v144, v145, vcc
	v_mul_f32_e32 v124, v124, v144
	v_mul_f32_e32 v120, v120, v144
	v_mul_f32_e32 v121, v121, v144
	v_mul_f32_e32 v125, v125, v144
	v_mul_f32_e32 v126, v126, v144
	v_mul_f32_e32 v127, v127, v144
	v_mul_f32_e32 v145, v122, v144
	v_mul_f32_e32 v146, v123, v144
	v_cvt_pk_bf16_f32 v122, v124, v125
	v_cvt_pk_bf16_f32 v123, v126, v127
	v_cvt_pk_bf16_f32 v124, v120, v121
	v_lshlrev_b64 v[120:121], 12, v[138:139]
	v_lshl_add_u64 v[126:127], s[2:3], 0, v[120:121]
	v_lshlrev_b64 v[120:121], 1, v[152:153]
	v_lshl_add_u64 v[126:127], v[126:127], 0, v[120:121]
	v_cvt_pk_bf16_f32 v125, v145, v146
	global_store_dwordx4 v[126:127], v[122:125], off
	v_mul_f32_e32 v116, v116, v144
	v_mul_f32_e32 v117, v117, v144
	v_mul_f32_e32 v122, v112, v144
	v_mul_f32_e32 v118, v118, v144
	v_mul_f32_e32 v119, v119, v144
	v_mul_f32_e32 v123, v113, v144
	v_mul_f32_e32 v124, v114, v144
	v_cvt_pk_bf16_f32 v112, v116, v117
	v_cvt_pk_bf16_f32 v113, v118, v119
	v_cvt_pk_bf16_f32 v114, v122, v123
	v_add_u32_e32 v122, 16, v138
	v_mul_f32_e32 v115, v115, v144
	v_ashrrev_i32_e32 v123, 31, v122
	v_cvt_pk_bf16_f32 v115, v124, v115
	global_store_dwordx4 v[126:127], v[112:115], off offset:256
	s_nop 1
	v_lshlrev_b64 v[112:113], 5, v[122:123]
	v_lshl_add_u64 v[116:117], s[4:5], 0, v[112:113]
	global_load_dwordx4 v[112:115], v[116:117], off offset:16
	s_nop 0
	global_load_dwordx4 v[116:119], v[116:117], off
	s_waitcnt vmcnt(0)
	v_add_f32_e32 v116, v116, v117
	v_add_f32_e32 v116, v118, v116
	v_add_f32_e32 v116, v119, v116
	v_add_f32_e32 v112, v112, v116
	v_add_f32_e32 v112, v113, v112
	v_add_f32_e32 v112, v114, v112
	v_add_f32_e32 v112, v115, v112
	v_add_f32_e32 v112, 0x3a0637bd, v112
	v_mul_f32_e32 v112, 0x3b000000, v112
	v_cmp_gt_f32_e32 vcc, s67, v112
	v_mul_f32_e32 v113, 0x4b800000, v112
	s_nop 0
	v_cndmask_b32_e32 v112, v112, v113, vcc
	v_rsq_f32_e32 v112, v112
	s_nop 0
	v_mul_f32_e32 v113, 0x45800000, v112
	v_cndmask_b32_e32 v112, v112, v113, vcc
	v_mul_f32_e32 v108, v108, v112
	v_mul_f32_e32 v109, v109, v112
	v_mul_f32_e32 v113, v104, v112
	v_cvt_pk_bf16_f32 v104, v108, v109
	v_lshlrev_b64 v[108:109], 12, v[122:123]
	v_lshl_add_u64 v[108:109], s[2:3], 0, v[108:109]
	v_mul_f32_e32 v107, v107, v112
	v_lshl_add_u64 v[108:109], v[108:109], 0, v[120:121]
	v_mul_f32_e32 v110, v110, v112
	v_mul_f32_e32 v111, v111, v112
	v_mul_f32_e32 v114, v105, v112
	v_mul_f32_e32 v115, v106, v112
	v_cvt_pk_bf16_f32 v105, v110, v111
	v_cvt_pk_bf16_f32 v106, v113, v114
	v_cvt_pk_bf16_f32 v107, v115, v107
	global_store_dwordx4 v[108:109], v[104:107], off
	v_mul_f32_e32 v100, v100, v112
	v_mul_f32_e32 v101, v101, v112
	v_mul_f32_e32 v104, v96, v112
	v_mul_f32_e32 v102, v102, v112
	v_mul_f32_e32 v103, v103, v112
	v_mul_f32_e32 v105, v97, v112
	v_mul_f32_e32 v106, v98, v112
	v_cvt_pk_bf16_f32 v96, v100, v101
	v_cvt_pk_bf16_f32 v97, v102, v103
	v_cvt_pk_bf16_f32 v98, v104, v105
	v_add_u32_e32 v104, 32, v138
	v_mul_f32_e32 v99, v99, v112
	v_ashrrev_i32_e32 v105, 31, v104
	v_cvt_pk_bf16_f32 v99, v106, v99
	global_store_dwordx4 v[108:109], v[96:99], off offset:256
	s_nop 1
	v_lshlrev_b64 v[96:97], 5, v[104:105]
	v_lshl_add_u64 v[100:101], s[4:5], 0, v[96:97]
	global_load_dwordx4 v[96:99], v[100:101], off offset:16
	s_nop 0
	global_load_dwordx4 v[100:103], v[100:101], off
	s_waitcnt vmcnt(0)
	v_add_f32_e32 v100, v100, v101
	v_add_f32_e32 v100, v102, v100
	v_add_f32_e32 v100, v103, v100
	v_add_f32_e32 v96, v96, v100
	v_add_f32_e32 v96, v97, v96
	v_add_f32_e32 v96, v98, v96
	v_add_f32_e32 v96, v99, v96
	v_add_f32_e32 v96, 0x3a0637bd, v96
	v_mul_f32_e32 v96, 0x3b000000, v96
	v_cmp_gt_f32_e32 vcc, s67, v96
	v_mul_f32_e32 v97, 0x4b800000, v96
	s_nop 0
	v_cndmask_b32_e32 v96, v96, v97, vcc
	v_rsq_f32_e32 v96, v96
	s_nop 0
	v_mul_f32_e32 v97, 0x45800000, v96
	v_cndmask_b32_e32 v96, v96, v97, vcc
	v_mul_f32_e32 v92, v92, v96
	v_mul_f32_e32 v93, v93, v96
	v_mul_f32_e32 v97, v88, v96
	v_cvt_pk_bf16_f32 v88, v92, v93
	v_lshlrev_b64 v[92:93], 12, v[104:105]
	v_lshl_add_u64 v[92:93], s[2:3], 0, v[92:93]
	v_mul_f32_e32 v91, v91, v96
	v_lshl_add_u64 v[92:93], v[92:93], 0, v[120:121]
	v_mul_f32_e32 v94, v94, v96
	v_mul_f32_e32 v95, v95, v96
	v_mul_f32_e32 v98, v89, v96
	v_mul_f32_e32 v99, v90, v96
	v_cvt_pk_bf16_f32 v89, v94, v95
	v_cvt_pk_bf16_f32 v90, v97, v98
	v_cvt_pk_bf16_f32 v91, v99, v91
	global_store_dwordx4 v[92:93], v[88:91], off
	v_mul_f32_e32 v84, v84, v96
	v_mul_f32_e32 v85, v85, v96
	v_mul_f32_e32 v88, v80, v96
	v_mul_f32_e32 v86, v86, v96
	v_mul_f32_e32 v87, v87, v96
	v_mul_f32_e32 v89, v81, v96
	v_mul_f32_e32 v90, v82, v96
	v_cvt_pk_bf16_f32 v80, v84, v85
	v_cvt_pk_bf16_f32 v81, v86, v87
	v_cvt_pk_bf16_f32 v82, v88, v89
	v_add_u32_e32 v88, 48, v138
	v_mul_f32_e32 v83, v83, v96
	v_ashrrev_i32_e32 v89, 31, v88
	v_cvt_pk_bf16_f32 v83, v90, v83
	global_store_dwordx4 v[92:93], v[80:83], off offset:256
	s_nop 1
	v_lshlrev_b64 v[80:81], 5, v[88:89]
	v_lshl_add_u64 v[84:85], s[4:5], 0, v[80:81]
	global_load_dwordx4 v[80:83], v[84:85], off offset:16
	s_nop 0
	global_load_dwordx4 v[84:87], v[84:85], off
	s_waitcnt vmcnt(0)
	v_add_f32_e32 v84, v84, v85
	v_add_f32_e32 v84, v86, v84
	v_add_f32_e32 v84, v87, v84
	v_add_f32_e32 v80, v80, v84
	v_add_f32_e32 v80, v81, v80
	v_add_f32_e32 v80, v82, v80
	v_add_f32_e32 v80, v83, v80
	v_add_f32_e32 v80, 0x3a0637bd, v80
	v_mul_f32_e32 v80, 0x3b000000, v80
	v_cmp_gt_f32_e32 vcc, s67, v80
	v_mul_f32_e32 v81, 0x4b800000, v80
	s_nop 0
	v_cndmask_b32_e32 v80, v80, v81, vcc
	v_rsq_f32_e32 v80, v80
	s_nop 0
	v_mul_f32_e32 v81, 0x45800000, v80
	v_cndmask_b32_e32 v80, v80, v81, vcc
	v_mul_f32_e32 v76, v76, v80
	v_mul_f32_e32 v77, v77, v80
	v_mul_f32_e32 v81, v72, v80
	v_cvt_pk_bf16_f32 v72, v76, v77
	v_lshlrev_b64 v[76:77], 12, v[88:89]
	v_lshl_add_u64 v[76:77], s[2:3], 0, v[76:77]
	v_mul_f32_e32 v75, v75, v80
	v_lshl_add_u64 v[76:77], v[76:77], 0, v[120:121]
	v_mul_f32_e32 v78, v78, v80
	v_mul_f32_e32 v79, v79, v80
	v_mul_f32_e32 v82, v73, v80
	v_mul_f32_e32 v83, v74, v80
	v_cvt_pk_bf16_f32 v73, v78, v79
	v_cvt_pk_bf16_f32 v74, v81, v82
	v_cvt_pk_bf16_f32 v75, v83, v75
	global_store_dwordx4 v[76:77], v[72:75], off
	v_mul_f32_e32 v68, v68, v80
	v_mul_f32_e32 v69, v69, v80
	v_mul_f32_e32 v72, v64, v80
	v_mul_f32_e32 v70, v70, v80
	v_mul_f32_e32 v71, v71, v80
	v_mul_f32_e32 v73, v65, v80
	v_mul_f32_e32 v74, v66, v80
	v_cvt_pk_bf16_f32 v64, v68, v69
	v_cvt_pk_bf16_f32 v65, v70, v71
	v_cvt_pk_bf16_f32 v66, v72, v73
	v_add_u32_e32 v72, 0x80, v138
	v_mul_f32_e32 v67, v67, v80
	v_ashrrev_i32_e32 v73, 31, v72
	v_cvt_pk_bf16_f32 v67, v74, v67
	global_store_dwordx4 v[76:77], v[64:67], off offset:256
	s_nop 1
	v_lshlrev_b64 v[64:65], 5, v[72:73]
	v_lshl_add_u64 v[68:69], s[4:5], 0, v[64:65]
	global_load_dwordx4 v[64:67], v[68:69], off offset:16
	s_nop 0
	global_load_dwordx4 v[68:71], v[68:69], off
	s_waitcnt vmcnt(0)
	v_add_f32_e32 v68, v68, v69
	v_add_f32_e32 v68, v70, v68
	v_add_f32_e32 v68, v71, v68
	v_add_f32_e32 v64, v64, v68
	v_add_f32_e32 v64, v65, v64
	v_add_f32_e32 v64, v66, v64
	v_add_f32_e32 v64, v67, v64
	v_add_f32_e32 v64, 0x3a0637bd, v64
	v_mul_f32_e32 v64, 0x3b000000, v64
	v_cmp_gt_f32_e32 vcc, s67, v64
	v_mul_f32_e32 v65, 0x4b800000, v64
	s_nop 0
	v_cndmask_b32_e32 v64, v64, v65, vcc
	v_rsq_f32_e32 v64, v64
	s_nop 0
	v_mul_f32_e32 v65, 0x45800000, v64
	v_cndmask_b32_e32 v64, v64, v65, vcc
	v_mul_f32_e32 v60, v60, v64
	v_mul_f32_e32 v61, v61, v64
	v_mul_f32_e32 v65, v56, v64
	v_cvt_pk_bf16_f32 v56, v60, v61
	v_lshlrev_b64 v[60:61], 12, v[72:73]
	v_lshl_add_u64 v[60:61], s[2:3], 0, v[60:61]
	v_mul_f32_e32 v59, v59, v64
	v_lshl_add_u64 v[60:61], v[60:61], 0, v[120:121]
	v_mul_f32_e32 v62, v62, v64
	v_mul_f32_e32 v63, v63, v64
	v_mul_f32_e32 v66, v57, v64
	v_mul_f32_e32 v67, v58, v64
	v_cvt_pk_bf16_f32 v57, v62, v63
	v_cvt_pk_bf16_f32 v58, v65, v66
	v_cvt_pk_bf16_f32 v59, v67, v59
	global_store_dwordx4 v[60:61], v[56:59], off
	v_mul_f32_e32 v52, v52, v64
	v_mul_f32_e32 v53, v53, v64
	v_mul_f32_e32 v56, v48, v64
	v_mul_f32_e32 v54, v54, v64
	v_mul_f32_e32 v55, v55, v64
	v_mul_f32_e32 v57, v49, v64
	v_mul_f32_e32 v58, v50, v64
	v_cvt_pk_bf16_f32 v48, v52, v53
	v_cvt_pk_bf16_f32 v49, v54, v55
	v_cvt_pk_bf16_f32 v50, v56, v57
	v_add_u32_e32 v56, 0x90, v138
	v_mul_f32_e32 v51, v51, v64
	v_ashrrev_i32_e32 v57, 31, v56
	v_cvt_pk_bf16_f32 v51, v58, v51
	global_store_dwordx4 v[60:61], v[48:51], off offset:256
	s_nop 1
	v_lshlrev_b64 v[48:49], 5, v[56:57]
	v_lshl_add_u64 v[52:53], s[4:5], 0, v[48:49]
	global_load_dwordx4 v[48:51], v[52:53], off offset:16
	s_nop 0
	global_load_dwordx4 v[52:55], v[52:53], off
	s_waitcnt vmcnt(0)
	v_add_f32_e32 v52, v52, v53
	v_add_f32_e32 v52, v54, v52
	v_add_f32_e32 v52, v55, v52
	v_add_f32_e32 v48, v48, v52
	v_add_f32_e32 v48, v49, v48
	v_add_f32_e32 v48, v50, v48
	v_add_f32_e32 v48, v51, v48
	v_add_f32_e32 v48, 0x3a0637bd, v48
	v_mul_f32_e32 v48, 0x3b000000, v48
	v_cmp_gt_f32_e32 vcc, s67, v48
	v_mul_f32_e32 v49, 0x4b800000, v48
	s_nop 0
	v_cndmask_b32_e32 v48, v48, v49, vcc
	v_rsq_f32_e32 v48, v48
	s_nop 0
	v_mul_f32_e32 v49, 0x45800000, v48
	v_cndmask_b32_e32 v48, v48, v49, vcc
	v_mul_f32_e32 v44, v44, v48
	v_mul_f32_e32 v45, v45, v48
	v_mul_f32_e32 v49, v40, v48
	v_cvt_pk_bf16_f32 v40, v44, v45
	v_lshlrev_b64 v[44:45], 12, v[56:57]
	v_lshl_add_u64 v[44:45], s[2:3], 0, v[44:45]
	v_mul_f32_e32 v43, v43, v48
	v_lshl_add_u64 v[44:45], v[44:45], 0, v[120:121]
	v_mul_f32_e32 v46, v46, v48
	v_mul_f32_e32 v47, v47, v48
	v_mul_f32_e32 v50, v41, v48
	v_mul_f32_e32 v51, v42, v48
	v_cvt_pk_bf16_f32 v41, v46, v47
	v_cvt_pk_bf16_f32 v42, v49, v50
	v_cvt_pk_bf16_f32 v43, v51, v43
	global_store_dwordx4 v[44:45], v[40:43], off
	v_mul_f32_e32 v36, v36, v48
	v_mul_f32_e32 v37, v37, v48
	v_mul_f32_e32 v40, v32, v48
	v_mul_f32_e32 v38, v38, v48
	v_mul_f32_e32 v39, v39, v48
	v_mul_f32_e32 v41, v33, v48
	v_mul_f32_e32 v42, v34, v48
	v_cvt_pk_bf16_f32 v32, v36, v37
	v_cvt_pk_bf16_f32 v33, v38, v39
	v_cvt_pk_bf16_f32 v34, v40, v41
	v_add_u32_e32 v40, 0xa0, v138
	v_mul_f32_e32 v35, v35, v48
	v_ashrrev_i32_e32 v41, 31, v40
	v_cvt_pk_bf16_f32 v35, v42, v35
	global_store_dwordx4 v[44:45], v[32:35], off offset:256
	s_nop 1
	v_lshlrev_b64 v[32:33], 5, v[40:41]
	v_lshl_add_u64 v[36:37], s[4:5], 0, v[32:33]
	global_load_dwordx4 v[32:35], v[36:37], off offset:16
	s_nop 0
	global_load_dwordx4 v[36:39], v[36:37], off
	s_waitcnt vmcnt(0)
	v_add_f32_e32 v36, v36, v37
	v_add_f32_e32 v36, v38, v36
	v_add_f32_e32 v36, v39, v36
	v_add_f32_e32 v32, v32, v36
	v_add_f32_e32 v32, v33, v32
	v_add_f32_e32 v32, v34, v32
	v_add_f32_e32 v32, v35, v32
	v_add_f32_e32 v32, 0x3a0637bd, v32
	v_mul_f32_e32 v32, 0x3b000000, v32
	v_cmp_gt_f32_e32 vcc, s67, v32
	v_mul_f32_e32 v33, 0x4b800000, v32
	s_nop 0
	v_cndmask_b32_e32 v32, v32, v33, vcc
	v_rsq_f32_e32 v32, v32
	s_nop 0
	v_mul_f32_e32 v33, 0x45800000, v32
	v_cndmask_b32_e32 v32, v32, v33, vcc
	v_mul_f32_e32 v28, v28, v32
	v_mul_f32_e32 v29, v29, v32
	v_mul_f32_e32 v33, v24, v32
	v_cvt_pk_bf16_f32 v24, v28, v29
	v_lshlrev_b64 v[28:29], 12, v[40:41]
	v_lshl_add_u64 v[28:29], s[2:3], 0, v[28:29]
	v_mul_f32_e32 v27, v27, v32
	v_lshl_add_u64 v[28:29], v[28:29], 0, v[120:121]
	v_mul_f32_e32 v30, v30, v32
	v_mul_f32_e32 v31, v31, v32
	v_mul_f32_e32 v34, v25, v32
	v_mul_f32_e32 v35, v26, v32
	v_cvt_pk_bf16_f32 v25, v30, v31
	v_cvt_pk_bf16_f32 v26, v33, v34
	v_cvt_pk_bf16_f32 v27, v35, v27
	global_store_dwordx4 v[28:29], v[24:27], off
	v_mul_f32_e32 v20, v20, v32
	v_mul_f32_e32 v21, v21, v32
	v_mul_f32_e32 v24, v16, v32
	v_mul_f32_e32 v22, v22, v32
	v_mul_f32_e32 v23, v23, v32
	v_mul_f32_e32 v25, v17, v32
	v_mul_f32_e32 v26, v18, v32
	v_cvt_pk_bf16_f32 v16, v20, v21
	v_cvt_pk_bf16_f32 v17, v22, v23
	v_cvt_pk_bf16_f32 v18, v24, v25
	v_add_u32_e32 v24, 0xb0, v138
	v_mul_f32_e32 v19, v19, v32
	v_ashrrev_i32_e32 v25, 31, v24
	v_cvt_pk_bf16_f32 v19, v26, v19
	global_store_dwordx4 v[28:29], v[16:19], off offset:256
	s_nop 1
	v_lshlrev_b64 v[16:17], 5, v[24:25]
	v_lshl_add_u64 v[20:21], s[4:5], 0, v[16:17]
	global_load_dwordx4 v[16:19], v[20:21], off offset:16
	s_nop 0
	global_load_dwordx4 v[20:23], v[20:21], off
	s_waitcnt vmcnt(0)
	v_add_f32_e32 v20, v20, v21
	v_add_f32_e32 v20, v22, v20
	v_add_f32_e32 v20, v23, v20
	v_add_f32_e32 v16, v16, v20
	v_add_f32_e32 v16, v17, v16
	v_add_f32_e32 v16, v18, v16
	v_add_f32_e32 v16, v19, v16
	v_add_f32_e32 v16, 0x3a0637bd, v16
	v_mul_f32_e32 v16, 0x3b000000, v16
	v_cmp_gt_f32_e32 vcc, s67, v16
	v_mul_f32_e32 v17, 0x4b800000, v16
	s_nop 0
	v_cndmask_b32_e32 v16, v16, v17, vcc
	v_rsq_f32_e32 v16, v16
	s_nop 0
	v_mul_f32_e32 v17, 0x45800000, v16
	v_cndmask_b32_e32 v16, v16, v17, vcc
	v_mul_f32_e32 v12, v12, v16
	v_mul_f32_e32 v13, v13, v16
	v_mul_f32_e32 v17, v8, v16
	v_cvt_pk_bf16_f32 v8, v12, v13
	v_lshlrev_b64 v[12:13], 12, v[24:25]
	v_lshl_add_u64 v[12:13], s[2:3], 0, v[12:13]
	v_mul_f32_e32 v14, v14, v16
	v_mul_f32_e32 v15, v15, v16
	v_mul_f32_e32 v18, v9, v16
	v_mul_f32_e32 v19, v10, v16
	v_mul_f32_e32 v11, v11, v16
	v_cvt_pk_bf16_f32 v9, v14, v15
	v_cvt_pk_bf16_f32 v10, v17, v18
	v_lshl_add_u64 v[12:13], v[12:13], 0, v[120:121]
	v_mul_f32_e32 v3, v3, v16
	s_and_b64 vcc, exec, s[10:11]
	v_cvt_pk_bf16_f32 v11, v19, v11
	global_store_dwordx4 v[12:13], v[8:11], off
	v_mul_f32_e32 v4, v4, v16
	v_mul_f32_e32 v5, v5, v16
	v_mul_f32_e32 v6, v6, v16
	v_mul_f32_e32 v7, v7, v16
	v_mul_f32_e32 v8, v0, v16
	v_mul_f32_e32 v9, v1, v16
	v_mul_f32_e32 v10, v2, v16
	v_cvt_pk_bf16_f32 v0, v4, v5
	v_cvt_pk_bf16_f32 v1, v6, v7
	v_cvt_pk_bf16_f32 v2, v8, v9
	v_cvt_pk_bf16_f32 v3, v10, v3
	global_store_dwordx4 v[12:13], v[0:3], off offset:256
	s_cbranch_vccz .LBB0_114
	s_waitcnt vmcnt(0)
	v_readlane_b32 s40, v244, 49
	s_cmpk_gt_u32 s27, 0xff
	v_readlane_b32 s41, v244, 50
	v_readlane_b32 s46, v244, 55
	v_readlane_b32 s47, v244, 56
	v_readlane_b32 s48, v244, 57
	v_readlane_b32 s49, v244, 58
	v_readlane_b32 s50, v244, 59
	v_readlane_b32 s51, v244, 60
	v_readlane_b32 s42, v244, 51
	v_readlane_b32 s43, v244, 52
	v_readlane_b32 s44, v244, 53
	v_readlane_b32 s45, v244, 54
	v_readlane_b32 s52, v244, 61
	v_readlane_b32 s53, v244, 62
	v_readlane_b32 s54, v244, 63
	v_readlane_b32 s55, v243, 0
	s_cbranch_scc1 .LBB0_121
	s_barrier

.LBB0_136:
	s_ashr_i32 s9, s8, 31
	s_lshl_b64 s[12:13], s[8:9], 18
	s_add_u32 s12, s23, s12
	s_addc_u32 s13, s27, s13
	s_and_b64 s[14:15], s[20:21], exec
	s_cselect_b32 s9, s13, s17
	s_cselect_b32 s39, s12, s16
	s_ashr_i32 s11, s10, 31
	s_lshl_b64 s[14:15], s[10:11], 18
	s_add_u32 s14, s24, s14
	s_addc_u32 s15, s25, s15
	s_and_b64 s[20:21], s[20:21], exec
	s_cselect_b32 s11, s15, s19
	s_cselect_b32 s40, s14, s18
	s_add_u32 s16, s16, 0x20080
	s_addc_u32 s17, s17, 0
	s_add_u32 s41, s18, 0x100
	v_mov_b32_e32 v0, 0
	s_addc_u32 s42, s19, 0
	s_mov_b32 s43, -2
	v_mov_b32_e32 v1, v0
	v_mov_b32_e32 v2, v0
	v_mov_b32_e32 v3, v0
	v_mov_b32_e32 v32, v0
	v_mov_b32_e32 v33, v0
	v_mov_b32_e32 v34, v0
	v_mov_b32_e32 v35, v0
	v_mov_b32_e32 v4, v0
	v_mov_b32_e32 v5, v0
	v_mov_b32_e32 v6, v0
	v_mov_b32_e32 v7, v0
	v_mov_b32_e32 v36, v0
	v_mov_b32_e32 v37, v0
	v_mov_b32_e32 v38, v0
	v_mov_b32_e32 v39, v0
	v_mov_b32_e32 v8, v0
	v_mov_b32_e32 v9, v0
	v_mov_b32_e32 v10, v0
	v_mov_b32_e32 v11, v0
	v_mov_b32_e32 v40, v0
	v_mov_b32_e32 v41, v0
	v_mov_b32_e32 v42, v0
	v_mov_b32_e32 v43, v0
	v_mov_b32_e32 v12, v0
	v_mov_b32_e32 v13, v0
	v_mov_b32_e32 v14, v0
	v_mov_b32_e32 v15, v0
	v_mov_b32_e32 v44, v0
	v_mov_b32_e32 v45, v0
	v_mov_b32_e32 v46, v0
	v_mov_b32_e32 v47, v0
	v_mov_b32_e32 v64, v0
	v_mov_b32_e32 v65, v0
	v_mov_b32_e32 v66, v0
	v_mov_b32_e32 v67, v0
	v_mov_b32_e32 v96, v0
	v_mov_b32_e32 v97, v0
	v_mov_b32_e32 v98, v0
	v_mov_b32_e32 v99, v0
	v_mov_b32_e32 v68, v0
	v_mov_b32_e32 v69, v0
	v_mov_b32_e32 v70, v0
	v_mov_b32_e32 v71, v0
	v_mov_b32_e32 v100, v0
	v_mov_b32_e32 v101, v0
	v_mov_b32_e32 v102, v0
	v_mov_b32_e32 v103, v0
	v_mov_b32_e32 v72, v0
	v_mov_b32_e32 v73, v0
	v_mov_b32_e32 v74, v0
	v_mov_b32_e32 v75, v0
	v_mov_b32_e32 v104, v0
	v_mov_b32_e32 v105, v0
	v_mov_b32_e32 v106, v0
	v_mov_b32_e32 v107, v0
	v_mov_b32_e32 v76, v0
	v_mov_b32_e32 v77, v0
	v_mov_b32_e32 v78, v0
	v_mov_b32_e32 v79, v0
	v_mov_b32_e32 v108, v0
	v_mov_b32_e32 v109, v0
	v_mov_b32_e32 v110, v0
	v_mov_b32_e32 v111, v0
	v_mov_b32_e32 v16, v0
	v_mov_b32_e32 v17, v0
	v_mov_b32_e32 v18, v0
	v_mov_b32_e32 v19, v0
	v_mov_b32_e32 v48, v0
	v_mov_b32_e32 v49, v0
	v_mov_b32_e32 v50, v0
	v_mov_b32_e32 v51, v0
	v_mov_b32_e32 v20, v0
	v_mov_b32_e32 v21, v0
	v_mov_b32_e32 v22, v0
	v_mov_b32_e32 v23, v0
	v_mov_b32_e32 v52, v0
	v_mov_b32_e32 v53, v0
	v_mov_b32_e32 v54, v0
	v_mov_b32_e32 v55, v0
	v_mov_b32_e32 v24, v0
	v_mov_b32_e32 v25, v0
	v_mov_b32_e32 v26, v0
	v_mov_b32_e32 v27, v0
	v_mov_b32_e32 v56, v0
	v_mov_b32_e32 v57, v0
	v_mov_b32_e32 v58, v0
	v_mov_b32_e32 v59, v0
	v_mov_b32_e32 v28, v0
	v_mov_b32_e32 v29, v0
	v_mov_b32_e32 v30, v0
	v_mov_b32_e32 v31, v0
	v_mov_b32_e32 v60, v0
	v_mov_b32_e32 v61, v0
	v_mov_b32_e32 v62, v0
	v_mov_b32_e32 v63, v0
	v_mov_b32_e32 v80, v0
	v_mov_b32_e32 v81, v0
	v_mov_b32_e32 v82, v0
	v_mov_b32_e32 v83, v0
	v_mov_b32_e32 v112, v0
	v_mov_b32_e32 v113, v0
	v_mov_b32_e32 v114, v0
	v_mov_b32_e32 v115, v0
	v_mov_b32_e32 v84, v0
	v_mov_b32_e32 v85, v0
	v_mov_b32_e32 v86, v0
	v_mov_b32_e32 v87, v0
	v_mov_b32_e32 v116, v0
	v_mov_b32_e32 v117, v0
	v_mov_b32_e32 v118, v0
	v_mov_b32_e32 v119, v0
	v_mov_b32_e32 v88, v0
	v_mov_b32_e32 v89, v0
	v_mov_b32_e32 v90, v0
	v_mov_b32_e32 v91, v0
	v_mov_b32_e32 v120, v0
	v_mov_b32_e32 v121, v0
	v_mov_b32_e32 v122, v0
	v_mov_b32_e32 v123, v0
	v_mov_b32_e32 v92, v0
	v_mov_b32_e32 v93, v0
	v_mov_b32_e32 v94, v0
	v_mov_b32_e32 v95, v0
	v_mov_b32_e32 v124, v0
	v_mov_b32_e32 v125, v0
	v_mov_b32_e32 v126, v0
	v_mov_b32_e32 v127, v0
	s_mov_b64 s[48:49], 0x80
	v_add_u32_e32 v152, 0x10000, v146
	ds_read_b128 v[134:137], v152
	ds_read_b128 v[138:141], v152 offset:1024
	ds_read_b128 v[148:151], v152 offset:2048
	ds_read_b128 v[152:155], v152 offset:3072
	ds_read_b128 v[248:251], v147 offset:6144
	ds_read_b128 v[252:255], v147 offset:7168
.LBB0_137:
	s_add_u32 s18, s16, 0xfffe0080
	s_addc_u32 s19, s17, -1
	s_add_i32 s44, 0, 0x10000
	v_add_u32_e32 v142, s44, v146
	s_cmp_eq_u32 s43, 4
	s_cselect_b32 s21, s9, s19
	s_cselect_b32 s20, s39, s18
	s_cselect_b32 s19, s11, s42
	s_cselect_b32 s18, s40, s41
	v_lshl_add_u64 v[142:143], s[16:17], 0, v[130:131]
	s_add_i32 m0, s29, 0xc000
	ds_read_b128 v[156:159], v147
	ds_read_b128 v[160:163], v147 offset:1024
	ds_read_b128 v[164:167], v147 offset:2048
	ds_read_b128 v[168:171], v147 offset:3072
	ds_read_b128 v[172:175], v147 offset:4096
	ds_read_b128 v[176:179], v147 offset:5120
	global_load_lds_dwordx4 v[142:143], off
	v_lshl_add_u64 v[142:143], s[16:17], 0, v[132:133]
	s_add_i32 m0, s29, 0xe000
	s_nop 0
	global_load_lds_dwordx4 v[142:143], off
	s_waitcnt lgkmcnt(8)
	s_setprio 1
	s_waitcnt vmcnt(8)
	s_barrier
	s_waitcnt lgkmcnt(0)
	v_mfma_f32_16x16x32_bf16 v[124:127], v[134:137], v[156:159], v[124:127]
	v_mfma_f32_16x16x32_bf16 v[92:95], v[148:151], v[156:159], v[92:95]
	v_mfma_f32_16x16x32_bf16 v[120:123], v[134:137], v[164:167], v[120:123]
	v_mfma_f32_16x16x32_bf16 v[88:91], v[148:151], v[164:167], v[88:91]
	v_mfma_f32_16x16x32_bf16 v[116:119], v[134:137], v[172:175], v[116:119]
	v_mfma_f32_16x16x32_bf16 v[84:87], v[148:151], v[172:175], v[84:87]
	v_mfma_f32_16x16x32_bf16 v[112:115], v[134:137], v[248:251], v[112:115]
	v_mfma_f32_16x16x32_bf16 v[80:83], v[148:151], v[248:251], v[80:83]
	v_mfma_f32_16x16x32_bf16 v[124:127], v[138:141], v[160:163], v[124:127]
	v_mfma_f32_16x16x32_bf16 v[92:95], v[152:155], v[160:163], v[92:95]
	v_mfma_f32_16x16x32_bf16 v[120:123], v[138:141], v[168:171], v[120:123]
	v_mfma_f32_16x16x32_bf16 v[88:91], v[152:155], v[168:171], v[88:91]
	v_mfma_f32_16x16x32_bf16 v[116:119], v[138:141], v[176:179], v[116:119]
	v_mfma_f32_16x16x32_bf16 v[84:87], v[152:155], v[176:179], v[84:87]
	v_mfma_f32_16x16x32_bf16 v[112:115], v[138:141], v[252:255], v[112:115]
	v_mfma_f32_16x16x32_bf16 v[80:83], v[152:155], v[252:255], v[80:83]
	s_barrier
	s_setprio 0
	ds_read_b128 v[180:183], v147 offset:22528
	ds_read_b128 v[188:191], v147 offset:23552
	s_add_i32 s46, 0, 0x14000
	v_add_u32_e32 v142, s46, v146
	s_add_i32 s44, s44, s28
	ds_read_b128 v[192:195], v142
	ds_read_b128 v[202:205], v142 offset:1024
	ds_read_b128 v[206:209], v142 offset:2048
	ds_read_b128 v[210:213], v142 offset:3072
	v_lshl_add_u64 v[142:143], s[18:19], 0, v[184:185]
	s_mov_b32 m0, s44
	v_lshl_add_u64 v[196:197], s[18:19], 0, v[128:129]
	global_load_lds_dwordx4 v[142:143], off
	s_add_i32 m0, s44, 0x2000
	s_nop 0
	global_load_lds_dwordx4 v[196:197], off
	s_setprio 1
	s_barrier
	s_waitcnt lgkmcnt(0)
	v_mfma_f32_16x16x32_bf16 v[60:63], v[192:195], v[156:159], v[60:63]
	v_mfma_f32_16x16x32_bf16 v[28:31], v[206:209], v[156:159], v[28:31]
	v_mfma_f32_16x16x32_bf16 v[56:59], v[192:195], v[164:167], v[56:59]
	v_mfma_f32_16x16x32_bf16 v[24:27], v[206:209], v[164:167], v[24:27]
	v_mfma_f32_16x16x32_bf16 v[52:55], v[192:195], v[172:175], v[52:55]
	v_mfma_f32_16x16x32_bf16 v[20:23], v[206:209], v[172:175], v[20:23]
	v_mfma_f32_16x16x32_bf16 v[48:51], v[192:195], v[248:251], v[48:51]
	v_mfma_f32_16x16x32_bf16 v[16:19], v[206:209], v[248:251], v[16:19]
	v_mfma_f32_16x16x32_bf16 v[60:63], v[202:205], v[160:163], v[60:63]
	v_mfma_f32_16x16x32_bf16 v[28:31], v[210:213], v[160:163], v[28:31]
	v_mfma_f32_16x16x32_bf16 v[56:59], v[202:205], v[168:171], v[56:59]
	v_mfma_f32_16x16x32_bf16 v[24:27], v[210:213], v[168:171], v[24:27]
	v_mfma_f32_16x16x32_bf16 v[52:55], v[202:205], v[176:179], v[52:55]
	v_mfma_f32_16x16x32_bf16 v[20:23], v[210:213], v[176:179], v[20:23]
	v_mfma_f32_16x16x32_bf16 v[48:51], v[202:205], v[252:255], v[48:51]
	v_mfma_f32_16x16x32_bf16 v[16:19], v[210:213], v[252:255], v[16:19]
	s_barrier
	s_setprio 0
	s_mov_b32 m0, s29
	v_lshl_add_u64 v[214:215], s[20:21], 0, v[184:185]
	ds_read_b128 v[156:159], v147 offset:16384
	ds_read_b128 v[160:163], v147 offset:17408
	ds_read_b128 v[164:167], v147 offset:18432
	ds_read_b128 v[168:171], v147 offset:19456
	ds_read_b128 v[172:175], v147 offset:20480
	ds_read_b128 v[176:179], v147 offset:21504
	global_load_lds_dwordx4 v[214:215], off
	v_lshl_add_u64 v[216:217], s[20:21], 0, v[128:129]
	s_mov_b32 m0, s30
	s_nop 0
	global_load_lds_dwordx4 v[216:217], off
	s_setprio 1
	s_waitcnt vmcnt(8)
	s_barrier
	s_waitcnt lgkmcnt(0)
	v_mfma_f32_16x16x32_bf16 v[108:111], v[134:137], v[156:159], v[108:111]
	v_mfma_f32_16x16x32_bf16 v[76:79], v[148:151], v[156:159], v[76:79]
	v_mfma_f32_16x16x32_bf16 v[104:107], v[134:137], v[164:167], v[104:107]
	v_mfma_f32_16x16x32_bf16 v[72:75], v[148:151], v[164:167], v[72:75]
	v_mfma_f32_16x16x32_bf16 v[100:103], v[134:137], v[172:175], v[100:103]
	v_mfma_f32_16x16x32_bf16 v[68:71], v[148:151], v[172:175], v[68:71]
	v_mfma_f32_16x16x32_bf16 v[96:99], v[134:137], v[180:183], v[96:99]
	v_mfma_f32_16x16x32_bf16 v[64:67], v[148:151], v[180:183], v[64:67]
	v_mfma_f32_16x16x32_bf16 v[108:111], v[138:141], v[160:163], v[108:111]
	v_mfma_f32_16x16x32_bf16 v[76:79], v[152:155], v[160:163], v[76:79]
	v_mfma_f32_16x16x32_bf16 v[104:107], v[138:141], v[168:171], v[104:107]
	v_mfma_f32_16x16x32_bf16 v[72:75], v[152:155], v[168:171], v[72:75]
	v_mfma_f32_16x16x32_bf16 v[100:103], v[138:141], v[176:179], v[100:103]
	v_mfma_f32_16x16x32_bf16 v[68:71], v[152:155], v[176:179], v[68:71]
	v_mfma_f32_16x16x32_bf16 v[96:99], v[138:141], v[188:191], v[96:99]
	v_mfma_f32_16x16x32_bf16 v[64:67], v[152:155], v[188:191], v[64:67]
	s_barrier
	s_setprio 0
	v_add_u32_e32 v152, 0x18000, v146
	ds_read_b128 v[134:137], v152
	ds_read_b128 v[138:141], v152 offset:1024
	ds_read_b128 v[148:151], v152 offset:2048
	ds_read_b128 v[152:155], v152 offset:3072
	ds_read_b128 v[248:251], v147 offset:38912
	ds_read_b128 v[252:255], v147 offset:39936
	s_add_u32 s44, s18, 0x20000
	s_addc_u32 s45, s19, 0
	s_add_i32 s46, s46, s28
	v_lshl_add_u64 v[246:247], s[44:45], 0, v[184:185]
	s_mov_b32 m0, s46
	s_nop 0
	global_load_lds_dwordx4 v[246:247], off
	v_lshl_add_u64 v[246:247], s[44:45], 0, v[128:129]
	s_add_i32 m0, s46, 0x2000
	s_nop 0
	global_load_lds_dwordx4 v[246:247], off
	s_waitcnt vmcnt(6)
	s_setprio 1
	s_barrier
	v_mfma_f32_16x16x32_bf16 v[44:47], v[192:195], v[156:159], v[44:47]
	v_mfma_f32_16x16x32_bf16 v[12:15], v[206:209], v[156:159], v[12:15]
	v_mfma_f32_16x16x32_bf16 v[40:43], v[192:195], v[164:167], v[40:43]
	v_mfma_f32_16x16x32_bf16 v[8:11], v[206:209], v[164:167], v[8:11]
	v_mfma_f32_16x16x32_bf16 v[36:39], v[192:195], v[172:175], v[36:39]
	v_mfma_f32_16x16x32_bf16 v[4:7], v[206:209], v[172:175], v[4:7]
	v_mfma_f32_16x16x32_bf16 v[32:35], v[192:195], v[180:183], v[32:35]
	v_mfma_f32_16x16x32_bf16 v[0:3], v[206:209], v[180:183], v[0:3]
	v_mfma_f32_16x16x32_bf16 v[44:47], v[202:205], v[160:163], v[44:47]
	v_mfma_f32_16x16x32_bf16 v[12:15], v[210:213], v[160:163], v[12:15]
	v_mfma_f32_16x16x32_bf16 v[40:43], v[202:205], v[168:171], v[40:43]
	v_mfma_f32_16x16x32_bf16 v[8:11], v[210:213], v[168:171], v[8:11]
	v_mfma_f32_16x16x32_bf16 v[36:39], v[202:205], v[176:179], v[36:39]
	v_mfma_f32_16x16x32_bf16 v[4:7], v[210:213], v[176:179], v[4:7]
	v_mfma_f32_16x16x32_bf16 v[32:35], v[202:205], v[188:191], v[32:35]
	v_mfma_f32_16x16x32_bf16 v[0:3], v[210:213], v[188:191], v[0:3]
	s_barrier
	s_setprio 0
	s_add_i32 s44, 0, 0x18000
	s_add_u32 s20, s20, 0x20000
	s_addc_u32 s21, s21, 0
	s_mov_b32 m0, s31
	v_lshl_add_u64 v[192:193], s[20:21], 0, v[184:185]
	ds_read_b128 v[156:159], v147 offset:32768
	ds_read_b128 v[160:163], v147 offset:33792
	ds_read_b128 v[164:167], v147 offset:34816
	ds_read_b128 v[168:171], v147 offset:35840
	ds_read_b128 v[172:175], v147 offset:36864
	ds_read_b128 v[176:179], v147 offset:37888
	global_load_lds_dwordx4 v[192:193], off
	v_lshl_add_u64 v[192:193], s[20:21], 0, v[128:129]
	s_mov_b32 m0, s33
	s_nop 0
	global_load_lds_dwordx4 v[192:193], off
	s_waitcnt lgkmcnt(8)
	s_setprio 1
	s_waitcnt vmcnt(8)
	s_barrier
	s_waitcnt lgkmcnt(0)
	v_mfma_f32_16x16x32_bf16 v[124:127], v[134:137], v[156:159], v[124:127]
	v_mfma_f32_16x16x32_bf16 v[92:95], v[148:151], v[156:159], v[92:95]
	v_mfma_f32_16x16x32_bf16 v[120:123], v[134:137], v[164:167], v[120:123]
	v_mfma_f32_16x16x32_bf16 v[88:91], v[148:151], v[164:167], v[88:91]
	v_mfma_f32_16x16x32_bf16 v[116:119], v[134:137], v[172:175], v[116:119]
	v_mfma_f32_16x16x32_bf16 v[84:87], v[148:151], v[172:175], v[84:87]
	v_mfma_f32_16x16x32_bf16 v[112:115], v[134:137], v[248:251], v[112:115]
	v_mfma_f32_16x16x32_bf16 v[80:83], v[148:151], v[248:251], v[80:83]
	v_mfma_f32_16x16x32_bf16 v[124:127], v[138:141], v[160:163], v[124:127]
	v_mfma_f32_16x16x32_bf16 v[92:95], v[152:155], v[160:163], v[92:95]
	v_mfma_f32_16x16x32_bf16 v[120:123], v[138:141], v[168:171], v[120:123]
	v_mfma_f32_16x16x32_bf16 v[88:91], v[152:155], v[168:171], v[88:91]
	v_mfma_f32_16x16x32_bf16 v[116:119], v[138:141], v[176:179], v[116:119]
	v_mfma_f32_16x16x32_bf16 v[84:87], v[152:155], v[176:179], v[84:87]
	v_mfma_f32_16x16x32_bf16 v[112:115], v[138:141], v[252:255], v[112:115]
	v_mfma_f32_16x16x32_bf16 v[80:83], v[152:155], v[252:255], v[80:83]
	s_barrier
	s_setprio 0
	ds_read_b128 v[180:183], v147 offset:55296
	ds_read_b128 v[188:191], v147 offset:56320
	s_add_i32 s20, 0, 0x1c000
	s_add_i32 s21, s44, s28
	v_add_u32_e32 v187, s20, v146
	v_lshl_add_u64 v[142:143], v[142:143], 0, s[48:49]
	s_mov_b32 m0, s21
	ds_read_b128 v[192:195], v187
	ds_read_b128 v[202:205], v187 offset:1024
	ds_read_b128 v[206:209], v187 offset:2048
	ds_read_b128 v[210:213], v187 offset:3072
	global_load_lds_dwordx4 v[142:143], off
	v_lshl_add_u64 v[142:143], v[196:197], 0, s[48:49]
	s_add_i32 m0, s21, 0x2000
	s_nop 0
	global_load_lds_dwordx4 v[142:143], off
	s_setprio 1
	s_barrier
	s_waitcnt lgkmcnt(0)
	v_mfma_f32_16x16x32_bf16 v[60:63], v[192:195], v[156:159], v[60:63]
	v_mfma_f32_16x16x32_bf16 v[28:31], v[206:209], v[156:159], v[28:31]
	v_mfma_f32_16x16x32_bf16 v[56:59], v[192:195], v[164:167], v[56:59]
	v_mfma_f32_16x16x32_bf16 v[24:27], v[206:209], v[164:167], v[24:27]
	v_mfma_f32_16x16x32_bf16 v[52:55], v[192:195], v[172:175], v[52:55]
	v_mfma_f32_16x16x32_bf16 v[20:23], v[206:209], v[172:175], v[20:23]
	v_mfma_f32_16x16x32_bf16 v[48:51], v[192:195], v[248:251], v[48:51]
	v_mfma_f32_16x16x32_bf16 v[16:19], v[206:209], v[248:251], v[16:19]
	v_mfma_f32_16x16x32_bf16 v[60:63], v[202:205], v[160:163], v[60:63]
	v_mfma_f32_16x16x32_bf16 v[28:31], v[210:213], v[160:163], v[28:31]
	v_mfma_f32_16x16x32_bf16 v[56:59], v[202:205], v[168:171], v[56:59]
	v_mfma_f32_16x16x32_bf16 v[24:27], v[210:213], v[168:171], v[24:27]
	v_mfma_f32_16x16x32_bf16 v[52:55], v[202:205], v[176:179], v[52:55]
	v_mfma_f32_16x16x32_bf16 v[20:23], v[210:213], v[176:179], v[20:23]
	v_mfma_f32_16x16x32_bf16 v[48:51], v[202:205], v[252:255], v[48:51]
	v_mfma_f32_16x16x32_bf16 v[16:19], v[210:213], v[252:255], v[16:19]
	s_barrier
	s_setprio 0
	s_mov_b32 m0, s36
	v_lshl_add_u64 v[142:143], v[214:215], 0, s[48:49]
	ds_read_b128 v[156:159], v147 offset:49152
	ds_read_b128 v[160:163], v147 offset:50176
	ds_read_b128 v[164:167], v147 offset:51200
	ds_read_b128 v[168:171], v147 offset:52224
	ds_read_b128 v[172:175], v147 offset:53248
	ds_read_b128 v[176:179], v147 offset:54272
	global_load_lds_dwordx4 v[142:143], off
	v_lshl_add_u64 v[142:143], v[216:217], 0, s[48:49]
	s_mov_b32 m0, s37
	s_nop 0
	global_load_lds_dwordx4 v[142:143], off
	s_setprio 1
	s_waitcnt vmcnt(8)
	s_barrier
	s_waitcnt lgkmcnt(0)
	v_mfma_f32_16x16x32_bf16 v[108:111], v[134:137], v[156:159], v[108:111]
	v_mfma_f32_16x16x32_bf16 v[76:79], v[148:151], v[156:159], v[76:79]
	v_mfma_f32_16x16x32_bf16 v[104:107], v[134:137], v[164:167], v[104:107]
	v_mfma_f32_16x16x32_bf16 v[72:75], v[148:151], v[164:167], v[72:75]
	v_mfma_f32_16x16x32_bf16 v[100:103], v[134:137], v[172:175], v[100:103]
	v_mfma_f32_16x16x32_bf16 v[68:71], v[148:151], v[172:175], v[68:71]
	v_mfma_f32_16x16x32_bf16 v[96:99], v[134:137], v[180:183], v[96:99]
	v_mfma_f32_16x16x32_bf16 v[64:67], v[148:151], v[180:183], v[64:67]
	v_mfma_f32_16x16x32_bf16 v[108:111], v[138:141], v[160:163], v[108:111]
	v_mfma_f32_16x16x32_bf16 v[76:79], v[152:155], v[160:163], v[76:79]
	v_mfma_f32_16x16x32_bf16 v[104:107], v[138:141], v[168:171], v[104:107]
	v_mfma_f32_16x16x32_bf16 v[72:75], v[152:155], v[168:171], v[72:75]
	v_mfma_f32_16x16x32_bf16 v[100:103], v[138:141], v[176:179], v[100:103]
	v_mfma_f32_16x16x32_bf16 v[68:71], v[152:155], v[176:179], v[68:71]
	v_mfma_f32_16x16x32_bf16 v[96:99], v[138:141], v[188:191], v[96:99]
	v_mfma_f32_16x16x32_bf16 v[64:67], v[152:155], v[188:191], v[64:67]
	s_barrier
	s_setprio 0
	v_add_u32_e32 v152, 0x10000, v146
	ds_read_b128 v[134:137], v152
	ds_read_b128 v[138:141], v152 offset:1024
	ds_read_b128 v[148:151], v152 offset:2048
	ds_read_b128 v[152:155], v152 offset:3072
	ds_read_b128 v[248:251], v147 offset:6144
	ds_read_b128 v[252:255], v147 offset:7168
	s_add_u32 s18, s18, 0x20080
	s_addc_u32 s19, s19, 0
	s_add_i32 s20, s20, s28
	v_lshl_add_u64 v[246:247], s[18:19], 0, v[184:185]
	s_mov_b32 m0, s20
	s_nop 0
	global_load_lds_dwordx4 v[246:247], off
	v_lshl_add_u64 v[246:247], s[18:19], 0, v[128:129]
	s_add_i32 m0, s20, 0x2000
	s_nop 0
	global_load_lds_dwordx4 v[246:247], off
	s_waitcnt vmcnt(6)
	s_setprio 1
	s_barrier
	v_mfma_f32_16x16x32_bf16 v[44:47], v[192:195], v[156:159], v[44:47]
	v_mfma_f32_16x16x32_bf16 v[12:15], v[206:209], v[156:159], v[12:15]
	v_mfma_f32_16x16x32_bf16 v[40:43], v[192:195], v[164:167], v[40:43]
	v_mfma_f32_16x16x32_bf16 v[8:11], v[206:209], v[164:167], v[8:11]
	v_mfma_f32_16x16x32_bf16 v[36:39], v[192:195], v[172:175], v[36:39]
	v_mfma_f32_16x16x32_bf16 v[4:7], v[206:209], v[172:175], v[4:7]
	v_mfma_f32_16x16x32_bf16 v[32:35], v[192:195], v[180:183], v[32:35]
	v_mfma_f32_16x16x32_bf16 v[0:3], v[206:209], v[180:183], v[0:3]
	v_mfma_f32_16x16x32_bf16 v[44:47], v[202:205], v[160:163], v[44:47]
	v_mfma_f32_16x16x32_bf16 v[12:15], v[210:213], v[160:163], v[12:15]
	v_mfma_f32_16x16x32_bf16 v[40:43], v[202:205], v[168:171], v[40:43]
	v_mfma_f32_16x16x32_bf16 v[8:11], v[210:213], v[168:171], v[8:11]
	v_mfma_f32_16x16x32_bf16 v[36:39], v[202:205], v[176:179], v[36:39]
	v_mfma_f32_16x16x32_bf16 v[4:7], v[210:213], v[176:179], v[4:7]
	v_mfma_f32_16x16x32_bf16 v[32:35], v[202:205], v[188:191], v[32:35]
	v_mfma_f32_16x16x32_bf16 v[0:3], v[210:213], v[188:191], v[0:3]
	s_barrier
	s_setprio 0
	s_add_i32 s43, s43, 2
	s_add_u32 s16, s16, 0x100
	s_addc_u32 s17, s17, 0
	s_add_u32 s41, s41, 0x100
	s_addc_u32 s42, s42, 0
	s_cmp_gt_u32 s43, 5
	s_cbranch_scc0 .LBB0_137
	s_waitcnt lgkmcnt(0)
	s_lshl_b32 s0, s0, 8
	v_mov_b32_e32 v134, v145
	v_mov_b32_e32 v135, v144
	s_add_i32 s0, s0, s34
	s_mov_b32 s20, 0x3a0637bd
	v_add_u32_e32 v142, s0, v135
	s_lshl_b32 s0, s1, 8
	v_lshlrev_b32_e32 v135, 1, v134
	v_lshrrev_b32_e32 v136, 1, v134
	s_or_b32 s16, s0, s35
	v_and_or_b32 v135, v135, 2, v136
	v_lshl_add_u32 v134, v134, 2, s16
	v_lshlrev_b32_e32 v136, 2, v135
	v_ashrrev_i32_e32 v135, 31, v134
	v_lshlrev_b64 v[138:139], 5, v[134:135]
	v_lshl_add_u64 v[156:157], s[4:5], 0, v[138:139]
	global_load_dwordx4 v[138:141], v[156:157], off offset:16
	global_load_dwordx4 v[148:151], v[156:157], off offset:48
	global_load_dwordx4 v[152:155], v[156:157], off
	s_nop 0
	global_load_dwordx4 v[156:159], v[156:157], off offset:32
	s_mov_b32 s40, 0x3b000000
	s_mov_b32 s18, 0x45800000
	v_ashrrev_i32_e32 v143, 31, v142
	v_ashrrev_i32_e32 v137, 31, v136
	s_ashr_i32 s17, s16, 31
	s_waitcnt vmcnt(0)
	v_mov_b32_e32 v160, v152
	v_mov_b32_e32 v161, v156
	v_mov_b32_e32 v156, v153
	v_pk_add_f32 v[152:153], v[160:161], v[156:157]
	v_mov_b32_e32 v156, v154
	v_mov_b32_e32 v157, v158
	v_pk_add_f32 v[152:153], v[156:157], v[152:153]
	v_mov_b32_e32 v158, v155
	v_pk_add_f32 v[152:153], v[158:159], v[152:153]
	v_mov_b32_e32 v154, v138
	v_mov_b32_e32 v155, v148
	v_pk_add_f32 v[152:153], v[154:155], v[152:153]
	v_mov_b32_e32 v148, v139
	v_pk_add_f32 v[138:139], v[148:149], v[152:153]
	v_mov_b32_e32 v148, v140
	v_mov_b32_e32 v149, v150
	v_pk_add_f32 v[138:139], v[148:149], v[138:139]
	v_mov_b32_e32 v150, v141
	v_pk_add_f32 v[138:139], v[150:151], v[138:139]
	s_nop 0
	v_pk_add_f32 v[138:139], v[138:139], s[20:21] op_sel_hi:[1,0]
	s_nop 0
	v_pk_mul_f32 v[138:139], v[138:139], s[40:41] op_sel_hi:[1,0]
	s_nop 0
	v_mul_f32_e32 v135, 0x4b800000, v138
	v_cmp_gt_f32_e64 s[0:1], s67, v138
	v_cmp_gt_f32_e32 vcc, s67, v139
	s_nop 0
	v_cndmask_b32_e64 v135, v138, v135, s[0:1]
	v_rsq_f32_e32 v138, v135
	v_mul_f32_e32 v135, 0x4b800000, v139
	v_cndmask_b32_e32 v135, v139, v135, vcc
	v_rsq_f32_e32 v139, v135
	s_nop 0
	v_pk_mul_f32 v[140:141], v[138:139], s[18:19] op_sel_hi:[1,0]
	s_nop 0
	v_cndmask_b32_e64 v138, v138, v140, s[0:1]
	v_or_b32_e32 v140, 2, v134
	v_cndmask_b32_e32 v139, v139, v141, vcc
	v_ashrrev_i32_e32 v141, 31, v140
	v_lshlrev_b64 v[140:141], 5, v[140:141]
	v_lshl_add_u64 v[140:141], s[4:5], 0, v[140:141]
	global_load_dwordx4 v[148:151], v[140:141], off offset:16
	global_load_dwordx4 v[152:155], v[140:141], off offset:48
	global_load_dwordx4 v[156:159], v[140:141], off
	global_load_dwordx4 v[160:163], v[140:141], off offset:32
	v_pk_mul_f32 v[124:125], v[124:125], v[138:139]
	v_pk_mul_f32 v[120:121], v[120:121], v[138:139]
	v_pk_mul_f32 v[116:117], v[116:117], v[138:139]
	v_pk_mul_f32 v[112:113], v[112:113], v[138:139]
	v_pk_mul_f32 v[108:109], v[108:109], v[138:139]
	v_pk_mul_f32 v[104:105], v[104:105], v[138:139]
	v_pk_mul_f32 v[100:101], v[100:101], v[138:139]
	v_pk_mul_f32 v[96:97], v[96:97], v[138:139]
	s_waitcnt vmcnt(0)
	v_mov_b32_e32 v140, v156
	v_mov_b32_e32 v141, v160
	v_mov_b32_e32 v160, v157
	v_pk_add_f32 v[140:141], v[140:141], v[160:161]
	v_mov_b32_e32 v156, v158
	v_mov_b32_e32 v157, v162
	v_pk_add_f32 v[140:141], v[156:157], v[140:141]
	v_mov_b32_e32 v162, v159
	v_pk_add_f32 v[140:141], v[162:163], v[140:141]
	v_mov_b32_e32 v156, v148
	v_mov_b32_e32 v157, v152
	v_pk_add_f32 v[140:141], v[156:157], v[140:141]
	v_mov_b32_e32 v152, v149
	v_pk_add_f32 v[140:141], v[152:153], v[140:141]
	v_mov_b32_e32 v148, v150
	v_mov_b32_e32 v149, v154
	v_pk_add_f32 v[140:141], v[148:149], v[140:141]
	v_mov_b32_e32 v154, v151
	v_pk_add_f32 v[140:141], v[154:155], v[140:141]
	v_cvt_pk_bf16_f32 v150, v124, v125
	v_lshlrev_b64 v[124:125], 16, v[142:143]
	v_pk_add_f32 v[140:141], v[140:141], s[20:21] op_sel_hi:[1,0]
	v_lshl_add_u64 v[124:125], s[2:3], 0, v[124:125]
	v_pk_mul_f32 v[140:141], v[140:141], s[40:41] op_sel_hi:[1,0]
	s_nop 0
	v_mul_f32_e32 v135, 0x4b800000, v140
	v_cmp_gt_f32_e64 s[0:1], s67, v140
	v_cmp_gt_f32_e32 vcc, s67, v141
	s_nop 0
	v_cndmask_b32_e64 v135, v140, v135, s[0:1]
	v_rsq_f32_e32 v140, v135
	v_mul_f32_e32 v135, 0x4b800000, v141
	v_cndmask_b32_e32 v135, v141, v135, vcc
	v_rsq_f32_e32 v141, v135
	s_nop 0
	v_pk_mul_f32 v[148:149], v[140:141], s[18:19] op_sel_hi:[1,0]
	s_nop 0
	v_cndmask_b32_e32 v141, v141, v149, vcc
	v_cndmask_b32_e64 v140, v140, v148, s[0:1]
	v_add_u32_e32 v148, s16, v136
	v_ashrrev_i32_e32 v149, 31, v148
	v_pk_mul_f32 v[126:127], v[126:127], v[140:141]
	s_mov_b64 s[0:1], 0x100000
	v_cvt_pk_bf16_f32 v151, v126, v127
	v_lshlrev_b64 v[126:127], 1, v[148:149]
	v_lshl_add_u64 v[142:143], v[124:125], 0, v[126:127]
	global_store_dwordx2 v[142:143], v[150:151], off
	v_pk_mul_f32 v[122:123], v[122:123], v[140:141]
	v_cvt_pk_bf16_f32 v142, v120, v121
	v_lshl_add_u64 v[120:121], v[124:125], 0, s[0:1]
	v_cvt_pk_bf16_f32 v143, v122, v123
	v_lshl_add_u64 v[122:123], v[120:121], 0, v[126:127]
	s_mov_b64 s[0:1], 0x200000
	global_store_dwordx2 v[122:123], v[142:143], off
	v_pk_mul_f32 v[118:119], v[118:119], v[140:141]
	v_cvt_pk_bf16_f32 v122, v116, v117
	v_lshl_add_u64 v[116:117], v[124:125], 0, s[0:1]
	v_cvt_pk_bf16_f32 v123, v118, v119
	v_lshl_add_u64 v[118:119], v[116:117], 0, v[126:127]
	s_mov_b64 s[0:1], 0x300000
	global_store_dwordx2 v[118:119], v[122:123], off
	v_pk_mul_f32 v[114:115], v[114:115], v[140:141]
	v_cvt_pk_bf16_f32 v118, v112, v113
	v_lshl_add_u64 v[112:113], v[124:125], 0, s[0:1]
	v_cvt_pk_bf16_f32 v119, v114, v115
	v_lshl_add_u64 v[114:115], v[112:113], 0, v[126:127]
	s_mov_b64 s[0:1], 0x800000
	global_store_dwordx2 v[114:115], v[118:119], off
	v_pk_mul_f32 v[110:111], v[110:111], v[140:141]
	v_cvt_pk_bf16_f32 v114, v108, v109
	v_lshl_add_u64 v[108:109], v[124:125], 0, s[0:1]
	v_cvt_pk_bf16_f32 v115, v110, v111
	v_lshl_add_u64 v[110:111], v[108:109], 0, v[126:127]
	s_mov_b64 s[0:1], 0x900000
	global_store_dwordx2 v[110:111], v[114:115], off
	v_pk_mul_f32 v[106:107], v[106:107], v[140:141]
	v_cvt_pk_bf16_f32 v110, v104, v105
	v_lshl_add_u64 v[104:105], v[124:125], 0, s[0:1]
	v_cvt_pk_bf16_f32 v111, v106, v107
	v_lshl_add_u64 v[106:107], v[104:105], 0, v[126:127]
	s_mov_b64 s[0:1], 0xa00000
	global_store_dwordx2 v[106:107], v[110:111], off
	v_pk_mul_f32 v[102:103], v[102:103], v[140:141]
	v_cvt_pk_bf16_f32 v106, v100, v101
	v_lshl_add_u64 v[100:101], v[124:125], 0, s[0:1]
	v_cvt_pk_bf16_f32 v107, v102, v103
	v_lshl_add_u64 v[102:103], v[100:101], 0, v[126:127]
	s_mov_b64 s[0:1], 0xb00000
	global_store_dwordx2 v[102:103], v[106:107], off
	v_pk_mul_f32 v[98:99], v[98:99], v[140:141]
	v_cvt_pk_bf16_f32 v102, v96, v97
	v_lshl_add_u64 v[96:97], v[124:125], 0, s[0:1]
	v_cvt_pk_bf16_f32 v103, v98, v99
	v_lshl_add_u64 v[98:99], v[96:97], 0, v[126:127]
	global_store_dwordx2 v[98:99], v[102:103], off
	v_add_u32_e32 v98, 16, v134
	v_ashrrev_i32_e32 v99, 31, v98
	v_lshlrev_b64 v[98:99], 5, v[98:99]
	v_lshl_add_u64 v[98:99], s[4:5], 0, v[98:99]
	global_load_dwordx4 v[138:141], v[98:99], off offset:16
	global_load_dwordx4 v[148:151], v[98:99], off offset:48
	global_load_dwordx4 v[152:155], v[98:99], off
	global_load_dwordx4 v[156:159], v[98:99], off offset:32
	s_waitcnt vmcnt(0)
	v_mov_b32_e32 v98, v152
	v_mov_b32_e32 v99, v156
	v_mov_b32_e32 v156, v153
	v_pk_add_f32 v[98:99], v[98:99], v[156:157]
	v_mov_b32_e32 v102, v154
	v_mov_b32_e32 v103, v158
	v_pk_add_f32 v[98:99], v[102:103], v[98:99]
	v_mov_b32_e32 v158, v155
	v_pk_add_f32 v[98:99], v[158:159], v[98:99]
	v_mov_b32_e32 v102, v138
	v_mov_b32_e32 v103, v148
	v_pk_add_f32 v[98:99], v[102:103], v[98:99]
	v_mov_b32_e32 v148, v139
	v_pk_add_f32 v[98:99], v[148:149], v[98:99]
	v_mov_b32_e32 v102, v140
	v_mov_b32_e32 v103, v150
	v_pk_add_f32 v[98:99], v[102:103], v[98:99]
	v_mov_b32_e32 v150, v141
	v_pk_add_f32 v[98:99], v[150:151], v[98:99]
	s_nop 0
	v_pk_add_f32 v[98:99], v[98:99], s[20:21] op_sel_hi:[1,0]
	s_nop 0
	v_pk_mul_f32 v[98:99], v[98:99], s[40:41] op_sel_hi:[1,0]
	s_nop 0
	v_mul_f32_e32 v102, 0x4b800000, v98
	v_cmp_gt_f32_e64 s[0:1], s67, v98
	v_cmp_gt_f32_e32 vcc, s67, v99
	s_nop 0
	v_cndmask_b32_e64 v98, v98, v102, s[0:1]
	v_mul_f32_e32 v102, 0x4b800000, v99
	v_cndmask_b32_e32 v99, v99, v102, vcc
	v_rsq_f32_e32 v98, v98
	v_rsq_f32_e32 v99, v99
	s_nop 0
	v_pk_mul_f32 v[102:103], v[98:99], s[18:19] op_sel_hi:[1,0]
	s_nop 0
	v_cndmask_b32_e64 v98, v98, v102, s[0:1]
	v_add_u32_e32 v102, 18, v134
	v_cndmask_b32_e32 v99, v99, v103, vcc
	v_ashrrev_i32_e32 v103, 31, v102
	v_lshlrev_b64 v[102:103], 5, v[102:103]
	v_lshl_add_u64 v[102:103], s[4:5], 0, v[102:103]
	global_load_dwordx4 v[138:141], v[102:103], off offset:16
	global_load_dwordx4 v[148:151], v[102:103], off offset:48
	global_load_dwordx4 v[152:155], v[102:103], off
	global_load_dwordx4 v[156:159], v[102:103], off offset:32
	v_pk_mul_f32 v[92:93], v[92:93], v[98:99]
	v_pk_mul_f32 v[88:89], v[88:89], v[98:99]
	v_pk_mul_f32 v[84:85], v[84:85], v[98:99]
	v_pk_mul_f32 v[80:81], v[80:81], v[98:99]
	v_pk_mul_f32 v[76:77], v[76:77], v[98:99]
	v_pk_mul_f32 v[72:73], v[72:73], v[98:99]
	v_pk_mul_f32 v[68:69], v[68:69], v[98:99]
	v_pk_mul_f32 v[64:65], v[64:65], v[98:99]
	s_waitcnt vmcnt(0)
	v_mov_b32_e32 v102, v152
	v_mov_b32_e32 v103, v156
	v_mov_b32_e32 v156, v153
	v_pk_add_f32 v[102:103], v[102:103], v[156:157]
	v_mov_b32_e32 v106, v154
	v_mov_b32_e32 v107, v158
	v_pk_add_f32 v[102:103], v[106:107], v[102:103]
	v_mov_b32_e32 v158, v155
	v_pk_add_f32 v[102:103], v[158:159], v[102:103]
	v_mov_b32_e32 v106, v138
	v_mov_b32_e32 v107, v148
	v_pk_add_f32 v[102:103], v[106:107], v[102:103]
	v_mov_b32_e32 v148, v139
	v_pk_add_f32 v[102:103], v[148:149], v[102:103]
	v_mov_b32_e32 v106, v140
	v_mov_b32_e32 v107, v150
	v_pk_add_f32 v[102:103], v[106:107], v[102:103]
	v_mov_b32_e32 v150, v141
	v_pk_add_f32 v[102:103], v[150:151], v[102:103]
	s_nop 0
	v_pk_add_f32 v[102:103], v[102:103], s[20:21] op_sel_hi:[1,0]
	s_nop 0
	v_pk_mul_f32 v[102:103], v[102:103], s[40:41] op_sel_hi:[1,0]
	s_nop 0
	v_mul_f32_e32 v106, 0x4b800000, v102
	v_cmp_gt_f32_e64 s[0:1], s67, v102
	v_cmp_gt_f32_e32 vcc, s67, v103
	s_nop 0
	v_cndmask_b32_e64 v102, v102, v106, s[0:1]
	v_mul_f32_e32 v106, 0x4b800000, v103
	v_cndmask_b32_e32 v103, v103, v106, vcc
	v_rsq_f32_e32 v102, v102
	v_rsq_f32_e32 v103, v103
	s_nop 0
	v_pk_mul_f32 v[106:107], v[102:103], s[18:19] op_sel_hi:[1,0]
	s_nop 0
	v_cndmask_b32_e32 v103, v103, v107, vcc
	v_cndmask_b32_e64 v102, v102, v106, s[0:1]
	v_pk_mul_f32 v[94:95], v[94:95], v[102:103]
	v_cvt_pk_bf16_f32 v106, v92, v93
	v_lshl_add_u64 v[92:93], v[136:137], 0, s[16:17]
	v_cvt_pk_bf16_f32 v107, v94, v95
	v_lshlrev_b64 v[94:95], 1, v[92:93]
	v_lshl_add_u64 v[92:93], v[124:125], 0, v[94:95]
	global_store_dwordx2 v[92:93], v[106:107], off offset:32
	v_pk_mul_f32 v[90:91], v[90:91], v[102:103]
	v_cvt_pk_bf16_f32 v106, v88, v89
	v_lshl_add_u64 v[88:89], v[120:121], 0, v[94:95]
	v_cvt_pk_bf16_f32 v107, v90, v91
	global_store_dwordx2 v[88:89], v[106:107], off offset:32
	v_pk_mul_f32 v[86:87], v[86:87], v[102:103]
	v_cvt_pk_bf16_f32 v90, v84, v85
	v_lshl_add_u64 v[84:85], v[116:117], 0, v[94:95]
	v_cvt_pk_bf16_f32 v91, v86, v87
	global_store_dwordx2 v[84:85], v[90:91], off offset:32
	v_pk_mul_f32 v[82:83], v[82:83], v[102:103]
	v_cvt_pk_bf16_f32 v86, v80, v81
	v_lshl_add_u64 v[80:81], v[112:113], 0, v[94:95]
	v_cvt_pk_bf16_f32 v87, v82, v83
	global_store_dwordx2 v[80:81], v[86:87], off offset:32
	v_pk_mul_f32 v[78:79], v[78:79], v[102:103]
	v_cvt_pk_bf16_f32 v82, v76, v77
	v_lshl_add_u64 v[76:77], v[108:109], 0, v[94:95]
	v_cvt_pk_bf16_f32 v83, v78, v79
	global_store_dwordx2 v[76:77], v[82:83], off offset:32
	v_pk_mul_f32 v[74:75], v[74:75], v[102:103]
	v_cvt_pk_bf16_f32 v78, v72, v73
	v_lshl_add_u64 v[72:73], v[104:105], 0, v[94:95]
	v_cvt_pk_bf16_f32 v79, v74, v75
	global_store_dwordx2 v[72:73], v[78:79], off offset:32
	v_pk_mul_f32 v[70:71], v[70:71], v[102:103]
	v_cvt_pk_bf16_f32 v74, v68, v69
	v_lshl_add_u64 v[68:69], v[100:101], 0, v[94:95]
	v_pk_mul_f32 v[66:67], v[66:67], v[102:103]
	v_cvt_pk_bf16_f32 v75, v70, v71
	global_store_dwordx2 v[68:69], v[74:75], off offset:32
	v_cvt_pk_bf16_f32 v70, v64, v65
	v_cvt_pk_bf16_f32 v71, v66, v67
	v_add_u32_e32 v66, 0x80, v134
	v_ashrrev_i32_e32 v67, 31, v66
	v_lshl_add_u64 v[64:65], v[96:97], 0, v[94:95]
	v_lshlrev_b64 v[66:67], 5, v[66:67]
	global_store_dwordx2 v[64:65], v[70:71], off offset:32
	v_lshl_add_u64 v[66:67], s[4:5], 0, v[66:67]
	global_load_dwordx4 v[94:97], v[66:67], off offset:16
	global_load_dwordx4 v[98:101], v[66:67], off offset:48
	global_load_dwordx4 v[102:105], v[66:67], off
	global_load_dwordx4 v[106:109], v[66:67], off offset:32
	s_mov_b64 s[16:17], s[12:13]
	s_waitcnt vmcnt(0)
	v_mov_b32_e32 v66, v102
	v_mov_b32_e32 v67, v106
	v_mov_b32_e32 v106, v103
	v_pk_add_f32 v[66:67], v[66:67], v[106:107]
	v_mov_b32_e32 v70, v104
	v_mov_b32_e32 v71, v108
	v_pk_add_f32 v[66:67], v[70:71], v[66:67]
	v_mov_b32_e32 v108, v105
	v_pk_add_f32 v[66:67], v[108:109], v[66:67]
	v_mov_b32_e32 v70, v94
	v_mov_b32_e32 v71, v98
	v_pk_add_f32 v[66:67], v[70:71], v[66:67]
	v_mov_b32_e32 v98, v95
	v_pk_add_f32 v[66:67], v[98:99], v[66:67]
	v_mov_b32_e32 v70, v96
	v_mov_b32_e32 v71, v100
	v_pk_add_f32 v[66:67], v[70:71], v[66:67]
	v_mov_b32_e32 v100, v97
	v_pk_add_f32 v[66:67], v[100:101], v[66:67]
	s_nop 0
	v_pk_add_f32 v[66:67], v[66:67], s[20:21] op_sel_hi:[1,0]
	s_nop 0
	v_pk_mul_f32 v[66:67], v[66:67], s[40:41] op_sel_hi:[1,0]
	s_nop 0
	v_mul_f32_e32 v70, 0x4b800000, v66
	v_cmp_gt_f32_e64 s[0:1], s67, v66
	v_cmp_gt_f32_e32 vcc, s67, v67
	s_nop 0
	v_cndmask_b32_e64 v66, v66, v70, s[0:1]
	v_mul_f32_e32 v70, 0x4b800000, v67
	v_cndmask_b32_e32 v67, v67, v70, vcc
	v_rsq_f32_e32 v66, v66
	v_rsq_f32_e32 v67, v67
	s_nop 0
	v_pk_mul_f32 v[70:71], v[66:67], s[18:19] op_sel_hi:[1,0]
	s_nop 0
	v_cndmask_b32_e64 v66, v66, v70, s[0:1]
	v_add_u32_e32 v70, 0x82, v134
	v_cndmask_b32_e32 v67, v67, v71, vcc
	v_ashrrev_i32_e32 v71, 31, v70
	v_lshlrev_b64 v[70:71], 5, v[70:71]
	v_lshl_add_u64 v[70:71], s[4:5], 0, v[70:71]
	global_load_dwordx4 v[94:97], v[70:71], off offset:16
	global_load_dwordx4 v[98:101], v[70:71], off offset:48
	global_load_dwordx4 v[102:105], v[70:71], off
	global_load_dwordx4 v[106:109], v[70:71], off offset:32
	v_pk_mul_f32 v[60:61], v[60:61], v[66:67]
	v_pk_mul_f32 v[56:57], v[56:57], v[66:67]
	v_pk_mul_f32 v[52:53], v[52:53], v[66:67]
	v_pk_mul_f32 v[48:49], v[48:49], v[66:67]
	v_pk_mul_f32 v[44:45], v[44:45], v[66:67]
	v_pk_mul_f32 v[40:41], v[40:41], v[66:67]
	v_pk_mul_f32 v[36:37], v[36:37], v[66:67]
	v_pk_mul_f32 v[32:33], v[32:33], v[66:67]
	v_cvt_pk_bf16_f32 v60, v60, v61
	s_waitcnt vmcnt(0)
	v_mov_b32_e32 v70, v102
	v_mov_b32_e32 v71, v106
	v_mov_b32_e32 v106, v103
	v_pk_add_f32 v[70:71], v[70:71], v[106:107]
	v_mov_b32_e32 v74, v104
	v_mov_b32_e32 v75, v108
	v_pk_add_f32 v[70:71], v[74:75], v[70:71]
	v_mov_b32_e32 v108, v105
	v_pk_add_f32 v[70:71], v[108:109], v[70:71]
	v_mov_b32_e32 v74, v94
	v_mov_b32_e32 v75, v98
	v_pk_add_f32 v[70:71], v[74:75], v[70:71]
	v_mov_b32_e32 v98, v95
	v_pk_add_f32 v[70:71], v[98:99], v[70:71]
	v_mov_b32_e32 v74, v96
	v_mov_b32_e32 v75, v100
	v_pk_add_f32 v[70:71], v[74:75], v[70:71]
	v_mov_b32_e32 v100, v97
	v_pk_add_f32 v[70:71], v[100:101], v[70:71]
	s_nop 0
	v_pk_add_f32 v[70:71], v[70:71], s[20:21] op_sel_hi:[1,0]
	s_nop 0
	v_pk_mul_f32 v[70:71], v[70:71], s[40:41] op_sel_hi:[1,0]
	s_nop 0
	v_mul_f32_e32 v74, 0x4b800000, v70
	v_cmp_gt_f32_e64 s[0:1], s67, v70
	v_cmp_gt_f32_e32 vcc, s67, v71
	s_nop 0
	v_cndmask_b32_e64 v70, v70, v74, s[0:1]
	v_mul_f32_e32 v74, 0x4b800000, v71
	v_cndmask_b32_e32 v71, v71, v74, vcc
	v_rsq_f32_e32 v70, v70
	v_rsq_f32_e32 v71, v71
	s_nop 0
	v_pk_mul_f32 v[74:75], v[70:71], s[18:19] op_sel_hi:[1,0]
	s_nop 0
	v_cndmask_b32_e32 v71, v71, v75, vcc
	v_cndmask_b32_e64 v70, v70, v74, s[0:1]
	v_pk_mul_f32 v[62:63], v[62:63], v[70:71]
	v_pk_mul_f32 v[58:59], v[58:59], v[70:71]
	v_cvt_pk_bf16_f32 v61, v62, v63
	global_store_dwordx2 v[92:93], v[60:61], off offset:256
	v_cvt_pk_bf16_f32 v56, v56, v57
	v_cvt_pk_bf16_f32 v57, v58, v59
	global_store_dwordx2 v[88:89], v[56:57], off offset:256
	v_pk_mul_f32 v[54:55], v[54:55], v[70:71]
	v_cvt_pk_bf16_f32 v52, v52, v53
	v_pk_mul_f32 v[50:51], v[50:51], v[70:71]
	v_cvt_pk_bf16_f32 v53, v54, v55
	global_store_dwordx2 v[84:85], v[52:53], off offset:256
	v_cvt_pk_bf16_f32 v48, v48, v49
	v_cvt_pk_bf16_f32 v49, v50, v51
	global_store_dwordx2 v[80:81], v[48:49], off offset:256
	v_pk_mul_f32 v[46:47], v[46:47], v[70:71]
	v_cvt_pk_bf16_f32 v44, v44, v45
	v_pk_mul_f32 v[42:43], v[42:43], v[70:71]
	v_cvt_pk_bf16_f32 v45, v46, v47
	global_store_dwordx2 v[76:77], v[44:45], off offset:256
	v_cvt_pk_bf16_f32 v40, v40, v41
	v_cvt_pk_bf16_f32 v41, v42, v43
	global_store_dwordx2 v[72:73], v[40:41], off offset:256
	v_pk_mul_f32 v[38:39], v[38:39], v[70:71]
	v_cvt_pk_bf16_f32 v36, v36, v37
	v_pk_mul_f32 v[34:35], v[34:35], v[70:71]
	v_cvt_pk_bf16_f32 v37, v38, v39
	global_store_dwordx2 v[68:69], v[36:37], off offset:256
	v_cvt_pk_bf16_f32 v32, v32, v33
	v_cvt_pk_bf16_f32 v33, v34, v35
	global_store_dwordx2 v[64:65], v[32:33], off offset:256
	v_add_u32_e32 v32, 0x90, v134
	v_ashrrev_i32_e32 v33, 31, v32
	v_lshlrev_b64 v[32:33], 5, v[32:33]
	v_lshl_add_u64 v[44:45], s[4:5], 0, v[32:33]
	global_load_dwordx4 v[32:35], v[44:45], off offset:16
	global_load_dwordx4 v[36:39], v[44:45], off offset:48
	global_load_dwordx4 v[40:43], v[44:45], off
	s_nop 0
	global_load_dwordx4 v[44:47], v[44:45], off offset:32
	s_waitcnt vmcnt(0)
	v_mov_b32_e32 v48, v40
	v_mov_b32_e32 v49, v44
	v_mov_b32_e32 v44, v41
	v_pk_add_f32 v[40:41], v[48:49], v[44:45]
	v_mov_b32_e32 v44, v42
	v_mov_b32_e32 v45, v46
	v_pk_add_f32 v[40:41], v[44:45], v[40:41]
	v_mov_b32_e32 v46, v43
	v_pk_add_f32 v[40:41], v[46:47], v[40:41]
	v_mov_b32_e32 v42, v32
	v_mov_b32_e32 v43, v36
	v_pk_add_f32 v[40:41], v[42:43], v[40:41]
	v_mov_b32_e32 v36, v33
	v_pk_add_f32 v[32:33], v[36:37], v[40:41]
	v_mov_b32_e32 v36, v34
	v_mov_b32_e32 v37, v38
	v_pk_add_f32 v[32:33], v[36:37], v[32:33]
	v_mov_b32_e32 v38, v35
	v_pk_add_f32 v[32:33], v[38:39], v[32:33]
	s_nop 0
	v_pk_add_f32 v[32:33], v[32:33], s[20:21] op_sel_hi:[1,0]
	s_nop 0
	v_pk_mul_f32 v[32:33], v[32:33], s[40:41] op_sel_hi:[1,0]
	s_nop 0
	v_mul_f32_e32 v34, 0x4b800000, v32
	v_cmp_gt_f32_e64 s[0:1], s67, v32
	v_cmp_gt_f32_e32 vcc, s67, v33
	s_nop 0
	v_cndmask_b32_e64 v32, v32, v34, s[0:1]
	v_mul_f32_e32 v34, 0x4b800000, v33
	v_cndmask_b32_e32 v33, v33, v34, vcc
	v_rsq_f32_e32 v32, v32
	v_rsq_f32_e32 v33, v33
	s_nop 0
	v_pk_mul_f32 v[34:35], v[32:33], s[18:19] op_sel_hi:[1,0]
	s_nop 0
	v_cndmask_b32_e64 v32, v32, v34, s[0:1]
	v_add_u32_e32 v34, 0x92, v134
	v_cndmask_b32_e32 v33, v33, v35, vcc
	v_ashrrev_i32_e32 v35, 31, v34
	v_lshlrev_b64 v[34:35], 5, v[34:35]
	v_lshl_add_u64 v[46:47], s[4:5], 0, v[34:35]
	global_load_dwordx4 v[34:37], v[46:47], off offset:16
	global_load_dwordx4 v[38:41], v[46:47], off offset:48
	global_load_dwordx4 v[42:45], v[46:47], off
	s_nop 0
	global_load_dwordx4 v[46:49], v[46:47], off offset:32
	v_pk_mul_f32 v[28:29], v[28:29], v[32:33]
	v_pk_mul_f32 v[24:25], v[24:25], v[32:33]
	v_pk_mul_f32 v[20:21], v[20:21], v[32:33]
	v_pk_mul_f32 v[16:17], v[16:17], v[32:33]
	v_pk_mul_f32 v[12:13], v[12:13], v[32:33]
	v_pk_mul_f32 v[8:9], v[8:9], v[32:33]
	v_pk_mul_f32 v[4:5], v[4:5], v[32:33]
	v_pk_mul_f32 v[0:1], v[0:1], v[32:33]
	v_cvt_pk_bf16_f32 v28, v28, v29
	s_waitcnt vmcnt(0)
	v_mov_b32_e32 v50, v42
	v_mov_b32_e32 v51, v46
	v_mov_b32_e32 v46, v43
	v_pk_add_f32 v[42:43], v[50:51], v[46:47]
	v_mov_b32_e32 v46, v44
	v_mov_b32_e32 v47, v48
	v_pk_add_f32 v[42:43], v[46:47], v[42:43]
	v_mov_b32_e32 v48, v45
	v_pk_add_f32 v[42:43], v[48:49], v[42:43]
	v_mov_b32_e32 v44, v34
	v_mov_b32_e32 v45, v38
	v_pk_add_f32 v[42:43], v[44:45], v[42:43]
	v_mov_b32_e32 v38, v35
	v_pk_add_f32 v[34:35], v[38:39], v[42:43]
	v_mov_b32_e32 v38, v36
	v_mov_b32_e32 v39, v40
	v_pk_add_f32 v[34:35], v[38:39], v[34:35]
	v_mov_b32_e32 v40, v37
	v_pk_add_f32 v[34:35], v[40:41], v[34:35]
	s_nop 0
	v_pk_add_f32 v[34:35], v[34:35], s[20:21] op_sel_hi:[1,0]
	s_nop 0
	v_pk_mul_f32 v[34:35], v[34:35], s[40:41] op_sel_hi:[1,0]
	v_readlane_b32 s40, v244, 49
	v_mul_f32_e32 v36, 0x4b800000, v34
	v_cmp_gt_f32_e64 s[0:1], s67, v34
	v_cmp_gt_f32_e32 vcc, s67, v35
	v_readlane_b32 s41, v244, 50
	v_cndmask_b32_e64 v34, v34, v36, s[0:1]
	v_mul_f32_e32 v36, 0x4b800000, v35
	v_cndmask_b32_e32 v35, v35, v36, vcc
	v_rsq_f32_e32 v34, v34
	v_rsq_f32_e32 v35, v35
	v_readlane_b32 s46, v244, 55
	v_readlane_b32 s47, v244, 56
	v_readlane_b32 s48, v244, 57
	v_pk_mul_f32 v[36:37], v[34:35], s[18:19] op_sel_hi:[1,0]
	s_mov_b64 s[18:19], s[14:15]
	v_cndmask_b32_e32 v35, v35, v37, vcc
	v_cndmask_b32_e64 v34, v34, v36, s[0:1]
	s_and_b64 vcc, exec, s[6:7]
	s_mov_b32 s1, s10
	s_mov_b32 s0, s8
	v_readlane_b32 s49, v244, 58
	v_readlane_b32 s50, v244, 59
	v_readlane_b32 s51, v244, 60
	v_pk_mul_f32 v[30:31], v[30:31], v[34:35]
	v_pk_mul_f32 v[26:27], v[26:27], v[34:35]
	v_cvt_pk_bf16_f32 v29, v30, v31
	global_store_dwordx2 v[92:93], v[28:29], off offset:288
	v_cvt_pk_bf16_f32 v24, v24, v25
	v_cvt_pk_bf16_f32 v25, v26, v27
	global_store_dwordx2 v[88:89], v[24:25], off offset:288
	v_pk_mul_f32 v[22:23], v[22:23], v[34:35]
	v_cvt_pk_bf16_f32 v20, v20, v21
	v_pk_mul_f32 v[18:19], v[18:19], v[34:35]
	v_cvt_pk_bf16_f32 v21, v22, v23
	global_store_dwordx2 v[84:85], v[20:21], off offset:288
	v_cvt_pk_bf16_f32 v16, v16, v17
	v_cvt_pk_bf16_f32 v17, v18, v19
	global_store_dwordx2 v[80:81], v[16:17], off offset:288
	v_pk_mul_f32 v[14:15], v[14:15], v[34:35]
	v_cvt_pk_bf16_f32 v12, v12, v13
	v_pk_mul_f32 v[10:11], v[10:11], v[34:35]
	v_cvt_pk_bf16_f32 v13, v14, v15
	global_store_dwordx2 v[76:77], v[12:13], off offset:288
	v_cvt_pk_bf16_f32 v8, v8, v9
	v_cvt_pk_bf16_f32 v9, v10, v11
	global_store_dwordx2 v[72:73], v[8:9], off offset:288
	v_pk_mul_f32 v[6:7], v[6:7], v[34:35]
	v_cvt_pk_bf16_f32 v4, v4, v5
	v_pk_mul_f32 v[2:3], v[2:3], v[34:35]
	v_cvt_pk_bf16_f32 v5, v6, v7
	global_store_dwordx2 v[68:69], v[4:5], off offset:288
	v_cvt_pk_bf16_f32 v0, v0, v1
	v_cvt_pk_bf16_f32 v1, v2, v3
	global_store_dwordx2 v[64:65], v[0:1], off offset:288
	v_readlane_b32 s42, v244, 51
	v_readlane_b32 s43, v244, 52
	v_readlane_b32 s44, v244, 53
	v_readlane_b32 s45, v244, 54
	v_readlane_b32 s52, v244, 61
	v_readlane_b32 s53, v244, 62
	v_readlane_b32 s54, v244, 63
	v_readlane_b32 s55, v243, 0
	s_cbranch_vccz .LBB0_130
	s_waitcnt vmcnt(0)
	s_cmpk_gt_u32 s22, 0xff
	s_cbranch_scc1 .LBB0_141
	s_barrier

.LBB0_151:
	s_ashr_i32 s9, s8, 31
	s_lshl_b64 s[12:13], s[8:9], 18
	s_add_u32 s12, s25, s12
	s_addc_u32 s13, s26, s13
	s_and_b64 s[14:15], s[22:23], exec
	s_cselect_b32 s9, s13, s19
	s_cselect_b32 s40, s12, s18
	s_ashr_i32 s7, s6, 31
	s_lshl_b64 s[14:15], s[6:7], 18
	s_add_u32 s14, s27, s14
	s_addc_u32 s15, s28, s15
	s_and_b64 s[22:23], s[22:23], exec
	s_cselect_b32 s7, s15, s21
	s_cselect_b32 s41, s14, s20
	s_add_u32 s18, s18, 0x20080
	s_addc_u32 s19, s19, 0
	s_add_u32 s42, s20, 0x100
	v_mov_b32_e32 v0, 0
	s_addc_u32 s43, s21, 0
	s_mov_b32 s44, -2
	v_mov_b32_e32 v1, v0
	v_mov_b32_e32 v2, v0
	v_mov_b32_e32 v3, v0
	v_mov_b32_e32 v4, v0
	v_mov_b32_e32 v5, v0
	v_mov_b32_e32 v6, v0
	v_mov_b32_e32 v7, v0
	v_mov_b32_e32 v16, v0
	v_mov_b32_e32 v17, v0
	v_mov_b32_e32 v18, v0
	v_mov_b32_e32 v19, v0
	v_mov_b32_e32 v20, v0
	v_mov_b32_e32 v21, v0
	v_mov_b32_e32 v22, v0
	v_mov_b32_e32 v23, v0
	v_mov_b32_e32 v32, v0
	v_mov_b32_e32 v33, v0
	v_mov_b32_e32 v34, v0
	v_mov_b32_e32 v35, v0
	v_mov_b32_e32 v36, v0
	v_mov_b32_e32 v37, v0
	v_mov_b32_e32 v38, v0
	v_mov_b32_e32 v39, v0
	v_mov_b32_e32 v48, v0
	v_mov_b32_e32 v49, v0
	v_mov_b32_e32 v50, v0
	v_mov_b32_e32 v51, v0
	v_mov_b32_e32 v52, v0
	v_mov_b32_e32 v53, v0
	v_mov_b32_e32 v54, v0
	v_mov_b32_e32 v55, v0
	v_mov_b32_e32 v8, v0
	v_mov_b32_e32 v9, v0
	v_mov_b32_e32 v10, v0
	v_mov_b32_e32 v11, v0
	v_mov_b32_e32 v12, v0
	v_mov_b32_e32 v13, v0
	v_mov_b32_e32 v14, v0
	v_mov_b32_e32 v15, v0
	v_mov_b32_e32 v24, v0
	v_mov_b32_e32 v25, v0
	v_mov_b32_e32 v26, v0
	v_mov_b32_e32 v27, v0
	v_mov_b32_e32 v28, v0
	v_mov_b32_e32 v29, v0
	v_mov_b32_e32 v30, v0
	v_mov_b32_e32 v31, v0
	v_mov_b32_e32 v40, v0
	v_mov_b32_e32 v41, v0
	v_mov_b32_e32 v42, v0
	v_mov_b32_e32 v43, v0
	v_mov_b32_e32 v44, v0
	v_mov_b32_e32 v45, v0
	v_mov_b32_e32 v46, v0
	v_mov_b32_e32 v47, v0
	v_mov_b32_e32 v56, v0
	v_mov_b32_e32 v57, v0
	v_mov_b32_e32 v58, v0
	v_mov_b32_e32 v59, v0
	v_mov_b32_e32 v60, v0
	v_mov_b32_e32 v61, v0
	v_mov_b32_e32 v62, v0
	v_mov_b32_e32 v63, v0
	v_mov_b32_e32 v64, v0
	v_mov_b32_e32 v65, v0
	v_mov_b32_e32 v66, v0
	v_mov_b32_e32 v67, v0
	v_mov_b32_e32 v68, v0
	v_mov_b32_e32 v69, v0
	v_mov_b32_e32 v70, v0
	v_mov_b32_e32 v71, v0
	v_mov_b32_e32 v80, v0
	v_mov_b32_e32 v81, v0
	v_mov_b32_e32 v82, v0
	v_mov_b32_e32 v83, v0
	v_mov_b32_e32 v84, v0
	v_mov_b32_e32 v85, v0
	v_mov_b32_e32 v86, v0
	v_mov_b32_e32 v87, v0
	v_mov_b32_e32 v96, v0
	v_mov_b32_e32 v97, v0
	v_mov_b32_e32 v98, v0
	v_mov_b32_e32 v99, v0
	v_mov_b32_e32 v100, v0
	v_mov_b32_e32 v101, v0
	v_mov_b32_e32 v102, v0
	v_mov_b32_e32 v103, v0
	v_mov_b32_e32 v112, v0
	v_mov_b32_e32 v113, v0
	v_mov_b32_e32 v114, v0
	v_mov_b32_e32 v115, v0
	v_mov_b32_e32 v116, v0
	v_mov_b32_e32 v117, v0
	v_mov_b32_e32 v118, v0
	v_mov_b32_e32 v119, v0
	v_mov_b32_e32 v72, v0
	v_mov_b32_e32 v73, v0
	v_mov_b32_e32 v74, v0
	v_mov_b32_e32 v75, v0
	v_mov_b32_e32 v76, v0
	v_mov_b32_e32 v77, v0
	v_mov_b32_e32 v78, v0
	v_mov_b32_e32 v79, v0
	v_mov_b32_e32 v88, v0
	v_mov_b32_e32 v89, v0
	v_mov_b32_e32 v90, v0
	v_mov_b32_e32 v91, v0
	v_mov_b32_e32 v92, v0
	v_mov_b32_e32 v93, v0
	v_mov_b32_e32 v94, v0
	v_mov_b32_e32 v95, v0
	v_mov_b32_e32 v104, v0
	v_mov_b32_e32 v105, v0
	v_mov_b32_e32 v106, v0
	v_mov_b32_e32 v107, v0
	v_mov_b32_e32 v108, v0
	v_mov_b32_e32 v109, v0
	v_mov_b32_e32 v110, v0
	v_mov_b32_e32 v111, v0
	v_mov_b32_e32 v120, v0
	v_mov_b32_e32 v121, v0
	v_mov_b32_e32 v122, v0
	v_mov_b32_e32 v123, v0
	v_mov_b32_e32 v124, v0
	v_mov_b32_e32 v125, v0
	v_mov_b32_e32 v126, v0
	v_mov_b32_e32 v127, v0
	s_mov_b64 s[50:51], 0x80
	v_add_u32_e32 v156, 0x10000, v142
	ds_read_b128 v[144:147], v156
	ds_read_b128 v[148:151], v156 offset:1024
	ds_read_b128 v[152:155], v156 offset:2048
	ds_read_b128 v[156:159], v156 offset:3072
	ds_read_b128 v[248:251], v143 offset:6144
	ds_read_b128 v[252:255], v143 offset:7168
.LBB0_152:
	s_add_u32 s20, s18, 0xfffe0080
	s_addc_u32 s21, s19, -1
	s_add_i32 s45, 0, 0x10000
	v_add_u32_e32 v138, s45, v142
	s_cmp_eq_u32 s44, 4
	s_cselect_b32 s23, s9, s21
	s_cselect_b32 s22, s40, s20
	s_cselect_b32 s21, s7, s43
	s_cselect_b32 s20, s41, s42
	v_lshl_add_u64 v[138:139], s[18:19], 0, v[134:135]
	s_add_i32 m0, s17, 0xc000
	ds_read_b128 v[160:163], v143
	ds_read_b128 v[164:167], v143 offset:1024
	ds_read_b128 v[168:171], v143 offset:2048
	ds_read_b128 v[172:175], v143 offset:3072
	ds_read_b128 v[176:179], v143 offset:4096
	ds_read_b128 v[180:183], v143 offset:5120
	global_load_lds_dwordx4 v[138:139], off
	v_lshl_add_u64 v[138:139], s[18:19], 0, v[136:137]
	s_add_i32 m0, s17, 0xe000
	s_nop 0
	global_load_lds_dwordx4 v[138:139], off
	s_waitcnt lgkmcnt(8)
	s_setprio 1
	s_waitcnt vmcnt(8)
	s_barrier
	s_waitcnt lgkmcnt(0)
	v_mfma_f32_16x16x32_bf16 v[124:127], v[144:147], v[160:163], v[124:127]
	v_mfma_f32_16x16x32_bf16 v[120:123], v[152:155], v[160:163], v[120:123]
	v_mfma_f32_16x16x32_bf16 v[108:111], v[144:147], v[168:171], v[108:111]
	v_mfma_f32_16x16x32_bf16 v[104:107], v[152:155], v[168:171], v[104:107]
	v_mfma_f32_16x16x32_bf16 v[92:95], v[144:147], v[176:179], v[92:95]
	v_mfma_f32_16x16x32_bf16 v[88:91], v[152:155], v[176:179], v[88:91]
	v_mfma_f32_16x16x32_bf16 v[76:79], v[144:147], v[248:251], v[76:79]
	v_mfma_f32_16x16x32_bf16 v[72:75], v[152:155], v[248:251], v[72:75]
	v_mfma_f32_16x16x32_bf16 v[124:127], v[148:151], v[164:167], v[124:127]
	v_mfma_f32_16x16x32_bf16 v[120:123], v[156:159], v[164:167], v[120:123]
	v_mfma_f32_16x16x32_bf16 v[108:111], v[148:151], v[172:175], v[108:111]
	v_mfma_f32_16x16x32_bf16 v[104:107], v[156:159], v[172:175], v[104:107]
	v_mfma_f32_16x16x32_bf16 v[92:95], v[148:151], v[180:183], v[92:95]
	v_mfma_f32_16x16x32_bf16 v[88:91], v[156:159], v[180:183], v[88:91]
	v_mfma_f32_16x16x32_bf16 v[76:79], v[148:151], v[252:255], v[76:79]
	v_mfma_f32_16x16x32_bf16 v[72:75], v[156:159], v[252:255], v[72:75]
	s_barrier
	s_setprio 0
	ds_read_b128 v[188:191], v143 offset:22528
	ds_read_b128 v[192:195], v143 offset:23552
	s_add_i32 s48, 0, 0x14000
	v_add_u32_e32 v138, s48, v142
	s_add_i32 s45, s45, s29
	ds_read_b128 v[202:205], v138
	ds_read_b128 v[206:209], v138 offset:1024
	ds_read_b128 v[210:213], v138 offset:2048
	ds_read_b128 v[214:217], v138 offset:3072
	v_lshl_add_u64 v[138:139], s[20:21], 0, v[184:185]
	s_mov_b32 m0, s45
	v_lshl_add_u64 v[196:197], s[20:21], 0, v[128:129]
	global_load_lds_dwordx4 v[138:139], off
	s_add_i32 m0, s45, 0x2000
	s_nop 0
	global_load_lds_dwordx4 v[196:197], off
	s_setprio 1
	s_barrier
	s_waitcnt lgkmcnt(0)
	v_mfma_f32_16x16x32_bf16 v[116:119], v[202:205], v[160:163], v[116:119]
	v_mfma_f32_16x16x32_bf16 v[112:115], v[210:213], v[160:163], v[112:115]
	v_mfma_f32_16x16x32_bf16 v[100:103], v[202:205], v[168:171], v[100:103]
	v_mfma_f32_16x16x32_bf16 v[96:99], v[210:213], v[168:171], v[96:99]
	v_mfma_f32_16x16x32_bf16 v[84:87], v[202:205], v[176:179], v[84:87]
	v_mfma_f32_16x16x32_bf16 v[80:83], v[210:213], v[176:179], v[80:83]
	v_mfma_f32_16x16x32_bf16 v[68:71], v[202:205], v[248:251], v[68:71]
	v_mfma_f32_16x16x32_bf16 v[64:67], v[210:213], v[248:251], v[64:67]
	v_mfma_f32_16x16x32_bf16 v[116:119], v[206:209], v[164:167], v[116:119]
	v_mfma_f32_16x16x32_bf16 v[112:115], v[214:217], v[164:167], v[112:115]
	v_mfma_f32_16x16x32_bf16 v[100:103], v[206:209], v[172:175], v[100:103]
	v_mfma_f32_16x16x32_bf16 v[96:99], v[214:217], v[172:175], v[96:99]
	v_mfma_f32_16x16x32_bf16 v[84:87], v[206:209], v[180:183], v[84:87]
	v_mfma_f32_16x16x32_bf16 v[80:83], v[214:217], v[180:183], v[80:83]
	v_mfma_f32_16x16x32_bf16 v[68:71], v[206:209], v[252:255], v[68:71]
	v_mfma_f32_16x16x32_bf16 v[64:67], v[214:217], v[252:255], v[64:67]
	s_barrier
	s_setprio 0
	s_mov_b32 m0, s17
	v_lshl_add_u64 v[218:219], s[22:23], 0, v[132:133]
	ds_read_b128 v[160:163], v143 offset:16384
	ds_read_b128 v[164:167], v143 offset:17408
	ds_read_b128 v[168:171], v143 offset:18432
	ds_read_b128 v[172:175], v143 offset:19456
	ds_read_b128 v[176:179], v143 offset:20480
	ds_read_b128 v[180:183], v143 offset:21504
	global_load_lds_dwordx4 v[218:219], off
	v_lshl_add_u64 v[220:221], s[22:23], 0, v[130:131]
	s_mov_b32 m0, s30
	s_nop 0
	global_load_lds_dwordx4 v[220:221], off
	s_setprio 1
	s_waitcnt vmcnt(8)
	s_barrier
	s_waitcnt lgkmcnt(0)
	v_mfma_f32_16x16x32_bf16 v[60:63], v[144:147], v[160:163], v[60:63]
	v_mfma_f32_16x16x32_bf16 v[56:59], v[152:155], v[160:163], v[56:59]
	v_mfma_f32_16x16x32_bf16 v[44:47], v[144:147], v[168:171], v[44:47]
	v_mfma_f32_16x16x32_bf16 v[40:43], v[152:155], v[168:171], v[40:43]
	v_mfma_f32_16x16x32_bf16 v[28:31], v[144:147], v[176:179], v[28:31]
	v_mfma_f32_16x16x32_bf16 v[24:27], v[152:155], v[176:179], v[24:27]
	v_mfma_f32_16x16x32_bf16 v[12:15], v[144:147], v[188:191], v[12:15]
	v_mfma_f32_16x16x32_bf16 v[8:11], v[152:155], v[188:191], v[8:11]
	v_mfma_f32_16x16x32_bf16 v[60:63], v[148:151], v[164:167], v[60:63]
	v_mfma_f32_16x16x32_bf16 v[56:59], v[156:159], v[164:167], v[56:59]
	v_mfma_f32_16x16x32_bf16 v[44:47], v[148:151], v[172:175], v[44:47]
	v_mfma_f32_16x16x32_bf16 v[40:43], v[156:159], v[172:175], v[40:43]
	v_mfma_f32_16x16x32_bf16 v[28:31], v[148:151], v[180:183], v[28:31]
	v_mfma_f32_16x16x32_bf16 v[24:27], v[156:159], v[180:183], v[24:27]
	v_mfma_f32_16x16x32_bf16 v[12:15], v[148:151], v[192:195], v[12:15]
	v_mfma_f32_16x16x32_bf16 v[8:11], v[156:159], v[192:195], v[8:11]
	s_barrier
	s_setprio 0
	v_add_u32_e32 v156, 0x18000, v142
	ds_read_b128 v[144:147], v156
	ds_read_b128 v[148:151], v156 offset:1024
	ds_read_b128 v[152:155], v156 offset:2048
	ds_read_b128 v[156:159], v156 offset:3072
	ds_read_b128 v[248:251], v143 offset:38912
	ds_read_b128 v[252:255], v143 offset:39936
	s_add_u32 s46, s20, 0x20000
	s_addc_u32 s47, s21, 0
	s_add_i32 s45, s48, s29
	v_lshl_add_u64 v[246:247], s[46:47], 0, v[184:185]
	s_mov_b32 m0, s45
	s_nop 0
	global_load_lds_dwordx4 v[246:247], off
	v_lshl_add_u64 v[246:247], s[46:47], 0, v[128:129]
	s_add_i32 m0, s45, 0x2000
	s_nop 0
	global_load_lds_dwordx4 v[246:247], off
	s_waitcnt vmcnt(6)
	s_setprio 1
	s_barrier
	v_mfma_f32_16x16x32_bf16 v[52:55], v[202:205], v[160:163], v[52:55]
	v_mfma_f32_16x16x32_bf16 v[48:51], v[210:213], v[160:163], v[48:51]
	v_mfma_f32_16x16x32_bf16 v[36:39], v[202:205], v[168:171], v[36:39]
	v_mfma_f32_16x16x32_bf16 v[32:35], v[210:213], v[168:171], v[32:35]
	v_mfma_f32_16x16x32_bf16 v[20:23], v[202:205], v[176:179], v[20:23]
	v_mfma_f32_16x16x32_bf16 v[16:19], v[210:213], v[176:179], v[16:19]
	v_mfma_f32_16x16x32_bf16 v[4:7], v[202:205], v[188:191], v[4:7]
	v_mfma_f32_16x16x32_bf16 v[0:3], v[210:213], v[188:191], v[0:3]
	v_mfma_f32_16x16x32_bf16 v[52:55], v[206:209], v[164:167], v[52:55]
	v_mfma_f32_16x16x32_bf16 v[48:51], v[214:217], v[164:167], v[48:51]
	v_mfma_f32_16x16x32_bf16 v[36:39], v[206:209], v[172:175], v[36:39]
	v_mfma_f32_16x16x32_bf16 v[32:35], v[214:217], v[172:175], v[32:35]
	v_mfma_f32_16x16x32_bf16 v[20:23], v[206:209], v[180:183], v[20:23]
	v_mfma_f32_16x16x32_bf16 v[16:19], v[214:217], v[180:183], v[16:19]
	v_mfma_f32_16x16x32_bf16 v[4:7], v[206:209], v[192:195], v[4:7]
	v_mfma_f32_16x16x32_bf16 v[0:3], v[214:217], v[192:195], v[0:3]
	s_barrier
	s_setprio 0
	s_add_i32 s45, 0, 0x18000
	s_add_u32 s22, s22, 0x20000
	s_addc_u32 s23, s23, 0
	s_mov_b32 m0, s31
	v_lshl_add_u64 v[202:203], s[22:23], 0, v[132:133]
	ds_read_b128 v[160:163], v143 offset:32768
	ds_read_b128 v[164:167], v143 offset:33792
	ds_read_b128 v[168:171], v143 offset:34816
	ds_read_b128 v[172:175], v143 offset:35840
	ds_read_b128 v[176:179], v143 offset:36864
	ds_read_b128 v[180:183], v143 offset:37888
	global_load_lds_dwordx4 v[202:203], off
	v_lshl_add_u64 v[202:203], s[22:23], 0, v[130:131]
	s_mov_b32 m0, s33
	s_nop 0
	global_load_lds_dwordx4 v[202:203], off
	s_waitcnt lgkmcnt(8)
	s_setprio 1
	s_waitcnt vmcnt(8)
	s_barrier
	s_waitcnt lgkmcnt(0)
	v_mfma_f32_16x16x32_bf16 v[124:127], v[144:147], v[160:163], v[124:127]
	v_mfma_f32_16x16x32_bf16 v[120:123], v[152:155], v[160:163], v[120:123]
	v_mfma_f32_16x16x32_bf16 v[108:111], v[144:147], v[168:171], v[108:111]
	v_mfma_f32_16x16x32_bf16 v[104:107], v[152:155], v[168:171], v[104:107]
	v_mfma_f32_16x16x32_bf16 v[92:95], v[144:147], v[176:179], v[92:95]
	v_mfma_f32_16x16x32_bf16 v[88:91], v[152:155], v[176:179], v[88:91]
	v_mfma_f32_16x16x32_bf16 v[76:79], v[144:147], v[248:251], v[76:79]
	v_mfma_f32_16x16x32_bf16 v[72:75], v[152:155], v[248:251], v[72:75]
	v_mfma_f32_16x16x32_bf16 v[124:127], v[148:151], v[164:167], v[124:127]
	v_mfma_f32_16x16x32_bf16 v[120:123], v[156:159], v[164:167], v[120:123]
	v_mfma_f32_16x16x32_bf16 v[108:111], v[148:151], v[172:175], v[108:111]
	v_mfma_f32_16x16x32_bf16 v[104:107], v[156:159], v[172:175], v[104:107]
	v_mfma_f32_16x16x32_bf16 v[92:95], v[148:151], v[180:183], v[92:95]
	v_mfma_f32_16x16x32_bf16 v[88:91], v[156:159], v[180:183], v[88:91]
	v_mfma_f32_16x16x32_bf16 v[76:79], v[148:151], v[252:255], v[76:79]
	v_mfma_f32_16x16x32_bf16 v[72:75], v[156:159], v[252:255], v[72:75]
	s_barrier
	s_setprio 0
	ds_read_b128 v[188:191], v143 offset:55296
	ds_read_b128 v[192:195], v143 offset:56320
	s_add_i32 s22, 0, 0x1c000
	s_add_i32 s23, s45, s29
	v_add_u32_e32 v187, s22, v142
	v_lshl_add_u64 v[138:139], v[138:139], 0, s[50:51]
	s_mov_b32 m0, s23
	ds_read_b128 v[202:205], v187
	ds_read_b128 v[206:209], v187 offset:1024
	ds_read_b128 v[210:213], v187 offset:2048
	ds_read_b128 v[214:217], v187 offset:3072
	global_load_lds_dwordx4 v[138:139], off
	v_lshl_add_u64 v[138:139], v[196:197], 0, s[50:51]
	s_add_i32 m0, s23, 0x2000
	s_nop 0
	global_load_lds_dwordx4 v[138:139], off
	s_setprio 1
	s_barrier
	s_waitcnt lgkmcnt(0)
	v_mfma_f32_16x16x32_bf16 v[116:119], v[202:205], v[160:163], v[116:119]
	v_mfma_f32_16x16x32_bf16 v[112:115], v[210:213], v[160:163], v[112:115]
	v_mfma_f32_16x16x32_bf16 v[100:103], v[202:205], v[168:171], v[100:103]
	v_mfma_f32_16x16x32_bf16 v[96:99], v[210:213], v[168:171], v[96:99]
	v_mfma_f32_16x16x32_bf16 v[84:87], v[202:205], v[176:179], v[84:87]
	v_mfma_f32_16x16x32_bf16 v[80:83], v[210:213], v[176:179], v[80:83]
	v_mfma_f32_16x16x32_bf16 v[68:71], v[202:205], v[248:251], v[68:71]
	v_mfma_f32_16x16x32_bf16 v[64:67], v[210:213], v[248:251], v[64:67]
	v_mfma_f32_16x16x32_bf16 v[116:119], v[206:209], v[164:167], v[116:119]
	v_mfma_f32_16x16x32_bf16 v[112:115], v[214:217], v[164:167], v[112:115]
	v_mfma_f32_16x16x32_bf16 v[100:103], v[206:209], v[172:175], v[100:103]
	v_mfma_f32_16x16x32_bf16 v[96:99], v[214:217], v[172:175], v[96:99]
	v_mfma_f32_16x16x32_bf16 v[84:87], v[206:209], v[180:183], v[84:87]
	v_mfma_f32_16x16x32_bf16 v[80:83], v[214:217], v[180:183], v[80:83]
	v_mfma_f32_16x16x32_bf16 v[68:71], v[206:209], v[252:255], v[68:71]
	v_mfma_f32_16x16x32_bf16 v[64:67], v[214:217], v[252:255], v[64:67]
	s_barrier
	s_setprio 0
	s_mov_b32 m0, s36
	v_lshl_add_u64 v[138:139], v[218:219], 0, s[50:51]
	ds_read_b128 v[160:163], v143 offset:49152
	ds_read_b128 v[164:167], v143 offset:50176
	ds_read_b128 v[168:171], v143 offset:51200
	ds_read_b128 v[172:175], v143 offset:52224
	ds_read_b128 v[176:179], v143 offset:53248
	ds_read_b128 v[180:183], v143 offset:54272
	global_load_lds_dwordx4 v[138:139], off
	v_lshl_add_u64 v[138:139], v[220:221], 0, s[50:51]
	s_mov_b32 m0, s37
	s_nop 0
	global_load_lds_dwordx4 v[138:139], off
	s_setprio 1
	s_waitcnt vmcnt(8)
	s_barrier
	s_waitcnt lgkmcnt(0)
	v_mfma_f32_16x16x32_bf16 v[60:63], v[144:147], v[160:163], v[60:63]
	v_mfma_f32_16x16x32_bf16 v[56:59], v[152:155], v[160:163], v[56:59]
	v_mfma_f32_16x16x32_bf16 v[44:47], v[144:147], v[168:171], v[44:47]
	v_mfma_f32_16x16x32_bf16 v[40:43], v[152:155], v[168:171], v[40:43]
	v_mfma_f32_16x16x32_bf16 v[28:31], v[144:147], v[176:179], v[28:31]
	v_mfma_f32_16x16x32_bf16 v[24:27], v[152:155], v[176:179], v[24:27]
	v_mfma_f32_16x16x32_bf16 v[12:15], v[144:147], v[188:191], v[12:15]
	v_mfma_f32_16x16x32_bf16 v[8:11], v[152:155], v[188:191], v[8:11]
	v_mfma_f32_16x16x32_bf16 v[60:63], v[148:151], v[164:167], v[60:63]
	v_mfma_f32_16x16x32_bf16 v[56:59], v[156:159], v[164:167], v[56:59]
	v_mfma_f32_16x16x32_bf16 v[44:47], v[148:151], v[172:175], v[44:47]
	v_mfma_f32_16x16x32_bf16 v[40:43], v[156:159], v[172:175], v[40:43]
	v_mfma_f32_16x16x32_bf16 v[28:31], v[148:151], v[180:183], v[28:31]
	v_mfma_f32_16x16x32_bf16 v[24:27], v[156:159], v[180:183], v[24:27]
	v_mfma_f32_16x16x32_bf16 v[12:15], v[148:151], v[192:195], v[12:15]
	v_mfma_f32_16x16x32_bf16 v[8:11], v[156:159], v[192:195], v[8:11]
	s_barrier
	s_setprio 0
	v_add_u32_e32 v156, 0x10000, v142
	ds_read_b128 v[144:147], v156
	ds_read_b128 v[148:151], v156 offset:1024
	ds_read_b128 v[152:155], v156 offset:2048
	ds_read_b128 v[156:159], v156 offset:3072
	ds_read_b128 v[248:251], v143 offset:6144
	ds_read_b128 v[252:255], v143 offset:7168
	s_add_u32 s20, s20, 0x20080
	s_addc_u32 s21, s21, 0
	s_add_i32 s22, s22, s29
	v_lshl_add_u64 v[138:139], s[20:21], 0, v[184:185]
	s_mov_b32 m0, s22
	s_nop 0
	global_load_lds_dwordx4 v[138:139], off
	v_lshl_add_u64 v[138:139], s[20:21], 0, v[128:129]
	s_add_i32 m0, s22, 0x2000
	s_nop 0
	global_load_lds_dwordx4 v[138:139], off
	s_waitcnt vmcnt(6)
	s_setprio 1
	s_barrier
	v_mfma_f32_16x16x32_bf16 v[52:55], v[202:205], v[160:163], v[52:55]
	v_mfma_f32_16x16x32_bf16 v[48:51], v[210:213], v[160:163], v[48:51]
	v_mfma_f32_16x16x32_bf16 v[36:39], v[202:205], v[168:171], v[36:39]
	v_mfma_f32_16x16x32_bf16 v[32:35], v[210:213], v[168:171], v[32:35]
	v_mfma_f32_16x16x32_bf16 v[20:23], v[202:205], v[176:179], v[20:23]
	v_mfma_f32_16x16x32_bf16 v[16:19], v[210:213], v[176:179], v[16:19]
	v_mfma_f32_16x16x32_bf16 v[4:7], v[202:205], v[188:191], v[4:7]
	v_mfma_f32_16x16x32_bf16 v[0:3], v[210:213], v[188:191], v[0:3]
	v_mfma_f32_16x16x32_bf16 v[52:55], v[206:209], v[164:167], v[52:55]
	v_mfma_f32_16x16x32_bf16 v[48:51], v[214:217], v[164:167], v[48:51]
	v_mfma_f32_16x16x32_bf16 v[36:39], v[206:209], v[172:175], v[36:39]
	v_mfma_f32_16x16x32_bf16 v[32:35], v[214:217], v[172:175], v[32:35]
	v_mfma_f32_16x16x32_bf16 v[20:23], v[206:209], v[180:183], v[20:23]
	v_mfma_f32_16x16x32_bf16 v[16:19], v[214:217], v[180:183], v[16:19]
	v_mfma_f32_16x16x32_bf16 v[4:7], v[206:209], v[192:195], v[4:7]
	v_mfma_f32_16x16x32_bf16 v[0:3], v[214:217], v[192:195], v[0:3]
	s_barrier
	s_setprio 0
	s_add_i32 s44, s44, 2
	s_add_u32 s18, s18, 0x100
	s_addc_u32 s19, s19, 0
	s_add_u32 s42, s42, 0x100
	s_addc_u32 s43, s43, 0
	s_cmp_gt_u32 s44, 5
	s_cbranch_scc0 .LBB0_152
	s_waitcnt lgkmcnt(0)
	v_mov_b32_e32 v139, v141
	v_mov_b32_e32 v138, v140
	s_lshl_b32 s7, s16, 8
	s_add_i32 s7, s7, s34
	v_add_u32_e32 v138, s7, v138
	s_lshl_b32 s7, s39, 8
	s_or_b32 s7, s7, s35
	v_lshl_add_u32 v152, v139, 3, s7
	v_ashrrev_i32_e32 v139, 31, v138
	v_lshlrev_b64 v[144:145], 5, v[138:139]
	v_lshl_add_u64 v[148:149], s[4:5], 0, v[144:145]
	global_load_dwordx4 v[144:147], v[148:149], off offset:16
	s_nop 0
	global_load_dwordx4 v[148:151], v[148:149], off
	s_movk_i32 s7, 0x1800
	v_ashrrev_i32_e32 v153, 31, v152
	s_mov_b32 s39, s6
	s_mov_b32 s16, s8
	s_mov_b64 s[20:21], s[14:15]
	s_waitcnt vmcnt(0)
	v_add_f32_e32 v139, v148, v149
	v_add_f32_e32 v139, v150, v139
	v_add_f32_e32 v139, v151, v139
	v_add_f32_e32 v139, v144, v139
	v_add_f32_e32 v139, v145, v139
	v_add_f32_e32 v139, v146, v139
	v_add_f32_e32 v139, v147, v139
	v_add_f32_e32 v139, 0x3a0637bd, v139
	v_mul_f32_e32 v139, 0x3b000000, v139
	v_cmp_gt_f32_e32 vcc, s67, v139
	v_mul_f32_e32 v144, 0x4b800000, v139
	s_nop 0
	v_cndmask_b32_e32 v139, v139, v144, vcc
	v_rsq_f32_e32 v139, v139
	s_nop 0
	v_mul_f32_e32 v144, 0x45800000, v139
	v_cndmask_b32_e32 v139, v139, v144, vcc
	v_mul_f32_e32 v124, v124, v139
	v_mul_f32_e32 v125, v125, v139
	v_mul_f32_e32 v126, v126, v139
	v_mul_f32_e32 v120, v120, v139
	v_mul_f32_e32 v121, v121, v139
	v_mul_f32_e32 v127, v127, v139
	v_mul_f32_e32 v122, v122, v139
	v_mul_f32_e32 v123, v123, v139
	v_cvt_pk_bf16_f32 v124, v124, v125
	v_cvt_pk_bf16_f32 v125, v126, v127
	v_cvt_pk_bf16_f32 v126, v120, v121
	v_mov_b64_e32 v[120:121], s[2:3]
	v_cvt_pk_bf16_f32 v127, v122, v123
	v_mad_i64_i32 v[144:145], s[18:19], v138, s7, v[120:121]
	v_lshlrev_b64 v[122:123], 1, v[152:153]
	v_lshl_add_u64 v[144:145], v[144:145], 0, v[122:123]
	global_store_dwordx4 v[144:145], v[124:127], off
	v_mul_f32_e32 v116, v116, v139
	v_mul_f32_e32 v117, v117, v139
	v_mul_f32_e32 v124, v112, v139
	v_mul_f32_e32 v118, v118, v139
	v_mul_f32_e32 v119, v119, v139
	v_mul_f32_e32 v125, v113, v139
	v_mul_f32_e32 v126, v114, v139
	v_cvt_pk_bf16_f32 v112, v116, v117
	v_cvt_pk_bf16_f32 v113, v118, v119
	v_cvt_pk_bf16_f32 v114, v124, v125
	v_add_u32_e32 v124, 16, v138
	v_mul_f32_e32 v115, v115, v139
	v_ashrrev_i32_e32 v125, 31, v124
	v_cvt_pk_bf16_f32 v115, v126, v115
	global_store_dwordx4 v[144:145], v[112:115], off offset:256
	s_nop 1
	v_lshlrev_b64 v[112:113], 5, v[124:125]
	v_lshl_add_u64 v[116:117], s[4:5], 0, v[112:113]
	global_load_dwordx4 v[112:115], v[116:117], off offset:16
	s_nop 0
	global_load_dwordx4 v[116:119], v[116:117], off
	s_waitcnt vmcnt(0)
	v_add_f32_e32 v116, v116, v117
	v_add_f32_e32 v116, v118, v116
	v_add_f32_e32 v116, v119, v116
	v_add_f32_e32 v112, v112, v116
	v_add_f32_e32 v112, v113, v112
	v_add_f32_e32 v112, v114, v112
	v_add_f32_e32 v112, v115, v112
	v_add_f32_e32 v112, 0x3a0637bd, v112
	v_mul_f32_e32 v112, 0x3b000000, v112
	v_cmp_gt_f32_e32 vcc, s67, v112
	v_mul_f32_e32 v113, 0x4b800000, v112
	s_nop 0
	v_cndmask_b32_e32 v112, v112, v113, vcc
	v_rsq_f32_e32 v112, v112
	s_nop 0
	v_mul_f32_e32 v113, 0x45800000, v112
	v_cndmask_b32_e32 v112, v112, v113, vcc
	v_mul_f32_e32 v108, v108, v112
	v_mul_f32_e32 v109, v109, v112
	v_mul_f32_e32 v113, v104, v112
	v_cvt_pk_bf16_f32 v104, v108, v109
	v_mad_i64_i32 v[108:109], s[18:19], v124, s7, v[120:121]
	v_mul_f32_e32 v107, v107, v112
	v_lshl_add_u64 v[108:109], v[108:109], 0, v[122:123]
	v_mul_f32_e32 v110, v110, v112
	v_mul_f32_e32 v111, v111, v112
	v_mul_f32_e32 v114, v105, v112
	v_mul_f32_e32 v115, v106, v112
	v_cvt_pk_bf16_f32 v105, v110, v111
	v_cvt_pk_bf16_f32 v106, v113, v114
	v_cvt_pk_bf16_f32 v107, v115, v107
	global_store_dwordx4 v[108:109], v[104:107], off
	v_mul_f32_e32 v100, v100, v112
	v_mul_f32_e32 v101, v101, v112
	v_mul_f32_e32 v104, v96, v112
	v_mul_f32_e32 v102, v102, v112
	v_mul_f32_e32 v103, v103, v112
	v_mul_f32_e32 v105, v97, v112
	v_mul_f32_e32 v106, v98, v112
	v_cvt_pk_bf16_f32 v96, v100, v101
	v_cvt_pk_bf16_f32 v97, v102, v103
	v_cvt_pk_bf16_f32 v98, v104, v105
	v_add_u32_e32 v104, 32, v138
	v_mul_f32_e32 v99, v99, v112
	v_ashrrev_i32_e32 v105, 31, v104
	v_cvt_pk_bf16_f32 v99, v106, v99
	global_store_dwordx4 v[108:109], v[96:99], off offset:256
	s_nop 1
	v_lshlrev_b64 v[96:97], 5, v[104:105]
	v_lshl_add_u64 v[100:101], s[4:5], 0, v[96:97]
	global_load_dwordx4 v[96:99], v[100:101], off offset:16
	s_nop 0
	global_load_dwordx4 v[100:103], v[100:101], off
	s_waitcnt vmcnt(0)
	v_add_f32_e32 v100, v100, v101
	v_add_f32_e32 v100, v102, v100
	v_add_f32_e32 v100, v103, v100
	v_add_f32_e32 v96, v96, v100
	v_add_f32_e32 v96, v97, v96
	v_add_f32_e32 v96, v98, v96
	v_add_f32_e32 v96, v99, v96
	v_add_f32_e32 v96, 0x3a0637bd, v96
	v_mul_f32_e32 v96, 0x3b000000, v96
	v_cmp_gt_f32_e32 vcc, s67, v96
	v_mul_f32_e32 v97, 0x4b800000, v96
	s_nop 0
	v_cndmask_b32_e32 v96, v96, v97, vcc
	v_rsq_f32_e32 v96, v96
	s_nop 0
	v_mul_f32_e32 v97, 0x45800000, v96
	v_cndmask_b32_e32 v96, v96, v97, vcc
	v_mul_f32_e32 v92, v92, v96
	v_mul_f32_e32 v93, v93, v96
	v_mul_f32_e32 v97, v88, v96
	v_cvt_pk_bf16_f32 v88, v92, v93
	v_mad_i64_i32 v[92:93], s[18:19], v104, s7, v[120:121]
	v_mul_f32_e32 v91, v91, v96
	v_lshl_add_u64 v[92:93], v[92:93], 0, v[122:123]
	v_mul_f32_e32 v94, v94, v96
	v_mul_f32_e32 v95, v95, v96
	v_mul_f32_e32 v98, v89, v96
	v_mul_f32_e32 v99, v90, v96
	v_cvt_pk_bf16_f32 v89, v94, v95
	v_cvt_pk_bf16_f32 v90, v97, v98
	v_cvt_pk_bf16_f32 v91, v99, v91
	global_store_dwordx4 v[92:93], v[88:91], off
	v_mul_f32_e32 v84, v84, v96
	v_mul_f32_e32 v85, v85, v96
	v_mul_f32_e32 v88, v80, v96
	v_mul_f32_e32 v86, v86, v96
	v_mul_f32_e32 v87, v87, v96
	v_mul_f32_e32 v89, v81, v96
	v_mul_f32_e32 v90, v82, v96
	v_cvt_pk_bf16_f32 v80, v84, v85
	v_cvt_pk_bf16_f32 v81, v86, v87
	v_cvt_pk_bf16_f32 v82, v88, v89
	v_add_u32_e32 v88, 48, v138
	v_mul_f32_e32 v83, v83, v96
	v_ashrrev_i32_e32 v89, 31, v88
	v_cvt_pk_bf16_f32 v83, v90, v83
	global_store_dwordx4 v[92:93], v[80:83], off offset:256
	s_nop 1
	v_lshlrev_b64 v[80:81], 5, v[88:89]
	v_lshl_add_u64 v[84:85], s[4:5], 0, v[80:81]
	global_load_dwordx4 v[80:83], v[84:85], off offset:16
	s_nop 0
	global_load_dwordx4 v[84:87], v[84:85], off
	s_waitcnt vmcnt(0)
	v_add_f32_e32 v84, v84, v85
	v_add_f32_e32 v84, v86, v84
	v_add_f32_e32 v84, v87, v84
	v_add_f32_e32 v80, v80, v84
	v_add_f32_e32 v80, v81, v80
	v_add_f32_e32 v80, v82, v80
	v_add_f32_e32 v80, v83, v80
	v_add_f32_e32 v80, 0x3a0637bd, v80
	v_mul_f32_e32 v80, 0x3b000000, v80
	v_cmp_gt_f32_e32 vcc, s67, v80
	v_mul_f32_e32 v81, 0x4b800000, v80
	s_nop 0
	v_cndmask_b32_e32 v80, v80, v81, vcc
	v_rsq_f32_e32 v80, v80
	s_nop 0
	v_mul_f32_e32 v81, 0x45800000, v80
	v_cndmask_b32_e32 v80, v80, v81, vcc
	v_mul_f32_e32 v76, v76, v80
	v_mul_f32_e32 v77, v77, v80
	v_mul_f32_e32 v81, v72, v80
	v_cvt_pk_bf16_f32 v72, v76, v77
	v_mad_i64_i32 v[76:77], s[18:19], v88, s7, v[120:121]
	v_mul_f32_e32 v75, v75, v80
	v_lshl_add_u64 v[76:77], v[76:77], 0, v[122:123]
	v_mul_f32_e32 v78, v78, v80
	v_mul_f32_e32 v79, v79, v80
	v_mul_f32_e32 v82, v73, v80
	v_mul_f32_e32 v83, v74, v80
	v_cvt_pk_bf16_f32 v73, v78, v79
	v_cvt_pk_bf16_f32 v74, v81, v82
	v_cvt_pk_bf16_f32 v75, v83, v75
	global_store_dwordx4 v[76:77], v[72:75], off
	v_mul_f32_e32 v68, v68, v80
	v_mul_f32_e32 v69, v69, v80
	v_mul_f32_e32 v72, v64, v80
	v_mul_f32_e32 v70, v70, v80
	v_mul_f32_e32 v71, v71, v80
	v_mul_f32_e32 v73, v65, v80
	v_mul_f32_e32 v74, v66, v80
	v_cvt_pk_bf16_f32 v64, v68, v69
	v_cvt_pk_bf16_f32 v65, v70, v71
	v_cvt_pk_bf16_f32 v66, v72, v73
	v_add_u32_e32 v72, 0x80, v138
	v_mul_f32_e32 v67, v67, v80
	v_ashrrev_i32_e32 v73, 31, v72
	v_cvt_pk_bf16_f32 v67, v74, v67
	global_store_dwordx4 v[76:77], v[64:67], off offset:256
	s_nop 1
	v_lshlrev_b64 v[64:65], 5, v[72:73]
	v_lshl_add_u64 v[68:69], s[4:5], 0, v[64:65]
	global_load_dwordx4 v[64:67], v[68:69], off offset:16
	s_nop 0
	global_load_dwordx4 v[68:71], v[68:69], off
	s_waitcnt vmcnt(0)
	v_add_f32_e32 v68, v68, v69
	v_add_f32_e32 v68, v70, v68
	v_add_f32_e32 v68, v71, v68
	v_add_f32_e32 v64, v64, v68
	v_add_f32_e32 v64, v65, v64
	v_add_f32_e32 v64, v66, v64
	v_add_f32_e32 v64, v67, v64
	v_add_f32_e32 v64, 0x3a0637bd, v64
	v_mul_f32_e32 v64, 0x3b000000, v64
	v_cmp_gt_f32_e32 vcc, s67, v64
	v_mul_f32_e32 v65, 0x4b800000, v64
	s_nop 0
	v_cndmask_b32_e32 v64, v64, v65, vcc
	v_rsq_f32_e32 v64, v64
	s_nop 0
	v_mul_f32_e32 v65, 0x45800000, v64
	v_cndmask_b32_e32 v64, v64, v65, vcc
	v_mul_f32_e32 v60, v60, v64
	v_mul_f32_e32 v61, v61, v64
	v_mul_f32_e32 v65, v56, v64
	v_cvt_pk_bf16_f32 v56, v60, v61
	v_mad_i64_i32 v[60:61], s[18:19], v72, s7, v[120:121]
	v_mul_f32_e32 v59, v59, v64
	v_lshl_add_u64 v[60:61], v[60:61], 0, v[122:123]
	v_mul_f32_e32 v62, v62, v64
	v_mul_f32_e32 v63, v63, v64
	v_mul_f32_e32 v66, v57, v64
	v_mul_f32_e32 v67, v58, v64
	v_cvt_pk_bf16_f32 v57, v62, v63
	v_cvt_pk_bf16_f32 v58, v65, v66
	v_cvt_pk_bf16_f32 v59, v67, v59
	global_store_dwordx4 v[60:61], v[56:59], off
	v_mul_f32_e32 v52, v52, v64
	v_mul_f32_e32 v53, v53, v64
	v_mul_f32_e32 v56, v48, v64
	v_mul_f32_e32 v54, v54, v64
	v_mul_f32_e32 v55, v55, v64
	v_mul_f32_e32 v57, v49, v64
	v_mul_f32_e32 v58, v50, v64
	v_cvt_pk_bf16_f32 v48, v52, v53
	v_cvt_pk_bf16_f32 v49, v54, v55
	v_cvt_pk_bf16_f32 v50, v56, v57
	v_add_u32_e32 v56, 0x90, v138
	v_mul_f32_e32 v51, v51, v64
	v_ashrrev_i32_e32 v57, 31, v56
	v_cvt_pk_bf16_f32 v51, v58, v51
	global_store_dwordx4 v[60:61], v[48:51], off offset:256
	s_nop 1
	v_lshlrev_b64 v[48:49], 5, v[56:57]
	v_lshl_add_u64 v[52:53], s[4:5], 0, v[48:49]
	global_load_dwordx4 v[48:51], v[52:53], off offset:16
	s_nop 0
	global_load_dwordx4 v[52:55], v[52:53], off
	s_waitcnt vmcnt(0)
	v_add_f32_e32 v52, v52, v53
	v_add_f32_e32 v52, v54, v52
	v_add_f32_e32 v52, v55, v52
	v_add_f32_e32 v48, v48, v52
	v_add_f32_e32 v48, v49, v48
	v_add_f32_e32 v48, v50, v48
	v_add_f32_e32 v48, v51, v48
	v_add_f32_e32 v48, 0x3a0637bd, v48
	v_mul_f32_e32 v48, 0x3b000000, v48
	v_cmp_gt_f32_e32 vcc, s67, v48
	v_mul_f32_e32 v49, 0x4b800000, v48
	s_nop 0
	v_cndmask_b32_e32 v48, v48, v49, vcc
	v_rsq_f32_e32 v48, v48
	s_nop 0
	v_mul_f32_e32 v49, 0x45800000, v48
	v_cndmask_b32_e32 v48, v48, v49, vcc
	v_mul_f32_e32 v44, v44, v48
	v_mul_f32_e32 v45, v45, v48
	v_mul_f32_e32 v49, v40, v48
	v_cvt_pk_bf16_f32 v40, v44, v45
	v_mad_i64_i32 v[44:45], s[18:19], v56, s7, v[120:121]
	v_mul_f32_e32 v43, v43, v48
	v_lshl_add_u64 v[44:45], v[44:45], 0, v[122:123]
	v_mul_f32_e32 v46, v46, v48
	v_mul_f32_e32 v47, v47, v48
	v_mul_f32_e32 v50, v41, v48
	v_mul_f32_e32 v51, v42, v48
	v_cvt_pk_bf16_f32 v41, v46, v47
	v_cvt_pk_bf16_f32 v42, v49, v50
	v_cvt_pk_bf16_f32 v43, v51, v43
	global_store_dwordx4 v[44:45], v[40:43], off
	v_mul_f32_e32 v36, v36, v48
	v_mul_f32_e32 v37, v37, v48
	v_mul_f32_e32 v40, v32, v48
	v_mul_f32_e32 v38, v38, v48
	v_mul_f32_e32 v39, v39, v48
	v_mul_f32_e32 v41, v33, v48
	v_mul_f32_e32 v42, v34, v48
	v_cvt_pk_bf16_f32 v32, v36, v37
	v_cvt_pk_bf16_f32 v33, v38, v39
	v_cvt_pk_bf16_f32 v34, v40, v41
	v_add_u32_e32 v40, 0xa0, v138
	v_mul_f32_e32 v35, v35, v48
	v_ashrrev_i32_e32 v41, 31, v40
	v_cvt_pk_bf16_f32 v35, v42, v35
	global_store_dwordx4 v[44:45], v[32:35], off offset:256
	s_nop 1
	v_lshlrev_b64 v[32:33], 5, v[40:41]
	v_lshl_add_u64 v[36:37], s[4:5], 0, v[32:33]
	global_load_dwordx4 v[32:35], v[36:37], off offset:16
	s_nop 0
	global_load_dwordx4 v[36:39], v[36:37], off
	s_waitcnt vmcnt(0)
	v_add_f32_e32 v36, v36, v37
	v_add_f32_e32 v36, v38, v36
	v_add_f32_e32 v36, v39, v36
	v_add_f32_e32 v32, v32, v36
	v_add_f32_e32 v32, v33, v32
	v_add_f32_e32 v32, v34, v32
	v_add_f32_e32 v32, v35, v32
	v_add_f32_e32 v32, 0x3a0637bd, v32
	v_mul_f32_e32 v32, 0x3b000000, v32
	v_cmp_gt_f32_e32 vcc, s67, v32
	v_mul_f32_e32 v33, 0x4b800000, v32
	s_nop 0
	v_cndmask_b32_e32 v32, v32, v33, vcc
	v_rsq_f32_e32 v32, v32
	s_nop 0
	v_mul_f32_e32 v33, 0x45800000, v32
	v_cndmask_b32_e32 v32, v32, v33, vcc
	v_mul_f32_e32 v28, v28, v32
	v_mul_f32_e32 v29, v29, v32
	v_mul_f32_e32 v33, v24, v32
	v_cvt_pk_bf16_f32 v24, v28, v29
	v_mad_i64_i32 v[28:29], s[18:19], v40, s7, v[120:121]
	v_mul_f32_e32 v27, v27, v32
	v_lshl_add_u64 v[28:29], v[28:29], 0, v[122:123]
	v_mul_f32_e32 v30, v30, v32
	v_mul_f32_e32 v31, v31, v32
	v_mul_f32_e32 v34, v25, v32
	v_mul_f32_e32 v35, v26, v32
	v_cvt_pk_bf16_f32 v25, v30, v31
	v_cvt_pk_bf16_f32 v26, v33, v34
	v_cvt_pk_bf16_f32 v27, v35, v27
	global_store_dwordx4 v[28:29], v[24:27], off
	v_mul_f32_e32 v20, v20, v32
	v_mul_f32_e32 v21, v21, v32
	v_mul_f32_e32 v24, v16, v32
	v_mul_f32_e32 v22, v22, v32
	v_mul_f32_e32 v23, v23, v32
	v_mul_f32_e32 v25, v17, v32
	v_mul_f32_e32 v26, v18, v32
	v_cvt_pk_bf16_f32 v16, v20, v21
	v_cvt_pk_bf16_f32 v17, v22, v23
	v_cvt_pk_bf16_f32 v18, v24, v25
	v_add_u32_e32 v24, 0xb0, v138
	v_mul_f32_e32 v19, v19, v32
	v_ashrrev_i32_e32 v25, 31, v24
	v_cvt_pk_bf16_f32 v19, v26, v19
	global_store_dwordx4 v[28:29], v[16:19], off offset:256
	s_nop 1
	v_lshlrev_b64 v[16:17], 5, v[24:25]
	v_lshl_add_u64 v[20:21], s[4:5], 0, v[16:17]
	global_load_dwordx4 v[16:19], v[20:21], off offset:16
	s_nop 0
	global_load_dwordx4 v[20:23], v[20:21], off
	s_waitcnt vmcnt(0)
	v_add_f32_e32 v20, v20, v21
	v_add_f32_e32 v20, v22, v20
	v_add_f32_e32 v20, v23, v20
	v_add_f32_e32 v16, v16, v20
	v_add_f32_e32 v16, v17, v16
	v_add_f32_e32 v16, v18, v16
	v_add_f32_e32 v16, v19, v16
	v_add_f32_e32 v16, 0x3a0637bd, v16
	v_mul_f32_e32 v16, 0x3b000000, v16
	v_cmp_gt_f32_e32 vcc, s67, v16
	v_mul_f32_e32 v17, 0x4b800000, v16
	s_nop 0
	v_cndmask_b32_e32 v16, v16, v17, vcc
	v_rsq_f32_e32 v16, v16
	s_nop 0
	v_mul_f32_e32 v17, 0x45800000, v16
	v_cndmask_b32_e32 v16, v16, v17, vcc
	v_mul_f32_e32 v12, v12, v16
	v_mul_f32_e32 v13, v13, v16
	v_mul_f32_e32 v17, v8, v16
	v_cvt_pk_bf16_f32 v8, v12, v13
	v_mad_i64_i32 v[12:13], s[18:19], v24, s7, v[120:121]
	v_mul_f32_e32 v14, v14, v16
	v_mul_f32_e32 v15, v15, v16
	v_mul_f32_e32 v18, v9, v16
	v_mul_f32_e32 v19, v10, v16
	v_mul_f32_e32 v11, v11, v16
	v_cvt_pk_bf16_f32 v9, v14, v15
	v_cvt_pk_bf16_f32 v10, v17, v18
	v_lshl_add_u64 v[12:13], v[12:13], 0, v[122:123]
	v_mul_f32_e32 v3, v3, v16
	s_and_b64 vcc, exec, s[10:11]
	s_mov_b64 s[18:19], s[12:13]
	v_cvt_pk_bf16_f32 v11, v19, v11
	global_store_dwordx4 v[12:13], v[8:11], off
	v_mul_f32_e32 v4, v4, v16
	v_mul_f32_e32 v5, v5, v16
	v_mul_f32_e32 v6, v6, v16
	v_mul_f32_e32 v7, v7, v16
	v_mul_f32_e32 v8, v0, v16
	v_mul_f32_e32 v9, v1, v16
	v_mul_f32_e32 v10, v2, v16
	v_cvt_pk_bf16_f32 v0, v4, v5
	v_cvt_pk_bf16_f32 v1, v6, v7
	v_cvt_pk_bf16_f32 v2, v8, v9
	v_cvt_pk_bf16_f32 v3, v10, v3
	global_store_dwordx4 v[12:13], v[0:3], off offset:256
	s_cbranch_vccz .LBB0_149
	s_waitcnt vmcnt(0)
	s_cmpk_gt_u32 s24, 0xff
	s_cbranch_scc1 .LBB0_156
	s_barrier

.LBB0_168:
	s_ashr_i32 s11, s10, 31
	s_lshl_b64 s[16:17], s[10:11], 20
	s_add_u32 s16, s29, s16
	s_addc_u32 s17, s30, s17
	s_and_b64 s[18:19], s[26:27], exec
	s_cselect_b32 s1, s17, s23
	s_cselect_b32 s11, s16, s22
	s_ashr_i32 s13, s12, 31
	s_lshl_b64 s[18:19], s[12:13], 20
	s_add_u32 s18, s31, s18
	s_addc_u32 s19, s33, s19
	s_and_b64 s[26:27], s[26:27], exec
	s_cselect_b32 s13, s19, s25
	s_cselect_b32 s21, s18, s24
	s_add_u32 s22, s22, 0x80080
	s_addc_u32 s23, s23, 0
	s_add_u32 s45, s24, 0x100
	v_mov_b32_e32 v0, 0
	s_addc_u32 s46, s25, 0
	s_mov_b32 s47, -2
	v_mov_b32_e32 v1, v0
	v_mov_b32_e32 v2, v0
	v_mov_b32_e32 v3, v0
	v_mov_b32_e32 v4, v0
	v_mov_b32_e32 v5, v0
	v_mov_b32_e32 v6, v0
	v_mov_b32_e32 v7, v0
	v_mov_b32_e32 v16, v0
	v_mov_b32_e32 v17, v0
	v_mov_b32_e32 v18, v0
	v_mov_b32_e32 v19, v0
	v_mov_b32_e32 v20, v0
	v_mov_b32_e32 v21, v0
	v_mov_b32_e32 v22, v0
	v_mov_b32_e32 v23, v0
	v_mov_b32_e32 v32, v0
	v_mov_b32_e32 v33, v0
	v_mov_b32_e32 v34, v0
	v_mov_b32_e32 v35, v0
	v_mov_b32_e32 v36, v0
	v_mov_b32_e32 v37, v0
	v_mov_b32_e32 v38, v0
	v_mov_b32_e32 v39, v0
	v_mov_b32_e32 v48, v0
	v_mov_b32_e32 v49, v0
	v_mov_b32_e32 v50, v0
	v_mov_b32_e32 v51, v0
	v_mov_b32_e32 v52, v0
	v_mov_b32_e32 v53, v0
	v_mov_b32_e32 v54, v0
	v_mov_b32_e32 v55, v0
	v_mov_b32_e32 v8, v0
	v_mov_b32_e32 v9, v0
	v_mov_b32_e32 v10, v0
	v_mov_b32_e32 v11, v0
	v_mov_b32_e32 v12, v0
	v_mov_b32_e32 v13, v0
	v_mov_b32_e32 v14, v0
	v_mov_b32_e32 v15, v0
	v_mov_b32_e32 v24, v0
	v_mov_b32_e32 v25, v0
	v_mov_b32_e32 v26, v0
	v_mov_b32_e32 v27, v0
	v_mov_b32_e32 v28, v0
	v_mov_b32_e32 v29, v0
	v_mov_b32_e32 v30, v0
	v_mov_b32_e32 v31, v0
	v_mov_b32_e32 v40, v0
	v_mov_b32_e32 v41, v0
	v_mov_b32_e32 v42, v0
	v_mov_b32_e32 v43, v0
	v_mov_b32_e32 v44, v0
	v_mov_b32_e32 v45, v0
	v_mov_b32_e32 v46, v0
	v_mov_b32_e32 v47, v0
	v_mov_b32_e32 v56, v0
	v_mov_b32_e32 v57, v0
	v_mov_b32_e32 v58, v0
	v_mov_b32_e32 v59, v0
	v_mov_b32_e32 v60, v0
	v_mov_b32_e32 v61, v0
	v_mov_b32_e32 v62, v0
	v_mov_b32_e32 v63, v0
	v_mov_b32_e32 v64, v0
	v_mov_b32_e32 v65, v0
	v_mov_b32_e32 v66, v0
	v_mov_b32_e32 v67, v0
	v_mov_b32_e32 v68, v0
	v_mov_b32_e32 v69, v0
	v_mov_b32_e32 v70, v0
	v_mov_b32_e32 v71, v0
	v_mov_b32_e32 v80, v0
	v_mov_b32_e32 v81, v0
	v_mov_b32_e32 v82, v0
	v_mov_b32_e32 v83, v0
	v_mov_b32_e32 v84, v0
	v_mov_b32_e32 v85, v0
	v_mov_b32_e32 v86, v0
	v_mov_b32_e32 v87, v0
	v_mov_b32_e32 v96, v0
	v_mov_b32_e32 v97, v0
	v_mov_b32_e32 v98, v0
	v_mov_b32_e32 v99, v0
	v_mov_b32_e32 v100, v0
	v_mov_b32_e32 v101, v0
	v_mov_b32_e32 v102, v0
	v_mov_b32_e32 v103, v0
	v_mov_b32_e32 v112, v0
	v_mov_b32_e32 v113, v0
	v_mov_b32_e32 v114, v0
	v_mov_b32_e32 v115, v0
	v_mov_b32_e32 v116, v0
	v_mov_b32_e32 v117, v0
	v_mov_b32_e32 v118, v0
	v_mov_b32_e32 v119, v0
	v_mov_b32_e32 v72, v0
	v_mov_b32_e32 v73, v0
	v_mov_b32_e32 v74, v0
	v_mov_b32_e32 v75, v0
	v_mov_b32_e32 v76, v0
	v_mov_b32_e32 v77, v0
	v_mov_b32_e32 v78, v0
	v_mov_b32_e32 v79, v0
	v_mov_b32_e32 v88, v0
	v_mov_b32_e32 v89, v0
	v_mov_b32_e32 v90, v0
	v_mov_b32_e32 v91, v0
	v_mov_b32_e32 v92, v0
	v_mov_b32_e32 v93, v0
	v_mov_b32_e32 v94, v0
	v_mov_b32_e32 v95, v0
	v_mov_b32_e32 v104, v0
	v_mov_b32_e32 v105, v0
	v_mov_b32_e32 v106, v0
	v_mov_b32_e32 v107, v0
	v_mov_b32_e32 v108, v0
	v_mov_b32_e32 v109, v0
	v_mov_b32_e32 v110, v0
	v_mov_b32_e32 v111, v0
	v_mov_b32_e32 v120, v0
	v_mov_b32_e32 v121, v0
	v_mov_b32_e32 v122, v0
	v_mov_b32_e32 v123, v0
	v_mov_b32_e32 v124, v0
	v_mov_b32_e32 v125, v0
	v_mov_b32_e32 v126, v0
	v_mov_b32_e32 v127, v0
	s_mov_b64 s[52:53], 0x80
	v_add_u32_e32 v154, 0x10000, v144
	ds_read_b128 v[138:141], v154
	ds_read_b128 v[146:149], v154 offset:1024
	ds_read_b128 v[150:153], v154 offset:2048
	ds_read_b128 v[154:157], v154 offset:3072
	ds_read_b128 v[248:251], v145 offset:6144
	ds_read_b128 v[252:255], v145 offset:7168
.LBB0_169:
	s_add_u32 s24, s22, 0xfff80080
	s_addc_u32 s25, s23, -1
	s_add_i32 s48, 0, 0x10000
	s_cmp_eq_u32 s47, 28
	s_cselect_b32 s27, s1, s25
	s_cselect_b32 s26, s11, s24
	s_cselect_b32 s25, s13, s46
	s_cselect_b32 s24, s21, s45
	v_lshl_add_u64 v[182:183], s[22:23], 0, v[134:135]
	s_add_i32 m0, s35, 0xc000
	ds_read_b128 v[158:161], v145
	ds_read_b128 v[162:165], v145 offset:1024
	ds_read_b128 v[166:169], v145 offset:2048
	ds_read_b128 v[170:173], v145 offset:3072
	ds_read_b128 v[174:177], v145 offset:4096
	ds_read_b128 v[178:181], v145 offset:5120
	global_load_lds_dwordx4 v[182:183], off
	v_lshl_add_u64 v[182:183], s[22:23], 0, v[136:137]
	s_add_i32 m0, s35, 0xe000
	s_nop 0
	global_load_lds_dwordx4 v[182:183], off
	s_waitcnt lgkmcnt(8)
	s_setprio 1
	s_waitcnt vmcnt(8)
	s_barrier
	s_waitcnt lgkmcnt(0)
	v_mfma_f32_16x16x32_bf16 v[124:127], v[138:141], v[158:161], v[124:127]
	v_mfma_f32_16x16x32_bf16 v[120:123], v[150:153], v[158:161], v[120:123]
	v_mfma_f32_16x16x32_bf16 v[108:111], v[138:141], v[166:169], v[108:111]
	v_mfma_f32_16x16x32_bf16 v[104:107], v[150:153], v[166:169], v[104:107]
	v_mfma_f32_16x16x32_bf16 v[92:95], v[138:141], v[174:177], v[92:95]
	v_mfma_f32_16x16x32_bf16 v[88:91], v[150:153], v[174:177], v[88:91]
	v_mfma_f32_16x16x32_bf16 v[76:79], v[138:141], v[248:251], v[76:79]
	v_mfma_f32_16x16x32_bf16 v[72:75], v[150:153], v[248:251], v[72:75]
	v_mfma_f32_16x16x32_bf16 v[124:127], v[146:149], v[162:165], v[124:127]
	v_mfma_f32_16x16x32_bf16 v[120:123], v[154:157], v[162:165], v[120:123]
	v_mfma_f32_16x16x32_bf16 v[108:111], v[146:149], v[170:173], v[108:111]
	v_mfma_f32_16x16x32_bf16 v[104:107], v[154:157], v[170:173], v[104:107]
	v_mfma_f32_16x16x32_bf16 v[92:95], v[146:149], v[178:181], v[92:95]
	v_mfma_f32_16x16x32_bf16 v[88:91], v[154:157], v[178:181], v[88:91]
	v_mfma_f32_16x16x32_bf16 v[76:79], v[146:149], v[252:255], v[76:79]
	v_mfma_f32_16x16x32_bf16 v[72:75], v[154:157], v[252:255], v[72:75]
	s_barrier
	s_setprio 0
	ds_read_b128 v[188:191], v145 offset:22528
	ds_read_b128 v[192:195], v145 offset:23552
	s_add_i32 s50, 0, 0x14000
	v_add_u32_e32 v182, s50, v144
	s_add_i32 s48, s48, s34
	ds_read_b128 v[202:205], v182
	ds_read_b128 v[206:209], v182 offset:1024
	ds_read_b128 v[210:213], v182 offset:2048
	ds_read_b128 v[214:217], v182 offset:3072
	v_lshl_add_u64 v[182:183], s[24:25], 0, v[184:185]
	s_mov_b32 m0, s48
	v_lshl_add_u64 v[196:197], s[24:25], 0, v[132:133]
	global_load_lds_dwordx4 v[182:183], off
	s_add_i32 m0, s48, 0x2000
	s_nop 0
	global_load_lds_dwordx4 v[196:197], off
	s_setprio 1
	s_barrier
	s_waitcnt lgkmcnt(0)
	v_mfma_f32_16x16x32_bf16 v[116:119], v[202:205], v[158:161], v[116:119]
	v_mfma_f32_16x16x32_bf16 v[112:115], v[210:213], v[158:161], v[112:115]
	v_mfma_f32_16x16x32_bf16 v[100:103], v[202:205], v[166:169], v[100:103]
	v_mfma_f32_16x16x32_bf16 v[96:99], v[210:213], v[166:169], v[96:99]
	v_mfma_f32_16x16x32_bf16 v[84:87], v[202:205], v[174:177], v[84:87]
	v_mfma_f32_16x16x32_bf16 v[80:83], v[210:213], v[174:177], v[80:83]
	v_mfma_f32_16x16x32_bf16 v[68:71], v[202:205], v[248:251], v[68:71]
	v_mfma_f32_16x16x32_bf16 v[64:67], v[210:213], v[248:251], v[64:67]
	v_mfma_f32_16x16x32_bf16 v[116:119], v[206:209], v[162:165], v[116:119]
	v_mfma_f32_16x16x32_bf16 v[112:115], v[214:217], v[162:165], v[112:115]
	v_mfma_f32_16x16x32_bf16 v[100:103], v[206:209], v[170:173], v[100:103]
	v_mfma_f32_16x16x32_bf16 v[96:99], v[214:217], v[170:173], v[96:99]
	v_mfma_f32_16x16x32_bf16 v[84:87], v[206:209], v[178:181], v[84:87]
	v_mfma_f32_16x16x32_bf16 v[80:83], v[214:217], v[178:181], v[80:83]
	v_mfma_f32_16x16x32_bf16 v[68:71], v[206:209], v[252:255], v[68:71]
	v_mfma_f32_16x16x32_bf16 v[64:67], v[214:217], v[252:255], v[64:67]
	s_barrier
	s_setprio 0
	s_mov_b32 m0, s35
	v_lshl_add_u64 v[218:219], s[26:27], 0, v[128:129]
	ds_read_b128 v[158:161], v145 offset:16384
	ds_read_b128 v[162:165], v145 offset:17408
	ds_read_b128 v[166:169], v145 offset:18432
	ds_read_b128 v[170:173], v145 offset:19456
	ds_read_b128 v[174:177], v145 offset:20480
	ds_read_b128 v[178:181], v145 offset:21504
	global_load_lds_dwordx4 v[218:219], off
	v_lshl_add_u64 v[220:221], s[26:27], 0, v[130:131]
	s_mov_b32 m0, s36
	s_nop 0
	global_load_lds_dwordx4 v[220:221], off
	s_setprio 1
	s_waitcnt vmcnt(8)
	s_barrier
	s_waitcnt lgkmcnt(0)
	v_mfma_f32_16x16x32_bf16 v[60:63], v[138:141], v[158:161], v[60:63]
	v_mfma_f32_16x16x32_bf16 v[56:59], v[150:153], v[158:161], v[56:59]
	v_mfma_f32_16x16x32_bf16 v[44:47], v[138:141], v[166:169], v[44:47]
	v_mfma_f32_16x16x32_bf16 v[40:43], v[150:153], v[166:169], v[40:43]
	v_mfma_f32_16x16x32_bf16 v[28:31], v[138:141], v[174:177], v[28:31]
	v_mfma_f32_16x16x32_bf16 v[24:27], v[150:153], v[174:177], v[24:27]
	v_mfma_f32_16x16x32_bf16 v[12:15], v[138:141], v[188:191], v[12:15]
	v_mfma_f32_16x16x32_bf16 v[8:11], v[150:153], v[188:191], v[8:11]
	v_mfma_f32_16x16x32_bf16 v[60:63], v[146:149], v[162:165], v[60:63]
	v_mfma_f32_16x16x32_bf16 v[56:59], v[154:157], v[162:165], v[56:59]
	v_mfma_f32_16x16x32_bf16 v[44:47], v[146:149], v[170:173], v[44:47]
	v_mfma_f32_16x16x32_bf16 v[40:43], v[154:157], v[170:173], v[40:43]
	v_mfma_f32_16x16x32_bf16 v[28:31], v[146:149], v[178:181], v[28:31]
	v_mfma_f32_16x16x32_bf16 v[24:27], v[154:157], v[178:181], v[24:27]
	v_mfma_f32_16x16x32_bf16 v[12:15], v[146:149], v[192:195], v[12:15]
	v_mfma_f32_16x16x32_bf16 v[8:11], v[154:157], v[192:195], v[8:11]
	s_barrier
	s_setprio 0
	v_add_u32_e32 v154, 0x18000, v144
	ds_read_b128 v[138:141], v154
	ds_read_b128 v[146:149], v154 offset:1024
	ds_read_b128 v[150:153], v154 offset:2048
	ds_read_b128 v[154:157], v154 offset:3072
	ds_read_b128 v[248:251], v145 offset:38912
	ds_read_b128 v[252:255], v145 offset:39936
	s_add_u32 s48, s24, 0x80000
	s_addc_u32 s49, s25, 0
	s_add_i32 s50, s50, s34
	v_lshl_add_u64 v[246:247], s[48:49], 0, v[184:185]
	s_mov_b32 m0, s50
	s_nop 0
	global_load_lds_dwordx4 v[246:247], off
	v_lshl_add_u64 v[246:247], s[48:49], 0, v[132:133]
	s_add_i32 m0, s50, 0x2000
	s_nop 0
	global_load_lds_dwordx4 v[246:247], off
	s_waitcnt vmcnt(6)
	s_setprio 1
	s_barrier
	v_mfma_f32_16x16x32_bf16 v[52:55], v[202:205], v[158:161], v[52:55]
	v_mfma_f32_16x16x32_bf16 v[48:51], v[210:213], v[158:161], v[48:51]
	v_mfma_f32_16x16x32_bf16 v[36:39], v[202:205], v[166:169], v[36:39]
	v_mfma_f32_16x16x32_bf16 v[32:35], v[210:213], v[166:169], v[32:35]
	v_mfma_f32_16x16x32_bf16 v[20:23], v[202:205], v[174:177], v[20:23]
	v_mfma_f32_16x16x32_bf16 v[16:19], v[210:213], v[174:177], v[16:19]
	v_mfma_f32_16x16x32_bf16 v[4:7], v[202:205], v[188:191], v[4:7]
	v_mfma_f32_16x16x32_bf16 v[0:3], v[210:213], v[188:191], v[0:3]
	v_mfma_f32_16x16x32_bf16 v[52:55], v[206:209], v[162:165], v[52:55]
	v_mfma_f32_16x16x32_bf16 v[48:51], v[214:217], v[162:165], v[48:51]
	v_mfma_f32_16x16x32_bf16 v[36:39], v[206:209], v[170:173], v[36:39]
	v_mfma_f32_16x16x32_bf16 v[32:35], v[214:217], v[170:173], v[32:35]
	v_mfma_f32_16x16x32_bf16 v[20:23], v[206:209], v[178:181], v[20:23]
	v_mfma_f32_16x16x32_bf16 v[16:19], v[214:217], v[178:181], v[16:19]
	v_mfma_f32_16x16x32_bf16 v[4:7], v[206:209], v[192:195], v[4:7]
	v_mfma_f32_16x16x32_bf16 v[0:3], v[214:217], v[192:195], v[0:3]
	s_barrier
	s_setprio 0
	s_add_i32 s48, 0, 0x18000
	s_add_u32 s26, s26, 0x80000
	s_addc_u32 s27, s27, 0
	s_mov_b32 m0, s37
	v_lshl_add_u64 v[202:203], s[26:27], 0, v[128:129]
	ds_read_b128 v[158:161], v145 offset:32768
	ds_read_b128 v[162:165], v145 offset:33792
	ds_read_b128 v[166:169], v145 offset:34816
	ds_read_b128 v[170:173], v145 offset:35840
	ds_read_b128 v[174:177], v145 offset:36864
	ds_read_b128 v[178:181], v145 offset:37888
	global_load_lds_dwordx4 v[202:203], off
	v_lshl_add_u64 v[202:203], s[26:27], 0, v[130:131]
	s_mov_b32 m0, s38
	s_nop 0
	global_load_lds_dwordx4 v[202:203], off
	s_waitcnt lgkmcnt(8)
	s_setprio 1
	s_waitcnt vmcnt(8)
	s_barrier
	s_waitcnt lgkmcnt(0)
	v_mfma_f32_16x16x32_bf16 v[124:127], v[138:141], v[158:161], v[124:127]
	v_mfma_f32_16x16x32_bf16 v[120:123], v[150:153], v[158:161], v[120:123]
	v_mfma_f32_16x16x32_bf16 v[108:111], v[138:141], v[166:169], v[108:111]
	v_mfma_f32_16x16x32_bf16 v[104:107], v[150:153], v[166:169], v[104:107]
	v_mfma_f32_16x16x32_bf16 v[92:95], v[138:141], v[174:177], v[92:95]
	v_mfma_f32_16x16x32_bf16 v[88:91], v[150:153], v[174:177], v[88:91]
	v_mfma_f32_16x16x32_bf16 v[76:79], v[138:141], v[248:251], v[76:79]
	v_mfma_f32_16x16x32_bf16 v[72:75], v[150:153], v[248:251], v[72:75]
	v_mfma_f32_16x16x32_bf16 v[124:127], v[146:149], v[162:165], v[124:127]
	v_mfma_f32_16x16x32_bf16 v[120:123], v[154:157], v[162:165], v[120:123]
	v_mfma_f32_16x16x32_bf16 v[108:111], v[146:149], v[170:173], v[108:111]
	v_mfma_f32_16x16x32_bf16 v[104:107], v[154:157], v[170:173], v[104:107]
	v_mfma_f32_16x16x32_bf16 v[92:95], v[146:149], v[178:181], v[92:95]
	v_mfma_f32_16x16x32_bf16 v[88:91], v[154:157], v[178:181], v[88:91]
	v_mfma_f32_16x16x32_bf16 v[76:79], v[146:149], v[252:255], v[76:79]
	v_mfma_f32_16x16x32_bf16 v[72:75], v[154:157], v[252:255], v[72:75]
	s_barrier
	s_setprio 0
	ds_read_b128 v[188:191], v145 offset:55296
	ds_read_b128 v[192:195], v145 offset:56320
	s_add_i32 s26, 0, 0x1c000
	s_add_i32 s27, s48, s34
	v_add_u32_e32 v187, s26, v144
	v_lshl_add_u64 v[182:183], v[182:183], 0, s[52:53]
	s_mov_b32 m0, s27
	ds_read_b128 v[202:205], v187
	ds_read_b128 v[206:209], v187 offset:1024
	ds_read_b128 v[210:213], v187 offset:2048
	ds_read_b128 v[214:217], v187 offset:3072
	global_load_lds_dwordx4 v[182:183], off
	v_lshl_add_u64 v[182:183], v[196:197], 0, s[52:53]
	s_add_i32 m0, s27, 0x2000
	s_nop 0
	global_load_lds_dwordx4 v[182:183], off
	s_setprio 1
	s_barrier
	s_waitcnt lgkmcnt(0)
	v_mfma_f32_16x16x32_bf16 v[116:119], v[202:205], v[158:161], v[116:119]
	v_mfma_f32_16x16x32_bf16 v[112:115], v[210:213], v[158:161], v[112:115]
	v_mfma_f32_16x16x32_bf16 v[100:103], v[202:205], v[166:169], v[100:103]
	v_mfma_f32_16x16x32_bf16 v[96:99], v[210:213], v[166:169], v[96:99]
	v_mfma_f32_16x16x32_bf16 v[84:87], v[202:205], v[174:177], v[84:87]
	v_mfma_f32_16x16x32_bf16 v[80:83], v[210:213], v[174:177], v[80:83]
	v_mfma_f32_16x16x32_bf16 v[68:71], v[202:205], v[248:251], v[68:71]
	v_mfma_f32_16x16x32_bf16 v[64:67], v[210:213], v[248:251], v[64:67]
	v_mfma_f32_16x16x32_bf16 v[116:119], v[206:209], v[162:165], v[116:119]
	v_mfma_f32_16x16x32_bf16 v[112:115], v[214:217], v[162:165], v[112:115]
	v_mfma_f32_16x16x32_bf16 v[100:103], v[206:209], v[170:173], v[100:103]
	v_mfma_f32_16x16x32_bf16 v[96:99], v[214:217], v[170:173], v[96:99]
	v_mfma_f32_16x16x32_bf16 v[84:87], v[206:209], v[178:181], v[84:87]
	v_mfma_f32_16x16x32_bf16 v[80:83], v[214:217], v[178:181], v[80:83]
	v_mfma_f32_16x16x32_bf16 v[68:71], v[206:209], v[252:255], v[68:71]
	v_mfma_f32_16x16x32_bf16 v[64:67], v[214:217], v[252:255], v[64:67]
	s_barrier
	s_setprio 0
	s_mov_b32 m0, s42
	v_lshl_add_u64 v[182:183], v[218:219], 0, s[52:53]
	ds_read_b128 v[158:161], v145 offset:49152
	ds_read_b128 v[162:165], v145 offset:50176
	ds_read_b128 v[166:169], v145 offset:51200
	ds_read_b128 v[170:173], v145 offset:52224
	ds_read_b128 v[174:177], v145 offset:53248
	ds_read_b128 v[178:181], v145 offset:54272
	global_load_lds_dwordx4 v[182:183], off
	v_lshl_add_u64 v[182:183], v[220:221], 0, s[52:53]
	s_mov_b32 m0, s43
	s_nop 0
	global_load_lds_dwordx4 v[182:183], off
	s_setprio 1
	s_waitcnt vmcnt(8)
	s_barrier
	s_waitcnt lgkmcnt(0)
	v_mfma_f32_16x16x32_bf16 v[60:63], v[138:141], v[158:161], v[60:63]
	v_mfma_f32_16x16x32_bf16 v[56:59], v[150:153], v[158:161], v[56:59]
	v_mfma_f32_16x16x32_bf16 v[44:47], v[138:141], v[166:169], v[44:47]
	v_mfma_f32_16x16x32_bf16 v[40:43], v[150:153], v[166:169], v[40:43]
	v_mfma_f32_16x16x32_bf16 v[28:31], v[138:141], v[174:177], v[28:31]
	v_mfma_f32_16x16x32_bf16 v[24:27], v[150:153], v[174:177], v[24:27]
	v_mfma_f32_16x16x32_bf16 v[12:15], v[138:141], v[188:191], v[12:15]
	v_mfma_f32_16x16x32_bf16 v[8:11], v[150:153], v[188:191], v[8:11]
	v_mfma_f32_16x16x32_bf16 v[60:63], v[146:149], v[162:165], v[60:63]
	v_mfma_f32_16x16x32_bf16 v[56:59], v[154:157], v[162:165], v[56:59]
	v_mfma_f32_16x16x32_bf16 v[44:47], v[146:149], v[170:173], v[44:47]
	v_mfma_f32_16x16x32_bf16 v[40:43], v[154:157], v[170:173], v[40:43]
	v_mfma_f32_16x16x32_bf16 v[28:31], v[146:149], v[178:181], v[28:31]
	v_mfma_f32_16x16x32_bf16 v[24:27], v[154:157], v[178:181], v[24:27]
	v_mfma_f32_16x16x32_bf16 v[12:15], v[146:149], v[192:195], v[12:15]
	v_mfma_f32_16x16x32_bf16 v[8:11], v[154:157], v[192:195], v[8:11]
	s_barrier
	s_setprio 0
	v_add_u32_e32 v154, 0x10000, v144
	ds_read_b128 v[138:141], v154
	ds_read_b128 v[146:149], v154 offset:1024
	ds_read_b128 v[150:153], v154 offset:2048
	ds_read_b128 v[154:157], v154 offset:3072
	ds_read_b128 v[248:251], v145 offset:6144
	ds_read_b128 v[252:255], v145 offset:7168
	s_add_u32 s24, s24, 0x80080
	s_addc_u32 s25, s25, 0
	s_add_i32 s26, s26, s34
	v_lshl_add_u64 v[246:247], s[24:25], 0, v[184:185]
	s_mov_b32 m0, s26
	s_nop 0
	global_load_lds_dwordx4 v[246:247], off
	v_lshl_add_u64 v[246:247], s[24:25], 0, v[132:133]
	s_add_i32 m0, s26, 0x2000
	s_nop 0
	global_load_lds_dwordx4 v[246:247], off
	s_waitcnt vmcnt(6)
	s_setprio 1
	s_barrier
	v_mfma_f32_16x16x32_bf16 v[52:55], v[202:205], v[158:161], v[52:55]
	v_mfma_f32_16x16x32_bf16 v[48:51], v[210:213], v[158:161], v[48:51]
	v_mfma_f32_16x16x32_bf16 v[36:39], v[202:205], v[166:169], v[36:39]
	v_mfma_f32_16x16x32_bf16 v[32:35], v[210:213], v[166:169], v[32:35]
	v_mfma_f32_16x16x32_bf16 v[20:23], v[202:205], v[174:177], v[20:23]
	v_mfma_f32_16x16x32_bf16 v[16:19], v[210:213], v[174:177], v[16:19]
	v_mfma_f32_16x16x32_bf16 v[4:7], v[202:205], v[188:191], v[4:7]
	v_mfma_f32_16x16x32_bf16 v[0:3], v[210:213], v[188:191], v[0:3]
	v_mfma_f32_16x16x32_bf16 v[52:55], v[206:209], v[162:165], v[52:55]
	v_mfma_f32_16x16x32_bf16 v[48:51], v[214:217], v[162:165], v[48:51]
	v_mfma_f32_16x16x32_bf16 v[36:39], v[206:209], v[170:173], v[36:39]
	v_mfma_f32_16x16x32_bf16 v[32:35], v[214:217], v[170:173], v[32:35]
	v_mfma_f32_16x16x32_bf16 v[20:23], v[206:209], v[178:181], v[20:23]
	v_mfma_f32_16x16x32_bf16 v[16:19], v[214:217], v[178:181], v[16:19]
	v_mfma_f32_16x16x32_bf16 v[4:7], v[206:209], v[192:195], v[4:7]
	v_mfma_f32_16x16x32_bf16 v[0:3], v[214:217], v[192:195], v[0:3]
	s_barrier
	s_setprio 0
	s_add_i32 s47, s47, 2
	s_add_u32 s22, s22, 0x100
	s_addc_u32 s23, s23, 0
	s_add_u32 s45, s45, 0x100
	s_addc_u32 s46, s46, 0
	s_cmp_gt_u32 s47, 29
	s_cbranch_scc0 .LBB0_169
	s_waitcnt lgkmcnt(0)
	v_mov_b32_e32 v141, v143
	v_mov_b32_e32 v138, v142
	s_lshl_b32 s1, s20, 8
	s_add_i32 s1, s1, s40
	v_add_u32_e32 v138, s1, v138
	s_cmp_gt_i32 s0, 1
	s_mov_b64 s[20:21], -1
	s_cbranch_scc0 .LBB0_174
	s_andn2_b64 vcc, exec, s[6:7]
	s_cbranch_vccnz .LBB0_173
	v_ashrrev_i32_e32 v139, 31, v138
	v_lshlrev_b32_e32 v146, 3, v141
	v_lshlrev_b64 v[148:149], 8, v[138:139]
	v_ashrrev_i32_e32 v147, 31, v146
	v_lshl_add_u64 v[148:149], s[8:9], 0, v[148:149]
	v_lshl_add_u64 v[146:147], v[146:147], 2, v[148:149]
	v_add_co_u32_e32 v150, vcc, 0x1000, v146
	s_mov_b64 s[20:21], 0x1000
	s_nop 0
	v_addc_co_u32_e32 v151, vcc, 0, v147, vcc
	s_movk_i32 s1, 0x2000
	global_store_dwordx4 v[146:147], v[124:127], off
	global_store_dwordx4 v[146:147], v[120:123], off offset:16
	v_lshl_add_u64 v[148:149], v[146:147], 0, s[20:21]
	global_store_dwordx4 v[150:151], v[108:111], off
	global_store_dwordx4 v[148:149], v[104:107], off offset:16
	v_add_co_u32_e32 v150, vcc, s1, v146
	v_lshl_add_u64 v[148:149], v[146:147], 0, s[82:83]
	s_nop 0
	v_addc_co_u32_e32 v151, vcc, 0, v147, vcc
	global_store_dwordx4 v[150:151], v[92:95], off
	global_store_dwordx4 v[148:149], v[88:91], off offset:16
	v_add_co_u32_e32 v150, vcc, 0x3000, v146
	s_mov_b64 s[20:21], 0x3000
	s_nop 0
	v_addc_co_u32_e32 v151, vcc, 0, v147, vcc
	s_mov_b32 s1, 0x8000
	v_lshl_add_u64 v[148:149], v[146:147], 0, s[20:21]
	global_store_dwordx4 v[150:151], v[76:79], off
	global_store_dwordx4 v[148:149], v[72:75], off offset:16
	v_add_co_u32_e32 v150, vcc, s1, v146
	v_lshl_add_u64 v[148:149], v[146:147], 0, s[84:85]
	s_nop 0
	v_addc_co_u32_e32 v151, vcc, 0, v147, vcc
	global_store_dwordx4 v[150:151], v[60:63], off
	global_store_dwordx4 v[148:149], v[56:59], off offset:16
	v_add_co_u32_e32 v150, vcc, 0x9000, v146
	s_mov_b64 s[20:21], 0x9000
	s_nop 0
	v_addc_co_u32_e32 v151, vcc, 0, v147, vcc
	v_lshl_add_u64 v[148:149], v[146:147], 0, s[20:21]
	global_store_dwordx4 v[150:151], v[44:47], off
	global_store_dwordx4 v[148:149], v[40:43], off offset:16
	s_mov_b64 s[20:21], 0xa000
	v_add_co_u32_e32 v150, vcc, 0xa000, v146
	v_lshl_add_u64 v[148:149], v[146:147], 0, s[20:21]
	s_nop 0
	v_addc_co_u32_e32 v151, vcc, 0, v147, vcc
	s_mov_b64 s[20:21], 0xb000
	global_store_dwordx4 v[150:151], v[28:31], off
	global_store_dwordx4 v[148:149], v[24:27], off offset:16
	v_lshl_add_u64 v[148:149], v[146:147], 0, s[20:21]
	v_add_co_u32_e32 v146, vcc, 0xb000, v146
	s_nop 1
	v_addc_co_u32_e32 v147, vcc, 0, v147, vcc
	global_store_dwordx4 v[146:147], v[12:15], off
	global_store_dwordx4 v[148:149], v[8:11], off offset:16

.LBB0_206:
	s_ashr_i32 s9, s8, 31
	s_lshl_b64 s[14:15], s[8:9], 20
	s_add_u32 s14, s27, s14
	s_addc_u32 s15, s28, s15
	s_and_b64 s[16:17], s[24:25], exec
	s_cselect_b32 s1, s15, s21
	s_cselect_b32 s9, s14, s20
	s_ashr_i32 s11, s10, 31
	s_lshl_b64 s[16:17], s[10:11], 20
	s_add_u32 s16, s29, s16
	s_addc_u32 s17, s30, s17
	s_and_b64 s[24:25], s[24:25], exec
	s_cselect_b32 s11, s17, s23
	s_cselect_b32 s19, s16, s22
	s_add_u32 s20, s20, 0x80080
	s_addc_u32 s21, s21, 0
	s_add_u32 s44, s22, 0x100
	v_mov_b32_e32 v0, 0
	s_addc_u32 s45, s23, 0
	s_mov_b32 s46, -2
	v_mov_b32_e32 v1, v0
	v_mov_b32_e32 v2, v0
	v_mov_b32_e32 v3, v0
	v_mov_b32_e32 v4, v0
	v_mov_b32_e32 v5, v0
	v_mov_b32_e32 v6, v0
	v_mov_b32_e32 v7, v0
	v_mov_b32_e32 v16, v0
	v_mov_b32_e32 v17, v0
	v_mov_b32_e32 v18, v0
	v_mov_b32_e32 v19, v0
	v_mov_b32_e32 v20, v0
	v_mov_b32_e32 v21, v0
	v_mov_b32_e32 v22, v0
	v_mov_b32_e32 v23, v0
	v_mov_b32_e32 v32, v0
	v_mov_b32_e32 v33, v0
	v_mov_b32_e32 v34, v0
	v_mov_b32_e32 v35, v0
	v_mov_b32_e32 v36, v0
	v_mov_b32_e32 v37, v0
	v_mov_b32_e32 v38, v0
	v_mov_b32_e32 v39, v0
	v_mov_b32_e32 v48, v0
	v_mov_b32_e32 v49, v0
	v_mov_b32_e32 v50, v0
	v_mov_b32_e32 v51, v0
	v_mov_b32_e32 v52, v0
	v_mov_b32_e32 v53, v0
	v_mov_b32_e32 v54, v0
	v_mov_b32_e32 v55, v0
	v_mov_b32_e32 v8, v0
	v_mov_b32_e32 v9, v0
	v_mov_b32_e32 v10, v0
	v_mov_b32_e32 v11, v0
	v_mov_b32_e32 v12, v0
	v_mov_b32_e32 v13, v0
	v_mov_b32_e32 v14, v0
	v_mov_b32_e32 v15, v0
	v_mov_b32_e32 v24, v0
	v_mov_b32_e32 v25, v0
	v_mov_b32_e32 v26, v0
	v_mov_b32_e32 v27, v0
	v_mov_b32_e32 v28, v0
	v_mov_b32_e32 v29, v0
	v_mov_b32_e32 v30, v0
	v_mov_b32_e32 v31, v0
	v_mov_b32_e32 v40, v0
	v_mov_b32_e32 v41, v0
	v_mov_b32_e32 v42, v0
	v_mov_b32_e32 v43, v0
	v_mov_b32_e32 v44, v0
	v_mov_b32_e32 v45, v0
	v_mov_b32_e32 v46, v0
	v_mov_b32_e32 v47, v0
	v_mov_b32_e32 v56, v0
	v_mov_b32_e32 v57, v0
	v_mov_b32_e32 v58, v0
	v_mov_b32_e32 v59, v0
	v_mov_b32_e32 v60, v0
	v_mov_b32_e32 v61, v0
	v_mov_b32_e32 v62, v0
	v_mov_b32_e32 v63, v0
	v_mov_b32_e32 v64, v0
	v_mov_b32_e32 v65, v0
	v_mov_b32_e32 v66, v0
	v_mov_b32_e32 v67, v0
	v_mov_b32_e32 v68, v0
	v_mov_b32_e32 v69, v0
	v_mov_b32_e32 v70, v0
	v_mov_b32_e32 v71, v0
	v_mov_b32_e32 v80, v0
	v_mov_b32_e32 v81, v0
	v_mov_b32_e32 v82, v0
	v_mov_b32_e32 v83, v0
	v_mov_b32_e32 v84, v0
	v_mov_b32_e32 v85, v0
	v_mov_b32_e32 v86, v0
	v_mov_b32_e32 v87, v0
	v_mov_b32_e32 v96, v0
	v_mov_b32_e32 v97, v0
	v_mov_b32_e32 v98, v0
	v_mov_b32_e32 v99, v0
	v_mov_b32_e32 v100, v0
	v_mov_b32_e32 v101, v0
	v_mov_b32_e32 v102, v0
	v_mov_b32_e32 v103, v0
	v_mov_b32_e32 v112, v0
	v_mov_b32_e32 v113, v0
	v_mov_b32_e32 v114, v0
	v_mov_b32_e32 v115, v0
	v_mov_b32_e32 v116, v0
	v_mov_b32_e32 v117, v0
	v_mov_b32_e32 v118, v0
	v_mov_b32_e32 v119, v0
	v_mov_b32_e32 v72, v0
	v_mov_b32_e32 v73, v0
	v_mov_b32_e32 v74, v0
	v_mov_b32_e32 v75, v0
	v_mov_b32_e32 v76, v0
	v_mov_b32_e32 v77, v0
	v_mov_b32_e32 v78, v0
	v_mov_b32_e32 v79, v0
	v_mov_b32_e32 v88, v0
	v_mov_b32_e32 v89, v0
	v_mov_b32_e32 v90, v0
	v_mov_b32_e32 v91, v0
	v_mov_b32_e32 v92, v0
	v_mov_b32_e32 v93, v0
	v_mov_b32_e32 v94, v0
	v_mov_b32_e32 v95, v0
	v_mov_b32_e32 v104, v0
	v_mov_b32_e32 v105, v0
	v_mov_b32_e32 v106, v0
	v_mov_b32_e32 v107, v0
	v_mov_b32_e32 v108, v0
	v_mov_b32_e32 v109, v0
	v_mov_b32_e32 v110, v0
	v_mov_b32_e32 v111, v0
	v_mov_b32_e32 v120, v0
	v_mov_b32_e32 v121, v0
	v_mov_b32_e32 v122, v0
	v_mov_b32_e32 v123, v0
	v_mov_b32_e32 v124, v0
	v_mov_b32_e32 v125, v0
	v_mov_b32_e32 v126, v0
	v_mov_b32_e32 v127, v0
	s_mov_b64 s[52:53], 0x80
	v_add_u32_e32 v154, 0x10000, v144
	ds_read_b128 v[138:141], v154
	ds_read_b128 v[146:149], v154 offset:1024
	ds_read_b128 v[150:153], v154 offset:2048
	ds_read_b128 v[154:157], v154 offset:3072
	ds_read_b128 v[248:251], v145 offset:6144
	ds_read_b128 v[252:255], v145 offset:7168
.LBB0_207:
	s_add_u32 s22, s20, 0xfff80080
	s_addc_u32 s23, s21, -1
	s_add_i32 s47, 0, 0x10000
	s_cmp_eq_u32 s46, 28
	s_cselect_b32 s25, s1, s23
	s_cselect_b32 s24, s9, s22
	s_cselect_b32 s23, s11, s45
	s_cselect_b32 s22, s19, s44
	v_lshl_add_u64 v[182:183], s[20:21], 0, v[134:135]
	s_add_i32 m0, s33, 0xc000
	ds_read_b128 v[158:161], v145
	ds_read_b128 v[162:165], v145 offset:1024
	ds_read_b128 v[166:169], v145 offset:2048
	ds_read_b128 v[170:173], v145 offset:3072
	ds_read_b128 v[174:177], v145 offset:4096
	ds_read_b128 v[178:181], v145 offset:5120
	global_load_lds_dwordx4 v[182:183], off
	v_lshl_add_u64 v[182:183], s[20:21], 0, v[136:137]
	s_add_i32 m0, s33, 0xe000
	s_nop 0
	global_load_lds_dwordx4 v[182:183], off
	s_waitcnt lgkmcnt(8)
	s_setprio 1
	s_waitcnt vmcnt(8)
	s_barrier
	s_waitcnt lgkmcnt(0)
	v_mfma_f32_16x16x32_bf16 v[124:127], v[138:141], v[158:161], v[124:127]
	v_mfma_f32_16x16x32_bf16 v[120:123], v[150:153], v[158:161], v[120:123]
	v_mfma_f32_16x16x32_bf16 v[108:111], v[138:141], v[166:169], v[108:111]
	v_mfma_f32_16x16x32_bf16 v[104:107], v[150:153], v[166:169], v[104:107]
	v_mfma_f32_16x16x32_bf16 v[92:95], v[138:141], v[174:177], v[92:95]
	v_mfma_f32_16x16x32_bf16 v[88:91], v[150:153], v[174:177], v[88:91]
	v_mfma_f32_16x16x32_bf16 v[76:79], v[138:141], v[248:251], v[76:79]
	v_mfma_f32_16x16x32_bf16 v[72:75], v[150:153], v[248:251], v[72:75]
	v_mfma_f32_16x16x32_bf16 v[124:127], v[146:149], v[162:165], v[124:127]
	v_mfma_f32_16x16x32_bf16 v[120:123], v[154:157], v[162:165], v[120:123]
	v_mfma_f32_16x16x32_bf16 v[108:111], v[146:149], v[170:173], v[108:111]
	v_mfma_f32_16x16x32_bf16 v[104:107], v[154:157], v[170:173], v[104:107]
	v_mfma_f32_16x16x32_bf16 v[92:95], v[146:149], v[178:181], v[92:95]
	v_mfma_f32_16x16x32_bf16 v[88:91], v[154:157], v[178:181], v[88:91]
	v_mfma_f32_16x16x32_bf16 v[76:79], v[146:149], v[252:255], v[76:79]
	v_mfma_f32_16x16x32_bf16 v[72:75], v[154:157], v[252:255], v[72:75]
	s_barrier
	s_setprio 0
	ds_read_b128 v[188:191], v145 offset:22528
	ds_read_b128 v[192:195], v145 offset:23552
	s_add_i32 s50, 0, 0x14000
	v_add_u32_e32 v182, s50, v144
	s_add_i32 s47, s47, s31
	ds_read_b128 v[202:205], v182
	ds_read_b128 v[206:209], v182 offset:1024
	ds_read_b128 v[210:213], v182 offset:2048
	ds_read_b128 v[214:217], v182 offset:3072
	v_lshl_add_u64 v[182:183], s[22:23], 0, v[184:185]
	s_mov_b32 m0, s47
	v_lshl_add_u64 v[196:197], s[22:23], 0, v[132:133]
	global_load_lds_dwordx4 v[182:183], off
	s_add_i32 m0, s47, 0x2000
	s_nop 0
	global_load_lds_dwordx4 v[196:197], off
	s_setprio 1
	s_barrier
	s_waitcnt lgkmcnt(0)
	v_mfma_f32_16x16x32_bf16 v[116:119], v[202:205], v[158:161], v[116:119]
	v_mfma_f32_16x16x32_bf16 v[112:115], v[210:213], v[158:161], v[112:115]
	v_mfma_f32_16x16x32_bf16 v[100:103], v[202:205], v[166:169], v[100:103]
	v_mfma_f32_16x16x32_bf16 v[96:99], v[210:213], v[166:169], v[96:99]
	v_mfma_f32_16x16x32_bf16 v[84:87], v[202:205], v[174:177], v[84:87]
	v_mfma_f32_16x16x32_bf16 v[80:83], v[210:213], v[174:177], v[80:83]
	v_mfma_f32_16x16x32_bf16 v[68:71], v[202:205], v[248:251], v[68:71]
	v_mfma_f32_16x16x32_bf16 v[64:67], v[210:213], v[248:251], v[64:67]
	v_mfma_f32_16x16x32_bf16 v[116:119], v[206:209], v[162:165], v[116:119]
	v_mfma_f32_16x16x32_bf16 v[112:115], v[214:217], v[162:165], v[112:115]
	v_mfma_f32_16x16x32_bf16 v[100:103], v[206:209], v[170:173], v[100:103]
	v_mfma_f32_16x16x32_bf16 v[96:99], v[214:217], v[170:173], v[96:99]
	v_mfma_f32_16x16x32_bf16 v[84:87], v[206:209], v[178:181], v[84:87]
	v_mfma_f32_16x16x32_bf16 v[80:83], v[214:217], v[178:181], v[80:83]
	v_mfma_f32_16x16x32_bf16 v[68:71], v[206:209], v[252:255], v[68:71]
	v_mfma_f32_16x16x32_bf16 v[64:67], v[214:217], v[252:255], v[64:67]
	s_barrier
	s_setprio 0
	s_mov_b32 m0, s33
	v_lshl_add_u64 v[218:219], s[24:25], 0, v[128:129]
	ds_read_b128 v[158:161], v145 offset:16384
	ds_read_b128 v[162:165], v145 offset:17408
	ds_read_b128 v[166:169], v145 offset:18432
	ds_read_b128 v[170:173], v145 offset:19456
	ds_read_b128 v[174:177], v145 offset:20480
	ds_read_b128 v[178:181], v145 offset:21504
	global_load_lds_dwordx4 v[218:219], off
	v_lshl_add_u64 v[220:221], s[24:25], 0, v[130:131]
	s_mov_b32 m0, s34
	s_nop 0
	global_load_lds_dwordx4 v[220:221], off
	s_setprio 1
	s_waitcnt vmcnt(8)
	s_barrier
	s_waitcnt lgkmcnt(0)
	v_mfma_f32_16x16x32_bf16 v[60:63], v[138:141], v[158:161], v[60:63]
	v_mfma_f32_16x16x32_bf16 v[56:59], v[150:153], v[158:161], v[56:59]
	v_mfma_f32_16x16x32_bf16 v[44:47], v[138:141], v[166:169], v[44:47]
	v_mfma_f32_16x16x32_bf16 v[40:43], v[150:153], v[166:169], v[40:43]
	v_mfma_f32_16x16x32_bf16 v[28:31], v[138:141], v[174:177], v[28:31]
	v_mfma_f32_16x16x32_bf16 v[24:27], v[150:153], v[174:177], v[24:27]
	v_mfma_f32_16x16x32_bf16 v[12:15], v[138:141], v[188:191], v[12:15]
	v_mfma_f32_16x16x32_bf16 v[8:11], v[150:153], v[188:191], v[8:11]
	v_mfma_f32_16x16x32_bf16 v[60:63], v[146:149], v[162:165], v[60:63]
	v_mfma_f32_16x16x32_bf16 v[56:59], v[154:157], v[162:165], v[56:59]
	v_mfma_f32_16x16x32_bf16 v[44:47], v[146:149], v[170:173], v[44:47]
	v_mfma_f32_16x16x32_bf16 v[40:43], v[154:157], v[170:173], v[40:43]
	v_mfma_f32_16x16x32_bf16 v[28:31], v[146:149], v[178:181], v[28:31]
	v_mfma_f32_16x16x32_bf16 v[24:27], v[154:157], v[178:181], v[24:27]
	v_mfma_f32_16x16x32_bf16 v[12:15], v[146:149], v[192:195], v[12:15]
	v_mfma_f32_16x16x32_bf16 v[8:11], v[154:157], v[192:195], v[8:11]
	s_barrier
	s_setprio 0
	v_add_u32_e32 v154, 0x18000, v144
	ds_read_b128 v[138:141], v154
	ds_read_b128 v[146:149], v154 offset:1024
	ds_read_b128 v[150:153], v154 offset:2048
	ds_read_b128 v[154:157], v154 offset:3072
	ds_read_b128 v[248:251], v145 offset:38912
	ds_read_b128 v[252:255], v145 offset:39936
	s_add_u32 s48, s22, 0x80000
	s_addc_u32 s49, s23, 0
	s_add_i32 s47, s50, s31
	v_lshl_add_u64 v[246:247], s[48:49], 0, v[184:185]
	s_mov_b32 m0, s47
	s_nop 0
	global_load_lds_dwordx4 v[246:247], off
	v_lshl_add_u64 v[246:247], s[48:49], 0, v[132:133]
	s_add_i32 m0, s47, 0x2000
	s_nop 0
	global_load_lds_dwordx4 v[246:247], off
	s_waitcnt vmcnt(6)
	s_setprio 1
	s_barrier
	v_mfma_f32_16x16x32_bf16 v[52:55], v[202:205], v[158:161], v[52:55]
	v_mfma_f32_16x16x32_bf16 v[48:51], v[210:213], v[158:161], v[48:51]
	v_mfma_f32_16x16x32_bf16 v[36:39], v[202:205], v[166:169], v[36:39]
	v_mfma_f32_16x16x32_bf16 v[32:35], v[210:213], v[166:169], v[32:35]
	v_mfma_f32_16x16x32_bf16 v[20:23], v[202:205], v[174:177], v[20:23]
	v_mfma_f32_16x16x32_bf16 v[16:19], v[210:213], v[174:177], v[16:19]
	v_mfma_f32_16x16x32_bf16 v[4:7], v[202:205], v[188:191], v[4:7]
	v_mfma_f32_16x16x32_bf16 v[0:3], v[210:213], v[188:191], v[0:3]
	v_mfma_f32_16x16x32_bf16 v[52:55], v[206:209], v[162:165], v[52:55]
	v_mfma_f32_16x16x32_bf16 v[48:51], v[214:217], v[162:165], v[48:51]
	v_mfma_f32_16x16x32_bf16 v[36:39], v[206:209], v[170:173], v[36:39]
	v_mfma_f32_16x16x32_bf16 v[32:35], v[214:217], v[170:173], v[32:35]
	v_mfma_f32_16x16x32_bf16 v[20:23], v[206:209], v[178:181], v[20:23]
	v_mfma_f32_16x16x32_bf16 v[16:19], v[214:217], v[178:181], v[16:19]
	v_mfma_f32_16x16x32_bf16 v[4:7], v[206:209], v[192:195], v[4:7]
	v_mfma_f32_16x16x32_bf16 v[0:3], v[214:217], v[192:195], v[0:3]
	s_barrier
	s_setprio 0
	s_add_i32 s47, 0, 0x18000
	s_add_u32 s24, s24, 0x80000
	s_addc_u32 s25, s25, 0
	s_mov_b32 m0, s35
	v_lshl_add_u64 v[202:203], s[24:25], 0, v[128:129]
	ds_read_b128 v[158:161], v145 offset:32768
	ds_read_b128 v[162:165], v145 offset:33792
	ds_read_b128 v[166:169], v145 offset:34816
	ds_read_b128 v[170:173], v145 offset:35840
	ds_read_b128 v[174:177], v145 offset:36864
	ds_read_b128 v[178:181], v145 offset:37888
	global_load_lds_dwordx4 v[202:203], off
	v_lshl_add_u64 v[202:203], s[24:25], 0, v[130:131]
	s_mov_b32 m0, s36
	s_nop 0
	global_load_lds_dwordx4 v[202:203], off
	s_waitcnt lgkmcnt(8)
	s_setprio 1
	s_waitcnt vmcnt(8)
	s_barrier
	s_waitcnt lgkmcnt(0)
	v_mfma_f32_16x16x32_bf16 v[124:127], v[138:141], v[158:161], v[124:127]
	v_mfma_f32_16x16x32_bf16 v[120:123], v[150:153], v[158:161], v[120:123]
	v_mfma_f32_16x16x32_bf16 v[108:111], v[138:141], v[166:169], v[108:111]
	v_mfma_f32_16x16x32_bf16 v[104:107], v[150:153], v[166:169], v[104:107]
	v_mfma_f32_16x16x32_bf16 v[92:95], v[138:141], v[174:177], v[92:95]
	v_mfma_f32_16x16x32_bf16 v[88:91], v[150:153], v[174:177], v[88:91]
	v_mfma_f32_16x16x32_bf16 v[76:79], v[138:141], v[248:251], v[76:79]
	v_mfma_f32_16x16x32_bf16 v[72:75], v[150:153], v[248:251], v[72:75]
	v_mfma_f32_16x16x32_bf16 v[124:127], v[146:149], v[162:165], v[124:127]
	v_mfma_f32_16x16x32_bf16 v[120:123], v[154:157], v[162:165], v[120:123]
	v_mfma_f32_16x16x32_bf16 v[108:111], v[146:149], v[170:173], v[108:111]
	v_mfma_f32_16x16x32_bf16 v[104:107], v[154:157], v[170:173], v[104:107]
	v_mfma_f32_16x16x32_bf16 v[92:95], v[146:149], v[178:181], v[92:95]
	v_mfma_f32_16x16x32_bf16 v[88:91], v[154:157], v[178:181], v[88:91]
	v_mfma_f32_16x16x32_bf16 v[76:79], v[146:149], v[252:255], v[76:79]
	v_mfma_f32_16x16x32_bf16 v[72:75], v[154:157], v[252:255], v[72:75]
	s_barrier
	s_setprio 0
	ds_read_b128 v[188:191], v145 offset:55296
	ds_read_b128 v[192:195], v145 offset:56320
	s_add_i32 s24, 0, 0x1c000
	s_add_i32 s25, s47, s31
	v_add_u32_e32 v187, s24, v144
	v_lshl_add_u64 v[182:183], v[182:183], 0, s[52:53]
	s_mov_b32 m0, s25
	ds_read_b128 v[202:205], v187
	ds_read_b128 v[206:209], v187 offset:1024
	ds_read_b128 v[210:213], v187 offset:2048
	ds_read_b128 v[214:217], v187 offset:3072
	global_load_lds_dwordx4 v[182:183], off
	v_lshl_add_u64 v[182:183], v[196:197], 0, s[52:53]
	s_add_i32 m0, s25, 0x2000
	s_nop 0
	global_load_lds_dwordx4 v[182:183], off
	s_setprio 1
	s_barrier
	s_waitcnt lgkmcnt(0)
	v_mfma_f32_16x16x32_bf16 v[116:119], v[202:205], v[158:161], v[116:119]
	v_mfma_f32_16x16x32_bf16 v[112:115], v[210:213], v[158:161], v[112:115]
	v_mfma_f32_16x16x32_bf16 v[100:103], v[202:205], v[166:169], v[100:103]
	v_mfma_f32_16x16x32_bf16 v[96:99], v[210:213], v[166:169], v[96:99]
	v_mfma_f32_16x16x32_bf16 v[84:87], v[202:205], v[174:177], v[84:87]
	v_mfma_f32_16x16x32_bf16 v[80:83], v[210:213], v[174:177], v[80:83]
	v_mfma_f32_16x16x32_bf16 v[68:71], v[202:205], v[248:251], v[68:71]
	v_mfma_f32_16x16x32_bf16 v[64:67], v[210:213], v[248:251], v[64:67]
	v_mfma_f32_16x16x32_bf16 v[116:119], v[206:209], v[162:165], v[116:119]
	v_mfma_f32_16x16x32_bf16 v[112:115], v[214:217], v[162:165], v[112:115]
	v_mfma_f32_16x16x32_bf16 v[100:103], v[206:209], v[170:173], v[100:103]
	v_mfma_f32_16x16x32_bf16 v[96:99], v[214:217], v[170:173], v[96:99]
	v_mfma_f32_16x16x32_bf16 v[84:87], v[206:209], v[178:181], v[84:87]
	v_mfma_f32_16x16x32_bf16 v[80:83], v[214:217], v[178:181], v[80:83]
	v_mfma_f32_16x16x32_bf16 v[68:71], v[206:209], v[252:255], v[68:71]
	v_mfma_f32_16x16x32_bf16 v[64:67], v[214:217], v[252:255], v[64:67]
	s_barrier
	s_setprio 0
	s_mov_b32 m0, s40
	v_lshl_add_u64 v[182:183], v[218:219], 0, s[52:53]
	ds_read_b128 v[158:161], v145 offset:49152
	ds_read_b128 v[162:165], v145 offset:50176
	ds_read_b128 v[166:169], v145 offset:51200
	ds_read_b128 v[170:173], v145 offset:52224
	ds_read_b128 v[174:177], v145 offset:53248
	ds_read_b128 v[178:181], v145 offset:54272
	global_load_lds_dwordx4 v[182:183], off
	v_lshl_add_u64 v[182:183], v[220:221], 0, s[52:53]
	s_mov_b32 m0, s41
	s_nop 0
	global_load_lds_dwordx4 v[182:183], off
	s_setprio 1
	s_waitcnt vmcnt(8)
	s_barrier
	s_waitcnt lgkmcnt(0)
	v_mfma_f32_16x16x32_bf16 v[60:63], v[138:141], v[158:161], v[60:63]
	v_mfma_f32_16x16x32_bf16 v[56:59], v[150:153], v[158:161], v[56:59]
	v_mfma_f32_16x16x32_bf16 v[44:47], v[138:141], v[166:169], v[44:47]
	v_mfma_f32_16x16x32_bf16 v[40:43], v[150:153], v[166:169], v[40:43]
	v_mfma_f32_16x16x32_bf16 v[28:31], v[138:141], v[174:177], v[28:31]
	v_mfma_f32_16x16x32_bf16 v[24:27], v[150:153], v[174:177], v[24:27]
	v_mfma_f32_16x16x32_bf16 v[12:15], v[138:141], v[188:191], v[12:15]
	v_mfma_f32_16x16x32_bf16 v[8:11], v[150:153], v[188:191], v[8:11]
	v_mfma_f32_16x16x32_bf16 v[60:63], v[146:149], v[162:165], v[60:63]
	v_mfma_f32_16x16x32_bf16 v[56:59], v[154:157], v[162:165], v[56:59]
	v_mfma_f32_16x16x32_bf16 v[44:47], v[146:149], v[170:173], v[44:47]
	v_mfma_f32_16x16x32_bf16 v[40:43], v[154:157], v[170:173], v[40:43]
	v_mfma_f32_16x16x32_bf16 v[28:31], v[146:149], v[178:181], v[28:31]
	v_mfma_f32_16x16x32_bf16 v[24:27], v[154:157], v[178:181], v[24:27]
	v_mfma_f32_16x16x32_bf16 v[12:15], v[146:149], v[192:195], v[12:15]
	v_mfma_f32_16x16x32_bf16 v[8:11], v[154:157], v[192:195], v[8:11]
	s_barrier
	s_setprio 0
	v_add_u32_e32 v154, 0x10000, v144
	ds_read_b128 v[138:141], v154
	ds_read_b128 v[146:149], v154 offset:1024
	ds_read_b128 v[150:153], v154 offset:2048
	ds_read_b128 v[154:157], v154 offset:3072
	ds_read_b128 v[248:251], v145 offset:6144
	ds_read_b128 v[252:255], v145 offset:7168
	s_add_u32 s22, s22, 0x80080
	s_addc_u32 s23, s23, 0
	s_add_i32 s24, s24, s31
	v_lshl_add_u64 v[246:247], s[22:23], 0, v[184:185]
	s_mov_b32 m0, s24
	s_nop 0
	global_load_lds_dwordx4 v[246:247], off
	v_lshl_add_u64 v[246:247], s[22:23], 0, v[132:133]
	s_add_i32 m0, s24, 0x2000
	s_nop 0
	global_load_lds_dwordx4 v[246:247], off
	s_waitcnt vmcnt(6)
	s_setprio 1
	s_barrier
	v_mfma_f32_16x16x32_bf16 v[52:55], v[202:205], v[158:161], v[52:55]
	v_mfma_f32_16x16x32_bf16 v[48:51], v[210:213], v[158:161], v[48:51]
	v_mfma_f32_16x16x32_bf16 v[36:39], v[202:205], v[166:169], v[36:39]
	v_mfma_f32_16x16x32_bf16 v[32:35], v[210:213], v[166:169], v[32:35]
	v_mfma_f32_16x16x32_bf16 v[20:23], v[202:205], v[174:177], v[20:23]
	v_mfma_f32_16x16x32_bf16 v[16:19], v[210:213], v[174:177], v[16:19]
	v_mfma_f32_16x16x32_bf16 v[4:7], v[202:205], v[188:191], v[4:7]
	v_mfma_f32_16x16x32_bf16 v[0:3], v[210:213], v[188:191], v[0:3]
	v_mfma_f32_16x16x32_bf16 v[52:55], v[206:209], v[162:165], v[52:55]
	v_mfma_f32_16x16x32_bf16 v[48:51], v[214:217], v[162:165], v[48:51]
	v_mfma_f32_16x16x32_bf16 v[36:39], v[206:209], v[170:173], v[36:39]
	v_mfma_f32_16x16x32_bf16 v[32:35], v[214:217], v[170:173], v[32:35]
	v_mfma_f32_16x16x32_bf16 v[20:23], v[206:209], v[178:181], v[20:23]
	v_mfma_f32_16x16x32_bf16 v[16:19], v[214:217], v[178:181], v[16:19]
	v_mfma_f32_16x16x32_bf16 v[4:7], v[206:209], v[192:195], v[4:7]
	v_mfma_f32_16x16x32_bf16 v[0:3], v[214:217], v[192:195], v[0:3]
	s_barrier
	s_setprio 0
	s_add_i32 s46, s46, 2
	s_add_u32 s20, s20, 0x100
	s_addc_u32 s21, s21, 0
	s_add_u32 s44, s44, 0x100
	s_addc_u32 s45, s45, 0
	s_cmp_gt_u32 s46, 29
	s_cbranch_scc0 .LBB0_207
	s_waitcnt lgkmcnt(0)
	v_mov_b32_e32 v138, v142
	v_mov_b32_e32 v146, v143
	s_lshl_b32 s1, s18, 8
	s_add_i32 s1, s1, s38
	v_add_u32_e32 v138, s1, v138
	s_lshl_b32 s1, s0, 8
	s_cmp_lt_i32 s0, 2
	v_lshlrev_b32_e32 v147, 3, v146
	s_mov_b64 s[18:19], -1
	v_ashrrev_i32_e32 v139, 31, v138
	s_cbranch_scc1 .LBB0_210
	v_mul_f32_e32 v140, 0xbfb8aa3b, v124
	v_mul_f32_e32 v149, 0xbfb8aa3b, v125
	v_mul_f32_e32 v150, 0xbfb8aa3b, v126
	v_mul_f32_e32 v153, 0xbfb8aa3b, v120
	v_exp_f32_e32 v148, v140
	v_exp_f32_e32 v149, v149
	v_exp_f32_e32 v150, v150
	v_mul_f32_e32 v151, 0xbfb8aa3b, v127
	v_exp_f32_e32 v153, v153
	v_mul_f32_e32 v154, 0xbfb8aa3b, v121
	v_exp_f32_e32 v151, v151
	v_exp_f32_e32 v154, v154
	v_mul_f32_e32 v155, 0xbfb8aa3b, v122
	v_mul_f32_e32 v156, 0xbfb8aa3b, v123
	v_add_f32_e32 v148, 1.0, v148
	v_add_f32_e32 v149, 1.0, v149
	v_add_f32_e32 v150, 1.0, v150
	v_add_f32_e32 v153, 1.0, v153
	v_exp_f32_e32 v155, v155
	v_exp_f32_e32 v156, v156
	v_rcp_f32_e32 v148, v148
	v_rcp_f32_e32 v149, v149
	v_rcp_f32_e32 v150, v150
	v_add_f32_e32 v151, 1.0, v151
	v_rcp_f32_e32 v153, v153
	v_add_f32_e32 v154, 1.0, v154
	v_rcp_f32_e32 v151, v151
	v_rcp_f32_e32 v154, v154
	v_add_f32_e32 v155, 1.0, v155
	v_add_f32_e32 v156, 1.0, v156
	s_add_i32 s9, s42, s1
	v_mul_f32_e32 v148, v124, v148
	v_mul_f32_e32 v149, v125, v149
	v_mul_f32_e32 v150, v126, v150
	v_rcp_f32_e32 v155, v155
	v_rcp_f32_e32 v156, v156
	v_mul_f32_e32 v153, v120, v153
	v_lshlrev_b64 v[140:141], 12, v[138:139]
	v_add_u32_e32 v152, s9, v147
	v_mul_f32_e32 v151, v127, v151
	v_mul_f32_e32 v154, v121, v154
	v_cvt_pk_bf16_f32 v148, v148, v149
	v_cvt_pk_bf16_f32 v149, v150, v151
	v_cvt_pk_bf16_f32 v150, v153, v154
	v_mul_f32_e32 v153, 0xbfb8aa3b, v116
	v_lshl_add_u64 v[140:141], s[6:7], 0, v[140:141]
	v_exp_f32_e32 v154, v153
	v_ashrrev_i32_e32 v153, 31, v152
	v_lshl_add_u64 v[140:141], v[152:153], 1, v[140:141]
	v_mul_f32_e32 v155, v122, v155
	v_mul_f32_e32 v156, v123, v156
	v_cvt_pk_bf16_f32 v151, v155, v156
	global_store_dwordx4 v[140:141], v[148:151], off
	v_mul_f32_e32 v152, 0xbfb8aa3b, v112
	v_mul_f32_e32 v153, 0xbfb8aa3b, v113
	v_mul_f32_e32 v149, 0xbfb8aa3b, v117
	v_mul_f32_e32 v150, 0xbfb8aa3b, v118
	v_exp_f32_e32 v149, v149
	v_exp_f32_e32 v150, v150
	v_mul_f32_e32 v151, 0xbfb8aa3b, v119
	v_add_f32_e32 v148, 1.0, v154
	v_exp_f32_e32 v151, v151
	v_mul_f32_e32 v154, 0xbfb8aa3b, v114
	v_mul_f32_e32 v155, 0xbfb8aa3b, v115
	v_exp_f32_e32 v152, v152
	v_exp_f32_e32 v153, v153
	v_exp_f32_e32 v154, v154
	v_exp_f32_e32 v155, v155
	v_add_f32_e32 v149, 1.0, v149
	v_add_f32_e32 v150, 1.0, v150
	v_rcp_f32_e32 v148, v148
	v_rcp_f32_e32 v149, v149
	v_rcp_f32_e32 v150, v150
	v_add_f32_e32 v151, 1.0, v151
	v_rcp_f32_e32 v151, v151
	v_add_f32_e32 v152, 1.0, v152
	v_add_f32_e32 v153, 1.0, v153
	v_add_f32_e32 v154, 1.0, v154
	v_add_f32_e32 v155, 1.0, v155
	v_rcp_f32_e32 v152, v152
	v_rcp_f32_e32 v153, v153
	v_rcp_f32_e32 v154, v154
	v_rcp_f32_e32 v155, v155
	v_mul_f32_e32 v148, v116, v148
	v_mul_f32_e32 v149, v117, v149
	v_mul_f32_e32 v150, v118, v150
	v_mul_f32_e32 v151, v119, v151
	v_cvt_pk_bf16_f32 v148, v148, v149
	v_cvt_pk_bf16_f32 v149, v150, v151
	v_mul_f32_e32 v150, 0xbfb8aa3b, v108
	v_mul_f32_e32 v152, v112, v152
	v_mul_f32_e32 v153, v113, v153
	v_mul_f32_e32 v154, v114, v154
	v_mul_f32_e32 v155, v115, v155
	v_exp_f32_e32 v156, v150
	v_cvt_pk_bf16_f32 v150, v152, v153
	v_cvt_pk_bf16_f32 v151, v154, v155
	global_store_dwordx4 v[140:141], v[148:151], off offset:256
	v_mul_f32_e32 v154, 0xbfb8aa3b, v106
	v_mul_f32_e32 v152, 0xbfb8aa3b, v104
	v_mul_f32_e32 v149, 0xbfb8aa3b, v109
	v_mul_f32_e32 v150, 0xbfb8aa3b, v110
	v_mul_f32_e32 v151, 0xbfb8aa3b, v111
	v_exp_f32_e32 v149, v149
	v_exp_f32_e32 v150, v150
	v_exp_f32_e32 v151, v151
	v_mul_f32_e32 v153, 0xbfb8aa3b, v105
	v_exp_f32_e32 v154, v154
	v_mul_f32_e32 v155, 0xbfb8aa3b, v107
	v_exp_f32_e32 v152, v152
	v_exp_f32_e32 v153, v153
	v_exp_f32_e32 v155, v155
	v_add_f32_e32 v148, 1.0, v156
	v_add_f32_e32 v149, 1.0, v149
	v_add_f32_e32 v150, 1.0, v150
	v_add_f32_e32 v151, 1.0, v151
	v_add_f32_e32 v154, 1.0, v154
	v_rcp_f32_e32 v148, v148
	v_rcp_f32_e32 v149, v149
	v_rcp_f32_e32 v150, v150
	v_rcp_f32_e32 v151, v151
	v_add_f32_e32 v152, 1.0, v152
	v_add_f32_e32 v153, 1.0, v153
	v_rcp_f32_e32 v154, v154
	v_add_f32_e32 v155, 1.0, v155
	v_rcp_f32_e32 v152, v152
	v_rcp_f32_e32 v153, v153
	v_rcp_f32_e32 v155, v155
	v_mul_f32_e32 v148, v108, v148
	v_mul_f32_e32 v149, v109, v149
	v_mul_f32_e32 v150, v110, v150
	v_mul_f32_e32 v151, v111, v151
	v_mul_f32_e32 v154, v106, v154
	v_mul_f32_e32 v152, v104, v152
	v_mul_f32_e32 v153, v105, v153
	v_mul_f32_e32 v155, v107, v155
	v_cvt_pk_bf16_f32 v148, v148, v149
	v_cvt_pk_bf16_f32 v149, v150, v151
	v_cvt_pk_bf16_f32 v150, v152, v153
	v_cvt_pk_bf16_f32 v151, v154, v155
	v_mul_f32_e32 v154, 0xbfb8aa3b, v100
	s_mov_b32 s9, 0x10000
	v_exp_f32_e32 v156, v154
	v_add_co_u32_e32 v154, vcc, s9, v140
	v_mul_f32_e32 v157, 0xbfb8aa3b, v99
	s_nop 0
	v_addc_co_u32_e32 v155, vcc, 0, v141, vcc
	global_store_dwordx4 v[154:155], v[148:151], off
	v_mul_f32_e32 v154, 0xbfb8aa3b, v96
	v_mul_f32_e32 v155, 0xbfb8aa3b, v97
	v_mul_f32_e32 v149, 0xbfb8aa3b, v101
	v_mul_f32_e32 v150, 0xbfb8aa3b, v102
	v_exp_f32_e32 v149, v149
	v_exp_f32_e32 v150, v150
	v_mul_f32_e32 v151, 0xbfb8aa3b, v103
	v_add_f32_e32 v148, 1.0, v156
	v_exp_f32_e32 v151, v151
	v_mul_f32_e32 v156, 0xbfb8aa3b, v98
	v_exp_f32_e32 v154, v154
	v_exp_f32_e32 v155, v155
	v_exp_f32_e32 v156, v156
	v_exp_f32_e32 v157, v157
	v_add_f32_e32 v149, 1.0, v149
	v_add_f32_e32 v150, 1.0, v150
	v_rcp_f32_e32 v148, v148
	v_rcp_f32_e32 v149, v149
	v_rcp_f32_e32 v150, v150
	v_add_f32_e32 v151, 1.0, v151
	v_rcp_f32_e32 v151, v151
	v_add_f32_e32 v154, 1.0, v154
	v_add_f32_e32 v155, 1.0, v155
	v_add_f32_e32 v156, 1.0, v156
	v_add_f32_e32 v157, 1.0, v157
	v_rcp_f32_e32 v154, v154
	v_rcp_f32_e32 v155, v155
	v_rcp_f32_e32 v156, v156
	v_rcp_f32_e32 v157, v157
	v_mul_f32_e32 v148, v100, v148
	v_mul_f32_e32 v149, v101, v149
	v_mul_f32_e32 v150, v102, v150
	s_mov_b64 s[18:19], 0x10000
	v_mul_f32_e32 v151, v103, v151
	v_cvt_pk_bf16_f32 v148, v148, v149
	v_cvt_pk_bf16_f32 v149, v150, v151
	v_mul_f32_e32 v150, 0xbfb8aa3b, v92
	v_lshl_add_u64 v[152:153], v[140:141], 0, s[18:19]
	v_mul_f32_e32 v154, v96, v154
	v_mul_f32_e32 v155, v97, v155
	v_mul_f32_e32 v156, v98, v156
	v_mul_f32_e32 v157, v99, v157
	v_exp_f32_e32 v158, v150
	v_cvt_pk_bf16_f32 v150, v154, v155
	v_cvt_pk_bf16_f32 v151, v156, v157
	global_store_dwordx4 v[152:153], v[148:151], off offset:256
	v_mul_f32_e32 v154, 0xbfb8aa3b, v90
	v_mul_f32_e32 v152, 0xbfb8aa3b, v88
	v_mul_f32_e32 v149, 0xbfb8aa3b, v93
	v_mul_f32_e32 v150, 0xbfb8aa3b, v94
	v_mul_f32_e32 v151, 0xbfb8aa3b, v95
	v_exp_f32_e32 v149, v149
	v_exp_f32_e32 v150, v150
	v_exp_f32_e32 v151, v151
	v_mul_f32_e32 v153, 0xbfb8aa3b, v89
	v_exp_f32_e32 v154, v154
	v_mul_f32_e32 v155, 0xbfb8aa3b, v91
	v_exp_f32_e32 v152, v152
	v_exp_f32_e32 v153, v153
	v_exp_f32_e32 v155, v155
	v_add_f32_e32 v148, 1.0, v158
	v_add_f32_e32 v149, 1.0, v149
	v_add_f32_e32 v150, 1.0, v150
	v_add_f32_e32 v151, 1.0, v151
	v_add_f32_e32 v154, 1.0, v154
	v_rcp_f32_e32 v148, v148
	v_rcp_f32_e32 v149, v149
	v_rcp_f32_e32 v150, v150
	v_rcp_f32_e32 v151, v151
	v_add_f32_e32 v152, 1.0, v152
	v_add_f32_e32 v153, 1.0, v153
	v_rcp_f32_e32 v154, v154
	v_add_f32_e32 v155, 1.0, v155
	v_rcp_f32_e32 v152, v152
	v_rcp_f32_e32 v153, v153
	v_rcp_f32_e32 v155, v155
	v_mul_f32_e32 v148, v92, v148
	v_mul_f32_e32 v149, v93, v149
	v_mul_f32_e32 v150, v94, v150
	v_mul_f32_e32 v151, v95, v151
	v_mul_f32_e32 v154, v90, v154
	v_mul_f32_e32 v152, v88, v152
	v_mul_f32_e32 v153, v89, v153
	v_mul_f32_e32 v155, v91, v155
	v_cvt_pk_bf16_f32 v148, v148, v149
	v_cvt_pk_bf16_f32 v149, v150, v151
	v_cvt_pk_bf16_f32 v150, v152, v153
	v_cvt_pk_bf16_f32 v151, v154, v155
	v_mul_f32_e32 v154, 0xbfb8aa3b, v84
	s_mov_b32 s9, 0x20000
	v_exp_f32_e32 v156, v154
	v_add_co_u32_e32 v154, vcc, s9, v140
	v_mul_f32_e32 v157, 0xbfb8aa3b, v83
	s_nop 0
	v_addc_co_u32_e32 v155, vcc, 0, v141, vcc
	global_store_dwordx4 v[154:155], v[148:151], off
	v_mul_f32_e32 v154, 0xbfb8aa3b, v80
	v_mul_f32_e32 v155, 0xbfb8aa3b, v81
	v_mul_f32_e32 v149, 0xbfb8aa3b, v85
	v_mul_f32_e32 v150, 0xbfb8aa3b, v86
	v_exp_f32_e32 v149, v149
	v_exp_f32_e32 v150, v150
	v_mul_f32_e32 v151, 0xbfb8aa3b, v87
	v_add_f32_e32 v148, 1.0, v156
	v_exp_f32_e32 v151, v151
	v_mul_f32_e32 v156, 0xbfb8aa3b, v82
	v_exp_f32_e32 v154, v154
	v_exp_f32_e32 v155, v155
	v_exp_f32_e32 v156, v156
	v_exp_f32_e32 v157, v157
	v_add_f32_e32 v149, 1.0, v149
	v_add_f32_e32 v150, 1.0, v150
	v_rcp_f32_e32 v148, v148
	v_rcp_f32_e32 v149, v149
	v_rcp_f32_e32 v150, v150
	v_add_f32_e32 v151, 1.0, v151
	v_rcp_f32_e32 v151, v151
	v_add_f32_e32 v154, 1.0, v154
	v_add_f32_e32 v155, 1.0, v155
	v_add_f32_e32 v156, 1.0, v156
	v_add_f32_e32 v157, 1.0, v157
	v_rcp_f32_e32 v154, v154
	v_rcp_f32_e32 v155, v155
	v_rcp_f32_e32 v156, v156
	v_rcp_f32_e32 v157, v157
	v_mul_f32_e32 v148, v84, v148
	v_mul_f32_e32 v149, v85, v149
	v_mul_f32_e32 v150, v86, v150
	s_mov_b64 s[18:19], 0x20000
	v_mul_f32_e32 v151, v87, v151
	v_cvt_pk_bf16_f32 v148, v148, v149
	v_cvt_pk_bf16_f32 v149, v150, v151
	v_mul_f32_e32 v150, 0xbfb8aa3b, v76
	v_lshl_add_u64 v[152:153], v[140:141], 0, s[18:19]
	v_mul_f32_e32 v154, v80, v154
	v_mul_f32_e32 v155, v81, v155
	v_mul_f32_e32 v156, v82, v156
	v_mul_f32_e32 v157, v83, v157
	v_exp_f32_e32 v158, v150
	v_cvt_pk_bf16_f32 v150, v154, v155
	v_cvt_pk_bf16_f32 v151, v156, v157
	global_store_dwordx4 v[152:153], v[148:151], off offset:256
	v_mul_f32_e32 v154, 0xbfb8aa3b, v74
	v_mul_f32_e32 v152, 0xbfb8aa3b, v72
	v_mul_f32_e32 v149, 0xbfb8aa3b, v77
	v_mul_f32_e32 v150, 0xbfb8aa3b, v78
	v_mul_f32_e32 v151, 0xbfb8aa3b, v79
	v_exp_f32_e32 v149, v149
	v_exp_f32_e32 v150, v150
	v_exp_f32_e32 v151, v151
	v_mul_f32_e32 v153, 0xbfb8aa3b, v73
	v_exp_f32_e32 v154, v154
	v_mul_f32_e32 v155, 0xbfb8aa3b, v75
	v_exp_f32_e32 v152, v152
	v_exp_f32_e32 v153, v153
	v_exp_f32_e32 v155, v155
	v_add_f32_e32 v148, 1.0, v158
	v_add_f32_e32 v149, 1.0, v149
	v_add_f32_e32 v150, 1.0, v150
	v_add_f32_e32 v151, 1.0, v151
	v_add_f32_e32 v154, 1.0, v154
	v_rcp_f32_e32 v148, v148
	v_rcp_f32_e32 v149, v149
	v_rcp_f32_e32 v150, v150
	v_rcp_f32_e32 v151, v151
	v_add_f32_e32 v152, 1.0, v152
	v_add_f32_e32 v153, 1.0, v153
	v_rcp_f32_e32 v154, v154
	v_add_f32_e32 v155, 1.0, v155
	v_rcp_f32_e32 v152, v152
	v_rcp_f32_e32 v153, v153
	v_rcp_f32_e32 v155, v155
	v_mul_f32_e32 v148, v76, v148
	v_mul_f32_e32 v149, v77, v149
	v_mul_f32_e32 v150, v78, v150
	v_mul_f32_e32 v151, v79, v151
	v_mul_f32_e32 v154, v74, v154
	v_mul_f32_e32 v152, v72, v152
	v_mul_f32_e32 v153, v73, v153
	v_mul_f32_e32 v155, v75, v155
	v_cvt_pk_bf16_f32 v148, v148, v149
	v_cvt_pk_bf16_f32 v149, v150, v151
	v_cvt_pk_bf16_f32 v150, v152, v153
	v_cvt_pk_bf16_f32 v151, v154, v155
	v_mul_f32_e32 v154, 0xbfb8aa3b, v68
	s_mov_b32 s9, 0x30000
	v_exp_f32_e32 v156, v154
	v_add_co_u32_e32 v154, vcc, s9, v140
	v_mul_f32_e32 v157, 0xbfb8aa3b, v67
	s_nop 0
	v_addc_co_u32_e32 v155, vcc, 0, v141, vcc
	global_store_dwordx4 v[154:155], v[148:151], off
	v_mul_f32_e32 v154, 0xbfb8aa3b, v64
	v_mul_f32_e32 v155, 0xbfb8aa3b, v65
	v_mul_f32_e32 v149, 0xbfb8aa3b, v69
	v_mul_f32_e32 v150, 0xbfb8aa3b, v70
	v_exp_f32_e32 v149, v149
	v_exp_f32_e32 v150, v150
	v_mul_f32_e32 v151, 0xbfb8aa3b, v71
	v_add_f32_e32 v148, 1.0, v156
	v_exp_f32_e32 v151, v151
	v_mul_f32_e32 v156, 0xbfb8aa3b, v66
	v_exp_f32_e32 v154, v154
	v_exp_f32_e32 v155, v155
	v_exp_f32_e32 v156, v156
	v_exp_f32_e32 v157, v157
	v_add_f32_e32 v149, 1.0, v149
	v_add_f32_e32 v150, 1.0, v150
	v_rcp_f32_e32 v148, v148
	v_rcp_f32_e32 v149, v149
	v_rcp_f32_e32 v150, v150
	v_add_f32_e32 v151, 1.0, v151
	v_rcp_f32_e32 v151, v151
	v_add_f32_e32 v154, 1.0, v154
	v_add_f32_e32 v155, 1.0, v155
	v_add_f32_e32 v156, 1.0, v156
	v_add_f32_e32 v157, 1.0, v157
	v_rcp_f32_e32 v154, v154
	v_rcp_f32_e32 v155, v155
	v_rcp_f32_e32 v156, v156
	v_rcp_f32_e32 v157, v157
	v_mul_f32_e32 v148, v68, v148
	v_mul_f32_e32 v149, v69, v149
	v_mul_f32_e32 v150, v70, v150
	s_mov_b64 s[18:19], 0x30000
	v_mul_f32_e32 v151, v71, v151
	v_cvt_pk_bf16_f32 v148, v148, v149
	v_cvt_pk_bf16_f32 v149, v150, v151
	v_mul_f32_e32 v150, 0xbfb8aa3b, v60
	v_lshl_add_u64 v[152:153], v[140:141], 0, s[18:19]
	v_mul_f32_e32 v154, v64, v154
	v_mul_f32_e32 v155, v65, v155
	v_mul_f32_e32 v156, v66, v156
	v_mul_f32_e32 v157, v67, v157
	v_exp_f32_e32 v158, v150
	v_cvt_pk_bf16_f32 v150, v154, v155
	v_cvt_pk_bf16_f32 v151, v156, v157
	global_store_dwordx4 v[152:153], v[148:151], off offset:256
	v_mul_f32_e32 v154, 0xbfb8aa3b, v58
	v_mul_f32_e32 v152, 0xbfb8aa3b, v56
	v_mul_f32_e32 v149, 0xbfb8aa3b, v61
	v_mul_f32_e32 v150, 0xbfb8aa3b, v62
	v_mul_f32_e32 v151, 0xbfb8aa3b, v63
	v_exp_f32_e32 v149, v149
	v_exp_f32_e32 v150, v150
	v_exp_f32_e32 v151, v151
	v_mul_f32_e32 v153, 0xbfb8aa3b, v57
	v_exp_f32_e32 v154, v154
	v_mul_f32_e32 v155, 0xbfb8aa3b, v59
	v_exp_f32_e32 v152, v152
	v_exp_f32_e32 v153, v153
	v_exp_f32_e32 v155, v155
	v_add_f32_e32 v148, 1.0, v158
	v_add_f32_e32 v149, 1.0, v149
	v_add_f32_e32 v150, 1.0, v150
	v_add_f32_e32 v151, 1.0, v151
	v_add_f32_e32 v154, 1.0, v154
	v_rcp_f32_e32 v148, v148
	v_rcp_f32_e32 v149, v149
	v_rcp_f32_e32 v150, v150
	v_rcp_f32_e32 v151, v151
	v_add_f32_e32 v152, 1.0, v152
	v_add_f32_e32 v153, 1.0, v153
	v_rcp_f32_e32 v154, v154
	v_add_f32_e32 v155, 1.0, v155
	v_rcp_f32_e32 v152, v152
	v_rcp_f32_e32 v153, v153
	v_rcp_f32_e32 v155, v155
	v_mul_f32_e32 v148, v60, v148
	v_mul_f32_e32 v149, v61, v149
	v_mul_f32_e32 v150, v62, v150
	v_mul_f32_e32 v151, v63, v151
	v_mul_f32_e32 v154, v58, v154
	v_mul_f32_e32 v152, v56, v152
	v_mul_f32_e32 v153, v57, v153
	v_mul_f32_e32 v155, v59, v155
	v_cvt_pk_bf16_f32 v148, v148, v149
	v_cvt_pk_bf16_f32 v149, v150, v151
	v_cvt_pk_bf16_f32 v150, v152, v153
	v_cvt_pk_bf16_f32 v151, v154, v155
	v_mul_f32_e32 v154, 0xbfb8aa3b, v52
	s_mov_b32 s9, 0x80000
	v_exp_f32_e32 v156, v154
	v_add_co_u32_e32 v154, vcc, s9, v140
	v_mul_f32_e32 v157, 0xbfb8aa3b, v51
	s_nop 0
	v_addc_co_u32_e32 v155, vcc, 0, v141, vcc
	global_store_dwordx4 v[154:155], v[148:151], off
	v_mul_f32_e32 v154, 0xbfb8aa3b, v48
	v_mul_f32_e32 v155, 0xbfb8aa3b, v49
	v_mul_f32_e32 v149, 0xbfb8aa3b, v53
	v_mul_f32_e32 v150, 0xbfb8aa3b, v54
	v_exp_f32_e32 v149, v149
	v_exp_f32_e32 v150, v150
	v_mul_f32_e32 v151, 0xbfb8aa3b, v55
	v_add_f32_e32 v148, 1.0, v156
	v_exp_f32_e32 v151, v151
	v_mul_f32_e32 v156, 0xbfb8aa3b, v50
	v_exp_f32_e32 v154, v154
	v_exp_f32_e32 v155, v155
	v_exp_f32_e32 v156, v156
	v_exp_f32_e32 v157, v157
	v_add_f32_e32 v149, 1.0, v149
	v_add_f32_e32 v150, 1.0, v150
	v_rcp_f32_e32 v148, v148
	v_rcp_f32_e32 v149, v149
	v_rcp_f32_e32 v150, v150
	v_add_f32_e32 v151, 1.0, v151
	v_rcp_f32_e32 v151, v151
	v_add_f32_e32 v154, 1.0, v154
	v_add_f32_e32 v155, 1.0, v155
	v_add_f32_e32 v156, 1.0, v156
	v_add_f32_e32 v157, 1.0, v157
	v_rcp_f32_e32 v154, v154
	v_rcp_f32_e32 v155, v155
	v_rcp_f32_e32 v156, v156
	v_rcp_f32_e32 v157, v157
	v_mul_f32_e32 v148, v52, v148
	v_mul_f32_e32 v149, v53, v149
	v_mul_f32_e32 v150, v54, v150
	s_mov_b64 s[18:19], 0x80000
	v_mul_f32_e32 v151, v55, v151
	v_cvt_pk_bf16_f32 v148, v148, v149
	v_cvt_pk_bf16_f32 v149, v150, v151
	v_mul_f32_e32 v150, 0xbfb8aa3b, v44
	v_lshl_add_u64 v[152:153], v[140:141], 0, s[18:19]
	v_mul_f32_e32 v154, v48, v154
	v_mul_f32_e32 v155, v49, v155
	v_mul_f32_e32 v156, v50, v156
	v_mul_f32_e32 v157, v51, v157
	v_exp_f32_e32 v158, v150
	v_cvt_pk_bf16_f32 v150, v154, v155
	v_cvt_pk_bf16_f32 v151, v156, v157
	global_store_dwordx4 v[152:153], v[148:151], off offset:256
	v_mul_f32_e32 v154, 0xbfb8aa3b, v42
	v_mul_f32_e32 v152, 0xbfb8aa3b, v40
	v_mul_f32_e32 v149, 0xbfb8aa3b, v45
	v_mul_f32_e32 v150, 0xbfb8aa3b, v46
	v_mul_f32_e32 v151, 0xbfb8aa3b, v47
	v_exp_f32_e32 v149, v149
	v_exp_f32_e32 v150, v150
	v_exp_f32_e32 v151, v151
	v_mul_f32_e32 v153, 0xbfb8aa3b, v41
	v_exp_f32_e32 v154, v154
	v_mul_f32_e32 v155, 0xbfb8aa3b, v43
	v_exp_f32_e32 v152, v152
	v_exp_f32_e32 v153, v153
	v_exp_f32_e32 v155, v155
	v_add_f32_e32 v148, 1.0, v158
	v_add_f32_e32 v149, 1.0, v149
	v_add_f32_e32 v150, 1.0, v150
	v_add_f32_e32 v151, 1.0, v151
	v_add_f32_e32 v154, 1.0, v154
	v_rcp_f32_e32 v148, v148
	v_rcp_f32_e32 v149, v149
	v_rcp_f32_e32 v150, v150
	v_rcp_f32_e32 v151, v151
	v_add_f32_e32 v152, 1.0, v152
	v_add_f32_e32 v153, 1.0, v153
	v_rcp_f32_e32 v154, v154
	v_add_f32_e32 v155, 1.0, v155
	v_rcp_f32_e32 v152, v152
	v_rcp_f32_e32 v153, v153
	v_rcp_f32_e32 v155, v155
	v_mul_f32_e32 v148, v44, v148
	v_mul_f32_e32 v149, v45, v149
	v_mul_f32_e32 v150, v46, v150
	v_mul_f32_e32 v151, v47, v151
	v_mul_f32_e32 v154, v42, v154
	v_mul_f32_e32 v152, v40, v152
	v_mul_f32_e32 v153, v41, v153
	v_mul_f32_e32 v155, v43, v155
	v_cvt_pk_bf16_f32 v148, v148, v149
	v_cvt_pk_bf16_f32 v149, v150, v151
	v_cvt_pk_bf16_f32 v150, v152, v153
	v_cvt_pk_bf16_f32 v151, v154, v155
	v_mul_f32_e32 v154, 0xbfb8aa3b, v36
	s_mov_b32 s9, 0x90000
	v_exp_f32_e32 v156, v154
	v_add_co_u32_e32 v154, vcc, s9, v140
	v_mul_f32_e32 v157, 0xbfb8aa3b, v35
	s_nop 0
	v_addc_co_u32_e32 v155, vcc, 0, v141, vcc
	global_store_dwordx4 v[154:155], v[148:151], off
	v_mul_f32_e32 v154, 0xbfb8aa3b, v32
	v_mul_f32_e32 v155, 0xbfb8aa3b, v33
	v_mul_f32_e32 v149, 0xbfb8aa3b, v37
	v_mul_f32_e32 v150, 0xbfb8aa3b, v38
	v_exp_f32_e32 v149, v149
	v_exp_f32_e32 v150, v150
	v_mul_f32_e32 v151, 0xbfb8aa3b, v39
	v_add_f32_e32 v148, 1.0, v156
	v_exp_f32_e32 v151, v151
	v_mul_f32_e32 v156, 0xbfb8aa3b, v34
	v_exp_f32_e32 v154, v154
	v_exp_f32_e32 v155, v155
	v_exp_f32_e32 v156, v156
	v_exp_f32_e32 v157, v157
	v_add_f32_e32 v149, 1.0, v149
	v_add_f32_e32 v150, 1.0, v150
	v_rcp_f32_e32 v148, v148
	v_rcp_f32_e32 v149, v149
	v_rcp_f32_e32 v150, v150
	v_add_f32_e32 v151, 1.0, v151
	v_rcp_f32_e32 v151, v151
	v_add_f32_e32 v154, 1.0, v154
	v_add_f32_e32 v155, 1.0, v155
	v_add_f32_e32 v156, 1.0, v156
	v_add_f32_e32 v157, 1.0, v157
	v_rcp_f32_e32 v154, v154
	v_rcp_f32_e32 v155, v155
	v_rcp_f32_e32 v156, v156
	v_rcp_f32_e32 v157, v157
	v_mul_f32_e32 v148, v36, v148
	v_mul_f32_e32 v149, v37, v149
	v_mul_f32_e32 v150, v38, v150
	s_mov_b64 s[18:19], 0x90000
	v_mul_f32_e32 v151, v39, v151
	v_cvt_pk_bf16_f32 v148, v148, v149
	v_cvt_pk_bf16_f32 v149, v150, v151
	v_mul_f32_e32 v150, 0xbfb8aa3b, v28
	v_lshl_add_u64 v[152:153], v[140:141], 0, s[18:19]
	v_mul_f32_e32 v154, v32, v154
	v_mul_f32_e32 v155, v33, v155
	v_mul_f32_e32 v156, v34, v156
	v_mul_f32_e32 v157, v35, v157
	v_exp_f32_e32 v158, v150
	v_cvt_pk_bf16_f32 v150, v154, v155
	v_cvt_pk_bf16_f32 v151, v156, v157
	global_store_dwordx4 v[152:153], v[148:151], off offset:256
	v_mul_f32_e32 v154, 0xbfb8aa3b, v26
	v_mul_f32_e32 v152, 0xbfb8aa3b, v24
	v_mul_f32_e32 v149, 0xbfb8aa3b, v29
	v_mul_f32_e32 v150, 0xbfb8aa3b, v30
	v_mul_f32_e32 v151, 0xbfb8aa3b, v31
	v_exp_f32_e32 v149, v149
	v_exp_f32_e32 v150, v150
	v_exp_f32_e32 v151, v151
	v_mul_f32_e32 v153, 0xbfb8aa3b, v25
	v_exp_f32_e32 v154, v154
	v_mul_f32_e32 v155, 0xbfb8aa3b, v27
	v_exp_f32_e32 v152, v152
	v_exp_f32_e32 v153, v153
	v_exp_f32_e32 v155, v155
	v_add_f32_e32 v148, 1.0, v158
	v_add_f32_e32 v149, 1.0, v149
	v_add_f32_e32 v150, 1.0, v150
	v_add_f32_e32 v151, 1.0, v151
	v_add_f32_e32 v154, 1.0, v154
	v_rcp_f32_e32 v148, v148
	v_rcp_f32_e32 v149, v149
	v_rcp_f32_e32 v150, v150
	v_rcp_f32_e32 v151, v151
	v_add_f32_e32 v152, 1.0, v152
	v_add_f32_e32 v153, 1.0, v153
	v_rcp_f32_e32 v154, v154
	v_add_f32_e32 v155, 1.0, v155
	v_rcp_f32_e32 v152, v152
	v_rcp_f32_e32 v153, v153
	v_rcp_f32_e32 v155, v155
	v_mul_f32_e32 v148, v28, v148
	v_mul_f32_e32 v149, v29, v149
	v_mul_f32_e32 v150, v30, v150
	v_mul_f32_e32 v151, v31, v151
	v_mul_f32_e32 v154, v26, v154
	v_mul_f32_e32 v152, v24, v152
	v_mul_f32_e32 v153, v25, v153
	v_mul_f32_e32 v155, v27, v155
	v_cvt_pk_bf16_f32 v148, v148, v149
	v_cvt_pk_bf16_f32 v149, v150, v151
	v_cvt_pk_bf16_f32 v150, v152, v153
	v_cvt_pk_bf16_f32 v151, v154, v155
	v_mul_f32_e32 v154, 0xbfb8aa3b, v20
	s_mov_b32 s9, 0xa0000
	v_exp_f32_e32 v156, v154
	v_add_co_u32_e32 v154, vcc, s9, v140
	v_mul_f32_e32 v157, 0xbfb8aa3b, v19
	s_nop 0
	v_addc_co_u32_e32 v155, vcc, 0, v141, vcc
	global_store_dwordx4 v[154:155], v[148:151], off
	v_mul_f32_e32 v154, 0xbfb8aa3b, v16
	v_mul_f32_e32 v155, 0xbfb8aa3b, v17
	v_mul_f32_e32 v149, 0xbfb8aa3b, v21
	v_mul_f32_e32 v150, 0xbfb8aa3b, v22
	v_exp_f32_e32 v149, v149
	v_exp_f32_e32 v150, v150
	v_mul_f32_e32 v151, 0xbfb8aa3b, v23
	v_exp_f32_e32 v151, v151
	v_add_f32_e32 v148, 1.0, v156
	v_exp_f32_e32 v154, v154
	v_exp_f32_e32 v155, v155
	v_mul_f32_e32 v156, 0xbfb8aa3b, v18
	v_exp_f32_e32 v156, v156
	v_exp_f32_e32 v157, v157
	v_add_f32_e32 v149, 1.0, v149
	v_add_f32_e32 v150, 1.0, v150
	v_rcp_f32_e32 v148, v148
	v_rcp_f32_e32 v149, v149
	v_rcp_f32_e32 v150, v150
	v_add_f32_e32 v151, 1.0, v151
	v_rcp_f32_e32 v151, v151
	v_add_f32_e32 v154, 1.0, v154
	v_add_f32_e32 v155, 1.0, v155
	v_rcp_f32_e32 v154, v154
	v_rcp_f32_e32 v155, v155
	v_add_f32_e32 v156, 1.0, v156
	v_add_f32_e32 v157, 1.0, v157
	v_rcp_f32_e32 v156, v156
	v_rcp_f32_e32 v157, v157
	v_mul_f32_e32 v148, v20, v148
	v_mul_f32_e32 v149, v21, v149
	v_mul_f32_e32 v150, v22, v150
	s_mov_b64 s[18:19], 0xa0000
	v_mul_f32_e32 v151, v23, v151
	v_cvt_pk_bf16_f32 v148, v148, v149
	v_cvt_pk_bf16_f32 v149, v150, v151
	v_mul_f32_e32 v150, 0xbfb8aa3b, v12
	v_lshl_add_u64 v[152:153], v[140:141], 0, s[18:19]
	v_mul_f32_e32 v154, v16, v154
	v_mul_f32_e32 v155, v17, v155
	v_exp_f32_e32 v158, v150
	v_cvt_pk_bf16_f32 v150, v154, v155
	v_mul_f32_e32 v156, v18, v156
	v_mul_f32_e32 v157, v19, v157
	v_cvt_pk_bf16_f32 v151, v156, v157
	global_store_dwordx4 v[152:153], v[148:151], off offset:256
	v_mul_f32_e32 v152, 0xbfb8aa3b, v8
	v_mul_f32_e32 v153, 0xbfb8aa3b, v9
	v_mul_f32_e32 v149, 0xbfb8aa3b, v13
	v_mul_f32_e32 v150, 0xbfb8aa3b, v14
	v_exp_f32_e32 v149, v149
	v_exp_f32_e32 v150, v150
	v_mul_f32_e32 v151, 0xbfb8aa3b, v15
	v_exp_f32_e32 v152, v152
	v_exp_f32_e32 v153, v153
	v_exp_f32_e32 v151, v151
	v_mul_f32_e32 v154, 0xbfb8aa3b, v10
	v_mul_f32_e32 v155, 0xbfb8aa3b, v11
	v_exp_f32_e32 v154, v154
	v_exp_f32_e32 v155, v155
	v_add_f32_e32 v148, 1.0, v158
	v_add_f32_e32 v149, 1.0, v149
	v_add_f32_e32 v150, 1.0, v150
	v_add_f32_e32 v152, 1.0, v152
	v_add_f32_e32 v153, 1.0, v153
	v_rcp_f32_e32 v148, v148
	v_rcp_f32_e32 v149, v149
	v_rcp_f32_e32 v150, v150
	v_add_f32_e32 v151, 1.0, v151
	v_rcp_f32_e32 v152, v152
	v_rcp_f32_e32 v153, v153
	v_rcp_f32_e32 v151, v151
	v_add_f32_e32 v154, 1.0, v154
	v_add_f32_e32 v155, 1.0, v155
	v_rcp_f32_e32 v154, v154
	v_rcp_f32_e32 v155, v155
	v_mul_f32_e32 v148, v12, v148
	v_mul_f32_e32 v149, v13, v149
	v_mul_f32_e32 v150, v14, v150
	v_mul_f32_e32 v152, v8, v152
	v_mul_f32_e32 v153, v9, v153
	s_mov_b64 s[18:19], 0xb0000
	s_mov_b32 s9, 0xb0000
	v_mul_f32_e32 v151, v15, v151
	v_cvt_pk_bf16_f32 v148, v148, v149
	v_cvt_pk_bf16_f32 v149, v150, v151
	v_cvt_pk_bf16_f32 v150, v152, v153
	v_lshl_add_u64 v[152:153], v[140:141], 0, s[18:19]
	v_add_co_u32_e32 v140, vcc, s9, v140
	v_mul_f32_e32 v154, v10, v154
	s_nop 0
	v_addc_co_u32_e32 v141, vcc, 0, v141, vcc
	v_mul_f32_e32 v155, v11, v155
	v_cvt_pk_bf16_f32 v151, v154, v155
	global_store_dwordx4 v[140:141], v[148:151], off
	v_mul_f32_e32 v154, 0xbfb8aa3b, v4
	v_exp_f32_e32 v154, v154
	v_mul_f32_e32 v148, 0xbfb8aa3b, v6
	v_exp_f32_e32 v148, v148
	v_mul_f32_e32 v149, 0xbfb8aa3b, v7
	v_exp_f32_e32 v149, v149
	v_mul_f32_e32 v151, 0xbfb8aa3b, v1
	v_add_f32_e32 v148, 1.0, v148
	v_rcp_f32_e32 v148, v148
	v_exp_f32_e32 v151, v151
	v_add_f32_e32 v140, 1.0, v154
	v_mul_f32_e32 v141, 0xbfb8aa3b, v5
	v_mul_f32_e32 v150, v6, v148
	v_add_f32_e32 v148, 1.0, v149
	v_mul_f32_e32 v149, 0xbfb8aa3b, v0
	v_rcp_f32_e32 v148, v148
	v_exp_f32_e32 v149, v149
	v_mul_f32_e32 v155, 0xbfb8aa3b, v3
	v_exp_f32_e32 v141, v141
	v_mul_f32_e32 v154, v7, v148
	v_add_f32_e32 v148, 1.0, v149
	v_add_f32_e32 v149, 1.0, v151
	v_mul_f32_e32 v151, 0xbfb8aa3b, v2
	v_exp_f32_e32 v151, v151
	v_exp_f32_e32 v155, v155
	v_add_f32_e32 v141, 1.0, v141
	v_rcp_f32_e32 v140, v140
	v_add_f32_e32 v151, 1.0, v151
	v_rcp_f32_e32 v151, v151
	v_add_f32_e32 v155, 1.0, v155
	v_rcp_f32_e32 v141, v141
	v_rcp_f32_e32 v148, v148
	v_rcp_f32_e32 v149, v149
	v_rcp_f32_e32 v155, v155
	v_mul_f32_e32 v151, v2, v151
	s_mov_b64 s[18:19], 0
	v_mul_f32_e32 v140, v4, v140
	v_mul_f32_e32 v141, v5, v141
	v_mul_f32_e32 v156, v0, v148
	v_mul_f32_e32 v157, v1, v149
	v_mul_f32_e32 v155, v3, v155
	v_cvt_pk_bf16_f32 v148, v140, v141
	v_cvt_pk_bf16_f32 v149, v150, v154
	v_cvt_pk_bf16_f32 v150, v156, v157
	v_cvt_pk_bf16_f32 v151, v151, v155
	global_store_dwordx4 v[152:153], v[148:151], off offset:256

.LBB0_283:
	s_add_u32 s54, s16, s29
	s_addc_u32 s55, s17, 0
	s_add_u32 s56, s18, 0x100
	v_mov_b32_e32 v0, 0
	s_addc_u32 s57, s19, 0
	s_mov_b64 s[18:19], 0
	v_mov_b32_e32 v1, v0
	v_mov_b32_e32 v2, v0
	v_mov_b32_e32 v3, v0
	v_mov_b32_e32 v4, v0
	v_mov_b32_e32 v5, v0
	v_mov_b32_e32 v6, v0
	v_mov_b32_e32 v7, v0
	v_mov_b32_e32 v16, v0
	v_mov_b32_e32 v17, v0
	v_mov_b32_e32 v18, v0
	v_mov_b32_e32 v19, v0
	v_mov_b32_e32 v20, v0
	v_mov_b32_e32 v21, v0
	v_mov_b32_e32 v22, v0
	v_mov_b32_e32 v23, v0
	v_mov_b32_e32 v32, v0
	v_mov_b32_e32 v33, v0
	v_mov_b32_e32 v34, v0
	v_mov_b32_e32 v35, v0
	v_mov_b32_e32 v36, v0
	v_mov_b32_e32 v37, v0
	v_mov_b32_e32 v38, v0
	v_mov_b32_e32 v39, v0
	v_mov_b32_e32 v48, v0
	v_mov_b32_e32 v49, v0
	v_mov_b32_e32 v50, v0
	v_mov_b32_e32 v51, v0
	v_mov_b32_e32 v52, v0
	v_mov_b32_e32 v53, v0
	v_mov_b32_e32 v54, v0
	v_mov_b32_e32 v55, v0
	v_mov_b32_e32 v8, v0
	v_mov_b32_e32 v9, v0
	v_mov_b32_e32 v10, v0
	v_mov_b32_e32 v11, v0
	v_mov_b32_e32 v12, v0
	v_mov_b32_e32 v13, v0
	v_mov_b32_e32 v14, v0
	v_mov_b32_e32 v15, v0
	v_mov_b32_e32 v24, v0
	v_mov_b32_e32 v25, v0
	v_mov_b32_e32 v26, v0
	v_mov_b32_e32 v27, v0
	v_mov_b32_e32 v28, v0
	v_mov_b32_e32 v29, v0
	v_mov_b32_e32 v30, v0
	v_mov_b32_e32 v31, v0
	v_mov_b32_e32 v40, v0
	v_mov_b32_e32 v41, v0
	v_mov_b32_e32 v42, v0
	v_mov_b32_e32 v43, v0
	v_mov_b32_e32 v44, v0
	v_mov_b32_e32 v45, v0
	v_mov_b32_e32 v46, v0
	v_mov_b32_e32 v47, v0
	v_mov_b32_e32 v56, v0
	v_mov_b32_e32 v57, v0
	v_mov_b32_e32 v58, v0
	v_mov_b32_e32 v59, v0
	v_mov_b32_e32 v60, v0
	v_mov_b32_e32 v61, v0
	v_mov_b32_e32 v62, v0
	v_mov_b32_e32 v63, v0
	v_mov_b32_e32 v64, v0
	v_mov_b32_e32 v65, v0
	v_mov_b32_e32 v66, v0
	v_mov_b32_e32 v67, v0
	v_mov_b32_e32 v68, v0
	v_mov_b32_e32 v69, v0
	v_mov_b32_e32 v70, v0
	v_mov_b32_e32 v71, v0
	v_mov_b32_e32 v80, v0
	v_mov_b32_e32 v81, v0
	v_mov_b32_e32 v82, v0
	v_mov_b32_e32 v83, v0
	v_mov_b32_e32 v84, v0
	v_mov_b32_e32 v85, v0
	v_mov_b32_e32 v86, v0
	v_mov_b32_e32 v87, v0
	v_mov_b32_e32 v96, v0
	v_mov_b32_e32 v97, v0
	v_mov_b32_e32 v98, v0
	v_mov_b32_e32 v99, v0
	v_mov_b32_e32 v100, v0
	v_mov_b32_e32 v101, v0
	v_mov_b32_e32 v102, v0
	v_mov_b32_e32 v103, v0
	v_mov_b32_e32 v112, v0
	v_mov_b32_e32 v113, v0
	v_mov_b32_e32 v114, v0
	v_mov_b32_e32 v115, v0
	v_mov_b32_e32 v116, v0
	v_mov_b32_e32 v117, v0
	v_mov_b32_e32 v118, v0
	v_mov_b32_e32 v119, v0
	v_mov_b32_e32 v72, v0
	v_mov_b32_e32 v73, v0
	v_mov_b32_e32 v74, v0
	v_mov_b32_e32 v75, v0
	v_mov_b32_e32 v76, v0
	v_mov_b32_e32 v77, v0
	v_mov_b32_e32 v78, v0
	v_mov_b32_e32 v79, v0
	v_mov_b32_e32 v88, v0
	v_mov_b32_e32 v89, v0
	v_mov_b32_e32 v90, v0
	v_mov_b32_e32 v91, v0
	v_mov_b32_e32 v92, v0
	v_mov_b32_e32 v93, v0
	v_mov_b32_e32 v94, v0
	v_mov_b32_e32 v95, v0
	v_mov_b32_e32 v104, v0
	v_mov_b32_e32 v105, v0
	v_mov_b32_e32 v106, v0
	v_mov_b32_e32 v107, v0
	v_mov_b32_e32 v108, v0
	v_mov_b32_e32 v109, v0
	v_mov_b32_e32 v110, v0
	v_mov_b32_e32 v111, v0
	v_mov_b32_e32 v120, v0
	v_mov_b32_e32 v121, v0
	v_mov_b32_e32 v122, v0
	v_mov_b32_e32 v123, v0
	v_mov_b32_e32 v124, v0
	v_mov_b32_e32 v125, v0
	v_mov_b32_e32 v126, v0
	v_mov_b32_e32 v127, v0
	s_mov_b64 s[78:79], 0x80
	v_add_u32_e32 v140, 0x10000, v154
	ds_read_b128 v[128:131], v140
	ds_read_b128 v[132:135], v140 offset:1024
	ds_read_b128 v[136:139], v140 offset:2048
	ds_read_b128 v[140:143], v140 offset:3072
	ds_read_b128 v[248:251], v155 offset:6144
	ds_read_b128 v[252:255], v155 offset:7168
.LBB0_284:
	s_add_u32 s20, s18, 1
	s_addc_u32 s21, s19, 0
	s_lshl_b64 s[58:59], s[20:21], s48
	s_add_u32 s20, s18, 2
	s_addc_u32 s21, s19, 0
	s_lshl_b64 s[22:23], s[20:21], s48
	s_add_u32 s19, s16, s22
	s_addc_u32 s22, s17, s23
	s_cmp_eq_u32 s49, s18
	s_cselect_b32 s23, s15, s22
	s_cselect_b32 s22, s14, s19
	s_cselect_b32 s24, s0, s56
	s_cselect_b32 s25, s1, s57
	s_add_u32 s18, s22, s4
	s_addc_u32 s19, s23, s5
	s_add_i32 s60, 0, 0x10000
	s_add_u32 s58, s54, s58
	s_addc_u32 s59, s55, s59
	v_lshl_add_u64 v[150:151], s[58:59], 0, v[144:145]
	s_add_i32 m0, s36, 0xc000
	ds_read_b128 v[156:159], v155
	ds_read_b128 v[160:163], v155 offset:1024
	ds_read_b128 v[164:167], v155 offset:2048
	ds_read_b128 v[168:171], v155 offset:3072
	ds_read_b128 v[172:175], v155 offset:4096
	ds_read_b128 v[176:179], v155 offset:5120
	global_load_lds_dwordx4 v[150:151], off
	v_lshl_add_u64 v[150:151], s[58:59], 0, v[146:147]
	s_add_i32 m0, s36, 0xe000
	s_nop 0
	global_load_lds_dwordx4 v[150:151], off
	s_waitcnt lgkmcnt(8)
	s_setprio 1
	s_waitcnt vmcnt(8)
	s_barrier
	s_waitcnt lgkmcnt(0)
	v_mfma_f32_16x16x32_bf16 v[124:127], v[128:131], v[156:159], v[124:127]
	v_mfma_f32_16x16x32_bf16 v[120:123], v[136:139], v[156:159], v[120:123]
	v_mfma_f32_16x16x32_bf16 v[108:111], v[128:131], v[164:167], v[108:111]
	v_mfma_f32_16x16x32_bf16 v[104:107], v[136:139], v[164:167], v[104:107]
	v_mfma_f32_16x16x32_bf16 v[92:95], v[128:131], v[172:175], v[92:95]
	v_mfma_f32_16x16x32_bf16 v[88:91], v[136:139], v[172:175], v[88:91]
	v_mfma_f32_16x16x32_bf16 v[76:79], v[128:131], v[248:251], v[76:79]
	v_mfma_f32_16x16x32_bf16 v[72:75], v[136:139], v[248:251], v[72:75]
	v_mfma_f32_16x16x32_bf16 v[124:127], v[132:135], v[160:163], v[124:127]
	v_mfma_f32_16x16x32_bf16 v[120:123], v[140:143], v[160:163], v[120:123]
	v_mfma_f32_16x16x32_bf16 v[108:111], v[132:135], v[168:171], v[108:111]
	v_mfma_f32_16x16x32_bf16 v[104:107], v[140:143], v[168:171], v[104:107]
	v_mfma_f32_16x16x32_bf16 v[92:95], v[132:135], v[176:179], v[92:95]
	v_mfma_f32_16x16x32_bf16 v[88:91], v[140:143], v[176:179], v[88:91]
	v_mfma_f32_16x16x32_bf16 v[76:79], v[132:135], v[252:255], v[76:79]
	v_mfma_f32_16x16x32_bf16 v[72:75], v[140:143], v[252:255], v[72:75]
	s_barrier
	s_setprio 0
	ds_read_b128 v[180:183], v155 offset:22528
	ds_read_b128 v[188:191], v155 offset:23552
	s_add_i32 s58, 0, 0x14000
	v_add_u32_e32 v150, s58, v154
	s_add_i32 s59, s60, s33
	ds_read_b128 v[192:195], v150
	ds_read_b128 v[202:205], v150 offset:1024
	ds_read_b128 v[206:209], v150 offset:2048
	ds_read_b128 v[210:213], v150 offset:3072
	v_lshl_add_u64 v[150:151], s[24:25], 0, v[184:185]
	s_mov_b32 m0, s59
	v_lshl_add_u64 v[196:197], s[24:25], 0, v[148:149]
	global_load_lds_dwordx4 v[150:151], off
	s_add_i32 m0, s59, 0x2000
	s_nop 0
	global_load_lds_dwordx4 v[196:197], off
	s_setprio 1
	s_barrier
	s_waitcnt lgkmcnt(0)
	v_mfma_f32_16x16x32_bf16 v[116:119], v[192:195], v[156:159], v[116:119]
	v_mfma_f32_16x16x32_bf16 v[112:115], v[206:209], v[156:159], v[112:115]
	v_mfma_f32_16x16x32_bf16 v[100:103], v[192:195], v[164:167], v[100:103]
	v_mfma_f32_16x16x32_bf16 v[96:99], v[206:209], v[164:167], v[96:99]
	v_mfma_f32_16x16x32_bf16 v[84:87], v[192:195], v[172:175], v[84:87]
	v_mfma_f32_16x16x32_bf16 v[80:83], v[206:209], v[172:175], v[80:83]
	v_mfma_f32_16x16x32_bf16 v[68:71], v[192:195], v[248:251], v[68:71]
	v_mfma_f32_16x16x32_bf16 v[64:67], v[206:209], v[248:251], v[64:67]
	v_mfma_f32_16x16x32_bf16 v[116:119], v[202:205], v[160:163], v[116:119]
	v_mfma_f32_16x16x32_bf16 v[112:115], v[210:213], v[160:163], v[112:115]
	v_mfma_f32_16x16x32_bf16 v[100:103], v[202:205], v[168:171], v[100:103]
	v_mfma_f32_16x16x32_bf16 v[96:99], v[210:213], v[168:171], v[96:99]
	v_mfma_f32_16x16x32_bf16 v[84:87], v[202:205], v[176:179], v[84:87]
	v_mfma_f32_16x16x32_bf16 v[80:83], v[210:213], v[176:179], v[80:83]
	v_mfma_f32_16x16x32_bf16 v[68:71], v[202:205], v[252:255], v[68:71]
	v_mfma_f32_16x16x32_bf16 v[64:67], v[210:213], v[252:255], v[64:67]
	s_barrier
	s_setprio 0
	s_mov_b32 m0, s36
	v_lshl_add_u64 v[214:215], s[22:23], 0, v[144:145]
	ds_read_b128 v[156:159], v155 offset:16384
	ds_read_b128 v[160:163], v155 offset:17408
	ds_read_b128 v[164:167], v155 offset:18432
	ds_read_b128 v[168:171], v155 offset:19456
	ds_read_b128 v[172:175], v155 offset:20480
	ds_read_b128 v[176:179], v155 offset:21504
	global_load_lds_dwordx4 v[214:215], off
	v_lshl_add_u64 v[214:215], s[22:23], 0, v[146:147]
	s_mov_b32 m0, s37
	s_nop 0
	global_load_lds_dwordx4 v[214:215], off
	s_setprio 1
	s_waitcnt vmcnt(8)
	s_barrier
	s_waitcnt lgkmcnt(0)
	v_mfma_f32_16x16x32_bf16 v[60:63], v[128:131], v[156:159], v[60:63]
	v_mfma_f32_16x16x32_bf16 v[56:59], v[136:139], v[156:159], v[56:59]
	v_mfma_f32_16x16x32_bf16 v[44:47], v[128:131], v[164:167], v[44:47]
	v_mfma_f32_16x16x32_bf16 v[40:43], v[136:139], v[164:167], v[40:43]
	v_mfma_f32_16x16x32_bf16 v[28:31], v[128:131], v[172:175], v[28:31]
	v_mfma_f32_16x16x32_bf16 v[24:27], v[136:139], v[172:175], v[24:27]
	v_mfma_f32_16x16x32_bf16 v[12:15], v[128:131], v[180:183], v[12:15]
	v_mfma_f32_16x16x32_bf16 v[8:11], v[136:139], v[180:183], v[8:11]
	v_mfma_f32_16x16x32_bf16 v[60:63], v[132:135], v[160:163], v[60:63]
	v_mfma_f32_16x16x32_bf16 v[56:59], v[140:143], v[160:163], v[56:59]
	v_mfma_f32_16x16x32_bf16 v[44:47], v[132:135], v[168:171], v[44:47]
	v_mfma_f32_16x16x32_bf16 v[40:43], v[140:143], v[168:171], v[40:43]
	v_mfma_f32_16x16x32_bf16 v[28:31], v[132:135], v[176:179], v[28:31]
	v_mfma_f32_16x16x32_bf16 v[24:27], v[140:143], v[176:179], v[24:27]
	v_mfma_f32_16x16x32_bf16 v[12:15], v[132:135], v[188:191], v[12:15]
	v_mfma_f32_16x16x32_bf16 v[8:11], v[140:143], v[188:191], v[8:11]
	s_barrier
	s_setprio 0
	v_add_u32_e32 v140, 0x18000, v154
	ds_read_b128 v[128:131], v140
	ds_read_b128 v[132:135], v140 offset:1024
	ds_read_b128 v[136:139], v140 offset:2048
	ds_read_b128 v[140:143], v140 offset:3072
	ds_read_b128 v[248:251], v155 offset:38912
	ds_read_b128 v[252:255], v155 offset:39936
	s_add_u32 s24, s24, s28
	s_addc_u32 s25, s25, 0
	s_add_i32 s58, s58, s33
	v_lshl_add_u64 v[214:215], s[24:25], 0, v[184:185]
	s_mov_b32 m0, s58
	v_lshl_add_u64 v[216:217], s[24:25], 0, v[148:149]
	global_load_lds_dwordx4 v[214:215], off
	s_add_i32 m0, s58, 0x2000
	s_nop 0
	global_load_lds_dwordx4 v[216:217], off
	s_waitcnt vmcnt(6)
	s_setprio 1
	s_barrier
	v_mfma_f32_16x16x32_bf16 v[52:55], v[192:195], v[156:159], v[52:55]
	v_mfma_f32_16x16x32_bf16 v[48:51], v[206:209], v[156:159], v[48:51]
	v_mfma_f32_16x16x32_bf16 v[36:39], v[192:195], v[164:167], v[36:39]
	v_mfma_f32_16x16x32_bf16 v[32:35], v[206:209], v[164:167], v[32:35]
	v_mfma_f32_16x16x32_bf16 v[20:23], v[192:195], v[172:175], v[20:23]
	v_mfma_f32_16x16x32_bf16 v[16:19], v[206:209], v[172:175], v[16:19]
	v_mfma_f32_16x16x32_bf16 v[4:7], v[192:195], v[180:183], v[4:7]
	v_mfma_f32_16x16x32_bf16 v[0:3], v[206:209], v[180:183], v[0:3]
	v_mfma_f32_16x16x32_bf16 v[52:55], v[202:205], v[160:163], v[52:55]
	v_mfma_f32_16x16x32_bf16 v[48:51], v[210:213], v[160:163], v[48:51]
	v_mfma_f32_16x16x32_bf16 v[36:39], v[202:205], v[168:171], v[36:39]
	v_mfma_f32_16x16x32_bf16 v[32:35], v[210:213], v[168:171], v[32:35]
	v_mfma_f32_16x16x32_bf16 v[20:23], v[202:205], v[176:179], v[20:23]
	v_mfma_f32_16x16x32_bf16 v[16:19], v[210:213], v[176:179], v[16:19]
	v_mfma_f32_16x16x32_bf16 v[4:7], v[202:205], v[188:191], v[4:7]
	v_mfma_f32_16x16x32_bf16 v[0:3], v[210:213], v[188:191], v[0:3]
	s_barrier
	s_setprio 0
	s_add_i32 s24, 0, 0x18000
	s_add_u32 s22, s22, s29
	s_addc_u32 s23, s23, 0
	s_mov_b32 m0, s38
	v_lshl_add_u64 v[192:193], s[22:23], 0, v[144:145]
	ds_read_b128 v[156:159], v155 offset:32768
	ds_read_b128 v[160:163], v155 offset:33792
	ds_read_b128 v[164:167], v155 offset:34816
	ds_read_b128 v[168:171], v155 offset:35840
	ds_read_b128 v[172:175], v155 offset:36864
	ds_read_b128 v[176:179], v155 offset:37888
	global_load_lds_dwordx4 v[192:193], off
	v_lshl_add_u64 v[192:193], s[22:23], 0, v[146:147]
	s_mov_b32 m0, s39
	s_nop 0
	global_load_lds_dwordx4 v[192:193], off
	s_waitcnt lgkmcnt(8)
	s_setprio 1
	s_waitcnt vmcnt(8)
	s_barrier
	s_waitcnt lgkmcnt(0)
	v_mfma_f32_16x16x32_bf16 v[124:127], v[128:131], v[156:159], v[124:127]
	v_mfma_f32_16x16x32_bf16 v[120:123], v[136:139], v[156:159], v[120:123]
	v_mfma_f32_16x16x32_bf16 v[108:111], v[128:131], v[164:167], v[108:111]
	v_mfma_f32_16x16x32_bf16 v[104:107], v[136:139], v[164:167], v[104:107]
	v_mfma_f32_16x16x32_bf16 v[92:95], v[128:131], v[172:175], v[92:95]
	v_mfma_f32_16x16x32_bf16 v[88:91], v[136:139], v[172:175], v[88:91]
	v_mfma_f32_16x16x32_bf16 v[76:79], v[128:131], v[248:251], v[76:79]
	v_mfma_f32_16x16x32_bf16 v[72:75], v[136:139], v[248:251], v[72:75]
	v_mfma_f32_16x16x32_bf16 v[124:127], v[132:135], v[160:163], v[124:127]
	v_mfma_f32_16x16x32_bf16 v[120:123], v[140:143], v[160:163], v[120:123]
	v_mfma_f32_16x16x32_bf16 v[108:111], v[132:135], v[168:171], v[108:111]
	v_mfma_f32_16x16x32_bf16 v[104:107], v[140:143], v[168:171], v[104:107]
	v_mfma_f32_16x16x32_bf16 v[92:95], v[132:135], v[176:179], v[92:95]
	v_mfma_f32_16x16x32_bf16 v[88:91], v[140:143], v[176:179], v[88:91]
	v_mfma_f32_16x16x32_bf16 v[76:79], v[132:135], v[252:255], v[76:79]
	v_mfma_f32_16x16x32_bf16 v[72:75], v[140:143], v[252:255], v[72:75]
	s_barrier
	s_setprio 0
	ds_read_b128 v[180:183], v155 offset:55296
	ds_read_b128 v[188:191], v155 offset:56320
	s_add_i32 s22, 0, 0x1c000
	s_add_i32 s23, s24, s33
	v_add_u32_e32 v187, s22, v154
	v_lshl_add_u64 v[150:151], v[150:151], 0, s[78:79]
	s_mov_b32 m0, s23
	ds_read_b128 v[192:195], v187
	ds_read_b128 v[202:205], v187 offset:1024
	ds_read_b128 v[206:209], v187 offset:2048
	ds_read_b128 v[210:213], v187 offset:3072
	global_load_lds_dwordx4 v[150:151], off
	v_lshl_add_u64 v[150:151], v[196:197], 0, s[78:79]
	s_add_i32 m0, s23, 0x2000
	s_nop 0
	global_load_lds_dwordx4 v[150:151], off
	s_setprio 1
	s_barrier
	s_waitcnt lgkmcnt(0)
	v_mfma_f32_16x16x32_bf16 v[116:119], v[192:195], v[156:159], v[116:119]
	v_mfma_f32_16x16x32_bf16 v[112:115], v[206:209], v[156:159], v[112:115]
	v_mfma_f32_16x16x32_bf16 v[100:103], v[192:195], v[164:167], v[100:103]
	v_mfma_f32_16x16x32_bf16 v[96:99], v[206:209], v[164:167], v[96:99]
	v_mfma_f32_16x16x32_bf16 v[84:87], v[192:195], v[172:175], v[84:87]
	v_mfma_f32_16x16x32_bf16 v[80:83], v[206:209], v[172:175], v[80:83]
	v_mfma_f32_16x16x32_bf16 v[68:71], v[192:195], v[248:251], v[68:71]
	v_mfma_f32_16x16x32_bf16 v[64:67], v[206:209], v[248:251], v[64:67]
	v_mfma_f32_16x16x32_bf16 v[116:119], v[202:205], v[160:163], v[116:119]
	v_mfma_f32_16x16x32_bf16 v[112:115], v[210:213], v[160:163], v[112:115]
	v_mfma_f32_16x16x32_bf16 v[100:103], v[202:205], v[168:171], v[100:103]
	v_mfma_f32_16x16x32_bf16 v[96:99], v[210:213], v[168:171], v[96:99]
	v_mfma_f32_16x16x32_bf16 v[84:87], v[202:205], v[176:179], v[84:87]
	v_mfma_f32_16x16x32_bf16 v[80:83], v[210:213], v[176:179], v[80:83]
	v_mfma_f32_16x16x32_bf16 v[68:71], v[202:205], v[252:255], v[68:71]
	v_mfma_f32_16x16x32_bf16 v[64:67], v[210:213], v[252:255], v[64:67]
	s_barrier
	s_setprio 0
	s_mov_b32 m0, s46
	v_lshl_add_u64 v[150:151], s[18:19], 0, v[144:145]
	ds_read_b128 v[156:159], v155 offset:49152
	ds_read_b128 v[160:163], v155 offset:50176
	ds_read_b128 v[164:167], v155 offset:51200
	ds_read_b128 v[168:171], v155 offset:52224
	ds_read_b128 v[172:175], v155 offset:53248
	ds_read_b128 v[176:179], v155 offset:54272
	global_load_lds_dwordx4 v[150:151], off
	v_lshl_add_u64 v[150:151], s[18:19], 0, v[146:147]
	s_mov_b32 m0, s47
	s_nop 0
	global_load_lds_dwordx4 v[150:151], off
	s_setprio 1
	s_waitcnt vmcnt(8)
	s_barrier
	s_waitcnt lgkmcnt(0)
	v_mfma_f32_16x16x32_bf16 v[60:63], v[128:131], v[156:159], v[60:63]
	v_mfma_f32_16x16x32_bf16 v[56:59], v[136:139], v[156:159], v[56:59]
	v_mfma_f32_16x16x32_bf16 v[44:47], v[128:131], v[164:167], v[44:47]
	v_mfma_f32_16x16x32_bf16 v[40:43], v[136:139], v[164:167], v[40:43]
	v_mfma_f32_16x16x32_bf16 v[28:31], v[128:131], v[172:175], v[28:31]
	v_mfma_f32_16x16x32_bf16 v[24:27], v[136:139], v[172:175], v[24:27]
	v_mfma_f32_16x16x32_bf16 v[12:15], v[128:131], v[180:183], v[12:15]
	v_mfma_f32_16x16x32_bf16 v[8:11], v[136:139], v[180:183], v[8:11]
	v_mfma_f32_16x16x32_bf16 v[60:63], v[132:135], v[160:163], v[60:63]
	v_mfma_f32_16x16x32_bf16 v[56:59], v[140:143], v[160:163], v[56:59]
	v_mfma_f32_16x16x32_bf16 v[44:47], v[132:135], v[168:171], v[44:47]
	v_mfma_f32_16x16x32_bf16 v[40:43], v[140:143], v[168:171], v[40:43]
	v_mfma_f32_16x16x32_bf16 v[28:31], v[132:135], v[176:179], v[28:31]
	v_mfma_f32_16x16x32_bf16 v[24:27], v[140:143], v[176:179], v[24:27]
	v_mfma_f32_16x16x32_bf16 v[12:15], v[132:135], v[188:191], v[12:15]
	v_mfma_f32_16x16x32_bf16 v[8:11], v[140:143], v[188:191], v[8:11]
	s_barrier
	s_setprio 0
	v_add_u32_e32 v140, 0x10000, v154
	ds_read_b128 v[128:131], v140
	ds_read_b128 v[132:135], v140 offset:1024
	ds_read_b128 v[136:139], v140 offset:2048
	ds_read_b128 v[140:143], v140 offset:3072
	ds_read_b128 v[248:251], v155 offset:6144
	ds_read_b128 v[252:255], v155 offset:7168
	s_add_i32 s18, s22, s33
	v_lshl_add_u64 v[246:247], v[214:215], 0, s[78:79]
	s_mov_b32 m0, s18
	s_nop 0
	global_load_lds_dwordx4 v[246:247], off
	v_lshl_add_u64 v[246:247], v[216:217], 0, s[78:79]
	s_add_i32 m0, s18, 0x2000
	s_nop 0
	global_load_lds_dwordx4 v[246:247], off
	s_waitcnt vmcnt(6)
	s_setprio 1
	s_barrier
	v_mfma_f32_16x16x32_bf16 v[52:55], v[192:195], v[156:159], v[52:55]
	v_mfma_f32_16x16x32_bf16 v[48:51], v[206:209], v[156:159], v[48:51]
	v_mfma_f32_16x16x32_bf16 v[36:39], v[192:195], v[164:167], v[36:39]
	v_mfma_f32_16x16x32_bf16 v[32:35], v[206:209], v[164:167], v[32:35]
	v_mfma_f32_16x16x32_bf16 v[20:23], v[192:195], v[172:175], v[20:23]
	v_mfma_f32_16x16x32_bf16 v[16:19], v[206:209], v[172:175], v[16:19]
	v_mfma_f32_16x16x32_bf16 v[4:7], v[192:195], v[180:183], v[4:7]
	v_mfma_f32_16x16x32_bf16 v[0:3], v[206:209], v[180:183], v[0:3]
	v_mfma_f32_16x16x32_bf16 v[52:55], v[202:205], v[160:163], v[52:55]
	v_mfma_f32_16x16x32_bf16 v[48:51], v[210:213], v[160:163], v[48:51]
	v_mfma_f32_16x16x32_bf16 v[36:39], v[202:205], v[168:171], v[36:39]
	v_mfma_f32_16x16x32_bf16 v[32:35], v[210:213], v[168:171], v[32:35]
	v_mfma_f32_16x16x32_bf16 v[20:23], v[202:205], v[176:179], v[20:23]
	v_mfma_f32_16x16x32_bf16 v[16:19], v[210:213], v[176:179], v[16:19]
	v_mfma_f32_16x16x32_bf16 v[4:7], v[202:205], v[188:191], v[4:7]
	v_mfma_f32_16x16x32_bf16 v[0:3], v[210:213], v[188:191], v[0:3]
	s_barrier
	s_setprio 0
	s_add_u32 s56, s56, 0x100
	s_addc_u32 s57, s57, 0
	s_cmp_ge_u32 s20, s40
	s_mov_b64 s[18:19], s[20:21]
	s_cbranch_scc0 .LBB0_284
	s_waitcnt lgkmcnt(0)
	s_lshl_b32 s16, s52, 8
	s_add_i32 s18, s16, s41
	s_lshl_b32 s16, s53, 8
	v_mov_b32_e32 v156, v153
	v_mov_b32_e32 v128, v152
	s_or_b32 s16, s16, s42
	s_mov_b32 s53, s51
	v_lshl_add_u32 v150, v128, 2, s16
	s_ashr_i32 s16, s52, 5
	s_mul_hi_i32 s17, s16, 0x6000
	s_mulk_i32 s16, 0x6000
	v_add_u32_e32 v156, s18, v156
	s_add_u32 s16, s44, s16
	v_ashrrev_i32_e32 v157, 31, v156
	s_addc_u32 s17, s45, s17
	v_ashrrev_i32_e32 v151, 31, v150
	v_lshlrev_b64 v[156:157], 11, v[156:157]
	v_lshl_add_u64 v[128:129], v[150:151], 2, s[16:17]
	v_lshl_add_u64 v[150:151], v[156:157], 0, v[150:151]
	v_lshlrev_b64 v[150:151], 2, v[150:151]
	global_load_dwordx4 v[140:143], v[128:129], off
	global_load_dwordx4 v[136:139], v[128:129], off offset:64
	global_load_dwordx4 v[132:135], v[128:129], off offset:512
	s_nop 0
	global_load_dwordx4 v[128:131], v[128:129], off offset:576
	v_readlane_b32 s18, v244, 20
	v_readlane_b32 s19, v244, 21
	s_and_b64 vcc, exec, s[12:13]
	s_mov_b32 s52, s50
	s_add_u32 s16, s8, 0x0
	s_addc_u32 s17, s9, 0
	global_load_dwordx4 v[156:159], v150, s[16:17]
	global_load_dwordx4 v[160:163], v150, s[16:17] offset:64
	global_load_dwordx4 v[164:167], v150, s[16:17] offset:512
	global_load_dwordx4 v[168:171], v150, s[16:17] offset:576
	s_add_u32 s16, s8, 0x20000
	s_addc_u32 s17, s9, 0
	global_load_dwordx4 v[172:175], v150, s[16:17]
	global_load_dwordx4 v[176:179], v150, s[16:17] offset:64
	global_load_dwordx4 v[180:183], v150, s[16:17] offset:512
	global_load_dwordx4 v[188:191], v150, s[16:17] offset:576
	s_add_u32 s16, s8, 0x40000
	s_addc_u32 s17, s9, 0
	global_load_dwordx4 v[192:195], v150, s[16:17]
	global_load_dwordx4 v[202:205], v150, s[16:17] offset:64
	global_load_dwordx4 v[206:209], v150, s[16:17] offset:512
	global_load_dwordx4 v[210:213], v150, s[16:17] offset:576
	s_waitcnt vmcnt(8)
	v_pk_fma_f32 v[158:159], v[126:127], v[142:143], v[158:159]
	v_pk_fma_f32 v[156:157], v[124:125], v[140:141], v[156:157]
	v_pk_fma_f32 v[162:163], v[122:123], v[138:139], v[162:163]
	v_pk_fma_f32 v[160:161], v[120:121], v[136:137], v[160:161]
	v_pk_fma_f32 v[166:167], v[118:119], v[134:135], v[166:167]
	v_pk_fma_f32 v[164:165], v[116:117], v[132:133], v[164:165]
	v_pk_fma_f32 v[170:171], v[114:115], v[130:131], v[170:171]
	v_pk_fma_f32 v[168:169], v[112:113], v[128:129], v[168:169]
	s_add_u32 s16, s18, 0x0
	s_addc_u32 s17, s19, 0
	global_store_dwordx4 v150, v[156:159], s[16:17]
	global_store_dwordx4 v150, v[160:163], s[16:17] offset:64
	global_store_dwordx4 v150, v[164:167], s[16:17] offset:512
	global_store_dwordx4 v150, v[168:171], s[16:17] offset:576
	s_add_u32 s16, s8, 0x60000
	s_addc_u32 s17, s9, 0
	global_load_dwordx4 v[124:127], v150, s[16:17]
	global_load_dwordx4 v[120:123], v150, s[16:17] offset:64
	global_load_dwordx4 v[116:119], v150, s[16:17] offset:512
	global_load_dwordx4 v[112:115], v150, s[16:17] offset:576
	s_waitcnt vmcnt(12)
	v_pk_fma_f32 v[174:175], v[110:111], v[142:143], v[174:175]
	v_pk_fma_f32 v[172:173], v[108:109], v[140:141], v[172:173]
	v_pk_fma_f32 v[178:179], v[106:107], v[138:139], v[178:179]
	v_pk_fma_f32 v[176:177], v[104:105], v[136:137], v[176:177]
	v_pk_fma_f32 v[182:183], v[102:103], v[134:135], v[182:183]
	v_pk_fma_f32 v[180:181], v[100:101], v[132:133], v[180:181]
	v_pk_fma_f32 v[190:191], v[98:99], v[130:131], v[190:191]
	v_pk_fma_f32 v[188:189], v[96:97], v[128:129], v[188:189]
	s_add_u32 s16, s18, 0x20000
	s_addc_u32 s17, s19, 0
	global_store_dwordx4 v150, v[172:175], s[16:17]
	global_store_dwordx4 v150, v[176:179], s[16:17] offset:64
	global_store_dwordx4 v150, v[180:183], s[16:17] offset:512
	global_store_dwordx4 v150, v[188:191], s[16:17] offset:576
	s_add_u32 s16, s8, 0x100000
	s_addc_u32 s17, s9, 0
	global_load_dwordx4 v[108:111], v150, s[16:17]
	global_load_dwordx4 v[104:107], v150, s[16:17] offset:64
	global_load_dwordx4 v[100:103], v150, s[16:17] offset:512
	global_load_dwordx4 v[96:99], v150, s[16:17] offset:576
	s_waitcnt vmcnt(16)
	v_pk_fma_f32 v[194:195], v[94:95], v[142:143], v[194:195]
	v_pk_fma_f32 v[192:193], v[92:93], v[140:141], v[192:193]
	v_pk_fma_f32 v[204:205], v[90:91], v[138:139], v[204:205]
	v_pk_fma_f32 v[202:203], v[88:89], v[136:137], v[202:203]
	v_pk_fma_f32 v[208:209], v[86:87], v[134:135], v[208:209]
	v_pk_fma_f32 v[206:207], v[84:85], v[132:133], v[206:207]
	v_pk_fma_f32 v[212:213], v[82:83], v[130:131], v[212:213]
	v_pk_fma_f32 v[210:211], v[80:81], v[128:129], v[210:211]
	s_add_u32 s16, s18, 0x40000
	s_addc_u32 s17, s19, 0
	global_store_dwordx4 v150, v[192:195], s[16:17]
	global_store_dwordx4 v150, v[202:205], s[16:17] offset:64
	global_store_dwordx4 v150, v[206:209], s[16:17] offset:512
	global_store_dwordx4 v150, v[210:213], s[16:17] offset:576
	s_add_u32 s16, s8, 0x120000
	s_addc_u32 s17, s9, 0
	global_load_dwordx4 v[92:95], v150, s[16:17]
	global_load_dwordx4 v[88:91], v150, s[16:17] offset:64
	global_load_dwordx4 v[84:87], v150, s[16:17] offset:512
	global_load_dwordx4 v[80:83], v150, s[16:17] offset:576
	s_waitcnt vmcnt(16)
	v_pk_fma_f32 v[126:127], v[78:79], v[142:143], v[126:127]
	v_pk_fma_f32 v[124:125], v[76:77], v[140:141], v[124:125]
	v_pk_fma_f32 v[122:123], v[74:75], v[138:139], v[122:123]
	v_pk_fma_f32 v[120:121], v[72:73], v[136:137], v[120:121]
	v_pk_fma_f32 v[118:119], v[70:71], v[134:135], v[118:119]
	v_pk_fma_f32 v[116:117], v[68:69], v[132:133], v[116:117]
	v_pk_fma_f32 v[114:115], v[66:67], v[130:131], v[114:115]
	v_pk_fma_f32 v[112:113], v[64:65], v[128:129], v[112:113]
	s_add_u32 s16, s18, 0x60000
	s_addc_u32 s17, s19, 0
	global_store_dwordx4 v150, v[124:127], s[16:17]
	global_store_dwordx4 v150, v[120:123], s[16:17] offset:64
	global_store_dwordx4 v150, v[116:119], s[16:17] offset:512
	global_store_dwordx4 v150, v[112:115], s[16:17] offset:576
	s_add_u32 s16, s8, 0x140000
	s_addc_u32 s17, s9, 0
	global_load_dwordx4 v[76:79], v150, s[16:17]
	global_load_dwordx4 v[72:75], v150, s[16:17] offset:64
	global_load_dwordx4 v[68:71], v150, s[16:17] offset:512
	global_load_dwordx4 v[64:67], v150, s[16:17] offset:576
	s_waitcnt vmcnt(16)
	v_pk_fma_f32 v[110:111], v[62:63], v[142:143], v[110:111]
	v_pk_fma_f32 v[108:109], v[60:61], v[140:141], v[108:109]
	v_pk_fma_f32 v[106:107], v[58:59], v[138:139], v[106:107]
	v_pk_fma_f32 v[104:105], v[56:57], v[136:137], v[104:105]
	v_pk_fma_f32 v[102:103], v[54:55], v[134:135], v[102:103]
	v_pk_fma_f32 v[100:101], v[52:53], v[132:133], v[100:101]
	v_pk_fma_f32 v[98:99], v[50:51], v[130:131], v[98:99]
	v_pk_fma_f32 v[96:97], v[48:49], v[128:129], v[96:97]
	s_add_u32 s16, s18, 0x100000
	s_addc_u32 s17, s19, 0
	global_store_dwordx4 v150, v[108:111], s[16:17]
	global_store_dwordx4 v150, v[104:107], s[16:17] offset:64
	global_store_dwordx4 v150, v[100:103], s[16:17] offset:512
	global_store_dwordx4 v150, v[96:99], s[16:17] offset:576
	s_add_u32 s16, s8, 0x160000
	s_addc_u32 s17, s9, 0
	global_load_dwordx4 v[60:63], v150, s[16:17]
	global_load_dwordx4 v[56:59], v150, s[16:17] offset:64
	global_load_dwordx4 v[52:55], v150, s[16:17] offset:512
	global_load_dwordx4 v[48:51], v150, s[16:17] offset:576
	s_waitcnt vmcnt(16)
	v_pk_fma_f32 v[94:95], v[46:47], v[142:143], v[94:95]
	v_pk_fma_f32 v[92:93], v[44:45], v[140:141], v[92:93]
	v_pk_fma_f32 v[90:91], v[42:43], v[138:139], v[90:91]
	v_pk_fma_f32 v[88:89], v[40:41], v[136:137], v[88:89]
	v_pk_fma_f32 v[86:87], v[38:39], v[134:135], v[86:87]
	v_pk_fma_f32 v[84:85], v[36:37], v[132:133], v[84:85]
	v_pk_fma_f32 v[82:83], v[34:35], v[130:131], v[82:83]
	v_pk_fma_f32 v[80:81], v[32:33], v[128:129], v[80:81]
	s_add_u32 s16, s18, 0x120000
	s_addc_u32 s17, s19, 0
	global_store_dwordx4 v150, v[92:95], s[16:17]
	global_store_dwordx4 v150, v[88:91], s[16:17] offset:64
	global_store_dwordx4 v150, v[84:87], s[16:17] offset:512
	global_store_dwordx4 v150, v[80:83], s[16:17] offset:576
	s_waitcnt vmcnt(12)
	v_pk_fma_f32 v[78:79], v[30:31], v[142:143], v[78:79]
	v_pk_fma_f32 v[76:77], v[28:29], v[140:141], v[76:77]
	v_pk_fma_f32 v[74:75], v[26:27], v[138:139], v[74:75]
	v_pk_fma_f32 v[72:73], v[24:25], v[136:137], v[72:73]
	v_pk_fma_f32 v[70:71], v[22:23], v[134:135], v[70:71]
	v_pk_fma_f32 v[68:69], v[20:21], v[132:133], v[68:69]
	v_pk_fma_f32 v[66:67], v[18:19], v[130:131], v[66:67]
	v_pk_fma_f32 v[64:65], v[16:17], v[128:129], v[64:65]
	s_add_u32 s16, s18, 0x140000
	s_addc_u32 s17, s19, 0
	global_store_dwordx4 v150, v[76:79], s[16:17]
	global_store_dwordx4 v150, v[72:75], s[16:17] offset:64
	global_store_dwordx4 v150, v[68:71], s[16:17] offset:512
	global_store_dwordx4 v150, v[64:67], s[16:17] offset:576
	s_waitcnt vmcnt(8)
	v_pk_fma_f32 v[62:63], v[14:15], v[142:143], v[62:63]
	v_pk_fma_f32 v[60:61], v[12:13], v[140:141], v[60:61]
	v_pk_fma_f32 v[58:59], v[10:11], v[138:139], v[58:59]
	v_pk_fma_f32 v[56:57], v[8:9], v[136:137], v[56:57]
	v_pk_fma_f32 v[54:55], v[6:7], v[134:135], v[54:55]
	v_pk_fma_f32 v[52:53], v[4:5], v[132:133], v[52:53]
	v_pk_fma_f32 v[50:51], v[2:3], v[130:131], v[50:51]
	v_pk_fma_f32 v[48:49], v[0:1], v[128:129], v[48:49]
	s_add_u32 s16, s18, 0x160000
	s_addc_u32 s17, s19, 0
	global_store_dwordx4 v150, v[60:63], s[16:17]
	global_store_dwordx4 v150, v[56:59], s[16:17] offset:64
	global_store_dwordx4 v150, v[52:55], s[16:17] offset:512
	global_store_dwordx4 v150, v[48:51], s[16:17] offset:576
	s_mov_b64 s[16:17], s[14:15]
	s_mov_b64 s[18:19], s[0:1]
	s_cbranch_vccz .LBB0_273
	s_waitcnt vmcnt(0)
	s_cmpk_gt_u32 s27, 0xff
	s_cbranch_scc1 .LBB0_288
	s_barrier

.LBB0_313:
	s_ashr_i32 s5, s4, 31
	s_lshl_b64 s[12:13], s[4:5], 20
	s_add_u32 s12, s27, s12
	s_addc_u32 s13, s28, s13
	s_and_b64 s[14:15], s[22:23], exec
	s_cselect_b32 s5, s13, s19
	s_cselect_b32 s42, s12, s18
	s_ashr_i32 s9, s8, 31
	s_lshl_b64 s[14:15], s[8:9], 20
	s_add_u32 s14, s24, s14
	s_addc_u32 s15, s25, s15
	s_and_b64 s[22:23], s[22:23], exec
	s_cselect_b32 s9, s15, s21
	s_cselect_b32 s43, s14, s20
	s_add_u32 s18, s18, 0x80080
	s_addc_u32 s19, s19, 0
	s_add_u32 s44, s20, 0x100
	v_mov_b32_e32 v0, 0
	s_addc_u32 s45, s21, 0
	s_mov_b32 s46, -2
	v_mov_b32_e32 v1, v0
	v_mov_b32_e32 v2, v0
	v_mov_b32_e32 v3, v0
	v_mov_b32_e32 v8, v0
	v_mov_b32_e32 v9, v0
	v_mov_b32_e32 v10, v0
	v_mov_b32_e32 v11, v0
	v_mov_b32_e32 v16, v0
	v_mov_b32_e32 v17, v0
	v_mov_b32_e32 v18, v0
	v_mov_b32_e32 v19, v0
	v_mov_b32_e32 v24, v0
	v_mov_b32_e32 v25, v0
	v_mov_b32_e32 v26, v0
	v_mov_b32_e32 v27, v0
	v_mov_b32_e32 v32, v0
	v_mov_b32_e32 v33, v0
	v_mov_b32_e32 v34, v0
	v_mov_b32_e32 v35, v0
	v_mov_b32_e32 v40, v0
	v_mov_b32_e32 v41, v0
	v_mov_b32_e32 v42, v0
	v_mov_b32_e32 v43, v0
	v_mov_b32_e32 v48, v0
	v_mov_b32_e32 v49, v0
	v_mov_b32_e32 v50, v0
	v_mov_b32_e32 v51, v0
	v_mov_b32_e32 v56, v0
	v_mov_b32_e32 v57, v0
	v_mov_b32_e32 v58, v0
	v_mov_b32_e32 v59, v0
	v_mov_b32_e32 v4, v0
	v_mov_b32_e32 v5, v0
	v_mov_b32_e32 v6, v0
	v_mov_b32_e32 v7, v0
	v_mov_b32_e32 v12, v0
	v_mov_b32_e32 v13, v0
	v_mov_b32_e32 v14, v0
	v_mov_b32_e32 v15, v0
	v_mov_b32_e32 v20, v0
	v_mov_b32_e32 v21, v0
	v_mov_b32_e32 v22, v0
	v_mov_b32_e32 v23, v0
	v_mov_b32_e32 v28, v0
	v_mov_b32_e32 v29, v0
	v_mov_b32_e32 v30, v0
	v_mov_b32_e32 v31, v0
	v_mov_b32_e32 v36, v0
	v_mov_b32_e32 v37, v0
	v_mov_b32_e32 v38, v0
	v_mov_b32_e32 v39, v0
	v_mov_b32_e32 v44, v0
	v_mov_b32_e32 v45, v0
	v_mov_b32_e32 v46, v0
	v_mov_b32_e32 v47, v0
	v_mov_b32_e32 v52, v0
	v_mov_b32_e32 v53, v0
	v_mov_b32_e32 v54, v0
	v_mov_b32_e32 v55, v0
	v_mov_b32_e32 v60, v0
	v_mov_b32_e32 v61, v0
	v_mov_b32_e32 v62, v0
	v_mov_b32_e32 v63, v0
	v_mov_b32_e32 v64, v0
	v_mov_b32_e32 v65, v0
	v_mov_b32_e32 v66, v0
	v_mov_b32_e32 v67, v0
	v_mov_b32_e32 v72, v0
	v_mov_b32_e32 v73, v0
	v_mov_b32_e32 v74, v0
	v_mov_b32_e32 v75, v0
	v_mov_b32_e32 v80, v0
	v_mov_b32_e32 v81, v0
	v_mov_b32_e32 v82, v0
	v_mov_b32_e32 v83, v0
	v_mov_b32_e32 v88, v0
	v_mov_b32_e32 v89, v0
	v_mov_b32_e32 v90, v0
	v_mov_b32_e32 v91, v0
	v_mov_b32_e32 v96, v0
	v_mov_b32_e32 v97, v0
	v_mov_b32_e32 v98, v0
	v_mov_b32_e32 v99, v0
	v_mov_b32_e32 v104, v0
	v_mov_b32_e32 v105, v0
	v_mov_b32_e32 v106, v0
	v_mov_b32_e32 v107, v0
	v_mov_b32_e32 v112, v0
	v_mov_b32_e32 v113, v0
	v_mov_b32_e32 v114, v0
	v_mov_b32_e32 v115, v0
	v_mov_b32_e32 v120, v0
	v_mov_b32_e32 v121, v0
	v_mov_b32_e32 v122, v0
	v_mov_b32_e32 v123, v0
	v_mov_b32_e32 v68, v0
	v_mov_b32_e32 v69, v0
	v_mov_b32_e32 v70, v0
	v_mov_b32_e32 v71, v0
	v_mov_b32_e32 v76, v0
	v_mov_b32_e32 v77, v0
	v_mov_b32_e32 v78, v0
	v_mov_b32_e32 v79, v0
	v_mov_b32_e32 v84, v0
	v_mov_b32_e32 v85, v0
	v_mov_b32_e32 v86, v0
	v_mov_b32_e32 v87, v0
	v_mov_b32_e32 v92, v0
	v_mov_b32_e32 v93, v0
	v_mov_b32_e32 v94, v0
	v_mov_b32_e32 v95, v0
	v_mov_b32_e32 v100, v0
	v_mov_b32_e32 v101, v0
	v_mov_b32_e32 v102, v0
	v_mov_b32_e32 v103, v0
	v_mov_b32_e32 v108, v0
	v_mov_b32_e32 v109, v0
	v_mov_b32_e32 v110, v0
	v_mov_b32_e32 v111, v0
	v_mov_b32_e32 v116, v0
	v_mov_b32_e32 v117, v0
	v_mov_b32_e32 v118, v0
	v_mov_b32_e32 v119, v0
	v_mov_b32_e32 v124, v0
	v_mov_b32_e32 v125, v0
	v_mov_b32_e32 v126, v0
	v_mov_b32_e32 v127, v0
	s_mov_b64 s[52:53], 0x80
	v_add_u32_e32 v156, 0x10000, v142
	ds_read_b128 v[144:147], v156
	ds_read_b128 v[148:151], v156 offset:1024
	ds_read_b128 v[152:155], v156 offset:2048
	ds_read_b128 v[156:159], v156 offset:3072
	ds_read_b128 v[248:251], v143 offset:6144
	ds_read_b128 v[252:255], v143 offset:7168
.LBB0_314:
	s_add_u32 s20, s18, 0xfff80080
	s_addc_u32 s21, s19, -1
	s_add_i32 s47, 0, 0x10000
	s_cmp_eq_u32 s46, 28
	s_cselect_b32 s23, s5, s21
	s_cselect_b32 s22, s42, s20
	s_cselect_b32 s21, s9, s45
	s_cselect_b32 s20, s43, s44
	v_lshl_add_u64 v[196:197], s[18:19], 0, v[136:137]
	s_add_i32 m0, s17, 0xc000
	ds_read_b128 v[160:163], v143
	ds_read_b128 v[164:167], v143 offset:1024
	ds_read_b128 v[168:171], v143 offset:2048
	ds_read_b128 v[172:175], v143 offset:3072
	ds_read_b128 v[176:179], v143 offset:4096
	ds_read_b128 v[180:183], v143 offset:5120
	global_load_lds_dwordx4 v[196:197], off
	v_lshl_add_u64 v[196:197], s[18:19], 0, v[138:139]
	s_add_i32 m0, s17, 0xe000
	s_nop 0
	global_load_lds_dwordx4 v[196:197], off
	s_waitcnt lgkmcnt(8)
	s_setprio 1
	s_waitcnt vmcnt(8)
	s_barrier
	s_waitcnt lgkmcnt(0)
	v_mfma_f32_16x16x32_bf16 v[124:127], v[144:147], v[160:163], v[124:127]
	v_mfma_f32_16x16x32_bf16 v[116:119], v[152:155], v[160:163], v[116:119]
	v_mfma_f32_16x16x32_bf16 v[108:111], v[144:147], v[168:171], v[108:111]
	v_mfma_f32_16x16x32_bf16 v[100:103], v[152:155], v[168:171], v[100:103]
	v_mfma_f32_16x16x32_bf16 v[92:95], v[144:147], v[176:179], v[92:95]
	v_mfma_f32_16x16x32_bf16 v[84:87], v[152:155], v[176:179], v[84:87]
	v_mfma_f32_16x16x32_bf16 v[76:79], v[144:147], v[248:251], v[76:79]
	v_mfma_f32_16x16x32_bf16 v[68:71], v[152:155], v[248:251], v[68:71]
	v_mfma_f32_16x16x32_bf16 v[124:127], v[148:151], v[164:167], v[124:127]
	v_mfma_f32_16x16x32_bf16 v[116:119], v[156:159], v[164:167], v[116:119]
	v_mfma_f32_16x16x32_bf16 v[108:111], v[148:151], v[172:175], v[108:111]
	v_mfma_f32_16x16x32_bf16 v[100:103], v[156:159], v[172:175], v[100:103]
	v_mfma_f32_16x16x32_bf16 v[92:95], v[148:151], v[180:183], v[92:95]
	v_mfma_f32_16x16x32_bf16 v[84:87], v[156:159], v[180:183], v[84:87]
	v_mfma_f32_16x16x32_bf16 v[76:79], v[148:151], v[252:255], v[76:79]
	v_mfma_f32_16x16x32_bf16 v[68:71], v[156:159], v[252:255], v[68:71]
	s_barrier
	s_setprio 0
	ds_read_b128 v[188:191], v143 offset:22528
	ds_read_b128 v[192:195], v143 offset:23552
	s_add_i32 s50, 0, 0x14000
	s_add_i32 s47, s47, s31
	v_add_u32_e32 v184, s50, v142
	v_lshl_add_u64 v[196:197], s[20:21], 0, v[130:131]
	s_mov_b32 m0, s47
	ds_read_b128 v[202:205], v184
	ds_read_b128 v[206:209], v184 offset:1024
	ds_read_b128 v[210:213], v184 offset:2048
	ds_read_b128 v[214:217], v184 offset:3072
	global_load_lds_dwordx4 v[196:197], off
	v_lshl_add_u64 v[218:219], s[20:21], 0, v[134:135]
	s_add_i32 m0, s47, 0x2000
	s_nop 0
	global_load_lds_dwordx4 v[218:219], off
	s_setprio 1
	s_barrier
	s_waitcnt lgkmcnt(0)
	v_mfma_f32_16x16x32_bf16 v[120:123], v[202:205], v[160:163], v[120:123]
	v_mfma_f32_16x16x32_bf16 v[112:115], v[210:213], v[160:163], v[112:115]
	v_mfma_f32_16x16x32_bf16 v[104:107], v[202:205], v[168:171], v[104:107]
	v_mfma_f32_16x16x32_bf16 v[96:99], v[210:213], v[168:171], v[96:99]
	v_mfma_f32_16x16x32_bf16 v[88:91], v[202:205], v[176:179], v[88:91]
	v_mfma_f32_16x16x32_bf16 v[80:83], v[210:213], v[176:179], v[80:83]
	v_mfma_f32_16x16x32_bf16 v[72:75], v[202:205], v[248:251], v[72:75]
	v_mfma_f32_16x16x32_bf16 v[64:67], v[210:213], v[248:251], v[64:67]
	v_mfma_f32_16x16x32_bf16 v[120:123], v[206:209], v[164:167], v[120:123]
	v_mfma_f32_16x16x32_bf16 v[112:115], v[214:217], v[164:167], v[112:115]
	v_mfma_f32_16x16x32_bf16 v[104:107], v[206:209], v[172:175], v[104:107]
	v_mfma_f32_16x16x32_bf16 v[96:99], v[214:217], v[172:175], v[96:99]
	v_mfma_f32_16x16x32_bf16 v[88:91], v[206:209], v[180:183], v[88:91]
	v_mfma_f32_16x16x32_bf16 v[80:83], v[214:217], v[180:183], v[80:83]
	v_mfma_f32_16x16x32_bf16 v[72:75], v[206:209], v[252:255], v[72:75]
	v_mfma_f32_16x16x32_bf16 v[64:67], v[214:217], v[252:255], v[64:67]
	s_barrier
	s_setprio 0
	s_mov_b32 m0, s17
	v_lshl_add_u64 v[220:221], s[22:23], 0, v[128:129]
	ds_read_b128 v[160:163], v143 offset:16384
	ds_read_b128 v[164:167], v143 offset:17408
	ds_read_b128 v[168:171], v143 offset:18432
	ds_read_b128 v[172:175], v143 offset:19456
	ds_read_b128 v[176:179], v143 offset:20480
	ds_read_b128 v[180:183], v143 offset:21504
	global_load_lds_dwordx4 v[220:221], off
	v_lshl_add_u64 v[222:223], s[22:23], 0, v[132:133]
	s_mov_b32 m0, s33
	s_nop 0
	global_load_lds_dwordx4 v[222:223], off
	s_setprio 1
	s_waitcnt vmcnt(8)
	s_barrier
	s_waitcnt lgkmcnt(0)
	v_mfma_f32_16x16x32_bf16 v[60:63], v[144:147], v[160:163], v[60:63]
	v_mfma_f32_16x16x32_bf16 v[52:55], v[152:155], v[160:163], v[52:55]
	v_mfma_f32_16x16x32_bf16 v[44:47], v[144:147], v[168:171], v[44:47]
	v_mfma_f32_16x16x32_bf16 v[36:39], v[152:155], v[168:171], v[36:39]
	v_mfma_f32_16x16x32_bf16 v[28:31], v[144:147], v[176:179], v[28:31]
	v_mfma_f32_16x16x32_bf16 v[20:23], v[152:155], v[176:179], v[20:23]
	v_mfma_f32_16x16x32_bf16 v[12:15], v[144:147], v[188:191], v[12:15]
	v_mfma_f32_16x16x32_bf16 v[4:7], v[152:155], v[188:191], v[4:7]
	v_mfma_f32_16x16x32_bf16 v[60:63], v[148:151], v[164:167], v[60:63]
	v_mfma_f32_16x16x32_bf16 v[52:55], v[156:159], v[164:167], v[52:55]
	v_mfma_f32_16x16x32_bf16 v[44:47], v[148:151], v[172:175], v[44:47]
	v_mfma_f32_16x16x32_bf16 v[36:39], v[156:159], v[172:175], v[36:39]
	v_mfma_f32_16x16x32_bf16 v[28:31], v[148:151], v[180:183], v[28:31]
	v_mfma_f32_16x16x32_bf16 v[20:23], v[156:159], v[180:183], v[20:23]
	v_mfma_f32_16x16x32_bf16 v[12:15], v[148:151], v[192:195], v[12:15]
	v_mfma_f32_16x16x32_bf16 v[4:7], v[156:159], v[192:195], v[4:7]
	s_barrier
	s_setprio 0
	v_add_u32_e32 v156, 0x18000, v142
	ds_read_b128 v[144:147], v156
	ds_read_b128 v[148:151], v156 offset:1024
	ds_read_b128 v[152:155], v156 offset:2048
	ds_read_b128 v[156:159], v156 offset:3072
	ds_read_b128 v[248:251], v143 offset:38912
	ds_read_b128 v[252:255], v143 offset:39936
	s_add_u32 s48, s20, 0x80000
	s_addc_u32 s49, s21, 0
	s_add_i32 s47, s50, s31
	v_lshl_add_u64 v[246:247], s[48:49], 0, v[130:131]
	s_mov_b32 m0, s47
	s_nop 0
	global_load_lds_dwordx4 v[246:247], off
	v_lshl_add_u64 v[246:247], s[48:49], 0, v[134:135]
	s_add_i32 m0, s47, 0x2000
	s_nop 0
	global_load_lds_dwordx4 v[246:247], off
	s_waitcnt vmcnt(6)
	s_setprio 1
	s_barrier
	v_mfma_f32_16x16x32_bf16 v[56:59], v[202:205], v[160:163], v[56:59]
	v_mfma_f32_16x16x32_bf16 v[48:51], v[210:213], v[160:163], v[48:51]
	v_mfma_f32_16x16x32_bf16 v[40:43], v[202:205], v[168:171], v[40:43]
	v_mfma_f32_16x16x32_bf16 v[32:35], v[210:213], v[168:171], v[32:35]
	v_mfma_f32_16x16x32_bf16 v[24:27], v[202:205], v[176:179], v[24:27]
	v_mfma_f32_16x16x32_bf16 v[16:19], v[210:213], v[176:179], v[16:19]
	v_mfma_f32_16x16x32_bf16 v[8:11], v[202:205], v[188:191], v[8:11]
	v_mfma_f32_16x16x32_bf16 v[0:3], v[210:213], v[188:191], v[0:3]
	v_mfma_f32_16x16x32_bf16 v[56:59], v[206:209], v[164:167], v[56:59]
	v_mfma_f32_16x16x32_bf16 v[48:51], v[214:217], v[164:167], v[48:51]
	v_mfma_f32_16x16x32_bf16 v[40:43], v[206:209], v[172:175], v[40:43]
	v_mfma_f32_16x16x32_bf16 v[32:35], v[214:217], v[172:175], v[32:35]
	v_mfma_f32_16x16x32_bf16 v[24:27], v[206:209], v[180:183], v[24:27]
	v_mfma_f32_16x16x32_bf16 v[16:19], v[214:217], v[180:183], v[16:19]
	v_mfma_f32_16x16x32_bf16 v[8:11], v[206:209], v[192:195], v[8:11]
	v_mfma_f32_16x16x32_bf16 v[0:3], v[214:217], v[192:195], v[0:3]
	s_barrier
	s_setprio 0
	s_add_i32 s47, 0, 0x18000
	s_add_u32 s22, s22, 0x80000
	s_addc_u32 s23, s23, 0
	s_mov_b32 m0, s34
	v_lshl_add_u64 v[202:203], s[22:23], 0, v[128:129]
	ds_read_b128 v[160:163], v143 offset:32768
	ds_read_b128 v[164:167], v143 offset:33792
	ds_read_b128 v[168:171], v143 offset:34816
	ds_read_b128 v[172:175], v143 offset:35840
	ds_read_b128 v[176:179], v143 offset:36864
	ds_read_b128 v[180:183], v143 offset:37888
	global_load_lds_dwordx4 v[202:203], off
	v_lshl_add_u64 v[202:203], s[22:23], 0, v[132:133]
	s_mov_b32 m0, s35
	s_nop 0
	global_load_lds_dwordx4 v[202:203], off
	s_waitcnt lgkmcnt(8)
	s_setprio 1
	s_waitcnt vmcnt(8)
	s_barrier
	s_waitcnt lgkmcnt(0)
	v_mfma_f32_16x16x32_bf16 v[124:127], v[144:147], v[160:163], v[124:127]
	v_mfma_f32_16x16x32_bf16 v[116:119], v[152:155], v[160:163], v[116:119]
	v_mfma_f32_16x16x32_bf16 v[108:111], v[144:147], v[168:171], v[108:111]
	v_mfma_f32_16x16x32_bf16 v[100:103], v[152:155], v[168:171], v[100:103]
	v_mfma_f32_16x16x32_bf16 v[92:95], v[144:147], v[176:179], v[92:95]
	v_mfma_f32_16x16x32_bf16 v[84:87], v[152:155], v[176:179], v[84:87]
	v_mfma_f32_16x16x32_bf16 v[76:79], v[144:147], v[248:251], v[76:79]
	v_mfma_f32_16x16x32_bf16 v[68:71], v[152:155], v[248:251], v[68:71]
	v_mfma_f32_16x16x32_bf16 v[124:127], v[148:151], v[164:167], v[124:127]
	v_mfma_f32_16x16x32_bf16 v[116:119], v[156:159], v[164:167], v[116:119]
	v_mfma_f32_16x16x32_bf16 v[108:111], v[148:151], v[172:175], v[108:111]
	v_mfma_f32_16x16x32_bf16 v[100:103], v[156:159], v[172:175], v[100:103]
	v_mfma_f32_16x16x32_bf16 v[92:95], v[148:151], v[180:183], v[92:95]
	v_mfma_f32_16x16x32_bf16 v[84:87], v[156:159], v[180:183], v[84:87]
	v_mfma_f32_16x16x32_bf16 v[76:79], v[148:151], v[252:255], v[76:79]
	v_mfma_f32_16x16x32_bf16 v[68:71], v[156:159], v[252:255], v[68:71]
	s_barrier
	s_setprio 0
	ds_read_b128 v[188:191], v143 offset:55296
	ds_read_b128 v[192:195], v143 offset:56320
	s_add_i32 s22, 0, 0x1c000
	s_add_i32 s23, s47, s31
	v_add_u32_e32 v184, s22, v142
	v_lshl_add_u64 v[196:197], v[196:197], 0, s[52:53]
	s_mov_b32 m0, s23
	ds_read_b128 v[202:205], v184
	ds_read_b128 v[206:209], v184 offset:1024
	ds_read_b128 v[210:213], v184 offset:2048
	ds_read_b128 v[214:217], v184 offset:3072
	global_load_lds_dwordx4 v[196:197], off
	v_lshl_add_u64 v[196:197], v[218:219], 0, s[52:53]
	s_add_i32 m0, s23, 0x2000
	s_nop 0
	global_load_lds_dwordx4 v[196:197], off
	s_setprio 1
	s_barrier
	s_waitcnt lgkmcnt(0)
	v_mfma_f32_16x16x32_bf16 v[120:123], v[202:205], v[160:163], v[120:123]
	v_mfma_f32_16x16x32_bf16 v[112:115], v[210:213], v[160:163], v[112:115]
	v_mfma_f32_16x16x32_bf16 v[104:107], v[202:205], v[168:171], v[104:107]
	v_mfma_f32_16x16x32_bf16 v[96:99], v[210:213], v[168:171], v[96:99]
	v_mfma_f32_16x16x32_bf16 v[88:91], v[202:205], v[176:179], v[88:91]
	v_mfma_f32_16x16x32_bf16 v[80:83], v[210:213], v[176:179], v[80:83]
	v_mfma_f32_16x16x32_bf16 v[72:75], v[202:205], v[248:251], v[72:75]
	v_mfma_f32_16x16x32_bf16 v[64:67], v[210:213], v[248:251], v[64:67]
	v_mfma_f32_16x16x32_bf16 v[120:123], v[206:209], v[164:167], v[120:123]
	v_mfma_f32_16x16x32_bf16 v[112:115], v[214:217], v[164:167], v[112:115]
	v_mfma_f32_16x16x32_bf16 v[104:107], v[206:209], v[172:175], v[104:107]
	v_mfma_f32_16x16x32_bf16 v[96:99], v[214:217], v[172:175], v[96:99]
	v_mfma_f32_16x16x32_bf16 v[88:91], v[206:209], v[180:183], v[88:91]
	v_mfma_f32_16x16x32_bf16 v[80:83], v[214:217], v[180:183], v[80:83]
	v_mfma_f32_16x16x32_bf16 v[72:75], v[206:209], v[252:255], v[72:75]
	v_mfma_f32_16x16x32_bf16 v[64:67], v[214:217], v[252:255], v[64:67]
	s_barrier
	s_setprio 0
	s_mov_b32 m0, s38
	v_lshl_add_u64 v[196:197], v[220:221], 0, s[52:53]
	ds_read_b128 v[160:163], v143 offset:49152
	ds_read_b128 v[164:167], v143 offset:50176
	ds_read_b128 v[168:171], v143 offset:51200
	ds_read_b128 v[172:175], v143 offset:52224
	ds_read_b128 v[176:179], v143 offset:53248
	ds_read_b128 v[180:183], v143 offset:54272
	global_load_lds_dwordx4 v[196:197], off
	v_lshl_add_u64 v[196:197], v[222:223], 0, s[52:53]
	s_mov_b32 m0, s39
	s_nop 0
	global_load_lds_dwordx4 v[196:197], off
	s_setprio 1
	s_waitcnt vmcnt(8)
	s_barrier
	s_waitcnt lgkmcnt(0)
	v_mfma_f32_16x16x32_bf16 v[60:63], v[144:147], v[160:163], v[60:63]
	v_mfma_f32_16x16x32_bf16 v[52:55], v[152:155], v[160:163], v[52:55]
	v_mfma_f32_16x16x32_bf16 v[44:47], v[144:147], v[168:171], v[44:47]
	v_mfma_f32_16x16x32_bf16 v[36:39], v[152:155], v[168:171], v[36:39]
	v_mfma_f32_16x16x32_bf16 v[28:31], v[144:147], v[176:179], v[28:31]
	v_mfma_f32_16x16x32_bf16 v[20:23], v[152:155], v[176:179], v[20:23]
	v_mfma_f32_16x16x32_bf16 v[12:15], v[144:147], v[188:191], v[12:15]
	v_mfma_f32_16x16x32_bf16 v[4:7], v[152:155], v[188:191], v[4:7]
	v_mfma_f32_16x16x32_bf16 v[60:63], v[148:151], v[164:167], v[60:63]
	v_mfma_f32_16x16x32_bf16 v[52:55], v[156:159], v[164:167], v[52:55]
	v_mfma_f32_16x16x32_bf16 v[44:47], v[148:151], v[172:175], v[44:47]
	v_mfma_f32_16x16x32_bf16 v[36:39], v[156:159], v[172:175], v[36:39]
	v_mfma_f32_16x16x32_bf16 v[28:31], v[148:151], v[180:183], v[28:31]
	v_mfma_f32_16x16x32_bf16 v[20:23], v[156:159], v[180:183], v[20:23]
	v_mfma_f32_16x16x32_bf16 v[12:15], v[148:151], v[192:195], v[12:15]
	v_mfma_f32_16x16x32_bf16 v[4:7], v[156:159], v[192:195], v[4:7]
	s_barrier
	s_setprio 0
	v_add_u32_e32 v156, 0x10000, v142
	ds_read_b128 v[144:147], v156
	ds_read_b128 v[148:151], v156 offset:1024
	ds_read_b128 v[152:155], v156 offset:2048
	ds_read_b128 v[156:159], v156 offset:3072
	ds_read_b128 v[248:251], v143 offset:6144
	ds_read_b128 v[252:255], v143 offset:7168
	s_add_u32 s20, s20, 0x80080
	s_addc_u32 s21, s21, 0
	s_add_i32 s22, s22, s31
	v_lshl_add_u64 v[246:247], s[20:21], 0, v[130:131]
	s_mov_b32 m0, s22
	s_nop 0
	global_load_lds_dwordx4 v[246:247], off
	v_lshl_add_u64 v[246:247], s[20:21], 0, v[134:135]
	s_add_i32 m0, s22, 0x2000
	s_nop 0
	global_load_lds_dwordx4 v[246:247], off
	s_waitcnt vmcnt(6)
	s_setprio 1
	s_barrier
	v_mfma_f32_16x16x32_bf16 v[56:59], v[202:205], v[160:163], v[56:59]
	v_mfma_f32_16x16x32_bf16 v[48:51], v[210:213], v[160:163], v[48:51]
	v_mfma_f32_16x16x32_bf16 v[40:43], v[202:205], v[168:171], v[40:43]
	v_mfma_f32_16x16x32_bf16 v[32:35], v[210:213], v[168:171], v[32:35]
	v_mfma_f32_16x16x32_bf16 v[24:27], v[202:205], v[176:179], v[24:27]
	v_mfma_f32_16x16x32_bf16 v[16:19], v[210:213], v[176:179], v[16:19]
	v_mfma_f32_16x16x32_bf16 v[8:11], v[202:205], v[188:191], v[8:11]
	v_mfma_f32_16x16x32_bf16 v[0:3], v[210:213], v[188:191], v[0:3]
	v_mfma_f32_16x16x32_bf16 v[56:59], v[206:209], v[164:167], v[56:59]
	v_mfma_f32_16x16x32_bf16 v[48:51], v[214:217], v[164:167], v[48:51]
	v_mfma_f32_16x16x32_bf16 v[40:43], v[206:209], v[172:175], v[40:43]
	v_mfma_f32_16x16x32_bf16 v[32:35], v[214:217], v[172:175], v[32:35]
	v_mfma_f32_16x16x32_bf16 v[24:27], v[206:209], v[180:183], v[24:27]
	v_mfma_f32_16x16x32_bf16 v[16:19], v[214:217], v[180:183], v[16:19]
	v_mfma_f32_16x16x32_bf16 v[8:11], v[206:209], v[192:195], v[8:11]
	v_mfma_f32_16x16x32_bf16 v[0:3], v[214:217], v[192:195], v[0:3]
	s_barrier
	s_setprio 0
	s_add_i32 s46, s46, 2
	s_add_u32 s18, s18, 0x100
	s_addc_u32 s19, s19, 0
	s_add_u32 s44, s44, 0x100
	s_addc_u32 s45, s45, 0
	s_cmp_gt_u32 s46, 29
	s_cbranch_scc0 .LBB0_314
	s_waitcnt lgkmcnt(0)
	v_mov_b32_e32 v144, v140
	v_mov_b32_e32 v145, v141
	s_lshl_b32 s5, s16, 8
	s_add_i32 s5, s5, s36
	v_add_u32_e32 v144, s5, v144
	s_lshl_b32 s5, s41, 7
	s_or_b32 s5, s5, s37
	v_lshl_add_u32 v145, v145, 3, s5
	v_ashrrev_i32_e32 v146, 6, v145
	v_and_b32_e32 v152, 56, v145
	v_mul_f32_e32 v145, 0x3d372713, v124
	v_fma_f32 v145, v124, v145, 1.0
	v_mul_f32_e32 v145, v124, v145
	v_mul_f32_e32 v145, 0xc0135761, v145
	v_exp_f32_e32 v148, v145
	v_mul_f32_e32 v145, 0xbfb8aa3b, v120
	v_exp_f32_e32 v149, v145
	v_mul_f32_e32 v145, 0x3d372713, v125
	v_fma_f32 v145, v125, v145, 1.0
	v_mul_f32_e32 v145, v125, v145
	v_mul_f32_e32 v145, 0xc0135761, v145
	v_exp_f32_e32 v150, v145
	v_mul_f32_e32 v145, 0xbfb8aa3b, v121
	v_exp_f32_e32 v151, v145
	v_pk_add_f32 v[148:149], v[148:149], 1.0 op_sel_hi:[1,0]
	v_mul_f32_e32 v120, v124, v120
	v_mul_f32_e32 v145, v148, v149
	v_pk_add_f32 v[148:149], v[150:151], 1.0 op_sel_hi:[1,0]
	v_rcp_f32_e32 v145, v145
	v_mul_f32_e32 v148, v148, v149
	v_rcp_f32_e32 v148, v148
	v_mul_f32_e32 v124, 0x3d372713, v127
	v_mul_f32_e32 v149, v120, v145
	v_mul_f32_e32 v120, v125, v121
	v_mul_f32_e32 v148, v120, v148
	v_mul_f32_e32 v120, 0x3d372713, v126
	v_fma_f32 v120, v126, v120, 1.0
	v_mul_f32_e32 v120, v126, v120
	v_mul_f32_e32 v120, 0xc0135761, v120
	v_mul_f32_e32 v121, 0xbfb8aa3b, v122
	v_fma_f32 v124, v127, v124, 1.0
	v_exp_f32_e32 v120, v120
	v_exp_f32_e32 v121, v121
	v_mul_f32_e32 v124, v127, v124
	v_mul_f32_e32 v124, 0xc0135761, v124
	v_mul_f32_e32 v125, 0xbfb8aa3b, v123
	v_exp_f32_e32 v124, v124
	v_exp_f32_e32 v125, v125
	v_pk_add_f32 v[120:121], v[120:121], 1.0 op_sel_hi:[1,0]
	v_ashrrev_i32_e32 v147, 31, v146
	v_mul_f32_e32 v120, v120, v121
	v_rcp_f32_e32 v145, v120
	v_pk_add_f32 v[120:121], v[124:125], 1.0 op_sel_hi:[1,0]
	v_lshlrev_b64 v[146:147], 22, v[146:147]
	v_mul_f32_e32 v120, v120, v121
	v_rcp_f32_e32 v120, v120
	v_mul_f32_e32 v121, v126, v122
	v_mul_f32_e32 v124, v121, v145
	v_mul_f32_e32 v121, v127, v123
	v_mul_f32_e32 v125, v121, v120
	v_mul_f32_e32 v120, 0x3d372713, v116
	v_fma_f32 v120, v116, v120, 1.0
	v_mul_f32_e32 v120, v116, v120
	v_mul_f32_e32 v122, 0x3d372713, v117
	v_mul_f32_e32 v120, 0xc0135761, v120
	v_mul_f32_e32 v121, 0xbfb8aa3b, v112
	v_fma_f32 v122, v117, v122, 1.0
	v_exp_f32_e32 v120, v120
	v_exp_f32_e32 v121, v121
	v_mul_f32_e32 v122, v117, v122
	v_mul_f32_e32 v122, 0xc0135761, v122
	v_mul_f32_e32 v123, 0xbfb8aa3b, v113
	v_exp_f32_e32 v122, v122
	v_exp_f32_e32 v123, v123
	v_pk_add_f32 v[120:121], v[120:121], 1.0 op_sel_hi:[1,0]
	v_mul_f32_e32 v112, v116, v112
	v_mul_f32_e32 v120, v120, v121
	v_rcp_f32_e32 v126, v120
	v_pk_add_f32 v[120:121], v[122:123], 1.0 op_sel_hi:[1,0]
	v_mul_f32_e32 v116, 0x3d372713, v119
	v_mul_f32_e32 v120, v120, v121
	v_rcp_f32_e32 v120, v120
	v_mul_f32_e32 v121, v112, v126
	v_mul_f32_e32 v112, v117, v113
	v_mul_f32_e32 v113, 0xbfb8aa3b, v114
	v_mul_f32_e32 v120, v112, v120
	v_mul_f32_e32 v112, 0x3d372713, v118
	v_fma_f32 v112, v118, v112, 1.0
	v_mul_f32_e32 v112, v118, v112
	v_mul_f32_e32 v112, 0xc0135761, v112
	v_fma_f32 v116, v119, v116, 1.0
	v_exp_f32_e32 v112, v112
	v_exp_f32_e32 v113, v113
	v_mul_f32_e32 v116, v119, v116
	v_mul_f32_e32 v116, 0xc0135761, v116
	v_mul_f32_e32 v117, 0xbfb8aa3b, v115
	v_exp_f32_e32 v116, v116
	v_exp_f32_e32 v117, v117
	v_pk_add_f32 v[112:113], v[112:113], 1.0 op_sel_hi:[1,0]
	v_ashrrev_i32_e32 v145, 31, v144
	v_mul_f32_e32 v112, v112, v113
	v_rcp_f32_e32 v122, v112
	v_pk_add_f32 v[112:113], v[116:117], 1.0 op_sel_hi:[1,0]
	v_lshlrev_b32_e32 v184, 1, v152
	v_mul_f32_e32 v112, v112, v113
	v_rcp_f32_e32 v112, v112
	v_mul_f32_e32 v113, v118, v114
	v_mul_f32_e32 v114, v119, v115
	v_mul_f32_e32 v113, v113, v122
	v_mul_f32_e32 v112, v114, v112
	v_cvt_pk_bf16_f32 v114, v149, v148
	v_cvt_pk_bf16_f32 v115, v124, v125
	v_cvt_pk_bf16_f32 v116, v121, v120
	v_cvt_pk_bf16_f32 v117, v113, v112
	v_lshl_add_u64 v[112:113], s[0:1], 0, v[146:147]
	v_lshlrev_b64 v[118:119], 7, v[144:145]
	v_lshl_add_u64 v[112:113], v[112:113], 0, v[118:119]
	v_lshl_add_u64 v[112:113], v[112:113], 0, v[184:185]
	global_store_dwordx4 v[112:113], v[114:117], off
	s_movk_i32 s5, 0x1000
	s_mov_b32 s41, s8
	v_mul_f32_e32 v114, 0x3d372713, v108
	v_fma_f32 v114, v108, v114, 1.0
	v_mul_f32_e32 v114, v108, v114
	v_mul_f32_e32 v116, 0x3d372713, v109
	v_mul_f32_e32 v114, 0xc0135761, v114
	v_mul_f32_e32 v115, 0xbfb8aa3b, v104
	v_fma_f32 v116, v109, v116, 1.0
	v_exp_f32_e32 v114, v114
	v_exp_f32_e32 v115, v115
	v_mul_f32_e32 v116, v109, v116
	v_mul_f32_e32 v116, 0xc0135761, v116
	v_mul_f32_e32 v117, 0xbfb8aa3b, v105
	v_exp_f32_e32 v116, v116
	v_exp_f32_e32 v117, v117
	v_pk_add_f32 v[114:115], v[114:115], 1.0 op_sel_hi:[1,0]
	v_mul_f32_e32 v104, v108, v104
	v_mul_f32_e32 v114, v114, v115
	v_rcp_f32_e32 v118, v114
	v_pk_add_f32 v[114:115], v[116:117], 1.0 op_sel_hi:[1,0]
	v_mul_f32_e32 v108, 0x3d372713, v111
	v_mul_f32_e32 v114, v114, v115
	v_rcp_f32_e32 v114, v114
	v_mul_f32_e32 v115, v104, v118
	v_mul_f32_e32 v104, v109, v105
	v_mul_f32_e32 v105, 0xbfb8aa3b, v106
	v_mul_f32_e32 v114, v104, v114
	v_mul_f32_e32 v104, 0x3d372713, v110
	v_fma_f32 v104, v110, v104, 1.0
	v_mul_f32_e32 v104, v110, v104
	v_mul_f32_e32 v104, 0xc0135761, v104
	v_fma_f32 v108, v111, v108, 1.0
	v_exp_f32_e32 v104, v104
	v_exp_f32_e32 v105, v105
	v_mul_f32_e32 v108, v111, v108
	v_mul_f32_e32 v108, 0xc0135761, v108
	v_mul_f32_e32 v109, 0xbfb8aa3b, v107
	v_exp_f32_e32 v108, v108
	v_exp_f32_e32 v109, v109
	v_pk_add_f32 v[104:105], v[104:105], 1.0 op_sel_hi:[1,0]
	s_mov_b32 s16, s4
	v_mul_f32_e32 v104, v104, v105
	v_rcp_f32_e32 v116, v104
	v_pk_add_f32 v[104:105], v[108:109], 1.0 op_sel_hi:[1,0]
	s_mov_b64 s[20:21], s[14:15]
	v_mul_f32_e32 v104, v104, v105
	v_rcp_f32_e32 v104, v104
	v_mul_f32_e32 v105, v110, v106
	v_mul_f32_e32 v108, v105, v116
	v_mul_f32_e32 v105, v111, v107
	v_mul_f32_e32 v109, v105, v104
	v_mul_f32_e32 v104, 0x3d372713, v100
	v_fma_f32 v104, v100, v104, 1.0
	v_mul_f32_e32 v104, v100, v104
	v_mul_f32_e32 v106, 0x3d372713, v101
	v_mul_f32_e32 v104, 0xc0135761, v104
	v_mul_f32_e32 v105, 0xbfb8aa3b, v96
	v_fma_f32 v106, v101, v106, 1.0
	v_exp_f32_e32 v104, v104
	v_exp_f32_e32 v105, v105
	v_mul_f32_e32 v106, v101, v106
	v_mul_f32_e32 v106, 0xc0135761, v106
	v_mul_f32_e32 v107, 0xbfb8aa3b, v97
	v_exp_f32_e32 v106, v106
	v_exp_f32_e32 v107, v107
	v_pk_add_f32 v[104:105], v[104:105], 1.0 op_sel_hi:[1,0]
	v_mul_f32_e32 v96, v100, v96
	v_mul_f32_e32 v104, v104, v105
	v_rcp_f32_e32 v110, v104
	v_pk_add_f32 v[104:105], v[106:107], 1.0 op_sel_hi:[1,0]
	v_mul_f32_e32 v100, 0x3d372713, v103
	v_mul_f32_e32 v104, v104, v105
	v_rcp_f32_e32 v104, v104
	v_mul_f32_e32 v105, v96, v110
	v_mul_f32_e32 v96, v101, v97
	v_mul_f32_e32 v97, 0xbfb8aa3b, v98
	v_mul_f32_e32 v104, v96, v104
	v_mul_f32_e32 v96, 0x3d372713, v102
	v_fma_f32 v96, v102, v96, 1.0
	v_mul_f32_e32 v96, v102, v96
	v_mul_f32_e32 v96, 0xc0135761, v96
	v_fma_f32 v100, v103, v100, 1.0
	v_exp_f32_e32 v96, v96
	v_exp_f32_e32 v97, v97
	v_mul_f32_e32 v100, v103, v100
	v_mul_f32_e32 v100, 0xc0135761, v100
	v_mul_f32_e32 v101, 0xbfb8aa3b, v99
	v_exp_f32_e32 v100, v100
	v_exp_f32_e32 v101, v101
	v_pk_add_f32 v[96:97], v[96:97], 1.0 op_sel_hi:[1,0]
	s_mov_b64 s[18:19], s[12:13]
	v_mul_f32_e32 v96, v96, v97
	v_rcp_f32_e32 v106, v96
	v_pk_add_f32 v[96:97], v[100:101], 1.0 op_sel_hi:[1,0]
	s_nop 0
	v_mul_f32_e32 v96, v96, v97
	v_rcp_f32_e32 v96, v96
	v_mul_f32_e32 v97, v102, v98
	v_mul_f32_e32 v100, v97, v106
	v_mul_f32_e32 v97, v103, v99
	v_mul_f32_e32 v99, v97, v96
	v_cvt_pk_bf16_f32 v96, v115, v114
	v_cvt_pk_bf16_f32 v97, v108, v109
	v_cvt_pk_bf16_f32 v98, v105, v104
	v_cvt_pk_bf16_f32 v99, v100, v99
	global_store_dwordx4 v[112:113], v[96:99], off offset:2048
	s_nop 1
	v_mul_f32_e32 v96, 0x3d372713, v92
	v_fma_f32 v96, v92, v96, 1.0
	v_mul_f32_e32 v96, v92, v96
	v_mul_f32_e32 v98, 0x3d372713, v93
	v_mul_f32_e32 v96, 0xc0135761, v96
	v_mul_f32_e32 v97, 0xbfb8aa3b, v88
	v_fma_f32 v98, v93, v98, 1.0
	v_exp_f32_e32 v96, v96
	v_exp_f32_e32 v97, v97
	v_mul_f32_e32 v98, v93, v98
	v_mul_f32_e32 v98, 0xc0135761, v98
	v_mul_f32_e32 v99, 0xbfb8aa3b, v89
	v_exp_f32_e32 v98, v98
	v_exp_f32_e32 v99, v99
	v_pk_add_f32 v[96:97], v[96:97], 1.0 op_sel_hi:[1,0]
	v_mul_f32_e32 v88, v92, v88
	v_mul_f32_e32 v96, v96, v97
	v_rcp_f32_e32 v100, v96
	v_pk_add_f32 v[96:97], v[98:99], 1.0 op_sel_hi:[1,0]
	v_mul_f32_e32 v92, 0x3d372713, v95
	v_mul_f32_e32 v96, v96, v97
	v_rcp_f32_e32 v96, v96
	v_mul_f32_e32 v97, v88, v100
	v_mul_f32_e32 v88, v93, v89
	v_mul_f32_e32 v89, 0xbfb8aa3b, v90
	v_mul_f32_e32 v96, v88, v96
	v_mul_f32_e32 v88, 0x3d372713, v94
	v_fma_f32 v88, v94, v88, 1.0
	v_mul_f32_e32 v88, v94, v88
	v_mul_f32_e32 v88, 0xc0135761, v88
	v_fma_f32 v92, v95, v92, 1.0
	v_exp_f32_e32 v88, v88
	v_exp_f32_e32 v89, v89
	v_mul_f32_e32 v92, v95, v92
	v_mul_f32_e32 v92, 0xc0135761, v92
	v_mul_f32_e32 v93, 0xbfb8aa3b, v91
	v_exp_f32_e32 v92, v92
	v_exp_f32_e32 v93, v93
	v_pk_add_f32 v[88:89], v[88:89], 1.0 op_sel_hi:[1,0]
	s_nop 0
	v_mul_f32_e32 v88, v88, v89
	v_rcp_f32_e32 v98, v88
	v_pk_add_f32 v[88:89], v[92:93], 1.0 op_sel_hi:[1,0]
	s_nop 0
	v_mul_f32_e32 v88, v88, v89
	v_rcp_f32_e32 v88, v88
	v_mul_f32_e32 v89, v94, v90
	v_mul_f32_e32 v92, v89, v98
	v_mul_f32_e32 v89, v95, v91
	v_mul_f32_e32 v93, v89, v88
	v_mul_f32_e32 v88, 0x3d372713, v84
	v_fma_f32 v88, v84, v88, 1.0
	v_mul_f32_e32 v88, v84, v88
	v_mul_f32_e32 v90, 0x3d372713, v85
	v_mul_f32_e32 v88, 0xc0135761, v88
	v_mul_f32_e32 v89, 0xbfb8aa3b, v80
	v_fma_f32 v90, v85, v90, 1.0
	v_exp_f32_e32 v88, v88
	v_exp_f32_e32 v89, v89
	v_mul_f32_e32 v90, v85, v90
	v_mul_f32_e32 v90, 0xc0135761, v90
	v_mul_f32_e32 v91, 0xbfb8aa3b, v81
	v_exp_f32_e32 v90, v90
	v_exp_f32_e32 v91, v91
	v_pk_add_f32 v[88:89], v[88:89], 1.0 op_sel_hi:[1,0]
	v_mul_f32_e32 v80, v84, v80
	v_mul_f32_e32 v88, v88, v89
	v_rcp_f32_e32 v94, v88
	v_pk_add_f32 v[88:89], v[90:91], 1.0 op_sel_hi:[1,0]
	v_mul_f32_e32 v84, 0x3d372713, v87
	v_mul_f32_e32 v88, v88, v89
	v_rcp_f32_e32 v88, v88
	v_mul_f32_e32 v89, v80, v94
	v_mul_f32_e32 v80, v85, v81
	v_mul_f32_e32 v81, 0xbfb8aa3b, v82
	v_mul_f32_e32 v88, v80, v88
	v_mul_f32_e32 v80, 0x3d372713, v86
	v_fma_f32 v80, v86, v80, 1.0
	v_mul_f32_e32 v80, v86, v80
	v_mul_f32_e32 v80, 0xc0135761, v80
	v_fma_f32 v84, v87, v84, 1.0
	v_exp_f32_e32 v80, v80
	v_exp_f32_e32 v81, v81
	v_mul_f32_e32 v84, v87, v84
	v_mul_f32_e32 v84, 0xc0135761, v84
	v_mul_f32_e32 v85, 0xbfb8aa3b, v83
	v_exp_f32_e32 v84, v84
	v_exp_f32_e32 v85, v85
	v_pk_add_f32 v[80:81], v[80:81], 1.0 op_sel_hi:[1,0]
	s_nop 0
	v_mul_f32_e32 v80, v80, v81
	v_rcp_f32_e32 v90, v80
	v_pk_add_f32 v[80:81], v[84:85], 1.0 op_sel_hi:[1,0]
	s_nop 0
	v_mul_f32_e32 v80, v80, v81
	v_rcp_f32_e32 v80, v80
	v_mul_f32_e32 v81, v86, v82
	v_mul_f32_e32 v84, v81, v90
	v_mul_f32_e32 v81, v87, v83
	v_mul_f32_e32 v83, v81, v80
	v_cvt_pk_bf16_f32 v80, v97, v96
	v_cvt_pk_bf16_f32 v81, v92, v93
	v_cvt_pk_bf16_f32 v82, v89, v88
	v_cvt_pk_bf16_f32 v83, v84, v83
	v_add_co_u32_e32 v84, vcc, s5, v112
	s_movk_i32 s5, 0x4000
	s_nop 0
	v_addc_co_u32_e32 v85, vcc, 0, v113, vcc
	global_store_dwordx4 v[84:85], v[80:83], off
	s_nop 1
	v_mul_f32_e32 v80, 0x3d372713, v76
	v_fma_f32 v80, v76, v80, 1.0
	v_mul_f32_e32 v80, v76, v80
	v_mul_f32_e32 v82, 0x3d372713, v77
	v_mul_f32_e32 v80, 0xc0135761, v80
	v_mul_f32_e32 v81, 0xbfb8aa3b, v72
	v_fma_f32 v82, v77, v82, 1.0
	v_exp_f32_e32 v80, v80
	v_exp_f32_e32 v81, v81
	v_mul_f32_e32 v82, v77, v82
	v_mul_f32_e32 v82, 0xc0135761, v82
	v_mul_f32_e32 v83, 0xbfb8aa3b, v73
	v_exp_f32_e32 v82, v82
	v_exp_f32_e32 v83, v83
	v_pk_add_f32 v[80:81], v[80:81], 1.0 op_sel_hi:[1,0]
	v_mul_f32_e32 v72, v76, v72
	v_mul_f32_e32 v80, v80, v81
	v_rcp_f32_e32 v86, v80
	v_pk_add_f32 v[80:81], v[82:83], 1.0 op_sel_hi:[1,0]
	v_mul_f32_e32 v76, 0x3d372713, v79
	v_mul_f32_e32 v80, v80, v81
	v_rcp_f32_e32 v80, v80
	v_mul_f32_e32 v81, v72, v86
	v_mul_f32_e32 v72, v77, v73
	v_mul_f32_e32 v73, 0xbfb8aa3b, v74
	v_mul_f32_e32 v80, v72, v80
	v_mul_f32_e32 v72, 0x3d372713, v78
	v_fma_f32 v72, v78, v72, 1.0
	v_mul_f32_e32 v72, v78, v72
	v_mul_f32_e32 v72, 0xc0135761, v72
	v_fma_f32 v76, v79, v76, 1.0
	v_exp_f32_e32 v72, v72
	v_exp_f32_e32 v73, v73
	v_mul_f32_e32 v76, v79, v76
	v_mul_f32_e32 v76, 0xc0135761, v76
	v_mul_f32_e32 v77, 0xbfb8aa3b, v75
	v_exp_f32_e32 v76, v76
	v_exp_f32_e32 v77, v77
	v_pk_add_f32 v[72:73], v[72:73], 1.0 op_sel_hi:[1,0]
	s_nop 0
	v_mul_f32_e32 v72, v72, v73
	v_rcp_f32_e32 v82, v72
	v_pk_add_f32 v[72:73], v[76:77], 1.0 op_sel_hi:[1,0]
	s_nop 0
	v_mul_f32_e32 v72, v72, v73
	v_rcp_f32_e32 v72, v72
	v_mul_f32_e32 v73, v78, v74
	v_mul_f32_e32 v76, v73, v82
	v_mul_f32_e32 v73, v79, v75
	v_mul_f32_e32 v77, v73, v72
	v_mul_f32_e32 v72, 0x3d372713, v68
	v_fma_f32 v72, v68, v72, 1.0
	v_mul_f32_e32 v72, v68, v72
	v_mul_f32_e32 v74, 0x3d372713, v69
	v_mul_f32_e32 v72, 0xc0135761, v72
	v_mul_f32_e32 v73, 0xbfb8aa3b, v64
	v_fma_f32 v74, v69, v74, 1.0
	v_exp_f32_e32 v72, v72
	v_exp_f32_e32 v73, v73
	v_mul_f32_e32 v74, v69, v74
	v_mul_f32_e32 v74, 0xc0135761, v74
	v_mul_f32_e32 v75, 0xbfb8aa3b, v65
	v_exp_f32_e32 v74, v74
	v_exp_f32_e32 v75, v75
	v_pk_add_f32 v[72:73], v[72:73], 1.0 op_sel_hi:[1,0]
	v_mul_f32_e32 v64, v68, v64
	v_mul_f32_e32 v72, v72, v73
	v_rcp_f32_e32 v78, v72
	v_pk_add_f32 v[72:73], v[74:75], 1.0 op_sel_hi:[1,0]
	v_mul_f32_e32 v68, 0x3d372713, v71
	v_mul_f32_e32 v72, v72, v73
	v_rcp_f32_e32 v72, v72
	v_mul_f32_e32 v73, v64, v78
	v_mul_f32_e32 v64, v69, v65
	v_mul_f32_e32 v65, 0xbfb8aa3b, v66
	v_mul_f32_e32 v72, v64, v72
	v_mul_f32_e32 v64, 0x3d372713, v70
	v_fma_f32 v64, v70, v64, 1.0
	v_mul_f32_e32 v64, v70, v64
	v_mul_f32_e32 v64, 0xc0135761, v64
	v_fma_f32 v68, v71, v68, 1.0
	v_exp_f32_e32 v64, v64
	v_exp_f32_e32 v65, v65
	v_mul_f32_e32 v68, v71, v68
	v_mul_f32_e32 v68, 0xc0135761, v68
	v_mul_f32_e32 v69, 0xbfb8aa3b, v67
	v_exp_f32_e32 v68, v68
	v_exp_f32_e32 v69, v69
	v_pk_add_f32 v[64:65], v[64:65], 1.0 op_sel_hi:[1,0]
	s_nop 0
	v_mul_f32_e32 v64, v64, v65
	v_rcp_f32_e32 v74, v64
	v_pk_add_f32 v[64:65], v[68:69], 1.0 op_sel_hi:[1,0]
	s_nop 0
	v_mul_f32_e32 v64, v64, v65
	v_rcp_f32_e32 v64, v64
	v_mul_f32_e32 v65, v70, v66
	v_mul_f32_e32 v68, v65, v74
	v_mul_f32_e32 v65, v71, v67
	v_mul_f32_e32 v67, v65, v64
	v_cvt_pk_bf16_f32 v64, v81, v80
	v_cvt_pk_bf16_f32 v65, v76, v77
	v_cvt_pk_bf16_f32 v66, v73, v72
	v_cvt_pk_bf16_f32 v67, v68, v67
	global_store_dwordx4 v[84:85], v[64:67], off offset:2048
	s_nop 1
	v_mul_f32_e32 v64, 0x3d372713, v60
	v_fma_f32 v64, v60, v64, 1.0
	v_mul_f32_e32 v64, v60, v64
	v_mul_f32_e32 v66, 0x3d372713, v61
	v_mul_f32_e32 v64, 0xc0135761, v64
	v_mul_f32_e32 v65, 0xbfb8aa3b, v56
	v_fma_f32 v66, v61, v66, 1.0
	v_exp_f32_e32 v64, v64
	v_exp_f32_e32 v65, v65
	v_mul_f32_e32 v66, v61, v66
	v_mul_f32_e32 v66, 0xc0135761, v66
	v_mul_f32_e32 v67, 0xbfb8aa3b, v57
	v_exp_f32_e32 v66, v66
	v_exp_f32_e32 v67, v67
	v_pk_add_f32 v[64:65], v[64:65], 1.0 op_sel_hi:[1,0]
	v_mul_f32_e32 v56, v60, v56
	v_mul_f32_e32 v64, v64, v65
	v_rcp_f32_e32 v68, v64
	v_pk_add_f32 v[64:65], v[66:67], 1.0 op_sel_hi:[1,0]
	v_mul_f32_e32 v60, 0x3d372713, v63
	v_mul_f32_e32 v64, v64, v65
	v_rcp_f32_e32 v64, v64
	v_mul_f32_e32 v65, v56, v68
	v_mul_f32_e32 v56, v61, v57
	v_mul_f32_e32 v57, 0xbfb8aa3b, v58
	v_mul_f32_e32 v64, v56, v64
	v_mul_f32_e32 v56, 0x3d372713, v62
	v_fma_f32 v56, v62, v56, 1.0
	v_mul_f32_e32 v56, v62, v56
	v_mul_f32_e32 v56, 0xc0135761, v56
	v_fma_f32 v60, v63, v60, 1.0
	v_exp_f32_e32 v56, v56
	v_exp_f32_e32 v57, v57
	v_mul_f32_e32 v60, v63, v60
	v_mul_f32_e32 v60, 0xc0135761, v60
	v_mul_f32_e32 v61, 0xbfb8aa3b, v59
	v_exp_f32_e32 v60, v60
	v_exp_f32_e32 v61, v61
	v_pk_add_f32 v[56:57], v[56:57], 1.0 op_sel_hi:[1,0]
	s_nop 0
	v_mul_f32_e32 v56, v56, v57
	v_rcp_f32_e32 v66, v56
	v_pk_add_f32 v[56:57], v[60:61], 1.0 op_sel_hi:[1,0]
	s_nop 0
	v_mul_f32_e32 v56, v56, v57
	v_rcp_f32_e32 v56, v56
	v_mul_f32_e32 v57, v62, v58
	v_mul_f32_e32 v60, v57, v66
	v_mul_f32_e32 v57, v63, v59
	v_mul_f32_e32 v61, v57, v56
	v_mul_f32_e32 v56, 0x3d372713, v52
	v_fma_f32 v56, v52, v56, 1.0
	v_mul_f32_e32 v56, v52, v56
	v_mul_f32_e32 v58, 0x3d372713, v53
	v_mul_f32_e32 v56, 0xc0135761, v56
	v_mul_f32_e32 v57, 0xbfb8aa3b, v48
	v_fma_f32 v58, v53, v58, 1.0
	v_exp_f32_e32 v56, v56
	v_exp_f32_e32 v57, v57
	v_mul_f32_e32 v58, v53, v58
	v_mul_f32_e32 v58, 0xc0135761, v58
	v_mul_f32_e32 v59, 0xbfb8aa3b, v49
	v_exp_f32_e32 v58, v58
	v_exp_f32_e32 v59, v59
	v_pk_add_f32 v[56:57], v[56:57], 1.0 op_sel_hi:[1,0]
	v_mul_f32_e32 v48, v52, v48
	v_mul_f32_e32 v56, v56, v57
	v_rcp_f32_e32 v62, v56
	v_pk_add_f32 v[56:57], v[58:59], 1.0 op_sel_hi:[1,0]
	v_mul_f32_e32 v52, 0x3d372713, v55
	v_mul_f32_e32 v56, v56, v57
	v_rcp_f32_e32 v56, v56
	v_mul_f32_e32 v57, v48, v62
	v_mul_f32_e32 v48, v53, v49
	v_mul_f32_e32 v49, 0xbfb8aa3b, v50
	v_mul_f32_e32 v56, v48, v56
	v_mul_f32_e32 v48, 0x3d372713, v54
	v_fma_f32 v48, v54, v48, 1.0
	v_mul_f32_e32 v48, v54, v48
	v_mul_f32_e32 v48, 0xc0135761, v48
	v_fma_f32 v52, v55, v52, 1.0
	v_exp_f32_e32 v48, v48
	v_exp_f32_e32 v49, v49
	v_mul_f32_e32 v52, v55, v52
	v_mul_f32_e32 v52, 0xc0135761, v52
	v_mul_f32_e32 v53, 0xbfb8aa3b, v51
	v_exp_f32_e32 v52, v52
	v_exp_f32_e32 v53, v53
	v_pk_add_f32 v[48:49], v[48:49], 1.0 op_sel_hi:[1,0]
	s_nop 0
	v_mul_f32_e32 v48, v48, v49
	v_rcp_f32_e32 v58, v48
	v_pk_add_f32 v[48:49], v[52:53], 1.0 op_sel_hi:[1,0]
	s_nop 0
	v_mul_f32_e32 v48, v48, v49
	v_rcp_f32_e32 v48, v48
	v_mul_f32_e32 v49, v54, v50
	v_mul_f32_e32 v50, v55, v51
	v_add_co_u32_e32 v54, vcc, s5, v112
	v_mul_f32_e32 v48, v50, v48
	s_nop 0
	v_addc_co_u32_e32 v55, vcc, 0, v113, vcc
	s_movk_i32 s5, 0x5000
	v_mul_f32_e32 v49, v49, v58
	v_cvt_pk_bf16_f32 v50, v65, v64
	v_cvt_pk_bf16_f32 v51, v60, v61
	v_cvt_pk_bf16_f32 v52, v57, v56
	v_cvt_pk_bf16_f32 v53, v49, v48
	v_add_co_u32_e32 v48, vcc, s5, v112
	s_nop 1
	v_addc_co_u32_e32 v49, vcc, 0, v113, vcc
	global_store_dwordx4 v[48:49], v[50:53], off offset:-4096
	s_and_b64 vcc, exec, s[2:3]
	s_nop 0
	v_mul_f32_e32 v50, 0x3d372713, v44
	v_fma_f32 v50, v44, v50, 1.0
	v_mul_f32_e32 v50, v44, v50
	v_mul_f32_e32 v52, 0x3d372713, v45
	v_mul_f32_e32 v50, 0xc0135761, v50
	v_mul_f32_e32 v51, 0xbfb8aa3b, v40
	v_fma_f32 v52, v45, v52, 1.0
	v_exp_f32_e32 v50, v50
	v_exp_f32_e32 v51, v51
	v_mul_f32_e32 v52, v45, v52
	v_mul_f32_e32 v52, 0xc0135761, v52
	v_mul_f32_e32 v53, 0xbfb8aa3b, v41
	v_exp_f32_e32 v52, v52
	v_exp_f32_e32 v53, v53
	v_pk_add_f32 v[50:51], v[50:51], 1.0 op_sel_hi:[1,0]
	v_mul_f32_e32 v40, v44, v40
	v_mul_f32_e32 v50, v50, v51
	v_rcp_f32_e32 v56, v50
	v_pk_add_f32 v[50:51], v[52:53], 1.0 op_sel_hi:[1,0]
	v_mul_f32_e32 v44, 0x3d372713, v47
	v_mul_f32_e32 v50, v50, v51
	v_rcp_f32_e32 v50, v50
	v_mul_f32_e32 v51, v40, v56
	v_mul_f32_e32 v40, v45, v41
	v_mul_f32_e32 v41, 0xbfb8aa3b, v42
	v_mul_f32_e32 v50, v40, v50
	v_mul_f32_e32 v40, 0x3d372713, v46
	v_fma_f32 v40, v46, v40, 1.0
	v_mul_f32_e32 v40, v46, v40
	v_mul_f32_e32 v40, 0xc0135761, v40
	v_fma_f32 v44, v47, v44, 1.0
	v_exp_f32_e32 v40, v40
	v_exp_f32_e32 v41, v41
	v_mul_f32_e32 v44, v47, v44
	v_mul_f32_e32 v44, 0xc0135761, v44
	v_mul_f32_e32 v45, 0xbfb8aa3b, v43
	v_exp_f32_e32 v44, v44
	v_exp_f32_e32 v45, v45
	v_pk_add_f32 v[40:41], v[40:41], 1.0 op_sel_hi:[1,0]
	s_nop 0
	v_mul_f32_e32 v40, v40, v41
	v_rcp_f32_e32 v52, v40
	v_pk_add_f32 v[40:41], v[44:45], 1.0 op_sel_hi:[1,0]
	s_nop 0
	v_mul_f32_e32 v40, v40, v41
	v_rcp_f32_e32 v40, v40
	v_mul_f32_e32 v41, v46, v42
	v_mul_f32_e32 v44, v41, v52
	v_mul_f32_e32 v41, v47, v43
	v_mul_f32_e32 v45, v41, v40
	v_mul_f32_e32 v40, 0x3d372713, v36
	v_fma_f32 v40, v36, v40, 1.0
	v_mul_f32_e32 v40, v36, v40
	v_mul_f32_e32 v42, 0x3d372713, v37
	v_mul_f32_e32 v40, 0xc0135761, v40
	v_mul_f32_e32 v41, 0xbfb8aa3b, v32
	v_fma_f32 v42, v37, v42, 1.0
	v_exp_f32_e32 v40, v40
	v_exp_f32_e32 v41, v41
	v_mul_f32_e32 v42, v37, v42
	v_mul_f32_e32 v42, 0xc0135761, v42
	v_mul_f32_e32 v43, 0xbfb8aa3b, v33
	v_exp_f32_e32 v42, v42
	v_exp_f32_e32 v43, v43
	v_pk_add_f32 v[40:41], v[40:41], 1.0 op_sel_hi:[1,0]
	v_mul_f32_e32 v32, v36, v32
	v_mul_f32_e32 v40, v40, v41
	v_rcp_f32_e32 v46, v40
	v_pk_add_f32 v[40:41], v[42:43], 1.0 op_sel_hi:[1,0]
	v_mul_f32_e32 v36, 0x3d372713, v39
	v_mul_f32_e32 v40, v40, v41
	v_rcp_f32_e32 v40, v40
	v_mul_f32_e32 v41, v32, v46
	v_mul_f32_e32 v32, v37, v33
	v_mul_f32_e32 v33, 0xbfb8aa3b, v34
	v_mul_f32_e32 v40, v32, v40
	v_mul_f32_e32 v32, 0x3d372713, v38
	v_fma_f32 v32, v38, v32, 1.0
	v_mul_f32_e32 v32, v38, v32
	v_mul_f32_e32 v32, 0xc0135761, v32
	v_fma_f32 v36, v39, v36, 1.0
	v_exp_f32_e32 v32, v32
	v_exp_f32_e32 v33, v33
	v_mul_f32_e32 v36, v39, v36
	v_mul_f32_e32 v36, 0xc0135761, v36
	v_mul_f32_e32 v37, 0xbfb8aa3b, v35
	v_exp_f32_e32 v36, v36
	v_exp_f32_e32 v37, v37
	v_pk_add_f32 v[32:33], v[32:33], 1.0 op_sel_hi:[1,0]
	s_nop 0
	v_mul_f32_e32 v32, v32, v33
	v_rcp_f32_e32 v42, v32
	v_pk_add_f32 v[32:33], v[36:37], 1.0 op_sel_hi:[1,0]
	s_nop 0
	v_mul_f32_e32 v32, v32, v33
	v_rcp_f32_e32 v32, v32
	v_mul_f32_e32 v33, v38, v34
	v_mul_f32_e32 v36, v33, v42
	v_mul_f32_e32 v33, v39, v35
	v_mul_f32_e32 v35, v33, v32
	v_cvt_pk_bf16_f32 v32, v51, v50
	v_cvt_pk_bf16_f32 v33, v44, v45
	v_cvt_pk_bf16_f32 v34, v41, v40
	v_cvt_pk_bf16_f32 v35, v36, v35
	global_store_dwordx4 v[54:55], v[32:35], off offset:2048
	s_nop 1
	v_mul_f32_e32 v32, 0x3d372713, v28
	v_fma_f32 v32, v28, v32, 1.0
	v_mul_f32_e32 v32, v28, v32
	v_mul_f32_e32 v34, 0x3d372713, v29
	v_mul_f32_e32 v32, 0xc0135761, v32
	v_mul_f32_e32 v33, 0xbfb8aa3b, v24
	v_fma_f32 v34, v29, v34, 1.0
	v_exp_f32_e32 v32, v32
	v_exp_f32_e32 v33, v33
	v_mul_f32_e32 v34, v29, v34
	v_mul_f32_e32 v34, 0xc0135761, v34
	v_mul_f32_e32 v35, 0xbfb8aa3b, v25
	v_exp_f32_e32 v34, v34
	v_exp_f32_e32 v35, v35
	v_pk_add_f32 v[32:33], v[32:33], 1.0 op_sel_hi:[1,0]
	v_mul_f32_e32 v24, v28, v24
	v_mul_f32_e32 v32, v32, v33
	v_rcp_f32_e32 v36, v32
	v_pk_add_f32 v[32:33], v[34:35], 1.0 op_sel_hi:[1,0]
	v_mul_f32_e32 v28, 0x3d372713, v31
	v_mul_f32_e32 v32, v32, v33
	v_rcp_f32_e32 v32, v32
	v_mul_f32_e32 v33, v24, v36
	v_mul_f32_e32 v24, v29, v25
	v_mul_f32_e32 v25, 0xbfb8aa3b, v26
	v_mul_f32_e32 v32, v24, v32
	v_mul_f32_e32 v24, 0x3d372713, v30
	v_fma_f32 v24, v30, v24, 1.0
	v_mul_f32_e32 v24, v30, v24
	v_mul_f32_e32 v24, 0xc0135761, v24
	v_fma_f32 v28, v31, v28, 1.0
	v_exp_f32_e32 v24, v24
	v_exp_f32_e32 v25, v25
	v_mul_f32_e32 v28, v31, v28
	v_mul_f32_e32 v28, 0xc0135761, v28
	v_mul_f32_e32 v29, 0xbfb8aa3b, v27
	v_exp_f32_e32 v28, v28
	v_exp_f32_e32 v29, v29
	v_pk_add_f32 v[24:25], v[24:25], 1.0 op_sel_hi:[1,0]
	s_nop 0
	v_mul_f32_e32 v24, v24, v25
	v_rcp_f32_e32 v34, v24
	v_pk_add_f32 v[24:25], v[28:29], 1.0 op_sel_hi:[1,0]
	s_nop 0
	v_mul_f32_e32 v24, v24, v25
	v_rcp_f32_e32 v24, v24
	v_mul_f32_e32 v25, v30, v26
	v_mul_f32_e32 v28, v25, v34
	v_mul_f32_e32 v25, v31, v27
	v_mul_f32_e32 v29, v25, v24
	v_mul_f32_e32 v24, 0x3d372713, v20
	v_fma_f32 v24, v20, v24, 1.0
	v_mul_f32_e32 v24, v20, v24
	v_mul_f32_e32 v26, 0x3d372713, v21
	v_mul_f32_e32 v24, 0xc0135761, v24
	v_mul_f32_e32 v25, 0xbfb8aa3b, v16
	v_fma_f32 v26, v21, v26, 1.0
	v_exp_f32_e32 v24, v24
	v_exp_f32_e32 v25, v25
	v_mul_f32_e32 v26, v21, v26
	v_mul_f32_e32 v26, 0xc0135761, v26
	v_mul_f32_e32 v27, 0xbfb8aa3b, v17
	v_exp_f32_e32 v26, v26
	v_exp_f32_e32 v27, v27
	v_pk_add_f32 v[24:25], v[24:25], 1.0 op_sel_hi:[1,0]
	v_mul_f32_e32 v16, v20, v16
	v_mul_f32_e32 v24, v24, v25
	v_rcp_f32_e32 v30, v24
	v_pk_add_f32 v[24:25], v[26:27], 1.0 op_sel_hi:[1,0]
	v_mul_f32_e32 v20, 0x3d372713, v23
	v_mul_f32_e32 v24, v24, v25
	v_rcp_f32_e32 v24, v24
	v_mul_f32_e32 v25, v16, v30
	v_mul_f32_e32 v16, v21, v17
	v_mul_f32_e32 v17, 0xbfb8aa3b, v18
	v_mul_f32_e32 v24, v16, v24
	v_mul_f32_e32 v16, 0x3d372713, v22
	v_fma_f32 v16, v22, v16, 1.0
	v_mul_f32_e32 v16, v22, v16
	v_mul_f32_e32 v16, 0xc0135761, v16
	v_fma_f32 v20, v23, v20, 1.0
	v_exp_f32_e32 v16, v16
	v_exp_f32_e32 v17, v17
	v_mul_f32_e32 v20, v23, v20
	v_mul_f32_e32 v20, 0xc0135761, v20
	v_mul_f32_e32 v21, 0xbfb8aa3b, v19
	v_exp_f32_e32 v20, v20
	v_exp_f32_e32 v21, v21
	v_pk_add_f32 v[16:17], v[16:17], 1.0 op_sel_hi:[1,0]
	s_nop 0
	v_mul_f32_e32 v16, v16, v17
	v_rcp_f32_e32 v26, v16
	v_pk_add_f32 v[16:17], v[20:21], 1.0 op_sel_hi:[1,0]
	s_nop 0
	v_mul_f32_e32 v16, v16, v17
	v_rcp_f32_e32 v16, v16
	v_mul_f32_e32 v17, v22, v18
	v_mul_f32_e32 v20, v17, v26
	v_mul_f32_e32 v17, v23, v19
	v_mul_f32_e32 v19, v17, v16
	v_cvt_pk_bf16_f32 v16, v33, v32
	v_cvt_pk_bf16_f32 v17, v28, v29
	v_cvt_pk_bf16_f32 v18, v25, v24
	v_cvt_pk_bf16_f32 v19, v20, v19
	global_store_dwordx4 v[48:49], v[16:19], off
	s_nop 1
	v_mul_f32_e32 v16, 0x3d372713, v12
	v_fma_f32 v16, v12, v16, 1.0
	v_mul_f32_e32 v16, v12, v16
	v_mul_f32_e32 v18, 0x3d372713, v13
	v_mul_f32_e32 v16, 0xc0135761, v16
	v_mul_f32_e32 v17, 0xbfb8aa3b, v8
	v_fma_f32 v18, v13, v18, 1.0
	v_exp_f32_e32 v16, v16
	v_exp_f32_e32 v17, v17
	v_mul_f32_e32 v18, v13, v18
	v_mul_f32_e32 v18, 0xc0135761, v18
	v_mul_f32_e32 v19, 0xbfb8aa3b, v9
	v_exp_f32_e32 v18, v18
	v_exp_f32_e32 v19, v19
	v_pk_add_f32 v[16:17], v[16:17], 1.0 op_sel_hi:[1,0]
	v_mul_f32_e32 v8, v12, v8
	v_mul_f32_e32 v16, v16, v17
	v_rcp_f32_e32 v20, v16
	v_pk_add_f32 v[16:17], v[18:19], 1.0 op_sel_hi:[1,0]
	v_mul_f32_e32 v12, 0x3d372713, v15
	v_mul_f32_e32 v16, v16, v17
	v_rcp_f32_e32 v16, v16
	v_mul_f32_e32 v17, v8, v20
	v_mul_f32_e32 v8, v13, v9
	v_mul_f32_e32 v9, 0xbfb8aa3b, v10
	v_mul_f32_e32 v16, v8, v16
	v_mul_f32_e32 v8, 0x3d372713, v14
	v_fma_f32 v8, v14, v8, 1.0
	v_mul_f32_e32 v8, v14, v8
	v_mul_f32_e32 v8, 0xc0135761, v8
	v_fma_f32 v12, v15, v12, 1.0
	v_exp_f32_e32 v8, v8
	v_exp_f32_e32 v9, v9
	v_mul_f32_e32 v12, v15, v12
	v_mul_f32_e32 v12, 0xc0135761, v12
	v_mul_f32_e32 v13, 0xbfb8aa3b, v11
	v_exp_f32_e32 v12, v12
	v_exp_f32_e32 v13, v13
	v_pk_add_f32 v[8:9], v[8:9], 1.0 op_sel_hi:[1,0]
	s_nop 0
	v_mul_f32_e32 v8, v8, v9
	v_rcp_f32_e32 v18, v8
	v_pk_add_f32 v[8:9], v[12:13], 1.0 op_sel_hi:[1,0]
	s_nop 0
	v_mul_f32_e32 v8, v8, v9
	v_rcp_f32_e32 v8, v8
	v_mul_f32_e32 v9, v14, v10
	v_mul_f32_e32 v12, v9, v18
	v_mul_f32_e32 v9, v15, v11
	v_mul_f32_e32 v13, v9, v8
	v_mul_f32_e32 v8, 0x3d372713, v4
	v_fma_f32 v8, v4, v8, 1.0
	v_mul_f32_e32 v8, v4, v8
	v_mul_f32_e32 v10, 0x3d372713, v5
	v_mul_f32_e32 v8, 0xc0135761, v8
	v_mul_f32_e32 v9, 0xbfb8aa3b, v0
	v_fma_f32 v10, v5, v10, 1.0
	v_exp_f32_e32 v8, v8
	v_exp_f32_e32 v9, v9
	v_mul_f32_e32 v10, v5, v10
	v_mul_f32_e32 v10, 0xc0135761, v10
	v_mul_f32_e32 v11, 0xbfb8aa3b, v1
	v_exp_f32_e32 v10, v10
	v_exp_f32_e32 v11, v11
	v_pk_add_f32 v[8:9], v[8:9], 1.0 op_sel_hi:[1,0]
	v_mul_f32_e32 v0, v4, v0
	v_mul_f32_e32 v8, v8, v9
	v_rcp_f32_e32 v14, v8
	v_pk_add_f32 v[8:9], v[10:11], 1.0 op_sel_hi:[1,0]
	v_mul_f32_e32 v4, 0x3d372713, v7
	v_mul_f32_e32 v8, v8, v9
	v_rcp_f32_e32 v8, v8
	v_mul_f32_e32 v9, v0, v14
	v_mul_f32_e32 v0, v5, v1
	v_mul_f32_e32 v1, 0xbfb8aa3b, v2
	v_mul_f32_e32 v8, v0, v8
	v_mul_f32_e32 v0, 0x3d372713, v6
	v_fma_f32 v0, v6, v0, 1.0
	v_mul_f32_e32 v0, v6, v0
	v_mul_f32_e32 v0, 0xc0135761, v0
	v_fma_f32 v4, v7, v4, 1.0
	v_exp_f32_e32 v0, v0
	v_exp_f32_e32 v1, v1
	v_mul_f32_e32 v4, v7, v4
	v_mul_f32_e32 v4, 0xc0135761, v4
	v_mul_f32_e32 v5, 0xbfb8aa3b, v3
	v_exp_f32_e32 v4, v4
	v_exp_f32_e32 v5, v5
	v_pk_add_f32 v[0:1], v[0:1], 1.0 op_sel_hi:[1,0]
	s_nop 0
	v_mul_f32_e32 v0, v0, v1
	v_rcp_f32_e32 v10, v0
	v_pk_add_f32 v[0:1], v[4:5], 1.0 op_sel_hi:[1,0]
	s_nop 0
	v_mul_f32_e32 v0, v0, v1
	v_rcp_f32_e32 v0, v0
	v_mul_f32_e32 v1, v6, v2
	v_mul_f32_e32 v4, v1, v10
	v_mul_f32_e32 v1, v7, v3
	v_mul_f32_e32 v3, v1, v0
	v_cvt_pk_bf16_f32 v0, v17, v16
	v_cvt_pk_bf16_f32 v1, v12, v13
	v_cvt_pk_bf16_f32 v2, v9, v8
	v_cvt_pk_bf16_f32 v3, v4, v3
	global_store_dwordx4 v[48:49], v[0:3], off offset:2048
	s_cbranch_vccz .LBB0_307
	s_waitcnt vmcnt(0)
	s_cmpk_gt_u32 s30, 0xff
	s_cbranch_scc1 .LBB0_318
	s_barrier

.LBB0_333:
	s_ashr_i32 s17, s16, 31
	s_lshl_b64 s[20:21], s[16:17], 20
	s_add_u32 s20, s31, s20
	s_addc_u32 s21, s33, s21
	s_and_b64 s[22:23], s[24:25], exec
	s_cselect_b32 s17, s21, s1
	s_cselect_b32 s46, s20, s0
	s_ashr_i32 s19, s18, 31
	s_lshl_b64 s[22:23], s[18:19], 20
	s_add_u32 s22, s27, s22
	s_addc_u32 s23, s28, s23
	s_and_b64 s[24:25], s[24:25], exec
	s_cselect_b32 s19, s23, s5
	s_cselect_b32 s47, s22, s4
	s_add_u32 s0, s0, 0x80080
	s_addc_u32 s1, s1, 0
	s_add_u32 s48, s4, 0x100
	v_mov_b32_e32 v0, 0
	s_addc_u32 s49, s5, 0
	s_mov_b32 s50, -2
	v_mov_b32_e32 v1, v0
	v_mov_b32_e32 v2, v0
	v_mov_b32_e32 v3, v0
	v_mov_b32_e32 v4, v0
	v_mov_b32_e32 v5, v0
	v_mov_b32_e32 v6, v0
	v_mov_b32_e32 v7, v0
	v_mov_b32_e32 v16, v0
	v_mov_b32_e32 v17, v0
	v_mov_b32_e32 v18, v0
	v_mov_b32_e32 v19, v0
	v_mov_b32_e32 v20, v0
	v_mov_b32_e32 v21, v0
	v_mov_b32_e32 v22, v0
	v_mov_b32_e32 v23, v0
	v_mov_b32_e32 v32, v0
	v_mov_b32_e32 v33, v0
	v_mov_b32_e32 v34, v0
	v_mov_b32_e32 v35, v0
	v_mov_b32_e32 v36, v0
	v_mov_b32_e32 v37, v0
	v_mov_b32_e32 v38, v0
	v_mov_b32_e32 v39, v0
	v_mov_b32_e32 v48, v0
	v_mov_b32_e32 v49, v0
	v_mov_b32_e32 v50, v0
	v_mov_b32_e32 v51, v0
	v_mov_b32_e32 v52, v0
	v_mov_b32_e32 v53, v0
	v_mov_b32_e32 v54, v0
	v_mov_b32_e32 v55, v0
	v_mov_b32_e32 v8, v0
	v_mov_b32_e32 v9, v0
	v_mov_b32_e32 v10, v0
	v_mov_b32_e32 v11, v0
	v_mov_b32_e32 v12, v0
	v_mov_b32_e32 v13, v0
	v_mov_b32_e32 v14, v0
	v_mov_b32_e32 v15, v0
	v_mov_b32_e32 v24, v0
	v_mov_b32_e32 v25, v0
	v_mov_b32_e32 v26, v0
	v_mov_b32_e32 v27, v0
	v_mov_b32_e32 v28, v0
	v_mov_b32_e32 v29, v0
	v_mov_b32_e32 v30, v0
	v_mov_b32_e32 v31, v0
	v_mov_b32_e32 v40, v0
	v_mov_b32_e32 v41, v0
	v_mov_b32_e32 v42, v0
	v_mov_b32_e32 v43, v0
	v_mov_b32_e32 v44, v0
	v_mov_b32_e32 v45, v0
	v_mov_b32_e32 v46, v0
	v_mov_b32_e32 v47, v0
	v_mov_b32_e32 v60, v0
	v_mov_b32_e32 v61, v0
	v_mov_b32_e32 v62, v0
	v_mov_b32_e32 v63, v0
	v_mov_b32_e32 v64, v0
	v_mov_b32_e32 v65, v0
	v_mov_b32_e32 v66, v0
	v_mov_b32_e32 v67, v0
	v_mov_b32_e32 v72, v0
	v_mov_b32_e32 v73, v0
	v_mov_b32_e32 v74, v0
	v_mov_b32_e32 v75, v0
	v_mov_b32_e32 v76, v0
	v_mov_b32_e32 v77, v0
	v_mov_b32_e32 v78, v0
	v_mov_b32_e32 v79, v0
	v_mov_b32_e32 v96, v0
	v_mov_b32_e32 v97, v0
	v_mov_b32_e32 v98, v0
	v_mov_b32_e32 v99, v0
	v_mov_b32_e32 v100, v0
	v_mov_b32_e32 v101, v0
	v_mov_b32_e32 v102, v0
	v_mov_b32_e32 v103, v0
	v_mov_b32_e32 v80, v0
	v_mov_b32_e32 v81, v0
	v_mov_b32_e32 v82, v0
	v_mov_b32_e32 v83, v0
	v_mov_b32_e32 v112, v0
	v_mov_b32_e32 v113, v0
	v_mov_b32_e32 v114, v0
	v_mov_b32_e32 v115, v0
	v_mov_b32_e32 v56, v0
	v_mov_b32_e32 v57, v0
	v_mov_b32_e32 v58, v0
	v_mov_b32_e32 v59, v0
	v_mov_b32_e32 v120, v0
	v_mov_b32_e32 v121, v0
	v_mov_b32_e32 v122, v0
	v_mov_b32_e32 v123, v0
	v_mov_b32_e32 v84, v0
	v_mov_b32_e32 v85, v0
	v_mov_b32_e32 v86, v0
	v_mov_b32_e32 v87, v0
	v_mov_b32_e32 v92, v0
	v_mov_b32_e32 v93, v0
	v_mov_b32_e32 v94, v0
	v_mov_b32_e32 v95, v0
	v_mov_b32_e32 v104, v0
	v_mov_b32_e32 v105, v0
	v_mov_b32_e32 v106, v0
	v_mov_b32_e32 v107, v0
	v_mov_b32_e32 v108, v0
	v_mov_b32_e32 v109, v0
	v_mov_b32_e32 v110, v0
	v_mov_b32_e32 v111, v0
	v_mov_b32_e32 v88, v0
	v_mov_b32_e32 v89, v0
	v_mov_b32_e32 v90, v0
	v_mov_b32_e32 v91, v0
	v_mov_b32_e32 v116, v0
	v_mov_b32_e32 v117, v0
	v_mov_b32_e32 v118, v0
	v_mov_b32_e32 v119, v0
	v_mov_b32_e32 v68, v0
	v_mov_b32_e32 v69, v0
	v_mov_b32_e32 v70, v0
	v_mov_b32_e32 v71, v0
	v_mov_b32_e32 v124, v0
	v_mov_b32_e32 v125, v0
	v_mov_b32_e32 v126, v0
	v_mov_b32_e32 v127, v0
	s_mov_b64 s[56:57], 0x80
	v_add_u32_e32 v156, 0x10000, v142
	ds_read_b128 v[144:147], v156
	ds_read_b128 v[148:151], v156 offset:1024
	ds_read_b128 v[152:155], v156 offset:2048
	ds_read_b128 v[156:159], v156 offset:3072
	ds_read_b128 v[248:251], v143 offset:6144
	ds_read_b128 v[252:255], v143 offset:7168
.LBB0_334:
	s_add_u32 s4, s0, 0xfff80080
	s_addc_u32 s5, s1, -1
	s_add_i32 s51, 0, 0x10000
	v_add_u32_e32 v138, s51, v142
	s_cmp_eq_u32 s50, 28
	s_cselect_b32 s25, s17, s5
	s_cselect_b32 s24, s46, s4
	s_cselect_b32 s5, s19, s49
	s_cselect_b32 s4, s47, s48
	v_lshl_add_u64 v[138:139], s[0:1], 0, v[134:135]
	s_add_i32 m0, s3, 0xc000
	ds_read_b128 v[160:163], v143
	ds_read_b128 v[164:167], v143 offset:1024
	ds_read_b128 v[168:171], v143 offset:2048
	ds_read_b128 v[172:175], v143 offset:3072
	ds_read_b128 v[176:179], v143 offset:4096
	ds_read_b128 v[180:183], v143 offset:5120
	global_load_lds_dwordx4 v[138:139], off
	v_lshl_add_u64 v[138:139], s[0:1], 0, v[136:137]
	s_add_i32 m0, s3, 0xe000
	s_nop 0
	global_load_lds_dwordx4 v[138:139], off
	s_waitcnt lgkmcnt(8)
	s_setprio 1
	s_waitcnt vmcnt(8)
	s_barrier
	s_waitcnt lgkmcnt(0)
	v_mfma_f32_16x16x32_bf16 v[124:127], v[144:147], v[160:163], v[124:127]
	v_mfma_f32_16x16x32_bf16 v[68:71], v[152:155], v[160:163], v[68:71]
	v_mfma_f32_16x16x32_bf16 v[116:119], v[144:147], v[168:171], v[116:119]
	v_mfma_f32_16x16x32_bf16 v[88:91], v[152:155], v[168:171], v[88:91]
	v_mfma_f32_16x16x32_bf16 v[108:111], v[144:147], v[176:179], v[108:111]
	v_mfma_f32_16x16x32_bf16 v[104:107], v[152:155], v[176:179], v[104:107]
	v_mfma_f32_16x16x32_bf16 v[92:95], v[144:147], v[248:251], v[92:95]
	v_mfma_f32_16x16x32_bf16 v[84:87], v[152:155], v[248:251], v[84:87]
	v_mfma_f32_16x16x32_bf16 v[124:127], v[148:151], v[164:167], v[124:127]
	v_mfma_f32_16x16x32_bf16 v[68:71], v[156:159], v[164:167], v[68:71]
	v_mfma_f32_16x16x32_bf16 v[116:119], v[148:151], v[172:175], v[116:119]
	v_mfma_f32_16x16x32_bf16 v[88:91], v[156:159], v[172:175], v[88:91]
	v_mfma_f32_16x16x32_bf16 v[108:111], v[148:151], v[180:183], v[108:111]
	v_mfma_f32_16x16x32_bf16 v[104:107], v[156:159], v[180:183], v[104:107]
	v_mfma_f32_16x16x32_bf16 v[92:95], v[148:151], v[252:255], v[92:95]
	v_mfma_f32_16x16x32_bf16 v[84:87], v[156:159], v[252:255], v[84:87]
	s_barrier
	s_setprio 0
	ds_read_b128 v[188:191], v143 offset:22528
	ds_read_b128 v[192:195], v143 offset:23552
	s_add_i32 s54, 0, 0x14000
	v_add_u32_e32 v138, s54, v142
	s_add_i32 s51, s51, s35
	ds_read_b128 v[202:205], v138
	ds_read_b128 v[206:209], v138 offset:1024
	ds_read_b128 v[210:213], v138 offset:2048
	ds_read_b128 v[214:217], v138 offset:3072
	v_lshl_add_u64 v[138:139], s[4:5], 0, v[184:185]
	s_mov_b32 m0, s51
	v_lshl_add_u64 v[196:197], s[4:5], 0, v[132:133]
	global_load_lds_dwordx4 v[138:139], off
	s_add_i32 m0, s51, 0x2000
	s_nop 0
	global_load_lds_dwordx4 v[196:197], off
	s_setprio 1
	s_barrier
	s_waitcnt lgkmcnt(0)
	v_mfma_f32_16x16x32_bf16 v[120:123], v[202:205], v[160:163], v[120:123]
	v_mfma_f32_16x16x32_bf16 v[56:59], v[210:213], v[160:163], v[56:59]
	v_mfma_f32_16x16x32_bf16 v[112:115], v[202:205], v[168:171], v[112:115]
	v_mfma_f32_16x16x32_bf16 v[80:83], v[210:213], v[168:171], v[80:83]
	v_mfma_f32_16x16x32_bf16 v[100:103], v[202:205], v[176:179], v[100:103]
	v_mfma_f32_16x16x32_bf16 v[96:99], v[210:213], v[176:179], v[96:99]
	v_mfma_f32_16x16x32_bf16 v[76:79], v[202:205], v[248:251], v[76:79]
	v_mfma_f32_16x16x32_bf16 v[72:75], v[210:213], v[248:251], v[72:75]
	v_mfma_f32_16x16x32_bf16 v[120:123], v[206:209], v[164:167], v[120:123]
	v_mfma_f32_16x16x32_bf16 v[56:59], v[214:217], v[164:167], v[56:59]
	v_mfma_f32_16x16x32_bf16 v[112:115], v[206:209], v[172:175], v[112:115]
	v_mfma_f32_16x16x32_bf16 v[80:83], v[214:217], v[172:175], v[80:83]
	v_mfma_f32_16x16x32_bf16 v[100:103], v[206:209], v[180:183], v[100:103]
	v_mfma_f32_16x16x32_bf16 v[96:99], v[214:217], v[180:183], v[96:99]
	v_mfma_f32_16x16x32_bf16 v[76:79], v[206:209], v[252:255], v[76:79]
	v_mfma_f32_16x16x32_bf16 v[72:75], v[214:217], v[252:255], v[72:75]
	s_barrier
	s_setprio 0
	s_mov_b32 m0, s3
	v_lshl_add_u64 v[218:219], s[24:25], 0, v[128:129]
	ds_read_b128 v[160:163], v143 offset:16384
	ds_read_b128 v[164:167], v143 offset:17408
	ds_read_b128 v[168:171], v143 offset:18432
	ds_read_b128 v[172:175], v143 offset:19456
	ds_read_b128 v[176:179], v143 offset:20480
	ds_read_b128 v[180:183], v143 offset:21504
	global_load_lds_dwordx4 v[218:219], off
	v_lshl_add_u64 v[220:221], s[24:25], 0, v[130:131]
	s_mov_b32 m0, s36
	s_nop 0
	global_load_lds_dwordx4 v[220:221], off
	s_setprio 1
	s_waitcnt vmcnt(8)
	s_barrier
	s_waitcnt lgkmcnt(0)
	v_mfma_f32_16x16x32_bf16 v[64:67], v[144:147], v[160:163], v[64:67]
	v_mfma_f32_16x16x32_bf16 v[60:63], v[152:155], v[160:163], v[60:63]
	v_mfma_f32_16x16x32_bf16 v[44:47], v[144:147], v[168:171], v[44:47]
	v_mfma_f32_16x16x32_bf16 v[40:43], v[152:155], v[168:171], v[40:43]
	v_mfma_f32_16x16x32_bf16 v[28:31], v[144:147], v[176:179], v[28:31]
	v_mfma_f32_16x16x32_bf16 v[24:27], v[152:155], v[176:179], v[24:27]
	v_mfma_f32_16x16x32_bf16 v[12:15], v[144:147], v[188:191], v[12:15]
	v_mfma_f32_16x16x32_bf16 v[8:11], v[152:155], v[188:191], v[8:11]
	v_mfma_f32_16x16x32_bf16 v[64:67], v[148:151], v[164:167], v[64:67]
	v_mfma_f32_16x16x32_bf16 v[60:63], v[156:159], v[164:167], v[60:63]
	v_mfma_f32_16x16x32_bf16 v[44:47], v[148:151], v[172:175], v[44:47]
	v_mfma_f32_16x16x32_bf16 v[40:43], v[156:159], v[172:175], v[40:43]
	v_mfma_f32_16x16x32_bf16 v[28:31], v[148:151], v[180:183], v[28:31]
	v_mfma_f32_16x16x32_bf16 v[24:27], v[156:159], v[180:183], v[24:27]
	v_mfma_f32_16x16x32_bf16 v[12:15], v[148:151], v[192:195], v[12:15]
	v_mfma_f32_16x16x32_bf16 v[8:11], v[156:159], v[192:195], v[8:11]
	s_barrier
	s_setprio 0
	v_add_u32_e32 v156, 0x18000, v142
	ds_read_b128 v[144:147], v156
	ds_read_b128 v[148:151], v156 offset:1024
	ds_read_b128 v[152:155], v156 offset:2048
	ds_read_b128 v[156:159], v156 offset:3072
	ds_read_b128 v[248:251], v143 offset:38912
	ds_read_b128 v[252:255], v143 offset:39936
	s_add_u32 s52, s4, 0x80000
	s_addc_u32 s53, s5, 0
	s_add_i32 s51, s54, s35
	v_lshl_add_u64 v[246:247], s[52:53], 0, v[184:185]
	s_mov_b32 m0, s51
	s_nop 0
	global_load_lds_dwordx4 v[246:247], off
	v_lshl_add_u64 v[246:247], s[52:53], 0, v[132:133]
	s_add_i32 m0, s51, 0x2000
	s_nop 0
	global_load_lds_dwordx4 v[246:247], off
	s_waitcnt vmcnt(6)
	s_setprio 1
	s_barrier
	v_mfma_f32_16x16x32_bf16 v[52:55], v[202:205], v[160:163], v[52:55]
	v_mfma_f32_16x16x32_bf16 v[48:51], v[210:213], v[160:163], v[48:51]
	v_mfma_f32_16x16x32_bf16 v[36:39], v[202:205], v[168:171], v[36:39]
	v_mfma_f32_16x16x32_bf16 v[32:35], v[210:213], v[168:171], v[32:35]
	v_mfma_f32_16x16x32_bf16 v[20:23], v[202:205], v[176:179], v[20:23]
	v_mfma_f32_16x16x32_bf16 v[16:19], v[210:213], v[176:179], v[16:19]
	v_mfma_f32_16x16x32_bf16 v[4:7], v[202:205], v[188:191], v[4:7]
	v_mfma_f32_16x16x32_bf16 v[0:3], v[210:213], v[188:191], v[0:3]
	v_mfma_f32_16x16x32_bf16 v[52:55], v[206:209], v[164:167], v[52:55]
	v_mfma_f32_16x16x32_bf16 v[48:51], v[214:217], v[164:167], v[48:51]
	v_mfma_f32_16x16x32_bf16 v[36:39], v[206:209], v[172:175], v[36:39]
	v_mfma_f32_16x16x32_bf16 v[32:35], v[214:217], v[172:175], v[32:35]
	v_mfma_f32_16x16x32_bf16 v[20:23], v[206:209], v[180:183], v[20:23]
	v_mfma_f32_16x16x32_bf16 v[16:19], v[214:217], v[180:183], v[16:19]
	v_mfma_f32_16x16x32_bf16 v[4:7], v[206:209], v[192:195], v[4:7]
	v_mfma_f32_16x16x32_bf16 v[0:3], v[214:217], v[192:195], v[0:3]
	s_barrier
	s_setprio 0
	s_add_i32 s51, 0, 0x18000
	s_add_u32 s24, s24, 0x80000
	s_addc_u32 s25, s25, 0
	s_mov_b32 m0, s37
	v_lshl_add_u64 v[202:203], s[24:25], 0, v[128:129]
	ds_read_b128 v[160:163], v143 offset:32768
	ds_read_b128 v[164:167], v143 offset:33792
	ds_read_b128 v[168:171], v143 offset:34816
	ds_read_b128 v[172:175], v143 offset:35840
	ds_read_b128 v[176:179], v143 offset:36864
	ds_read_b128 v[180:183], v143 offset:37888
	global_load_lds_dwordx4 v[202:203], off
	v_lshl_add_u64 v[202:203], s[24:25], 0, v[130:131]
	s_mov_b32 m0, s38
	s_nop 0
	global_load_lds_dwordx4 v[202:203], off
	s_waitcnt lgkmcnt(8)
	s_setprio 1
	s_waitcnt vmcnt(8)
	s_barrier
	s_waitcnt lgkmcnt(0)
	v_mfma_f32_16x16x32_bf16 v[124:127], v[144:147], v[160:163], v[124:127]
	v_mfma_f32_16x16x32_bf16 v[68:71], v[152:155], v[160:163], v[68:71]
	v_mfma_f32_16x16x32_bf16 v[116:119], v[144:147], v[168:171], v[116:119]
	v_mfma_f32_16x16x32_bf16 v[88:91], v[152:155], v[168:171], v[88:91]
	v_mfma_f32_16x16x32_bf16 v[108:111], v[144:147], v[176:179], v[108:111]
	v_mfma_f32_16x16x32_bf16 v[104:107], v[152:155], v[176:179], v[104:107]
	v_mfma_f32_16x16x32_bf16 v[92:95], v[144:147], v[248:251], v[92:95]
	v_mfma_f32_16x16x32_bf16 v[84:87], v[152:155], v[248:251], v[84:87]
	v_mfma_f32_16x16x32_bf16 v[124:127], v[148:151], v[164:167], v[124:127]
	v_mfma_f32_16x16x32_bf16 v[68:71], v[156:159], v[164:167], v[68:71]
	v_mfma_f32_16x16x32_bf16 v[116:119], v[148:151], v[172:175], v[116:119]
	v_mfma_f32_16x16x32_bf16 v[88:91], v[156:159], v[172:175], v[88:91]
	v_mfma_f32_16x16x32_bf16 v[108:111], v[148:151], v[180:183], v[108:111]
	v_mfma_f32_16x16x32_bf16 v[104:107], v[156:159], v[180:183], v[104:107]
	v_mfma_f32_16x16x32_bf16 v[92:95], v[148:151], v[252:255], v[92:95]
	v_mfma_f32_16x16x32_bf16 v[84:87], v[156:159], v[252:255], v[84:87]
	s_barrier
	s_setprio 0
	ds_read_b128 v[188:191], v143 offset:55296
	ds_read_b128 v[192:195], v143 offset:56320
	s_add_i32 s24, 0, 0x1c000
	s_add_i32 s25, s51, s35
	v_add_u32_e32 v187, s24, v142
	v_lshl_add_u64 v[138:139], v[138:139], 0, s[56:57]
	s_mov_b32 m0, s25
	ds_read_b128 v[202:205], v187
	ds_read_b128 v[206:209], v187 offset:1024
	ds_read_b128 v[210:213], v187 offset:2048
	ds_read_b128 v[214:217], v187 offset:3072
	global_load_lds_dwordx4 v[138:139], off
	v_lshl_add_u64 v[138:139], v[196:197], 0, s[56:57]
	s_add_i32 m0, s25, 0x2000
	s_nop 0
	global_load_lds_dwordx4 v[138:139], off
	s_setprio 1
	s_barrier
	s_waitcnt lgkmcnt(0)
	v_mfma_f32_16x16x32_bf16 v[120:123], v[202:205], v[160:163], v[120:123]
	v_mfma_f32_16x16x32_bf16 v[56:59], v[210:213], v[160:163], v[56:59]
	v_mfma_f32_16x16x32_bf16 v[112:115], v[202:205], v[168:171], v[112:115]
	v_mfma_f32_16x16x32_bf16 v[80:83], v[210:213], v[168:171], v[80:83]
	v_mfma_f32_16x16x32_bf16 v[100:103], v[202:205], v[176:179], v[100:103]
	v_mfma_f32_16x16x32_bf16 v[96:99], v[210:213], v[176:179], v[96:99]
	v_mfma_f32_16x16x32_bf16 v[76:79], v[202:205], v[248:251], v[76:79]
	v_mfma_f32_16x16x32_bf16 v[72:75], v[210:213], v[248:251], v[72:75]
	v_mfma_f32_16x16x32_bf16 v[120:123], v[206:209], v[164:167], v[120:123]
	v_mfma_f32_16x16x32_bf16 v[56:59], v[214:217], v[164:167], v[56:59]
	v_mfma_f32_16x16x32_bf16 v[112:115], v[206:209], v[172:175], v[112:115]
	v_mfma_f32_16x16x32_bf16 v[80:83], v[214:217], v[172:175], v[80:83]
	v_mfma_f32_16x16x32_bf16 v[100:103], v[206:209], v[180:183], v[100:103]
	v_mfma_f32_16x16x32_bf16 v[96:99], v[214:217], v[180:183], v[96:99]
	v_mfma_f32_16x16x32_bf16 v[76:79], v[206:209], v[252:255], v[76:79]
	v_mfma_f32_16x16x32_bf16 v[72:75], v[214:217], v[252:255], v[72:75]
	s_barrier
	s_setprio 0
	s_mov_b32 m0, s41
	v_lshl_add_u64 v[138:139], v[218:219], 0, s[56:57]
	ds_read_b128 v[160:163], v143 offset:49152
	ds_read_b128 v[164:167], v143 offset:50176
	ds_read_b128 v[168:171], v143 offset:51200
	ds_read_b128 v[172:175], v143 offset:52224
	ds_read_b128 v[176:179], v143 offset:53248
	ds_read_b128 v[180:183], v143 offset:54272
	global_load_lds_dwordx4 v[138:139], off
	v_lshl_add_u64 v[138:139], v[220:221], 0, s[56:57]
	s_mov_b32 m0, s42
	s_nop 0
	global_load_lds_dwordx4 v[138:139], off
	s_setprio 1
	s_waitcnt vmcnt(8)
	s_barrier
	s_waitcnt lgkmcnt(0)
	v_mfma_f32_16x16x32_bf16 v[64:67], v[144:147], v[160:163], v[64:67]
	v_mfma_f32_16x16x32_bf16 v[60:63], v[152:155], v[160:163], v[60:63]
	v_mfma_f32_16x16x32_bf16 v[44:47], v[144:147], v[168:171], v[44:47]
	v_mfma_f32_16x16x32_bf16 v[40:43], v[152:155], v[168:171], v[40:43]
	v_mfma_f32_16x16x32_bf16 v[28:31], v[144:147], v[176:179], v[28:31]
	v_mfma_f32_16x16x32_bf16 v[24:27], v[152:155], v[176:179], v[24:27]
	v_mfma_f32_16x16x32_bf16 v[12:15], v[144:147], v[188:191], v[12:15]
	v_mfma_f32_16x16x32_bf16 v[8:11], v[152:155], v[188:191], v[8:11]
	v_mfma_f32_16x16x32_bf16 v[64:67], v[148:151], v[164:167], v[64:67]
	v_mfma_f32_16x16x32_bf16 v[60:63], v[156:159], v[164:167], v[60:63]
	v_mfma_f32_16x16x32_bf16 v[44:47], v[148:151], v[172:175], v[44:47]
	v_mfma_f32_16x16x32_bf16 v[40:43], v[156:159], v[172:175], v[40:43]
	v_mfma_f32_16x16x32_bf16 v[28:31], v[148:151], v[180:183], v[28:31]
	v_mfma_f32_16x16x32_bf16 v[24:27], v[156:159], v[180:183], v[24:27]
	v_mfma_f32_16x16x32_bf16 v[12:15], v[148:151], v[192:195], v[12:15]
	v_mfma_f32_16x16x32_bf16 v[8:11], v[156:159], v[192:195], v[8:11]
	s_barrier
	s_setprio 0
	v_add_u32_e32 v156, 0x10000, v142
	ds_read_b128 v[144:147], v156
	ds_read_b128 v[148:151], v156 offset:1024
	ds_read_b128 v[152:155], v156 offset:2048
	ds_read_b128 v[156:159], v156 offset:3072
	ds_read_b128 v[248:251], v143 offset:6144
	ds_read_b128 v[252:255], v143 offset:7168
	s_add_u32 s4, s4, 0x80080
	s_addc_u32 s5, s5, 0
	s_add_i32 s24, s24, s35
	v_lshl_add_u64 v[138:139], s[4:5], 0, v[184:185]
	s_mov_b32 m0, s24
	s_nop 0
	global_load_lds_dwordx4 v[138:139], off
	v_lshl_add_u64 v[138:139], s[4:5], 0, v[132:133]
	s_add_i32 m0, s24, 0x2000
	s_nop 0
	global_load_lds_dwordx4 v[138:139], off
	s_waitcnt vmcnt(6)
	s_setprio 1
	s_barrier
	v_mfma_f32_16x16x32_bf16 v[52:55], v[202:205], v[160:163], v[52:55]
	v_mfma_f32_16x16x32_bf16 v[48:51], v[210:213], v[160:163], v[48:51]
	v_mfma_f32_16x16x32_bf16 v[36:39], v[202:205], v[168:171], v[36:39]
	v_mfma_f32_16x16x32_bf16 v[32:35], v[210:213], v[168:171], v[32:35]
	v_mfma_f32_16x16x32_bf16 v[20:23], v[202:205], v[176:179], v[20:23]
	v_mfma_f32_16x16x32_bf16 v[16:19], v[210:213], v[176:179], v[16:19]
	v_mfma_f32_16x16x32_bf16 v[4:7], v[202:205], v[188:191], v[4:7]
	v_mfma_f32_16x16x32_bf16 v[0:3], v[210:213], v[188:191], v[0:3]
	v_mfma_f32_16x16x32_bf16 v[52:55], v[206:209], v[164:167], v[52:55]
	v_mfma_f32_16x16x32_bf16 v[48:51], v[214:217], v[164:167], v[48:51]
	v_mfma_f32_16x16x32_bf16 v[36:39], v[206:209], v[172:175], v[36:39]
	v_mfma_f32_16x16x32_bf16 v[32:35], v[214:217], v[172:175], v[32:35]
	v_mfma_f32_16x16x32_bf16 v[20:23], v[206:209], v[180:183], v[20:23]
	v_mfma_f32_16x16x32_bf16 v[16:19], v[214:217], v[180:183], v[16:19]
	v_mfma_f32_16x16x32_bf16 v[4:7], v[206:209], v[192:195], v[4:7]
	v_mfma_f32_16x16x32_bf16 v[0:3], v[214:217], v[192:195], v[0:3]
	s_barrier
	s_setprio 0
	s_add_i32 s50, s50, 2
	s_add_u32 s0, s0, 0x100
	s_addc_u32 s1, s1, 0
	s_add_u32 s48, s48, 0x100
	s_addc_u32 s49, s49, 0
	s_cmp_gt_u32 s50, 29
	s_cbranch_scc0 .LBB0_334
	s_waitcnt lgkmcnt(0)
	v_mul_f32_e32 v148, 0x3d372713, v125
	v_fma_f32 v148, v125, v148, 1.0
	v_mul_f32_e32 v148, v125, v148
	v_mul_f32_e32 v139, 0x3d372713, v124
	v_mul_f32_e32 v148, 0xc0135761, v148
	v_fma_f32 v139, v124, v139, 1.0
	v_exp_f32_e32 v148, v148
	v_mul_f32_e32 v149, 0x3d372713, v126
	v_mul_f32_e32 v139, v124, v139
	v_fma_f32 v149, v126, v149, 1.0
	v_mul_f32_e32 v139, 0xc0135761, v139
	v_mul_f32_e32 v149, v126, v149
	v_exp_f32_e32 v145, v139
	v_mul_f32_e32 v149, 0xc0135761, v149
	v_exp_f32_e32 v149, v149
	v_add_f32_e32 v148, 1.0, v148
	v_mul_f32_e32 v150, 0x3d372713, v127
	v_rcp_f32_e32 v148, v148
	v_fma_f32 v150, v127, v150, 1.0
	v_mul_f32_e32 v150, v127, v150
	v_add_f32_e32 v145, 1.0, v145
	v_mul_f32_e32 v150, 0xc0135761, v150
	v_rcp_f32_e32 v145, v145
	v_add_f32_e32 v149, 1.0, v149
	v_exp_f32_e32 v150, v150
	v_rcp_f32_e32 v149, v149
	v_mul_f32_e32 v125, v125, v148
	v_mul_f32_e32 v148, 0x3d372713, v68
	v_fma_f32 v148, v68, v148, 1.0
	v_mul_f32_e32 v148, v68, v148
	v_mul_f32_e32 v124, v124, v145
	v_add_f32_e32 v145, 1.0, v150
	v_mul_f32_e32 v148, 0xc0135761, v148
	v_mul_f32_e32 v126, v126, v149
	v_rcp_f32_e32 v145, v145
	v_exp_f32_e32 v148, v148
	v_mul_f32_e32 v149, 0x3d372713, v69
	v_fma_f32 v149, v69, v149, 1.0
	v_mul_f32_e32 v149, v69, v149
	v_mul_f32_e32 v149, 0xc0135761, v149
	v_exp_f32_e32 v149, v149
	v_mul_f32_e32 v127, v127, v145
	v_add_f32_e32 v145, 1.0, v148
	v_rcp_f32_e32 v145, v145
	v_mov_b32_e32 v138, v141
	v_mov_b32_e32 v144, v140
	s_lshl_b32 s0, s2, 8
	v_add_f32_e32 v148, 1.0, v149
	s_add_i32 s0, s0, s39
	v_mul_f32_e32 v149, 0x3d372713, v70
	v_rcp_f32_e32 v148, v148
	v_mul_f32_e32 v145, v68, v145
	v_cvt_pk_bf16_f32 v68, v124, v125
	v_mul_f32_e32 v124, 0x3d372713, v120
	v_add_u32_e32 v146, s0, v144
	s_lshl_b32 s0, s45, 8
	v_fma_f32 v149, v70, v149, 1.0
	v_fma_f32 v124, v120, v124, 1.0
	s_or_b32 s0, s0, s40
	v_ashrrev_i32_e32 v147, 31, v146
	v_mul_f32_e32 v149, v70, v149
	v_mul_f32_e32 v124, v120, v124
	v_lshl_add_u32 v138, v138, 3, s0
	v_lshlrev_b64 v[146:147], 16, v[146:147]
	v_mul_f32_e32 v149, 0xc0135761, v149
	v_mul_f32_e32 v124, 0xc0135761, v124
	v_ashrrev_i32_e32 v139, 31, v138
	v_exp_f32_e32 v149, v149
	v_mul_f32_e32 v148, v69, v148
	v_cvt_pk_bf16_f32 v69, v126, v127
	v_exp_f32_e32 v126, v124
	v_lshl_add_u64 v[124:125], s[8:9], 0, v[146:147]
	v_lshl_add_u64 v[124:125], v[138:139], 1, v[124:125]
	v_mul_f32_e32 v127, 0x3d372713, v121
	v_mul_f32_e32 v139, 0x3d372713, v122
	v_fma_f32 v127, v121, v127, 1.0
	v_fma_f32 v139, v122, v139, 1.0
	v_mul_f32_e32 v127, v121, v127
	v_mul_f32_e32 v139, v122, v139
	v_add_f32_e32 v149, 1.0, v149
	v_mul_f32_e32 v127, 0xc0135761, v127
	v_mul_f32_e32 v139, 0xc0135761, v139
	v_rcp_f32_e32 v149, v149
	v_exp_f32_e32 v127, v127
	v_exp_f32_e32 v139, v139
	v_add_f32_e32 v126, 1.0, v126
	v_mul_f32_e32 v149, v70, v149
	v_cvt_pk_bf16_f32 v70, v145, v148
	v_add_f32_e32 v127, 1.0, v127
	v_add_f32_e32 v139, 1.0, v139
	v_mul_f32_e32 v145, 0x3d372713, v123
	v_rcp_f32_e32 v127, v127
	v_rcp_f32_e32 v139, v139
	v_fma_f32 v145, v123, v145, 1.0
	v_mul_f32_e32 v145, v123, v145
	v_mul_f32_e32 v145, 0xc0135761, v145
	v_rcp_f32_e32 v126, v126
	v_exp_f32_e32 v145, v145
	v_mul_f32_e32 v121, v121, v127
	v_mul_f32_e32 v122, v122, v139
	v_mul_f32_e32 v127, 0x3d372713, v56
	v_mul_f32_e32 v139, 0x3d372713, v57
	v_fma_f32 v127, v56, v127, 1.0
	v_fma_f32 v139, v57, v139, 1.0
	v_mul_f32_e32 v127, v56, v127
	v_mul_f32_e32 v139, v57, v139
	v_mul_f32_e32 v120, v120, v126
	v_add_f32_e32 v126, 1.0, v145
	v_mul_f32_e32 v127, 0xc0135761, v127
	v_mul_f32_e32 v139, 0xc0135761, v139
	v_mul_f32_e32 v150, 0x3d372713, v71
	v_rcp_f32_e32 v126, v126
	v_exp_f32_e32 v127, v127
	v_exp_f32_e32 v139, v139
	v_fma_f32 v150, v71, v150, 1.0
	v_mul_f32_e32 v150, v71, v150
	v_mul_f32_e32 v150, 0xc0135761, v150
	v_exp_f32_e32 v150, v150
	v_mul_f32_e32 v123, v123, v126
	v_add_f32_e32 v126, 1.0, v127
	v_add_f32_e32 v127, 1.0, v139
	v_mul_f32_e32 v139, 0x3d372713, v58
	v_fma_f32 v139, v58, v139, 1.0
	v_mul_f32_e32 v139, v58, v139
	v_mul_f32_e32 v139, 0xc0135761, v139
	v_add_f32_e32 v150, 1.0, v150
	v_exp_f32_e32 v139, v139
	v_rcp_f32_e32 v150, v150
	v_rcp_f32_e32 v126, v126
	v_rcp_f32_e32 v127, v127
	v_add_f32_e32 v139, 1.0, v139
	v_mul_f32_e32 v71, v71, v150
	v_rcp_f32_e32 v139, v139
	v_cvt_pk_bf16_f32 v71, v149, v71
	global_store_dwordx4 v[124:125], v[68:71], off
	v_mul_f32_e32 v126, v56, v126
	v_mul_f32_e32 v127, v57, v127
	v_cvt_pk_bf16_f32 v56, v120, v121
	v_cvt_pk_bf16_f32 v57, v122, v123
	v_mul_f32_e32 v121, 0x3d372713, v117
	v_mul_f32_e32 v122, 0x3d372713, v118
	v_fma_f32 v121, v117, v121, 1.0
	v_fma_f32 v122, v118, v122, 1.0
	v_mul_f32_e32 v121, v117, v121
	v_mul_f32_e32 v122, v118, v122
	v_mul_f32_e32 v139, v58, v139
	v_mul_f32_e32 v58, 0x3d372713, v116
	v_mul_f32_e32 v121, 0xc0135761, v121
	v_mul_f32_e32 v122, 0xc0135761, v122
	v_fma_f32 v58, v116, v58, 1.0
	v_exp_f32_e32 v121, v121
	v_exp_f32_e32 v122, v122
	v_mul_f32_e32 v58, v116, v58
	v_mul_f32_e32 v58, 0xc0135761, v58
	v_exp_f32_e32 v120, v58
	v_add_f32_e32 v121, 1.0, v121
	v_add_f32_e32 v122, 1.0, v122
	v_mul_f32_e32 v123, 0x3d372713, v119
	v_rcp_f32_e32 v121, v121
	v_rcp_f32_e32 v122, v122
	v_fma_f32 v123, v119, v123, 1.0
	v_mul_f32_e32 v123, v119, v123
	v_add_f32_e32 v120, 1.0, v120
	v_mul_f32_e32 v123, 0xc0135761, v123
	v_rcp_f32_e32 v120, v120
	v_exp_f32_e32 v123, v123
	v_mul_f32_e32 v117, v117, v121
	v_mul_f32_e32 v118, v118, v122
	v_mul_f32_e32 v121, 0x3d372713, v88
	v_mul_f32_e32 v122, 0x3d372713, v89
	v_fma_f32 v121, v88, v121, 1.0
	v_fma_f32 v122, v89, v122, 1.0
	v_mul_f32_e32 v121, v88, v121
	v_mul_f32_e32 v122, v89, v122
	v_mul_f32_e32 v145, 0x3d372713, v59
	v_mul_f32_e32 v116, v116, v120
	v_add_f32_e32 v120, 1.0, v123
	v_mul_f32_e32 v121, 0xc0135761, v121
	v_mul_f32_e32 v122, 0xc0135761, v122
	v_fma_f32 v145, v59, v145, 1.0
	v_rcp_f32_e32 v120, v120
	v_exp_f32_e32 v121, v121
	v_exp_f32_e32 v122, v122
	v_mul_f32_e32 v145, v59, v145
	v_mul_f32_e32 v145, 0xc0135761, v145
	v_exp_f32_e32 v145, v145
	v_mul_f32_e32 v119, v119, v120
	v_add_f32_e32 v120, 1.0, v121
	v_add_f32_e32 v121, 1.0, v122
	v_mul_f32_e32 v122, 0x3d372713, v90
	v_fma_f32 v122, v90, v122, 1.0
	v_mul_f32_e32 v122, v90, v122
	v_add_f32_e32 v145, 1.0, v145
	v_mul_f32_e32 v122, 0xc0135761, v122
	v_mul_f32_e32 v123, 0x3d372713, v91
	v_rcp_f32_e32 v145, v145
	v_exp_f32_e32 v122, v122
	v_fma_f32 v123, v91, v123, 1.0
	v_rcp_f32_e32 v120, v120
	v_mul_f32_e32 v123, v91, v123
	v_rcp_f32_e32 v121, v121
	v_mul_f32_e32 v123, 0xc0135761, v123
	v_exp_f32_e32 v123, v123
	v_mul_f32_e32 v59, v59, v145
	v_add_f32_e32 v122, 1.0, v122
	v_cvt_pk_bf16_f32 v58, v126, v127
	v_cvt_pk_bf16_f32 v59, v139, v59
	global_store_dwordx4 v[124:125], v[56:59], off offset:256
	v_rcp_f32_e32 v122, v122
	v_mul_f32_e32 v120, v88, v120
	v_mul_f32_e32 v121, v89, v121
	v_cvt_pk_bf16_f32 v88, v116, v117
	v_cvt_pk_bf16_f32 v89, v118, v119
	v_mul_f32_e32 v118, 0x3d372713, v112
	v_fma_f32 v118, v112, v118, 1.0
	v_add_f32_e32 v123, 1.0, v123
	v_mul_f32_e32 v118, v112, v118
	v_rcp_f32_e32 v123, v123
	v_mul_f32_e32 v118, 0xc0135761, v118
	v_mul_f32_e32 v122, v90, v122
	v_cvt_pk_bf16_f32 v90, v120, v121
	s_mov_b64 s[0:1], 0x100000
	v_exp_f32_e32 v120, v118
	v_lshl_add_u64 v[116:117], v[124:125], 0, s[0:1]
	s_mov_b32 s0, 0x100000
	v_add_co_u32_e32 v118, vcc, s0, v124
	v_mul_f32_e32 v91, v91, v123
	s_nop 0
	v_addc_co_u32_e32 v119, vcc, 0, v125, vcc
	v_cvt_pk_bf16_f32 v91, v122, v91
	global_store_dwordx4 v[118:119], v[88:91], off
	v_add_f32_e32 v118, 1.0, v120
	v_mul_f32_e32 v119, 0x3d372713, v113
	v_mul_f32_e32 v120, 0x3d372713, v114
	v_fma_f32 v119, v113, v119, 1.0
	v_fma_f32 v120, v114, v120, 1.0
	v_mul_f32_e32 v119, v113, v119
	v_mul_f32_e32 v120, v114, v120
	v_mul_f32_e32 v119, 0xc0135761, v119
	v_mul_f32_e32 v120, 0xc0135761, v120
	v_exp_f32_e32 v119, v119
	v_exp_f32_e32 v120, v120
	v_mul_f32_e32 v121, 0x3d372713, v115
	v_fma_f32 v121, v115, v121, 1.0
	v_add_f32_e32 v119, 1.0, v119
	v_add_f32_e32 v120, 1.0, v120
	v_rcp_f32_e32 v119, v119
	v_rcp_f32_e32 v120, v120
	v_mul_f32_e32 v121, v115, v121
	v_mul_f32_e32 v121, 0xc0135761, v121
	v_rcp_f32_e32 v118, v118
	v_exp_f32_e32 v121, v121
	v_mul_f32_e32 v113, v113, v119
	v_mul_f32_e32 v114, v114, v120
	v_mul_f32_e32 v119, 0x3d372713, v80
	v_mul_f32_e32 v120, 0x3d372713, v81
	v_fma_f32 v119, v80, v119, 1.0
	v_fma_f32 v120, v81, v120, 1.0
	v_mul_f32_e32 v119, v80, v119
	v_mul_f32_e32 v120, v81, v120
	v_mul_f32_e32 v112, v112, v118
	v_add_f32_e32 v118, 1.0, v121
	v_mul_f32_e32 v119, 0xc0135761, v119
	v_mul_f32_e32 v120, 0xc0135761, v120
	v_rcp_f32_e32 v118, v118
	v_exp_f32_e32 v119, v119
	v_exp_f32_e32 v120, v120
	v_mul_f32_e32 v121, 0x3d372713, v83
	v_mul_f32_e32 v115, v115, v118
	v_add_f32_e32 v118, 1.0, v119
	v_add_f32_e32 v119, 1.0, v120
	v_mul_f32_e32 v120, 0x3d372713, v82
	v_fma_f32 v120, v82, v120, 1.0
	v_mul_f32_e32 v120, v82, v120
	v_mul_f32_e32 v120, 0xc0135761, v120
	v_exp_f32_e32 v120, v120
	v_rcp_f32_e32 v118, v118
	v_rcp_f32_e32 v119, v119
	v_fma_f32 v121, v83, v121, 1.0
	v_add_f32_e32 v120, 1.0, v120
	v_rcp_f32_e32 v120, v120
	v_mul_f32_e32 v118, v80, v118
	v_mul_f32_e32 v119, v81, v119
	v_cvt_pk_bf16_f32 v80, v112, v113
	v_cvt_pk_bf16_f32 v81, v114, v115
	v_mul_f32_e32 v113, 0x3d372713, v109
	v_mul_f32_e32 v114, 0x3d372713, v110
	v_fma_f32 v113, v109, v113, 1.0
	v_fma_f32 v114, v110, v114, 1.0
	v_mul_f32_e32 v113, v109, v113
	v_mul_f32_e32 v114, v110, v114
	v_mul_f32_e32 v120, v82, v120
	v_mul_f32_e32 v82, 0x3d372713, v108
	v_mul_f32_e32 v113, 0xc0135761, v113
	v_mul_f32_e32 v114, 0xc0135761, v114
	v_fma_f32 v82, v108, v82, 1.0
	v_exp_f32_e32 v113, v113
	v_exp_f32_e32 v114, v114
	v_mul_f32_e32 v82, v108, v82
	v_mul_f32_e32 v82, 0xc0135761, v82
	v_exp_f32_e32 v112, v82
	v_add_f32_e32 v113, 1.0, v113
	v_add_f32_e32 v114, 1.0, v114
	v_mul_f32_e32 v115, 0x3d372713, v111
	v_rcp_f32_e32 v113, v113
	v_rcp_f32_e32 v114, v114
	v_fma_f32 v115, v111, v115, 1.0
	v_mul_f32_e32 v115, v111, v115
	v_add_f32_e32 v112, 1.0, v112
	v_mul_f32_e32 v115, 0xc0135761, v115
	v_rcp_f32_e32 v112, v112
	v_exp_f32_e32 v115, v115
	v_mul_f32_e32 v109, v109, v113
	v_mul_f32_e32 v110, v110, v114
	v_mul_f32_e32 v113, 0x3d372713, v104
	v_mul_f32_e32 v114, 0x3d372713, v105
	v_fma_f32 v113, v104, v113, 1.0
	v_fma_f32 v114, v105, v114, 1.0
	v_mul_f32_e32 v113, v104, v113
	v_mul_f32_e32 v114, v105, v114
	v_mul_f32_e32 v108, v108, v112
	v_add_f32_e32 v112, 1.0, v115
	v_mul_f32_e32 v113, 0xc0135761, v113
	v_mul_f32_e32 v114, 0xc0135761, v114
	v_rcp_f32_e32 v112, v112
	v_exp_f32_e32 v113, v113
	v_exp_f32_e32 v114, v114
	v_mul_f32_e32 v121, v83, v121
	v_mul_f32_e32 v121, 0xc0135761, v121
	v_exp_f32_e32 v121, v121
	v_mul_f32_e32 v111, v111, v112
	v_add_f32_e32 v112, 1.0, v113
	v_add_f32_e32 v113, 1.0, v114
	v_mul_f32_e32 v114, 0x3d372713, v106
	v_fma_f32 v114, v106, v114, 1.0
	v_mul_f32_e32 v114, v106, v114
	v_add_f32_e32 v121, 1.0, v121
	v_mul_f32_e32 v114, 0xc0135761, v114
	v_mul_f32_e32 v115, 0x3d372713, v107
	v_rcp_f32_e32 v121, v121
	v_exp_f32_e32 v114, v114
	v_fma_f32 v115, v107, v115, 1.0
	v_rcp_f32_e32 v112, v112
	v_mul_f32_e32 v115, v107, v115
	v_rcp_f32_e32 v113, v113
	v_mul_f32_e32 v115, 0xc0135761, v115
	v_exp_f32_e32 v115, v115
	v_mul_f32_e32 v83, v83, v121
	v_add_f32_e32 v114, 1.0, v114
	v_cvt_pk_bf16_f32 v82, v118, v119
	v_cvt_pk_bf16_f32 v83, v120, v83
	global_store_dwordx4 v[116:117], v[80:83], off offset:256
	v_rcp_f32_e32 v114, v114
	v_mul_f32_e32 v112, v104, v112
	v_mul_f32_e32 v113, v105, v113
	v_cvt_pk_bf16_f32 v104, v108, v109
	v_cvt_pk_bf16_f32 v105, v110, v111
	v_mul_f32_e32 v110, 0x3d372713, v100
	v_fma_f32 v110, v100, v110, 1.0
	v_add_f32_e32 v115, 1.0, v115
	v_mul_f32_e32 v110, v100, v110
	v_rcp_f32_e32 v115, v115
	v_mul_f32_e32 v110, 0xc0135761, v110
	v_mul_f32_e32 v114, v106, v114
	v_cvt_pk_bf16_f32 v106, v112, v113
	s_mov_b64 s[0:1], 0x200000
	v_exp_f32_e32 v112, v110
	v_lshl_add_u64 v[108:109], v[124:125], 0, s[0:1]
	s_mov_b32 s0, 0x200000
	v_add_co_u32_e32 v110, vcc, s0, v124
	v_mul_f32_e32 v107, v107, v115
	s_nop 0
	v_addc_co_u32_e32 v111, vcc, 0, v125, vcc
	v_cvt_pk_bf16_f32 v107, v114, v107
	global_store_dwordx4 v[110:111], v[104:107], off
	v_add_f32_e32 v110, 1.0, v112
	v_mul_f32_e32 v111, 0x3d372713, v101
	v_mul_f32_e32 v112, 0x3d372713, v102
	v_fma_f32 v111, v101, v111, 1.0
	v_fma_f32 v112, v102, v112, 1.0
	v_mul_f32_e32 v111, v101, v111
	v_mul_f32_e32 v112, v102, v112
	v_mul_f32_e32 v111, 0xc0135761, v111
	v_mul_f32_e32 v112, 0xc0135761, v112
	v_exp_f32_e32 v111, v111
	v_exp_f32_e32 v112, v112
	v_mul_f32_e32 v113, 0x3d372713, v103
	v_fma_f32 v113, v103, v113, 1.0
	v_add_f32_e32 v111, 1.0, v111
	v_add_f32_e32 v112, 1.0, v112
	v_rcp_f32_e32 v111, v111
	v_rcp_f32_e32 v112, v112
	v_mul_f32_e32 v113, v103, v113
	v_mul_f32_e32 v113, 0xc0135761, v113
	v_rcp_f32_e32 v110, v110
	v_exp_f32_e32 v113, v113
	v_mul_f32_e32 v101, v101, v111
	v_mul_f32_e32 v102, v102, v112
	v_mul_f32_e32 v111, 0x3d372713, v96
	v_mul_f32_e32 v112, 0x3d372713, v97
	v_fma_f32 v111, v96, v111, 1.0
	v_fma_f32 v112, v97, v112, 1.0
	v_mul_f32_e32 v111, v96, v111
	v_mul_f32_e32 v112, v97, v112
	v_mul_f32_e32 v100, v100, v110
	v_add_f32_e32 v110, 1.0, v113
	v_mul_f32_e32 v111, 0xc0135761, v111
	v_mul_f32_e32 v112, 0xc0135761, v112
	v_rcp_f32_e32 v110, v110
	v_exp_f32_e32 v111, v111
	v_exp_f32_e32 v112, v112
	v_mul_f32_e32 v113, 0x3d372713, v99
	v_mul_f32_e32 v103, v103, v110
	v_add_f32_e32 v110, 1.0, v111
	v_add_f32_e32 v111, 1.0, v112
	v_mul_f32_e32 v112, 0x3d372713, v98
	v_fma_f32 v112, v98, v112, 1.0
	v_mul_f32_e32 v112, v98, v112
	v_mul_f32_e32 v112, 0xc0135761, v112
	v_exp_f32_e32 v112, v112
	v_rcp_f32_e32 v110, v110
	v_rcp_f32_e32 v111, v111
	v_fma_f32 v113, v99, v113, 1.0
	v_add_f32_e32 v112, 1.0, v112
	v_rcp_f32_e32 v112, v112
	v_mul_f32_e32 v110, v96, v110
	v_mul_f32_e32 v111, v97, v111
	v_cvt_pk_bf16_f32 v96, v100, v101
	v_cvt_pk_bf16_f32 v97, v102, v103
	v_mul_f32_e32 v101, 0x3d372713, v93
	v_mul_f32_e32 v102, 0x3d372713, v94
	v_fma_f32 v101, v93, v101, 1.0
	v_fma_f32 v102, v94, v102, 1.0
	v_mul_f32_e32 v101, v93, v101
	v_mul_f32_e32 v102, v94, v102
	v_mul_f32_e32 v112, v98, v112
	v_mul_f32_e32 v98, 0x3d372713, v92
	v_mul_f32_e32 v101, 0xc0135761, v101
	v_mul_f32_e32 v102, 0xc0135761, v102
	v_fma_f32 v98, v92, v98, 1.0
	v_exp_f32_e32 v101, v101
	v_exp_f32_e32 v102, v102
	v_mul_f32_e32 v98, v92, v98
	v_mul_f32_e32 v98, 0xc0135761, v98
	v_exp_f32_e32 v100, v98
	v_add_f32_e32 v101, 1.0, v101
	v_add_f32_e32 v102, 1.0, v102
	v_mul_f32_e32 v103, 0x3d372713, v95
	v_rcp_f32_e32 v101, v101
	v_rcp_f32_e32 v102, v102
	v_fma_f32 v103, v95, v103, 1.0
	v_mul_f32_e32 v103, v95, v103
	v_add_f32_e32 v100, 1.0, v100
	v_mul_f32_e32 v103, 0xc0135761, v103
	v_rcp_f32_e32 v100, v100
	v_exp_f32_e32 v103, v103
	v_mul_f32_e32 v93, v93, v101
	v_mul_f32_e32 v94, v94, v102
	v_mul_f32_e32 v101, 0x3d372713, v84
	v_mul_f32_e32 v102, 0x3d372713, v85
	v_fma_f32 v101, v84, v101, 1.0
	v_fma_f32 v102, v85, v102, 1.0
	v_mul_f32_e32 v101, v84, v101
	v_mul_f32_e32 v102, v85, v102
	v_mul_f32_e32 v92, v92, v100
	v_add_f32_e32 v100, 1.0, v103
	v_mul_f32_e32 v101, 0xc0135761, v101
	v_mul_f32_e32 v102, 0xc0135761, v102
	v_rcp_f32_e32 v100, v100
	v_exp_f32_e32 v101, v101
	v_exp_f32_e32 v102, v102
	v_mul_f32_e32 v113, v99, v113
	v_mul_f32_e32 v113, 0xc0135761, v113
	v_exp_f32_e32 v113, v113
	v_mul_f32_e32 v95, v95, v100
	v_add_f32_e32 v100, 1.0, v101
	v_add_f32_e32 v101, 1.0, v102
	v_mul_f32_e32 v102, 0x3d372713, v86
	v_fma_f32 v102, v86, v102, 1.0
	v_mul_f32_e32 v102, v86, v102
	v_add_f32_e32 v113, 1.0, v113
	v_mul_f32_e32 v102, 0xc0135761, v102
	v_mul_f32_e32 v103, 0x3d372713, v87
	v_rcp_f32_e32 v113, v113
	v_exp_f32_e32 v102, v102
	v_fma_f32 v103, v87, v103, 1.0
	v_rcp_f32_e32 v100, v100
	v_mul_f32_e32 v103, v87, v103
	v_rcp_f32_e32 v101, v101
	v_mul_f32_e32 v103, 0xc0135761, v103
	v_exp_f32_e32 v103, v103
	v_mul_f32_e32 v99, v99, v113
	v_add_f32_e32 v102, 1.0, v102
	v_cvt_pk_bf16_f32 v98, v110, v111
	v_cvt_pk_bf16_f32 v99, v112, v99
	global_store_dwordx4 v[108:109], v[96:99], off offset:256
	v_rcp_f32_e32 v102, v102
	v_mul_f32_e32 v100, v84, v100
	v_mul_f32_e32 v101, v85, v101
	v_cvt_pk_bf16_f32 v84, v92, v93
	v_cvt_pk_bf16_f32 v85, v94, v95
	v_mul_f32_e32 v94, 0x3d372713, v76
	v_fma_f32 v94, v76, v94, 1.0
	v_add_f32_e32 v103, 1.0, v103
	v_mul_f32_e32 v94, v76, v94
	v_rcp_f32_e32 v103, v103
	v_mul_f32_e32 v94, 0xc0135761, v94
	v_mul_f32_e32 v102, v86, v102
	v_cvt_pk_bf16_f32 v86, v100, v101
	s_mov_b64 s[0:1], 0x300000
	v_exp_f32_e32 v100, v94
	v_lshl_add_u64 v[92:93], v[124:125], 0, s[0:1]
	s_mov_b32 s0, 0x300000
	v_add_co_u32_e32 v94, vcc, s0, v124
	v_mul_f32_e32 v87, v87, v103
	s_nop 0
	v_addc_co_u32_e32 v95, vcc, 0, v125, vcc
	v_cvt_pk_bf16_f32 v87, v102, v87
	global_store_dwordx4 v[94:95], v[84:87], off
	v_add_f32_e32 v94, 1.0, v100
	v_mul_f32_e32 v95, 0x3d372713, v77
	v_mul_f32_e32 v100, 0x3d372713, v78
	v_fma_f32 v95, v77, v95, 1.0
	v_fma_f32 v100, v78, v100, 1.0
	v_mul_f32_e32 v95, v77, v95
	v_mul_f32_e32 v100, v78, v100
	v_mul_f32_e32 v95, 0xc0135761, v95
	v_mul_f32_e32 v100, 0xc0135761, v100
	v_exp_f32_e32 v95, v95
	v_exp_f32_e32 v100, v100
	v_mul_f32_e32 v101, 0x3d372713, v79
	v_fma_f32 v101, v79, v101, 1.0
	v_add_f32_e32 v95, 1.0, v95
	v_add_f32_e32 v100, 1.0, v100
	v_rcp_f32_e32 v95, v95
	v_rcp_f32_e32 v100, v100
	v_mul_f32_e32 v101, v79, v101
	v_mul_f32_e32 v101, 0xc0135761, v101
	v_rcp_f32_e32 v94, v94
	v_exp_f32_e32 v101, v101
	v_mul_f32_e32 v77, v77, v95
	v_mul_f32_e32 v78, v78, v100
	v_mul_f32_e32 v95, 0x3d372713, v72
	v_mul_f32_e32 v100, 0x3d372713, v73
	v_fma_f32 v95, v72, v95, 1.0
	v_fma_f32 v100, v73, v100, 1.0
	v_mul_f32_e32 v95, v72, v95
	v_mul_f32_e32 v100, v73, v100
	v_mul_f32_e32 v76, v76, v94
	v_add_f32_e32 v94, 1.0, v101
	v_mul_f32_e32 v95, 0xc0135761, v95
	v_mul_f32_e32 v100, 0xc0135761, v100
	v_rcp_f32_e32 v94, v94
	v_exp_f32_e32 v95, v95
	v_exp_f32_e32 v100, v100
	v_mul_f32_e32 v101, 0x3d372713, v75
	v_mul_f32_e32 v79, v79, v94
	v_add_f32_e32 v94, 1.0, v95
	v_add_f32_e32 v95, 1.0, v100
	v_mul_f32_e32 v100, 0x3d372713, v74
	v_fma_f32 v100, v74, v100, 1.0
	v_mul_f32_e32 v100, v74, v100
	v_mul_f32_e32 v100, 0xc0135761, v100
	v_exp_f32_e32 v100, v100
	v_rcp_f32_e32 v94, v94
	v_rcp_f32_e32 v95, v95
	v_fma_f32 v101, v75, v101, 1.0
	v_add_f32_e32 v100, 1.0, v100
	v_rcp_f32_e32 v100, v100
	v_mul_f32_e32 v94, v72, v94
	v_mul_f32_e32 v95, v73, v95
	v_cvt_pk_bf16_f32 v72, v76, v77
	v_cvt_pk_bf16_f32 v73, v78, v79
	v_mul_f32_e32 v77, 0x3d372713, v65
	v_mul_f32_e32 v78, 0x3d372713, v66
	v_fma_f32 v77, v65, v77, 1.0
	v_fma_f32 v78, v66, v78, 1.0
	v_mul_f32_e32 v77, v65, v77
	v_mul_f32_e32 v78, v66, v78
	v_mul_f32_e32 v100, v74, v100
	v_mul_f32_e32 v74, 0x3d372713, v64
	v_mul_f32_e32 v77, 0xc0135761, v77
	v_mul_f32_e32 v78, 0xc0135761, v78
	v_fma_f32 v74, v64, v74, 1.0
	v_exp_f32_e32 v77, v77
	v_exp_f32_e32 v78, v78
	v_mul_f32_e32 v74, v64, v74
	v_mul_f32_e32 v74, 0xc0135761, v74
	v_exp_f32_e32 v76, v74
	v_add_f32_e32 v77, 1.0, v77
	v_add_f32_e32 v78, 1.0, v78
	v_mul_f32_e32 v79, 0x3d372713, v67
	v_rcp_f32_e32 v77, v77
	v_rcp_f32_e32 v78, v78
	v_fma_f32 v79, v67, v79, 1.0
	v_mul_f32_e32 v79, v67, v79
	v_add_f32_e32 v76, 1.0, v76
	v_mul_f32_e32 v79, 0xc0135761, v79
	v_rcp_f32_e32 v76, v76
	v_exp_f32_e32 v79, v79
	v_mul_f32_e32 v65, v65, v77
	v_mul_f32_e32 v66, v66, v78
	v_mul_f32_e32 v77, 0x3d372713, v60
	v_mul_f32_e32 v78, 0x3d372713, v61
	v_fma_f32 v77, v60, v77, 1.0
	v_fma_f32 v78, v61, v78, 1.0
	v_mul_f32_e32 v77, v60, v77
	v_mul_f32_e32 v78, v61, v78
	v_mul_f32_e32 v64, v64, v76
	v_add_f32_e32 v76, 1.0, v79
	v_mul_f32_e32 v77, 0xc0135761, v77
	v_mul_f32_e32 v78, 0xc0135761, v78
	v_rcp_f32_e32 v76, v76
	v_exp_f32_e32 v77, v77
	v_exp_f32_e32 v78, v78
	v_mul_f32_e32 v101, v75, v101
	v_mul_f32_e32 v101, 0xc0135761, v101
	v_exp_f32_e32 v101, v101
	v_mul_f32_e32 v67, v67, v76
	v_add_f32_e32 v76, 1.0, v77
	v_add_f32_e32 v77, 1.0, v78
	v_mul_f32_e32 v78, 0x3d372713, v62
	v_fma_f32 v78, v62, v78, 1.0
	v_mul_f32_e32 v78, v62, v78
	v_add_f32_e32 v101, 1.0, v101
	v_mul_f32_e32 v78, 0xc0135761, v78
	v_mul_f32_e32 v79, 0x3d372713, v63
	v_rcp_f32_e32 v101, v101
	v_exp_f32_e32 v78, v78
	v_fma_f32 v79, v63, v79, 1.0
	v_rcp_f32_e32 v76, v76
	v_mul_f32_e32 v79, v63, v79
	v_rcp_f32_e32 v77, v77
	v_mul_f32_e32 v79, 0xc0135761, v79
	v_exp_f32_e32 v79, v79
	v_mul_f32_e32 v75, v75, v101
	v_add_f32_e32 v78, 1.0, v78
	v_cvt_pk_bf16_f32 v74, v94, v95
	v_cvt_pk_bf16_f32 v75, v100, v75
	global_store_dwordx4 v[92:93], v[72:75], off offset:256
	v_rcp_f32_e32 v78, v78
	v_mul_f32_e32 v76, v60, v76
	v_mul_f32_e32 v77, v61, v77
	v_cvt_pk_bf16_f32 v60, v64, v65
	v_cvt_pk_bf16_f32 v61, v66, v67
	v_mul_f32_e32 v66, 0x3d372713, v52
	v_fma_f32 v66, v52, v66, 1.0
	v_add_f32_e32 v79, 1.0, v79
	v_mul_f32_e32 v66, v52, v66
	v_rcp_f32_e32 v79, v79
	v_mul_f32_e32 v66, 0xc0135761, v66
	v_mul_f32_e32 v78, v62, v78
	v_cvt_pk_bf16_f32 v62, v76, v77
	v_exp_f32_e32 v76, v66
	v_add_co_u32_e32 v66, vcc, s67, v124
	v_mul_f32_e32 v63, v63, v79
	s_nop 0
	v_addc_co_u32_e32 v67, vcc, 0, v125, vcc
	v_cvt_pk_bf16_f32 v63, v78, v63
	global_store_dwordx4 v[66:67], v[60:63], off
	v_add_f32_e32 v66, 1.0, v76
	v_mul_f32_e32 v67, 0x3d372713, v53
	v_mul_f32_e32 v76, 0x3d372713, v54
	v_fma_f32 v67, v53, v67, 1.0
	v_fma_f32 v76, v54, v76, 1.0
	v_mul_f32_e32 v67, v53, v67
	v_mul_f32_e32 v76, v54, v76
	v_mul_f32_e32 v67, 0xc0135761, v67
	v_mul_f32_e32 v76, 0xc0135761, v76
	v_exp_f32_e32 v67, v67
	v_exp_f32_e32 v76, v76
	v_mul_f32_e32 v77, 0x3d372713, v55
	v_fma_f32 v77, v55, v77, 1.0
	v_add_f32_e32 v67, 1.0, v67
	v_add_f32_e32 v76, 1.0, v76
	v_rcp_f32_e32 v67, v67
	v_rcp_f32_e32 v76, v76
	v_mul_f32_e32 v77, v55, v77
	v_mul_f32_e32 v77, 0xc0135761, v77
	v_rcp_f32_e32 v66, v66
	v_exp_f32_e32 v77, v77
	v_mul_f32_e32 v53, v53, v67
	v_mul_f32_e32 v54, v54, v76
	v_mul_f32_e32 v67, 0x3d372713, v48
	v_mul_f32_e32 v76, 0x3d372713, v49
	v_fma_f32 v67, v48, v67, 1.0
	v_fma_f32 v76, v49, v76, 1.0
	v_mul_f32_e32 v67, v48, v67
	v_mul_f32_e32 v76, v49, v76
	v_mul_f32_e32 v52, v52, v66
	v_add_f32_e32 v66, 1.0, v77
	v_mul_f32_e32 v67, 0xc0135761, v67
	v_mul_f32_e32 v76, 0xc0135761, v76
	v_rcp_f32_e32 v66, v66
	v_exp_f32_e32 v67, v67
	v_exp_f32_e32 v76, v76
	v_mul_f32_e32 v77, 0x3d372713, v51
	v_mul_f32_e32 v55, v55, v66
	v_add_f32_e32 v66, 1.0, v67
	v_add_f32_e32 v67, 1.0, v76
	v_mul_f32_e32 v76, 0x3d372713, v50
	v_fma_f32 v76, v50, v76, 1.0
	v_mul_f32_e32 v76, v50, v76
	v_mul_f32_e32 v76, 0xc0135761, v76
	v_exp_f32_e32 v76, v76
	v_rcp_f32_e32 v66, v66
	v_rcp_f32_e32 v67, v67
	v_fma_f32 v77, v51, v77, 1.0
	v_add_f32_e32 v76, 1.0, v76
	v_rcp_f32_e32 v76, v76
	v_mul_f32_e32 v66, v48, v66
	v_mul_f32_e32 v67, v49, v67
	v_cvt_pk_bf16_f32 v48, v52, v53
	v_cvt_pk_bf16_f32 v49, v54, v55
	v_mul_f32_e32 v53, 0x3d372713, v45
	v_mul_f32_e32 v54, 0x3d372713, v46
	v_fma_f32 v53, v45, v53, 1.0
	v_fma_f32 v54, v46, v54, 1.0
	v_mul_f32_e32 v53, v45, v53
	v_mul_f32_e32 v54, v46, v54
	v_mul_f32_e32 v76, v50, v76
	v_mul_f32_e32 v50, 0x3d372713, v44
	v_mul_f32_e32 v53, 0xc0135761, v53
	v_mul_f32_e32 v54, 0xc0135761, v54
	v_fma_f32 v50, v44, v50, 1.0
	v_exp_f32_e32 v53, v53
	v_exp_f32_e32 v54, v54
	v_mul_f32_e32 v50, v44, v50
	v_mul_f32_e32 v50, 0xc0135761, v50
	v_exp_f32_e32 v52, v50
	v_add_f32_e32 v53, 1.0, v53
	v_add_f32_e32 v54, 1.0, v54
	v_mul_f32_e32 v55, 0x3d372713, v47
	v_rcp_f32_e32 v53, v53
	v_rcp_f32_e32 v54, v54
	v_fma_f32 v55, v47, v55, 1.0
	v_mul_f32_e32 v55, v47, v55
	v_add_f32_e32 v52, 1.0, v52
	v_mul_f32_e32 v55, 0xc0135761, v55
	v_rcp_f32_e32 v52, v52
	v_exp_f32_e32 v55, v55
	v_mul_f32_e32 v45, v45, v53
	v_mul_f32_e32 v46, v46, v54
	v_mul_f32_e32 v53, 0x3d372713, v40
	v_mul_f32_e32 v54, 0x3d372713, v41
	v_fma_f32 v53, v40, v53, 1.0
	v_fma_f32 v54, v41, v54, 1.0
	v_mul_f32_e32 v53, v40, v53
	v_mul_f32_e32 v54, v41, v54
	v_mul_f32_e32 v44, v44, v52
	v_add_f32_e32 v52, 1.0, v55
	v_mul_f32_e32 v53, 0xc0135761, v53
	v_mul_f32_e32 v54, 0xc0135761, v54
	v_rcp_f32_e32 v52, v52
	v_exp_f32_e32 v53, v53
	v_exp_f32_e32 v54, v54
	v_mul_f32_e32 v77, v51, v77
	v_mul_f32_e32 v77, 0xc0135761, v77
	v_exp_f32_e32 v77, v77
	v_mul_f32_e32 v47, v47, v52
	v_add_f32_e32 v52, 1.0, v53
	v_add_f32_e32 v53, 1.0, v54
	v_mul_f32_e32 v54, 0x3d372713, v42
	v_fma_f32 v54, v42, v54, 1.0
	v_mul_f32_e32 v54, v42, v54
	v_add_f32_e32 v77, 1.0, v77
	v_mul_f32_e32 v54, 0xc0135761, v54
	v_mul_f32_e32 v55, 0x3d372713, v43
	v_rcp_f32_e32 v77, v77
	v_exp_f32_e32 v54, v54
	v_fma_f32 v55, v43, v55, 1.0
	v_rcp_f32_e32 v52, v52
	v_mul_f32_e32 v55, v43, v55
	v_rcp_f32_e32 v53, v53
	v_mul_f32_e32 v55, 0xc0135761, v55
	s_mov_b64 s[0:1], 0x800000
	v_exp_f32_e32 v55, v55
	v_lshl_add_u64 v[64:65], v[124:125], 0, s[0:1]
	v_mul_f32_e32 v51, v51, v77
	v_add_f32_e32 v54, 1.0, v54
	v_cvt_pk_bf16_f32 v50, v66, v67
	v_cvt_pk_bf16_f32 v51, v76, v51
	global_store_dwordx4 v[64:65], v[48:51], off offset:256
	v_rcp_f32_e32 v54, v54
	v_mul_f32_e32 v52, v40, v52
	v_mul_f32_e32 v53, v41, v53
	v_cvt_pk_bf16_f32 v40, v44, v45
	v_cvt_pk_bf16_f32 v41, v46, v47
	v_mul_f32_e32 v46, 0x3d372713, v36
	v_fma_f32 v46, v36, v46, 1.0
	v_add_f32_e32 v55, 1.0, v55
	v_mul_f32_e32 v46, v36, v46
	v_rcp_f32_e32 v55, v55
	v_mul_f32_e32 v46, 0xc0135761, v46
	v_mul_f32_e32 v54, v42, v54
	v_cvt_pk_bf16_f32 v42, v52, v53
	s_mov_b64 s[0:1], 0x900000
	v_exp_f32_e32 v52, v46
	v_lshl_add_u64 v[44:45], v[124:125], 0, s[0:1]
	s_mov_b32 s0, 0x900000
	v_add_co_u32_e32 v46, vcc, s0, v124
	v_mul_f32_e32 v43, v43, v55
	s_nop 0
	v_addc_co_u32_e32 v47, vcc, 0, v125, vcc
	v_cvt_pk_bf16_f32 v43, v54, v43
	global_store_dwordx4 v[46:47], v[40:43], off
	v_add_f32_e32 v46, 1.0, v52
	v_mul_f32_e32 v47, 0x3d372713, v37
	v_mul_f32_e32 v52, 0x3d372713, v38
	v_fma_f32 v47, v37, v47, 1.0
	v_fma_f32 v52, v38, v52, 1.0
	v_mul_f32_e32 v47, v37, v47
	v_mul_f32_e32 v52, v38, v52
	v_mul_f32_e32 v47, 0xc0135761, v47
	v_mul_f32_e32 v52, 0xc0135761, v52
	v_exp_f32_e32 v47, v47
	v_exp_f32_e32 v52, v52
	v_mul_f32_e32 v53, 0x3d372713, v39
	v_fma_f32 v53, v39, v53, 1.0
	v_add_f32_e32 v47, 1.0, v47
	v_add_f32_e32 v52, 1.0, v52
	v_rcp_f32_e32 v47, v47
	v_rcp_f32_e32 v52, v52
	v_mul_f32_e32 v53, v39, v53
	v_mul_f32_e32 v53, 0xc0135761, v53
	v_rcp_f32_e32 v46, v46
	v_exp_f32_e32 v53, v53
	v_mul_f32_e32 v37, v37, v47
	v_mul_f32_e32 v38, v38, v52
	v_mul_f32_e32 v47, 0x3d372713, v32
	v_mul_f32_e32 v52, 0x3d372713, v33
	v_fma_f32 v47, v32, v47, 1.0
	v_fma_f32 v52, v33, v52, 1.0
	v_mul_f32_e32 v47, v32, v47
	v_mul_f32_e32 v52, v33, v52
	v_mul_f32_e32 v36, v36, v46
	v_add_f32_e32 v46, 1.0, v53
	v_mul_f32_e32 v47, 0xc0135761, v47
	v_mul_f32_e32 v52, 0xc0135761, v52
	v_rcp_f32_e32 v46, v46
	v_exp_f32_e32 v47, v47
	v_exp_f32_e32 v52, v52
	v_mul_f32_e32 v53, 0x3d372713, v35
	v_mul_f32_e32 v39, v39, v46
	v_add_f32_e32 v46, 1.0, v47
	v_add_f32_e32 v47, 1.0, v52
	v_mul_f32_e32 v52, 0x3d372713, v34
	v_fma_f32 v52, v34, v52, 1.0
	v_mul_f32_e32 v52, v34, v52
	v_mul_f32_e32 v52, 0xc0135761, v52
	v_exp_f32_e32 v52, v52
	v_rcp_f32_e32 v46, v46
	v_rcp_f32_e32 v47, v47
	v_fma_f32 v53, v35, v53, 1.0
	v_add_f32_e32 v52, 1.0, v52
	v_rcp_f32_e32 v52, v52
	v_mul_f32_e32 v46, v32, v46
	v_mul_f32_e32 v47, v33, v47
	v_cvt_pk_bf16_f32 v32, v36, v37
	v_cvt_pk_bf16_f32 v33, v38, v39
	v_mul_f32_e32 v37, 0x3d372713, v29
	v_mul_f32_e32 v38, 0x3d372713, v30
	v_fma_f32 v37, v29, v37, 1.0
	v_fma_f32 v38, v30, v38, 1.0
	v_mul_f32_e32 v37, v29, v37
	v_mul_f32_e32 v38, v30, v38
	v_mul_f32_e32 v52, v34, v52
	v_mul_f32_e32 v34, 0x3d372713, v28
	v_mul_f32_e32 v37, 0xc0135761, v37
	v_mul_f32_e32 v38, 0xc0135761, v38
	v_fma_f32 v34, v28, v34, 1.0
	v_exp_f32_e32 v37, v37
	v_exp_f32_e32 v38, v38
	v_mul_f32_e32 v34, v28, v34
	v_mul_f32_e32 v34, 0xc0135761, v34
	v_exp_f32_e32 v36, v34
	v_add_f32_e32 v37, 1.0, v37
	v_add_f32_e32 v38, 1.0, v38
	v_mul_f32_e32 v39, 0x3d372713, v31
	v_rcp_f32_e32 v37, v37
	v_rcp_f32_e32 v38, v38
	v_fma_f32 v39, v31, v39, 1.0
	v_mul_f32_e32 v39, v31, v39
	v_add_f32_e32 v36, 1.0, v36
	v_mul_f32_e32 v39, 0xc0135761, v39
	v_rcp_f32_e32 v36, v36
	v_exp_f32_e32 v39, v39
	v_mul_f32_e32 v29, v29, v37
	v_mul_f32_e32 v30, v30, v38
	v_mul_f32_e32 v37, 0x3d372713, v24
	v_mul_f32_e32 v38, 0x3d372713, v25
	v_fma_f32 v37, v24, v37, 1.0
	v_fma_f32 v38, v25, v38, 1.0
	v_mul_f32_e32 v37, v24, v37
	v_mul_f32_e32 v38, v25, v38
	v_mul_f32_e32 v28, v28, v36
	v_add_f32_e32 v36, 1.0, v39
	v_mul_f32_e32 v37, 0xc0135761, v37
	v_mul_f32_e32 v38, 0xc0135761, v38
	v_rcp_f32_e32 v36, v36
	v_exp_f32_e32 v37, v37
	v_exp_f32_e32 v38, v38
	v_mul_f32_e32 v53, v35, v53
	v_mul_f32_e32 v53, 0xc0135761, v53
	v_exp_f32_e32 v53, v53
	v_mul_f32_e32 v31, v31, v36
	v_add_f32_e32 v36, 1.0, v37
	v_add_f32_e32 v37, 1.0, v38
	v_mul_f32_e32 v38, 0x3d372713, v26
	v_fma_f32 v38, v26, v38, 1.0
	v_mul_f32_e32 v38, v26, v38
	v_add_f32_e32 v53, 1.0, v53
	v_mul_f32_e32 v38, 0xc0135761, v38
	v_mul_f32_e32 v39, 0x3d372713, v27
	v_rcp_f32_e32 v53, v53
	v_exp_f32_e32 v38, v38
	v_fma_f32 v39, v27, v39, 1.0
	v_rcp_f32_e32 v36, v36
	v_mul_f32_e32 v39, v27, v39
	v_rcp_f32_e32 v37, v37
	v_mul_f32_e32 v39, 0xc0135761, v39
	v_exp_f32_e32 v39, v39
	v_mul_f32_e32 v35, v35, v53
	v_add_f32_e32 v38, 1.0, v38
	v_cvt_pk_bf16_f32 v34, v46, v47
	v_cvt_pk_bf16_f32 v35, v52, v35
	global_store_dwordx4 v[44:45], v[32:35], off offset:256
	v_rcp_f32_e32 v38, v38
	v_mul_f32_e32 v36, v24, v36
	v_mul_f32_e32 v37, v25, v37
	v_cvt_pk_bf16_f32 v24, v28, v29
	v_cvt_pk_bf16_f32 v25, v30, v31
	v_mul_f32_e32 v30, 0x3d372713, v20
	v_fma_f32 v30, v20, v30, 1.0
	v_add_f32_e32 v39, 1.0, v39
	v_mul_f32_e32 v30, v20, v30
	v_rcp_f32_e32 v39, v39
	v_mul_f32_e32 v30, 0xc0135761, v30
	v_mul_f32_e32 v38, v26, v38
	v_cvt_pk_bf16_f32 v26, v36, v37
	s_mov_b64 s[0:1], 0xa00000
	v_exp_f32_e32 v36, v30
	v_lshl_add_u64 v[28:29], v[124:125], 0, s[0:1]
	s_mov_b32 s0, 0xa00000
	v_add_co_u32_e32 v30, vcc, s0, v124
	v_mul_f32_e32 v27, v27, v39
	s_nop 0
	v_addc_co_u32_e32 v31, vcc, 0, v125, vcc
	v_cvt_pk_bf16_f32 v27, v38, v27
	global_store_dwordx4 v[30:31], v[24:27], off
	v_add_f32_e32 v30, 1.0, v36
	v_mul_f32_e32 v31, 0x3d372713, v21
	v_mul_f32_e32 v36, 0x3d372713, v22
	v_fma_f32 v31, v21, v31, 1.0
	v_fma_f32 v36, v22, v36, 1.0
	v_mul_f32_e32 v31, v21, v31
	v_mul_f32_e32 v36, v22, v36
	v_mul_f32_e32 v31, 0xc0135761, v31
	v_mul_f32_e32 v36, 0xc0135761, v36
	v_exp_f32_e32 v31, v31
	v_exp_f32_e32 v36, v36
	v_mul_f32_e32 v37, 0x3d372713, v23
	v_fma_f32 v37, v23, v37, 1.0
	v_add_f32_e32 v31, 1.0, v31
	v_add_f32_e32 v36, 1.0, v36
	v_rcp_f32_e32 v31, v31
	v_rcp_f32_e32 v36, v36
	v_mul_f32_e32 v37, v23, v37
	v_mul_f32_e32 v37, 0xc0135761, v37
	v_rcp_f32_e32 v30, v30
	v_exp_f32_e32 v37, v37
	v_mul_f32_e32 v21, v21, v31
	v_mul_f32_e32 v22, v22, v36
	v_mul_f32_e32 v31, 0x3d372713, v16
	v_mul_f32_e32 v36, 0x3d372713, v17
	v_fma_f32 v31, v16, v31, 1.0
	v_fma_f32 v36, v17, v36, 1.0
	v_mul_f32_e32 v31, v16, v31
	v_mul_f32_e32 v36, v17, v36
	v_mul_f32_e32 v20, v20, v30
	v_add_f32_e32 v30, 1.0, v37
	v_mul_f32_e32 v31, 0xc0135761, v31
	v_mul_f32_e32 v36, 0xc0135761, v36
	v_rcp_f32_e32 v30, v30
	v_exp_f32_e32 v31, v31
	v_exp_f32_e32 v36, v36
	v_mul_f32_e32 v37, 0x3d372713, v19
	v_mul_f32_e32 v23, v23, v30
	v_add_f32_e32 v30, 1.0, v31
	v_add_f32_e32 v31, 1.0, v36
	v_mul_f32_e32 v36, 0x3d372713, v18
	v_fma_f32 v36, v18, v36, 1.0
	v_mul_f32_e32 v36, v18, v36
	v_mul_f32_e32 v36, 0xc0135761, v36
	v_exp_f32_e32 v36, v36
	v_rcp_f32_e32 v30, v30
	v_rcp_f32_e32 v31, v31
	v_fma_f32 v37, v19, v37, 1.0
	v_add_f32_e32 v36, 1.0, v36
	v_rcp_f32_e32 v36, v36
	v_mul_f32_e32 v30, v16, v30
	v_mul_f32_e32 v31, v17, v31
	v_cvt_pk_bf16_f32 v16, v20, v21
	v_cvt_pk_bf16_f32 v17, v22, v23
	v_mul_f32_e32 v21, 0x3d372713, v13
	v_mul_f32_e32 v22, 0x3d372713, v14
	v_fma_f32 v21, v13, v21, 1.0
	v_fma_f32 v22, v14, v22, 1.0
	v_mul_f32_e32 v21, v13, v21
	v_mul_f32_e32 v22, v14, v22
	v_mul_f32_e32 v36, v18, v36
	v_mul_f32_e32 v18, 0x3d372713, v12
	v_mul_f32_e32 v21, 0xc0135761, v21
	v_mul_f32_e32 v22, 0xc0135761, v22
	v_fma_f32 v18, v12, v18, 1.0
	v_exp_f32_e32 v21, v21
	v_exp_f32_e32 v22, v22
	v_mul_f32_e32 v18, v12, v18
	v_mul_f32_e32 v18, 0xc0135761, v18
	v_exp_f32_e32 v20, v18
	v_add_f32_e32 v21, 1.0, v21
	v_add_f32_e32 v22, 1.0, v22
	v_mul_f32_e32 v23, 0x3d372713, v15
	v_rcp_f32_e32 v21, v21
	v_rcp_f32_e32 v22, v22
	v_fma_f32 v23, v15, v23, 1.0
	v_mul_f32_e32 v23, v15, v23
	v_add_f32_e32 v20, 1.0, v20
	v_mul_f32_e32 v23, 0xc0135761, v23
	v_rcp_f32_e32 v20, v20
	v_exp_f32_e32 v23, v23
	v_mul_f32_e32 v13, v13, v21
	v_mul_f32_e32 v14, v14, v22
	v_mul_f32_e32 v21, 0x3d372713, v8
	v_mul_f32_e32 v22, 0x3d372713, v9
	v_fma_f32 v21, v8, v21, 1.0
	v_fma_f32 v22, v9, v22, 1.0
	v_mul_f32_e32 v21, v8, v21
	v_mul_f32_e32 v22, v9, v22
	v_mul_f32_e32 v12, v12, v20
	v_add_f32_e32 v20, 1.0, v23
	v_mul_f32_e32 v21, 0xc0135761, v21
	v_mul_f32_e32 v22, 0xc0135761, v22
	v_rcp_f32_e32 v20, v20
	v_exp_f32_e32 v21, v21
	v_exp_f32_e32 v22, v22
	v_mul_f32_e32 v37, v19, v37
	v_mul_f32_e32 v37, 0xc0135761, v37
	v_exp_f32_e32 v37, v37
	v_mul_f32_e32 v15, v15, v20
	v_add_f32_e32 v20, 1.0, v21
	v_add_f32_e32 v21, 1.0, v22
	v_mul_f32_e32 v22, 0x3d372713, v10
	v_fma_f32 v22, v10, v22, 1.0
	v_mul_f32_e32 v22, v10, v22
	v_add_f32_e32 v37, 1.0, v37
	v_mul_f32_e32 v22, 0xc0135761, v22
	v_mul_f32_e32 v23, 0x3d372713, v11
	v_rcp_f32_e32 v37, v37
	v_exp_f32_e32 v22, v22
	v_fma_f32 v23, v11, v23, 1.0
	v_rcp_f32_e32 v20, v20
	v_mul_f32_e32 v23, v11, v23
	v_rcp_f32_e32 v21, v21
	v_mul_f32_e32 v23, 0xc0135761, v23
	v_exp_f32_e32 v23, v23
	v_mul_f32_e32 v19, v19, v37
	v_add_f32_e32 v22, 1.0, v22
	v_cvt_pk_bf16_f32 v18, v30, v31
	v_cvt_pk_bf16_f32 v19, v36, v19
	global_store_dwordx4 v[28:29], v[16:19], off offset:256
	v_rcp_f32_e32 v22, v22
	v_mul_f32_e32 v20, v8, v20
	v_mul_f32_e32 v21, v9, v21
	v_cvt_pk_bf16_f32 v8, v12, v13
	v_cvt_pk_bf16_f32 v9, v14, v15
	v_mul_f32_e32 v14, 0x3d372713, v4
	v_fma_f32 v14, v4, v14, 1.0
	v_add_f32_e32 v23, 1.0, v23
	v_mul_f32_e32 v14, v4, v14
	v_rcp_f32_e32 v23, v23
	v_mul_f32_e32 v14, 0xc0135761, v14
	v_mul_f32_e32 v22, v10, v22
	v_cvt_pk_bf16_f32 v10, v20, v21
	s_mov_b64 s[0:1], 0xb00000
	v_exp_f32_e32 v20, v14
	v_lshl_add_u64 v[12:13], v[124:125], 0, s[0:1]
	s_mov_b32 s0, 0xb00000
	v_add_co_u32_e32 v14, vcc, s0, v124
	v_mul_f32_e32 v11, v11, v23
	s_nop 0
	v_addc_co_u32_e32 v15, vcc, 0, v125, vcc
	v_cvt_pk_bf16_f32 v11, v22, v11
	global_store_dwordx4 v[14:15], v[8:11], off
	v_add_f32_e32 v14, 1.0, v20
	v_mul_f32_e32 v15, 0x3d372713, v5
	v_mul_f32_e32 v20, 0x3d372713, v6
	v_fma_f32 v15, v5, v15, 1.0
	v_fma_f32 v20, v6, v20, 1.0
	v_mul_f32_e32 v15, v5, v15
	v_mul_f32_e32 v20, v6, v20
	v_mul_f32_e32 v15, 0xc0135761, v15
	v_mul_f32_e32 v20, 0xc0135761, v20
	v_exp_f32_e32 v15, v15
	v_exp_f32_e32 v20, v20
	v_mul_f32_e32 v21, 0x3d372713, v7
	v_fma_f32 v21, v7, v21, 1.0
	v_add_f32_e32 v15, 1.0, v15
	v_add_f32_e32 v20, 1.0, v20
	v_rcp_f32_e32 v15, v15
	v_rcp_f32_e32 v20, v20
	v_mul_f32_e32 v21, v7, v21
	v_mul_f32_e32 v21, 0xc0135761, v21
	v_rcp_f32_e32 v14, v14
	v_exp_f32_e32 v21, v21
	v_mul_f32_e32 v5, v5, v15
	v_mul_f32_e32 v6, v6, v20
	v_mul_f32_e32 v15, 0x3d372713, v0
	v_mul_f32_e32 v20, 0x3d372713, v1
	v_fma_f32 v15, v0, v15, 1.0
	v_fma_f32 v20, v1, v20, 1.0
	v_mul_f32_e32 v15, v0, v15
	v_mul_f32_e32 v20, v1, v20
	v_mul_f32_e32 v4, v4, v14
	v_add_f32_e32 v14, 1.0, v21
	v_mul_f32_e32 v15, 0xc0135761, v15
	v_mul_f32_e32 v20, 0xc0135761, v20
	v_rcp_f32_e32 v14, v14
	v_exp_f32_e32 v15, v15
	v_exp_f32_e32 v20, v20
	v_mul_f32_e32 v21, 0x3d372713, v3
	v_mul_f32_e32 v7, v7, v14
	v_add_f32_e32 v14, 1.0, v15
	v_add_f32_e32 v15, 1.0, v20
	v_mul_f32_e32 v20, 0x3d372713, v2
	v_fma_f32 v21, v3, v21, 1.0
	v_fma_f32 v20, v2, v20, 1.0
	v_mul_f32_e32 v21, v3, v21
	v_mul_f32_e32 v20, v2, v20
	v_mul_f32_e32 v21, 0xc0135761, v21
	v_mul_f32_e32 v20, 0xc0135761, v20
	v_exp_f32_e32 v21, v21
	v_exp_f32_e32 v20, v20
	v_rcp_f32_e32 v14, v14
	v_rcp_f32_e32 v15, v15
	v_add_f32_e32 v21, 1.0, v21
	v_add_f32_e32 v20, 1.0, v20
	v_rcp_f32_e32 v21, v21
	v_rcp_f32_e32 v20, v20
	v_lshlrev_b32_e32 v46, 16, v88
	v_and_b32_e32 v47, 0xffff0000, v88
	v_mul_f32_e32 v14, v0, v14
	v_cvt_pk_bf16_f32 v0, v4, v5
	v_lshlrev_b32_e32 v64, 16, v68
	v_and_b32_e32 v65, 0xffff0000, v68
	v_pk_mul_f32 v[4:5], v[46:47], v[46:47]
	v_lshlrev_b32_e32 v52, 16, v104
	v_pk_fma_f32 v[4:5], v[64:65], v[64:65], v[4:5]
	v_and_b32_e32 v53, 0xffff0000, v104
	v_mul_f32_e32 v3, v3, v21
	v_pk_fma_f32 v[4:5], v[52:53], v[52:53], v[4:5]
	v_lshlrev_b32_e32 v44, 16, v84
	v_and_b32_e32 v45, 0xffff0000, v84
	v_mul_f32_e32 v15, v1, v15
	v_mul_f32_e32 v20, v2, v20
	v_cvt_pk_bf16_f32 v1, v6, v7
	v_cvt_pk_bf16_f32 v2, v14, v15
	v_cvt_pk_bf16_f32 v3, v20, v3
	global_store_dwordx4 v[12:13], v[0:3], off offset:256
	v_pk_fma_f32 v[12:13], v[44:45], v[44:45], v[4:5]
	v_and_b32_e32 v4, 0xffff0000, v60
	v_and_b32_e32 v5, 0xffff0000, v40
	v_pk_mul_f32 v[6:7], v[4:5], v[4:5]
	v_and_b32_e32 v28, 0xffff0000, v24
	v_and_b32_e32 v29, 0xffff0000, v8
	v_add_f32_e32 v6, v13, v6
	v_pk_mul_f32 v[30:31], v[28:29], v[28:29]
	v_add_f32_e32 v6, v6, v7
	v_add_f32_e32 v6, v6, v30
	v_lshlrev_b32_e32 v78, 16, v69
	v_and_b32_e32 v79, 0xffff0000, v69
	v_lshlrev_b32_e32 v68, 16, v89
	v_and_b32_e32 v69, 0xffff0000, v89
	v_add_f32_e32 v108, v6, v31
	v_pk_mul_f32 v[6:7], v[68:69], v[68:69]
	v_lshlrev_b32_e32 v76, 16, v105
	v_pk_fma_f32 v[6:7], v[78:79], v[78:79], v[6:7]
	v_and_b32_e32 v77, 0xffff0000, v105
	v_pk_fma_f32 v[6:7], v[76:77], v[76:77], v[6:7]
	v_lshlrev_b32_e32 v66, 16, v85
	v_and_b32_e32 v67, 0xffff0000, v85
	v_lshlrev_b32_e32 v38, 16, v61
	v_lshlrev_b32_e32 v39, 16, v41
	v_lshlrev_b32_e32 v20, 16, v40
	v_pk_fma_f32 v[54:55], v[66:67], v[66:67], v[6:7]
	v_and_b32_e32 v7, 0xffff0000, v41
	v_pk_mul_f32 v[40:41], v[38:39], v[38:39]
	v_and_b32_e32 v6, 0xffff0000, v61
	v_lshlrev_b32_e32 v36, 16, v25
	v_lshlrev_b32_e32 v37, 16, v9
	v_add_f32_e32 v13, v54, v40
	v_lshlrev_b32_e32 v14, 16, v60
	v_lshlrev_b32_e32 v22, 16, v24
	v_lshlrev_b32_e32 v24, 16, v8
	v_pk_mul_f32 v[60:61], v[6:7], v[6:7]
	v_and_b32_e32 v31, 0xffff0000, v9
	v_pk_mul_f32 v[8:9], v[36:37], v[36:37]
	v_add_f32_e32 v13, v13, v41
	v_and_b32_e32 v30, 0xffff0000, v25
	v_add_f32_e32 v8, v13, v8
	v_add_f32_e32 v13, v55, v60
	v_add_f32_e32 v105, v8, v9
	v_pk_mul_f32 v[8:9], v[30:31], v[30:31]
	v_add_f32_e32 v13, v13, v61
	v_add_f32_e32 v8, v13, v8
	v_lshlrev_b32_e32 v88, 16, v90
	v_and_b32_e32 v89, 0xffff0000, v90
	v_add_f32_e32 v104, v8, v9
	v_lshlrev_b32_e32 v94, 16, v70
	v_and_b32_e32 v95, 0xffff0000, v70
	v_pk_mul_f32 v[8:9], v[88:89], v[88:89]
	v_lshlrev_b32_e32 v92, 16, v106
	v_pk_fma_f32 v[8:9], v[94:95], v[94:95], v[8:9]
	v_and_b32_e32 v93, 0xffff0000, v106
	v_pk_fma_f32 v[8:9], v[92:93], v[92:93], v[8:9]
	v_lshlrev_b32_e32 v84, 16, v86
	v_and_b32_e32 v85, 0xffff0000, v86
	v_lshlrev_b32_e32 v60, 16, v62
	v_lshlrev_b32_e32 v61, 16, v42
	v_pk_fma_f32 v[110:111], v[84:85], v[84:85], v[8:9]
	v_pk_mul_f32 v[102:103], v[60:61], v[60:61]
	v_lshlrev_b32_e32 v54, 16, v26
	v_lshlrev_b32_e32 v55, 16, v10
	v_and_b32_e32 v41, 0xffff0000, v10
	v_add_f32_e32 v10, v110, v102
	v_and_b32_e32 v8, 0xffff0000, v62
	v_and_b32_e32 v9, 0xffff0000, v42
	v_pk_mul_f32 v[114:115], v[54:55], v[54:55]
	v_add_f32_e32 v10, v10, v103
	v_pk_mul_f32 v[112:113], v[8:9], v[8:9]
	v_add_f32_e32 v10, v10, v114
	v_add_f32_e32 v103, v10, v115
	v_add_f32_e32 v10, v111, v112
	v_and_b32_e32 v40, 0xffff0000, v26
	v_add_f32_e32 v10, v10, v113
	v_lshlrev_b32_e32 v112, 16, v91
	v_and_b32_e32 v113, 0xffff0000, v91
	v_pk_mul_f32 v[114:115], v[40:41], v[40:41]
	v_lshlrev_b32_e32 v110, 16, v71
	v_and_b32_e32 v111, 0xffff0000, v71
	v_pk_mul_f32 v[70:71], v[112:113], v[112:113]
	v_add_f32_e32 v10, v10, v114
	v_pk_fma_f32 v[70:71], v[110:111], v[110:111], v[70:71]
	v_lshlrev_b32_e32 v106, 16, v107
	v_and_b32_e32 v107, 0xffff0000, v107
	v_add_f32_e32 v102, v10, v115
	v_pk_fma_f32 v[70:71], v[106:107], v[106:107], v[70:71]
	v_lshlrev_b32_e32 v114, 16, v87
	v_and_b32_e32 v115, 0xffff0000, v87
	v_lshlrev_b32_e32 v86, 16, v63
	v_lshlrev_b32_e32 v87, 16, v43
	v_pk_fma_f32 v[90:91], v[114:115], v[114:115], v[70:71]
	v_and_b32_e32 v71, 0xffff0000, v43
	v_pk_mul_f32 v[42:43], v[86:87], v[86:87]
	v_lshlrev_b32_e32 v26, 16, v27
	v_and_b32_e32 v10, 0xffff0000, v27
	v_lshlrev_b32_e32 v27, 16, v11
	v_add_f32_e32 v13, v90, v42
	v_and_b32_e32 v70, 0xffff0000, v63
	v_pk_mul_f32 v[116:117], v[26:27], v[26:27]
	v_add_f32_e32 v13, v13, v43
	v_pk_mul_f32 v[62:63], v[70:71], v[70:71]
	v_add_f32_e32 v13, v13, v116
	v_and_b32_e32 v11, 0xffff0000, v11
	v_add_f32_e32 v101, v13, v117
	v_add_f32_e32 v13, v91, v62
	v_pk_mul_f32 v[42:43], v[10:11], v[10:11]
	v_add_f32_e32 v13, v13, v63
	v_add_f32_e32 v13, v13, v42
	v_lshlrev_b32_e32 v118, 16, v80
	v_and_b32_e32 v119, 0xffff0000, v80
	v_add_f32_e32 v13, v13, v43
	v_lshlrev_b32_e32 v116, 16, v56
	v_and_b32_e32 v117, 0xffff0000, v56
	v_pk_mul_f32 v[42:43], v[118:119], v[118:119]
	v_lshlrev_b32_e32 v120, 16, v96
	v_pk_fma_f32 v[42:43], v[116:117], v[116:117], v[42:43]
	v_and_b32_e32 v121, 0xffff0000, v96
	v_pk_fma_f32 v[42:43], v[120:121], v[120:121], v[42:43]
	v_lshlrev_b32_e32 v122, 16, v72
	v_and_b32_e32 v123, 0xffff0000, v72
	v_and_b32_e32 v124, 0xffff0000, v48
	v_and_b32_e32 v125, 0xffff0000, v32
	v_pk_fma_f32 v[42:43], v[122:123], v[122:123], v[42:43]
	v_pk_mul_f32 v[126:127], v[124:125], v[124:125]
	v_and_b32_e32 v90, 0xffff0000, v16
	v_lshlrev_b32_e32 v62, 16, v0
	v_and_b32_e32 v91, 0xffff0000, v0
	v_add_f32_e32 v0, v43, v126
	v_pk_mul_f32 v[146:147], v[90:91], v[90:91]
	v_add_f32_e32 v0, v0, v127
	v_add_f32_e32 v0, v0, v146
	v_lshlrev_b32_e32 v80, 16, v81
	v_and_b32_e32 v81, 0xffff0000, v81
	v_add_f32_e32 v109, v0, v147
	v_lshlrev_b32_e32 v126, 16, v57
	v_and_b32_e32 v127, 0xffff0000, v57
	v_pk_mul_f32 v[146:147], v[80:81], v[80:81]
	v_lshlrev_b32_e32 v96, 16, v97
	v_pk_fma_f32 v[146:147], v[126:127], v[126:127], v[146:147]
	v_and_b32_e32 v97, 0xffff0000, v97
	v_pk_fma_f32 v[146:147], v[96:97], v[96:97], v[146:147]
	v_lshlrev_b32_e32 v148, 16, v73
	v_and_b32_e32 v149, 0xffff0000, v73
	v_pk_fma_f32 v[72:73], v[148:149], v[148:149], v[146:147]
	v_lshlrev_b32_e32 v146, 16, v49
	v_lshlrev_b32_e32 v147, 16, v33
	v_pk_mul_f32 v[152:153], v[146:147], v[146:147]
	v_lshlrev_b32_e32 v56, 16, v48
	v_lshlrev_b32_e32 v48, 16, v32
	v_lshlrev_b32_e32 v32, 16, v16
	v_lshlrev_b32_e32 v16, 16, v17
	v_and_b32_e32 v0, 0xffff0000, v17
	v_lshlrev_b32_e32 v17, 16, v1
	v_add_f32_e32 v15, v72, v152
	v_and_b32_e32 v150, 0xffff0000, v49
	v_and_b32_e32 v151, 0xffff0000, v33
	v_pk_mul_f32 v[156:157], v[16:17], v[16:17]
	v_add_f32_e32 v15, v15, v153
	v_pk_mul_f32 v[154:155], v[150:151], v[150:151]
	v_add_f32_e32 v15, v15, v156
	v_and_b32_e32 v1, 0xffff0000, v1
	v_add_f32_e32 v139, v15, v157
	v_add_f32_e32 v15, v73, v154
	v_pk_mul_f32 v[152:153], v[0:1], v[0:1]
	v_add_f32_e32 v15, v15, v155
	v_add_f32_e32 v15, v15, v152
	v_lshlrev_b32_e32 v154, 16, v82
	v_and_b32_e32 v155, 0xffff0000, v82
	v_add_f32_e32 v72, v15, v153
	v_lshlrev_b32_e32 v152, 16, v58
	v_and_b32_e32 v153, 0xffff0000, v58
	v_pk_mul_f32 v[156:157], v[154:155], v[154:155]
	v_lshlrev_b32_e32 v158, 16, v98
	v_pk_fma_f32 v[156:157], v[152:153], v[152:153], v[156:157]
	v_and_b32_e32 v159, 0xffff0000, v98
	v_pk_fma_f32 v[156:157], v[158:159], v[158:159], v[156:157]
	v_lshlrev_b32_e32 v160, 16, v74
	v_and_b32_e32 v161, 0xffff0000, v74
	v_lshlrev_b32_e32 v162, 16, v50
	v_lshlrev_b32_e32 v163, 16, v34
	v_pk_fma_f32 v[156:157], v[160:161], v[160:161], v[156:157]
	v_pk_mul_f32 v[166:167], v[162:163], v[162:163]
	v_lshlrev_b32_e32 v170, 16, v18
	v_lshlrev_b32_e32 v171, 16, v2
	v_and_b32_e32 v173, 0xffff0000, v2
	v_add_f32_e32 v2, v156, v166
	v_and_b32_e32 v164, 0xffff0000, v50
	v_and_b32_e32 v165, 0xffff0000, v34
	v_pk_mul_f32 v[174:175], v[170:171], v[170:171]
	v_add_f32_e32 v2, v2, v167
	v_pk_mul_f32 v[168:169], v[164:165], v[164:165]
	v_add_f32_e32 v2, v2, v174
	v_and_b32_e32 v172, 0xffff0000, v18
	v_add_f32_e32 v50, v2, v175
	v_add_f32_e32 v2, v157, v168
	v_lshlrev_b32_e32 v82, 16, v83
	v_and_b32_e32 v83, 0xffff0000, v83
	v_pk_mul_f32 v[166:167], v[172:173], v[172:173]
	v_add_f32_e32 v2, v2, v169
	v_lshlrev_b32_e32 v58, 16, v59
	v_and_b32_e32 v59, 0xffff0000, v59
	v_pk_mul_f32 v[156:157], v[82:83], v[82:83]
	v_add_f32_e32 v2, v2, v166
	v_pk_fma_f32 v[156:157], v[58:59], v[58:59], v[156:157]
	v_lshlrev_b32_e32 v98, 16, v99
	v_and_b32_e32 v99, 0xffff0000, v99
	v_add_f32_e32 v43, v2, v167
	v_pk_fma_f32 v[156:157], v[98:99], v[98:99], v[156:157]
	v_lshlrev_b32_e32 v74, 16, v75
	v_and_b32_e32 v75, 0xffff0000, v75
	v_lshlrev_b32_e32 v166, 16, v51
	v_lshlrev_b32_e32 v167, 16, v35
	v_pk_fma_f32 v[156:157], v[74:75], v[74:75], v[156:157]
	v_and_b32_e32 v169, 0xffff0000, v35
	v_pk_mul_f32 v[34:35], v[166:167], v[166:167]
	v_lshlrev_b32_e32 v18, 16, v19
	v_and_b32_e32 v2, 0xffff0000, v19
	v_lshlrev_b32_e32 v19, 16, v3
	v_add_f32_e32 v15, v156, v34
	v_and_b32_e32 v168, 0xffff0000, v51
	v_pk_mul_f32 v[176:177], v[18:19], v[18:19]
	v_add_f32_e32 v15, v15, v35
	v_pk_mul_f32 v[174:175], v[168:169], v[168:169]
	v_add_f32_e32 v15, v15, v176
	v_and_b32_e32 v3, 0xffff0000, v3
	v_add_f32_e32 v35, v15, v177
	v_add_f32_e32 v15, v157, v174
	v_pk_add_f32 v[64:65], v[64:65], 0 op_sel_hi:[1,0]
	v_pk_mul_f32 v[176:177], v[2:3], v[2:3]
	v_add_f32_e32 v15, v15, v175
	v_pk_add_f32 v[78:79], v[78:79], 0 op_sel_hi:[1,0]
	v_pk_add_f32 v[46:47], v[64:65], v[46:47]
	v_add_f32_e32 v15, v15, v176
	v_pk_add_f32 v[94:95], v[94:95], 0 op_sel_hi:[1,0]
	v_pk_add_f32 v[68:69], v[78:79], v[68:69]
	v_pk_add_f32 v[46:47], v[46:47], v[52:53]
	v_add_f32_e32 v34, v15, v177
	v_pk_add_f32 v[110:111], v[110:111], 0 op_sel_hi:[1,0]
	v_pk_add_f32 v[88:89], v[94:95], v[88:89]
	v_pk_add_f32 v[52:53], v[68:69], v[76:77]
	v_pk_add_f32 v[44:45], v[46:47], v[44:45]
	v_mov_b32_e32 v15, v4
	v_pk_add_f32 v[116:117], v[116:117], 0 op_sel_hi:[1,0]
	v_pk_add_f32 v[126:127], v[126:127], 0 op_sel_hi:[1,0]
	v_pk_add_f32 v[110:111], v[110:111], v[112:113]
	v_pk_add_f32 v[64:65], v[88:89], v[92:93]
	v_pk_add_f32 v[52:53], v[52:53], v[66:67]
	v_pk_add_f32 v[44:45], v[44:45], v[14:15]
	v_mov_b32_e32 v46, v38
	v_mov_b32_e32 v47, v6
	v_mov_b32_e32 v21, v5
	v_pk_add_f32 v[80:81], v[126:127], v[80:81]
	v_pk_add_f32 v[116:117], v[116:117], v[118:119]
	v_pk_add_f32 v[68:69], v[110:111], v[106:107]
	v_pk_add_f32 v[64:65], v[64:65], v[84:85]
	v_pk_add_f32 v[46:47], v[52:53], v[46:47]
	v_mov_b32_e32 v52, v60
	v_mov_b32_e32 v53, v8
	v_mov_b32_e32 v6, v39
	v_pk_add_f32 v[4:5], v[44:45], v[20:21]
	v_mov_b32_e32 v23, v28
	v_pk_add_f32 v[76:77], v[116:117], v[120:121]
	v_pk_add_f32 v[78:79], v[80:81], v[96:97]
	v_pk_add_f32 v[68:69], v[68:69], v[114:115]
	v_pk_add_f32 v[52:53], v[64:65], v[52:53]
	v_mov_b32_e32 v64, v86
	v_mov_b32_e32 v65, v70
	v_mov_b32_e32 v8, v61
	v_pk_add_f32 v[6:7], v[46:47], v[6:7]
	v_pk_add_f32 v[38:39], v[4:5], v[22:23]
	v_mov_b32_e32 v4, v36
	v_mov_b32_e32 v5, v30
	v_pk_add_f32 v[78:79], v[78:79], v[148:149]
	v_pk_add_f32 v[76:77], v[76:77], v[122:123]
	v_pk_add_f32 v[64:65], v[68:69], v[64:65]
	v_mov_b32_e32 v57, v124
	v_mov_b32_e32 v68, v146
	v_mov_b32_e32 v69, v150
	v_mov_b32_e32 v70, v87
	v_pk_add_f32 v[8:9], v[52:53], v[8:9]
	v_pk_add_f32 v[44:45], v[6:7], v[4:5]
	v_mov_b32_e32 v4, v54
	v_mov_b32_e32 v5, v40
	v_pk_add_f32 v[66:67], v[76:77], v[56:57]
	v_pk_add_f32 v[68:69], v[78:79], v[68:69]
	v_mov_b32_e32 v150, v147
	v_mov_b32_e32 v49, v125
	v_pk_add_f32 v[64:65], v[64:65], v[70:71]
	v_pk_add_f32 v[46:47], v[8:9], v[4:5]
	v_mov_b32_e32 v4, v26
	v_mov_b32_e32 v5, v10
	v_mov_b32_e32 v57, v48
	v_pk_add_f32 v[68:69], v[68:69], v[150:151]
	v_pk_add_f32 v[66:67], v[66:67], v[48:49]
	v_pk_add_f32 v[52:53], v[64:65], v[4:5]
	v_mov_b32_e32 v33, v90
	v_mov_b32_e32 v4, v16
	v_mov_b32_e32 v5, v0
	v_mov_b32_e32 v25, v29
	v_pk_mul_f32 v[28:29], v[56:57], v[56:57]
	v_pk_add_f32 v[8:9], v[66:67], v[32:33]
	v_pk_add_f32 v[6:7], v[68:69], v[4:5]
	v_mov_b32_e32 v0, v17
	v_mov_b32_e32 v33, v62
	v_add_f32_e32 v15, v42, v28
	v_pk_add_f32 v[6:7], v[6:7], v[0:1]
	v_pk_mul_f32 v[0:1], v[32:33], v[32:33]
	v_add_f32_e32 v15, v15, v29
	v_add_f32_e32 v0, v15, v0
	v_mov_b32_e32 v15, v20
	v_pk_mul_f32 v[14:15], v[14:15], v[14:15]
	v_mov_b32_e32 v23, v24
	v_add_f32_e32 v12, v12, v14
	v_add_f32_e32 v21, v0, v1
	v_pk_mul_f32 v[0:1], v[22:23], v[22:23]
	v_add_f32_e32 v12, v12, v15
	v_add_f32_e32 v0, v12, v0
	v_add_f32_e32 v0, v0, v1
	v_bitop3_b32 v1, v144, 8, v144 bitop3:0xc
	v_mov_b32_e32 v10, v27
	v_mov_b32_e32 v30, v37
	v_pk_add_f32 v[26:27], v[38:39], v[24:25]
	v_cmp_eq_u32_e32 vcc, 1, v1
	v_mov_b32_e32 v60, v18
	v_mov_b32_e32 v61, v2
	v_mov_b32_e32 v2, v19
	v_pk_add_f32 v[18:19], v[44:45], v[30:31]
	v_cndmask_b32_e32 v12, v26, v27, vcc
	v_cmp_eq_u32_e32 vcc, 2, v1
	v_mov_b32_e32 v40, v55
	v_pk_add_f32 v[16:17], v[46:47], v[40:41]
	v_cndmask_b32_e32 v12, v12, v18, vcc
	v_cmp_eq_u32_e32 vcc, 3, v1
	v_pk_add_f32 v[152:153], v[152:153], 0 op_sel_hi:[1,0]
	v_pk_add_f32 v[58:59], v[58:59], 0 op_sel_hi:[1,0]
	v_cndmask_b32_e32 v12, v12, v19, vcc
	v_cmp_eq_u32_e32 vcc, 4, v1
	v_pk_add_f32 v[58:59], v[58:59], v[82:83]
	v_pk_add_f32 v[82:83], v[152:153], v[154:155]
	v_cndmask_b32_e32 v12, v12, v16, vcc
	v_cmp_eq_u32_e32 vcc, 5, v1
	v_pk_add_f32 v[10:11], v[52:53], v[10:11]
	v_pk_add_f32 v[80:81], v[82:83], v[158:159]
	v_cndmask_b32_e32 v12, v12, v17, vcc
	v_cmp_eq_u32_e32 vcc, 6, v1
	v_pk_add_f32 v[58:59], v[58:59], v[98:99]
	v_mov_b32_e32 v63, v91
	v_cndmask_b32_e32 v12, v12, v10, vcc
	v_cmp_eq_u32_e32 vcc, 7, v1
	v_pk_add_f32 v[58:59], v[58:59], v[74:75]
	v_pk_add_f32 v[74:75], v[80:81], v[160:161]
	v_mov_b32_e32 v76, v162
	v_mov_b32_e32 v77, v164
	v_pk_add_f32 v[8:9], v[8:9], v[62:63]
	v_cndmask_b32_e32 v12, v12, v11, vcc
	v_cmp_eq_u32_e32 vcc, 8, v1
	v_pk_add_f32 v[74:75], v[74:75], v[76:77]
	v_mov_b32_e32 v164, v163
	v_cndmask_b32_e32 v12, v12, v8, vcc
	v_cmp_eq_u32_e32 vcc, 9, v1
	v_mov_b32_e32 v76, v166
	v_mov_b32_e32 v77, v168
	v_pk_add_f32 v[74:75], v[74:75], v[164:165]
	v_mov_b32_e32 v4, v170
	v_mov_b32_e32 v5, v172
	v_cndmask_b32_e32 v12, v12, v9, vcc
	v_cmp_eq_u32_e32 vcc, 10, v1
	v_pk_add_f32 v[58:59], v[58:59], v[76:77]
	v_mov_b32_e32 v168, v167
	v_pk_add_f32 v[4:5], v[74:75], v[4:5]
	v_mov_b32_e32 v172, v171
	v_cndmask_b32_e32 v12, v12, v6, vcc
	v_cmp_eq_u32_e32 vcc, 11, v1
	v_pk_add_f32 v[58:59], v[58:59], v[168:169]
	v_pk_add_f32 v[4:5], v[4:5], v[172:173]
	v_cndmask_b32_e32 v12, v12, v7, vcc
	v_cmp_eq_u32_e32 vcc, 12, v1
	v_pk_add_f32 v[58:59], v[58:59], v[60:61]
	v_and_b32_e32 v100, 8, v144
	v_cndmask_b32_e32 v12, v12, v4, vcc
	v_cmp_eq_u32_e32 vcc, 13, v1
	v_pk_add_f32 v[2:3], v[58:59], v[2:3]
	v_xor_b32_e32 v20, 8, v199
	v_cndmask_b32_e32 v12, v12, v5, vcc
	v_cmp_eq_u32_e32 vcc, 14, v1
	s_mov_b32 s45, s18
	s_nop 0
	v_cndmask_b32_e32 v12, v12, v2, vcc
	v_cmp_eq_u32_e32 vcc, 15, v1
	s_nop 1
	v_cndmask_b32_e32 v12, v12, v3, vcc
	v_cmp_eq_u32_e32 vcc, 1, v100
	s_nop 1
	v_cndmask_b32_e32 v1, v26, v27, vcc
	v_cmp_eq_u32_e32 vcc, 2, v100
	s_nop 1
	v_cndmask_b32_e32 v1, v1, v18, vcc
	v_cmp_eq_u32_e32 vcc, 3, v100
	s_nop 1
	v_cndmask_b32_e32 v1, v1, v19, vcc
	v_cmp_eq_u32_e32 vcc, 4, v100
	s_nop 1
	v_cndmask_b32_e32 v1, v1, v16, vcc
	v_cmp_eq_u32_e32 vcc, 5, v100
	s_nop 1
	v_cndmask_b32_e32 v1, v1, v17, vcc
	v_cmp_eq_u32_e32 vcc, 6, v100
	s_nop 1
	v_cndmask_b32_e32 v1, v1, v10, vcc
	v_cmp_eq_u32_e32 vcc, 7, v100
	s_nop 1
	v_cndmask_b32_e32 v1, v1, v11, vcc
	v_cmp_ne_u32_e32 vcc, 0, v100
	s_nop 1
	v_cndmask_b32_e32 v1, v1, v8, vcc
	v_cmp_eq_u32_e32 vcc, 9, v100
	s_nop 1
	v_cndmask_b32_e32 v1, v1, v9, vcc
	v_cmp_eq_u32_e32 vcc, 10, v100
	s_nop 1
	v_cndmask_b32_e32 v1, v1, v6, vcc
	v_cmp_eq_u32_e32 vcc, 11, v100
	s_nop 1
	v_cndmask_b32_e32 v1, v1, v7, vcc
	v_cmp_eq_u32_e32 vcc, 12, v100
	s_nop 1
	v_cndmask_b32_e32 v1, v1, v4, vcc
	v_cmp_eq_u32_e32 vcc, 13, v100
	s_nop 1
	v_cndmask_b32_e32 v1, v1, v5, vcc
	v_cmp_eq_u32_e32 vcc, 14, v100
	s_nop 1
	v_cndmask_b32_e32 v14, v1, v2, vcc
	v_and_b32_e32 v1, 64, v199
	v_add_u32_e32 v1, 64, v1
	v_cmp_lt_i32_e64 s[0:1], v20, v1
	v_cmp_eq_u32_e32 vcc, 0, v100
	s_nop 0
	v_cndmask_b32_e64 v20, v199, v20, s[0:1]
	v_lshlrev_b32_e32 v24, 2, v20
	ds_bpermute_b32 v12, v24, v12
	v_cmp_eq_u32_e64 s[0:1], 15, v100
	v_cndmask_b32_e32 v15, v0, v21, vcc
	v_cndmask_b32_e32 v20, v21, v0, vcc
	v_cndmask_b32_e64 v14, v14, v3, s[0:1]
	s_waitcnt lgkmcnt(0)
	v_add_f32_e32 v0, v14, v12
	v_bitop3_b32 v12, v144, 9, 8 bitop3:0x6c
	v_cmp_eq_u32_e64 s[0:1], 1, v12
	ds_bpermute_b32 v15, v24, v15
	v_cndmask_b32_e32 v21, v108, v109, vcc
	v_cndmask_b32_e64 v14, v0, v27, s[0:1]
	v_cmp_eq_u32_e64 s[0:1], 2, v12
	ds_bpermute_b32 v21, v24, v21
	s_waitcnt lgkmcnt(0)
	v_add_f32_e32 v15, v20, v15
	v_cndmask_b32_e64 v14, v14, v18, s[0:1]
	v_cmp_eq_u32_e64 s[0:1], 3, v12
	s_nop 1
	v_cndmask_b32_e64 v14, v14, v19, s[0:1]
	v_cmp_eq_u32_e64 s[0:1], 4, v12
	s_nop 1
	v_cndmask_b32_e64 v14, v14, v16, s[0:1]
	v_cmp_eq_u32_e64 s[0:1], 5, v12
	s_nop 1
	v_cndmask_b32_e64 v14, v14, v17, s[0:1]
	v_cmp_eq_u32_e64 s[0:1], 6, v12
	s_nop 1
	v_cndmask_b32_e64 v14, v14, v10, s[0:1]
	v_cmp_eq_u32_e64 s[0:1], 7, v12
	s_nop 1
	v_cndmask_b32_e64 v14, v14, v11, s[0:1]
	v_cmp_eq_u32_e64 s[0:1], 8, v12
	s_nop 1
	v_cndmask_b32_e64 v14, v14, v8, s[0:1]
	v_cmp_eq_u32_e64 s[0:1], 9, v12
	s_nop 1
	v_cndmask_b32_e64 v14, v14, v9, s[0:1]
	v_cmp_eq_u32_e64 s[0:1], 10, v12
	s_nop 1
	v_cndmask_b32_e64 v14, v14, v6, s[0:1]
	v_cmp_eq_u32_e64 s[0:1], 11, v12
	s_nop 1
	v_cndmask_b32_e64 v14, v14, v7, s[0:1]
	v_cmp_eq_u32_e64 s[0:1], 12, v12
	s_nop 1
	v_cndmask_b32_e64 v14, v14, v4, s[0:1]
	v_cmp_eq_u32_e64 s[0:1], 13, v12
	s_nop 1
	v_cndmask_b32_e64 v14, v14, v5, s[0:1]
	v_cmp_eq_u32_e64 s[0:1], 14, v12
	s_nop 1
	v_cndmask_b32_e64 v14, v14, v2, s[0:1]
	v_cmp_eq_u32_e64 s[0:1], 15, v12
	s_nop 1
	v_cndmask_b32_e64 v12, v14, v3, s[0:1]
	v_or_b32_e32 v14, 1, v100
	v_cmp_eq_u32_e64 s[0:1], 1, v14
	ds_bpermute_b32 v12, v24, v12
	s_nop 0
	v_cndmask_b32_e64 v20, v0, v27, s[0:1]
	v_cmp_eq_u32_e64 s[0:1], 2, v14
	s_nop 1
	v_cndmask_b32_e64 v20, v20, v18, s[0:1]
	v_cmp_eq_u32_e64 s[0:1], 3, v14
	s_nop 1
	v_cndmask_b32_e64 v20, v20, v19, s[0:1]
	v_cmp_eq_u32_e64 s[0:1], 4, v14
	s_nop 1
	v_cndmask_b32_e64 v20, v20, v16, s[0:1]
	v_cmp_eq_u32_e64 s[0:1], 5, v14
	s_nop 1
	v_cndmask_b32_e64 v20, v20, v17, s[0:1]
	v_cmp_eq_u32_e64 s[0:1], 6, v14
	s_nop 1
	v_cndmask_b32_e64 v20, v20, v10, s[0:1]
	v_cmp_eq_u32_e64 s[0:1], 7, v14
	s_nop 1
	v_cndmask_b32_e64 v20, v20, v11, s[0:1]
	v_cmp_eq_u32_e64 s[0:1], 8, v14
	s_nop 1
	v_cndmask_b32_e64 v20, v20, v8, s[0:1]
	v_cmp_eq_u32_e64 s[0:1], 9, v14
	s_nop 1
	v_cndmask_b32_e64 v20, v20, v9, s[0:1]
	v_cmp_eq_u32_e64 s[0:1], 10, v14
	s_nop 1
	v_cndmask_b32_e64 v20, v20, v6, s[0:1]
	v_cmp_eq_u32_e64 s[0:1], 11, v14
	s_nop 1
	v_cndmask_b32_e64 v20, v20, v7, s[0:1]
	v_cmp_eq_u32_e64 s[0:1], 12, v14
	s_nop 1
	v_cndmask_b32_e64 v20, v20, v4, s[0:1]
	v_cmp_eq_u32_e64 s[0:1], 13, v14
	s_nop 1
	v_cndmask_b32_e64 v20, v20, v5, s[0:1]
	v_cmp_eq_u32_e64 s[0:1], 14, v14
	s_nop 1
	v_cndmask_b32_e64 v20, v20, v2, s[0:1]
	v_cmp_eq_u32_e64 s[0:1], 15, v14
	s_nop 1
	v_cndmask_b32_e64 v14, v20, v3, s[0:1]
	s_waitcnt lgkmcnt(0)
	v_add_f32_e32 v23, v14, v12
	v_bitop3_b32 v12, v144, 10, 8 bitop3:0x6c
	v_cmp_eq_u32_e64 s[0:1], 1, v12
	v_cndmask_b32_e32 v20, v109, v108, vcc
	v_add_f32_e32 v20, v20, v21
	v_cndmask_b32_e64 v14, v0, v23, s[0:1]
	v_cmp_eq_u32_e64 s[0:1], 2, v12
	s_nop 1
	v_cndmask_b32_e64 v14, v14, v18, s[0:1]
	v_cmp_eq_u32_e64 s[0:1], 3, v12
	s_nop 1
	v_cndmask_b32_e64 v14, v14, v19, s[0:1]
	v_cmp_eq_u32_e64 s[0:1], 4, v12
	s_nop 1
	v_cndmask_b32_e64 v14, v14, v16, s[0:1]
	v_cmp_eq_u32_e64 s[0:1], 5, v12
	s_nop 1
	v_cndmask_b32_e64 v14, v14, v17, s[0:1]
	v_cmp_eq_u32_e64 s[0:1], 6, v12
	s_nop 1
	v_cndmask_b32_e64 v14, v14, v10, s[0:1]
	v_cmp_eq_u32_e64 s[0:1], 7, v12
	s_nop 1
	v_cndmask_b32_e64 v14, v14, v11, s[0:1]
	v_cmp_eq_u32_e64 s[0:1], 8, v12
	s_nop 1
	v_cndmask_b32_e64 v14, v14, v8, s[0:1]
	v_cmp_eq_u32_e64 s[0:1], 9, v12
	s_nop 1
	v_cndmask_b32_e64 v14, v14, v9, s[0:1]
	v_cmp_eq_u32_e64 s[0:1], 10, v12
	s_nop 1
	v_cndmask_b32_e64 v14, v14, v6, s[0:1]
	v_cmp_eq_u32_e64 s[0:1], 11, v12
	s_nop 1
	v_cndmask_b32_e64 v14, v14, v7, s[0:1]
	v_cmp_eq_u32_e64 s[0:1], 12, v12
	s_nop 1
	v_cndmask_b32_e64 v14, v14, v4, s[0:1]
	v_cmp_eq_u32_e64 s[0:1], 13, v12
	s_nop 1
	v_cndmask_b32_e64 v14, v14, v5, s[0:1]
	v_cmp_eq_u32_e64 s[0:1], 14, v12
	s_nop 1
	v_cndmask_b32_e64 v14, v14, v2, s[0:1]
	v_cmp_eq_u32_e64 s[0:1], 15, v12
	s_nop 1
	v_cndmask_b32_e64 v12, v14, v3, s[0:1]
	v_or_b32_e32 v14, 2, v100
	v_cmp_eq_u32_e64 s[0:1], 1, v14
	ds_bpermute_b32 v12, v24, v12
	s_nop 0
	v_cndmask_b32_e64 v21, v0, v23, s[0:1]
	v_cmp_eq_u32_e64 s[0:1], 2, v14
	s_nop 1
	v_cndmask_b32_e64 v18, v21, v18, s[0:1]
	v_cmp_eq_u32_e64 s[0:1], 3, v14
	v_cndmask_b32_e32 v21, v105, v139, vcc
	ds_bpermute_b32 v21, v24, v21
	v_cndmask_b32_e64 v18, v18, v19, s[0:1]
	v_cmp_eq_u32_e64 s[0:1], 4, v14
	s_nop 1
	v_cndmask_b32_e64 v18, v18, v16, s[0:1]
	v_cmp_eq_u32_e64 s[0:1], 5, v14
	s_nop 1
	v_cndmask_b32_e64 v18, v18, v17, s[0:1]
	v_cmp_eq_u32_e64 s[0:1], 6, v14
	s_nop 1
	v_cndmask_b32_e64 v18, v18, v10, s[0:1]
	v_cmp_eq_u32_e64 s[0:1], 7, v14
	s_nop 1
	v_cndmask_b32_e64 v18, v18, v11, s[0:1]
	v_cmp_eq_u32_e64 s[0:1], 8, v14
	s_nop 1
	v_cndmask_b32_e64 v18, v18, v8, s[0:1]
	v_cmp_eq_u32_e64 s[0:1], 9, v14
	s_nop 1
	v_cndmask_b32_e64 v18, v18, v9, s[0:1]
	v_cmp_eq_u32_e64 s[0:1], 10, v14
	s_nop 1
	v_cndmask_b32_e64 v18, v18, v6, s[0:1]
	v_cmp_eq_u32_e64 s[0:1], 11, v14
	s_nop 1
	v_cndmask_b32_e64 v18, v18, v7, s[0:1]
	v_cmp_eq_u32_e64 s[0:1], 12, v14
	s_nop 1
	v_cndmask_b32_e64 v18, v18, v4, s[0:1]
	v_cmp_eq_u32_e64 s[0:1], 13, v14
	s_nop 1
	v_cndmask_b32_e64 v18, v18, v5, s[0:1]
	v_cmp_eq_u32_e64 s[0:1], 14, v14
	s_nop 1
	v_cndmask_b32_e64 v18, v18, v2, s[0:1]
	v_cmp_eq_u32_e64 s[0:1], 15, v14
	s_nop 1
	v_cndmask_b32_e64 v14, v18, v3, s[0:1]
	s_waitcnt lgkmcnt(0)
	v_add_f32_e32 v22, v14, v12
	v_bitop3_b32 v12, v144, 11, 8 bitop3:0x6c
	v_cmp_eq_u32_e64 s[0:1], 1, v12
	v_cndmask_b32_e32 v18, v139, v105, vcc
	v_add_f32_e32 v18, v18, v21
	v_cndmask_b32_e64 v14, v0, v23, s[0:1]
	v_cmp_eq_u32_e64 s[0:1], 2, v12
	s_nop 1
	v_cndmask_b32_e64 v14, v14, v22, s[0:1]
	v_cmp_eq_u32_e64 s[0:1], 3, v12
	s_nop 1
	v_cndmask_b32_e64 v14, v14, v19, s[0:1]
	v_cmp_eq_u32_e64 s[0:1], 4, v12
	s_nop 1
	v_cndmask_b32_e64 v14, v14, v16, s[0:1]
	v_cmp_eq_u32_e64 s[0:1], 5, v12
	s_nop 1
	v_cndmask_b32_e64 v14, v14, v17, s[0:1]
	v_cmp_eq_u32_e64 s[0:1], 6, v12
	s_nop 1
	v_cndmask_b32_e64 v14, v14, v10, s[0:1]
	v_cmp_eq_u32_e64 s[0:1], 7, v12
	s_nop 1
	v_cndmask_b32_e64 v14, v14, v11, s[0:1]
	v_cmp_eq_u32_e64 s[0:1], 8, v12
	s_nop 1
	v_cndmask_b32_e64 v14, v14, v8, s[0:1]
	v_cmp_eq_u32_e64 s[0:1], 9, v12
	s_nop 1
	v_cndmask_b32_e64 v14, v14, v9, s[0:1]
	v_cmp_eq_u32_e64 s[0:1], 10, v12
	s_nop 1
	v_cndmask_b32_e64 v14, v14, v6, s[0:1]
	v_cmp_eq_u32_e64 s[0:1], 11, v12
	s_nop 1
	v_cndmask_b32_e64 v14, v14, v7, s[0:1]
	v_cmp_eq_u32_e64 s[0:1], 12, v12
	s_nop 1
	v_cndmask_b32_e64 v14, v14, v4, s[0:1]
	v_cmp_eq_u32_e64 s[0:1], 13, v12
	s_nop 1
	v_cndmask_b32_e64 v14, v14, v5, s[0:1]
	v_cmp_eq_u32_e64 s[0:1], 14, v12
	s_nop 1
	v_cndmask_b32_e64 v14, v14, v2, s[0:1]
	v_cmp_eq_u32_e64 s[0:1], 15, v12
	s_nop 1
	v_cndmask_b32_e64 v12, v14, v3, s[0:1]
	v_or_b32_e32 v14, 3, v100
	v_cmp_eq_u32_e64 s[0:1], 1, v14
	ds_bpermute_b32 v12, v24, v12
	s_nop 0
	v_cndmask_b32_e64 v21, v0, v23, s[0:1]
	v_cmp_eq_u32_e64 s[0:1], 2, v14
	s_nop 1
	v_cndmask_b32_e64 v21, v21, v22, s[0:1]
	v_cmp_eq_u32_e64 s[0:1], 3, v14
	s_nop 1
	v_cndmask_b32_e64 v19, v21, v19, s[0:1]
	v_cmp_eq_u32_e64 s[0:1], 4, v14
	v_cndmask_b32_e32 v21, v104, v72, vcc
	ds_bpermute_b32 v25, v24, v21
	v_cndmask_b32_e64 v19, v19, v16, s[0:1]
	v_cmp_eq_u32_e64 s[0:1], 5, v14
	s_nop 1
	v_cndmask_b32_e64 v19, v19, v17, s[0:1]
	v_cmp_eq_u32_e64 s[0:1], 6, v14
	s_nop 1
	v_cndmask_b32_e64 v19, v19, v10, s[0:1]
	v_cmp_eq_u32_e64 s[0:1], 7, v14
	s_nop 1
	v_cndmask_b32_e64 v19, v19, v11, s[0:1]
	v_cmp_eq_u32_e64 s[0:1], 8, v14
	s_nop 1
	v_cndmask_b32_e64 v19, v19, v8, s[0:1]
	v_cmp_eq_u32_e64 s[0:1], 9, v14
	s_nop 1
	v_cndmask_b32_e64 v19, v19, v9, s[0:1]
	v_cmp_eq_u32_e64 s[0:1], 10, v14
	s_nop 1
	v_cndmask_b32_e64 v19, v19, v6, s[0:1]
	v_cmp_eq_u32_e64 s[0:1], 11, v14
	s_nop 1
	v_cndmask_b32_e64 v19, v19, v7, s[0:1]
	v_cmp_eq_u32_e64 s[0:1], 12, v14
	s_nop 1
	v_cndmask_b32_e64 v19, v19, v4, s[0:1]
	v_cmp_eq_u32_e64 s[0:1], 13, v14
	s_nop 1
	v_cndmask_b32_e64 v19, v19, v5, s[0:1]
	v_cmp_eq_u32_e64 s[0:1], 14, v14
	s_nop 1
	v_cndmask_b32_e64 v19, v19, v2, s[0:1]
	v_cmp_eq_u32_e64 s[0:1], 15, v14
	s_nop 1
	v_cndmask_b32_e64 v14, v19, v3, s[0:1]
	s_waitcnt lgkmcnt(0)
	v_add_f32_e32 v21, v14, v12
	v_bitop3_b32 v12, v144, 12, 8 bitop3:0x6c
	v_cmp_eq_u32_e64 s[0:1], 1, v12
	v_cndmask_b32_e32 v19, v72, v104, vcc
	v_add_f32_e32 v19, v19, v25
	v_cndmask_b32_e64 v14, v0, v23, s[0:1]
	v_cmp_eq_u32_e64 s[0:1], 2, v12
	s_nop 1
	v_cndmask_b32_e64 v14, v14, v22, s[0:1]
	v_cmp_eq_u32_e64 s[0:1], 3, v12
	s_nop 1
	v_cndmask_b32_e64 v14, v14, v21, s[0:1]
	v_cmp_eq_u32_e64 s[0:1], 4, v12
	s_nop 1
	v_cndmask_b32_e64 v14, v14, v16, s[0:1]
	v_cmp_eq_u32_e64 s[0:1], 5, v12
	s_nop 1
	v_cndmask_b32_e64 v14, v14, v17, s[0:1]
	v_cmp_eq_u32_e64 s[0:1], 6, v12
	s_nop 1
	v_cndmask_b32_e64 v14, v14, v10, s[0:1]
	v_cmp_eq_u32_e64 s[0:1], 7, v12
	s_nop 1
	v_cndmask_b32_e64 v14, v14, v11, s[0:1]
	v_cmp_eq_u32_e64 s[0:1], 8, v12
	s_nop 1
	v_cndmask_b32_e64 v14, v14, v8, s[0:1]
	v_cmp_eq_u32_e64 s[0:1], 9, v12
	s_nop 1
	v_cndmask_b32_e64 v14, v14, v9, s[0:1]
	v_cmp_eq_u32_e64 s[0:1], 10, v12
	s_nop 1
	v_cndmask_b32_e64 v14, v14, v6, s[0:1]
	v_cmp_eq_u32_e64 s[0:1], 11, v12
	s_nop 1
	v_cndmask_b32_e64 v14, v14, v7, s[0:1]
	v_cmp_eq_u32_e64 s[0:1], 12, v12
	s_nop 1
	v_cndmask_b32_e64 v14, v14, v4, s[0:1]
	v_cmp_eq_u32_e64 s[0:1], 13, v12
	s_nop 1
	v_cndmask_b32_e64 v14, v14, v5, s[0:1]
	v_cmp_eq_u32_e64 s[0:1], 14, v12
	s_nop 1
	v_cndmask_b32_e64 v14, v14, v2, s[0:1]
	v_cmp_eq_u32_e64 s[0:1], 15, v12
	s_nop 1
	v_cndmask_b32_e64 v12, v14, v3, s[0:1]
	v_or_b32_e32 v14, 4, v100
	v_cmp_eq_u32_e64 s[0:1], 1, v14
	ds_bpermute_b32 v12, v24, v12
	s_nop 0
	v_cndmask_b32_e64 v25, v0, v23, s[0:1]
	v_cmp_eq_u32_e64 s[0:1], 2, v14
	s_nop 1
	v_cndmask_b32_e64 v25, v25, v22, s[0:1]
	v_cmp_eq_u32_e64 s[0:1], 3, v14
	s_nop 1
	v_cndmask_b32_e64 v25, v25, v21, s[0:1]
	v_cmp_eq_u32_e64 s[0:1], 4, v14
	s_nop 1
	v_cndmask_b32_e64 v16, v25, v16, s[0:1]
	v_cmp_eq_u32_e64 s[0:1], 5, v14
	v_cndmask_b32_e32 v25, v103, v50, vcc
	ds_bpermute_b32 v25, v24, v25
	v_cndmask_b32_e64 v16, v16, v17, s[0:1]
	v_cmp_eq_u32_e64 s[0:1], 6, v14
	s_nop 1
	v_cndmask_b32_e64 v16, v16, v10, s[0:1]
	v_cmp_eq_u32_e64 s[0:1], 7, v14
	s_nop 1
	v_cndmask_b32_e64 v16, v16, v11, s[0:1]
	v_cmp_eq_u32_e64 s[0:1], 8, v14
	s_nop 1
	v_cndmask_b32_e64 v16, v16, v8, s[0:1]
	v_cmp_eq_u32_e64 s[0:1], 9, v14
	s_nop 1
	v_cndmask_b32_e64 v16, v16, v9, s[0:1]
	v_cmp_eq_u32_e64 s[0:1], 10, v14
	s_nop 1
	v_cndmask_b32_e64 v16, v16, v6, s[0:1]
	v_cmp_eq_u32_e64 s[0:1], 11, v14
	s_nop 1
	v_cndmask_b32_e64 v16, v16, v7, s[0:1]
	v_cmp_eq_u32_e64 s[0:1], 12, v14
	s_nop 1
	v_cndmask_b32_e64 v16, v16, v4, s[0:1]
	v_cmp_eq_u32_e64 s[0:1], 13, v14
	s_nop 1
	v_cndmask_b32_e64 v16, v16, v5, s[0:1]
	v_cmp_eq_u32_e64 s[0:1], 14, v14
	s_nop 1
	v_cndmask_b32_e64 v16, v16, v2, s[0:1]
	v_cmp_eq_u32_e64 s[0:1], 15, v14
	s_nop 1
	v_cndmask_b32_e64 v14, v16, v3, s[0:1]
	s_waitcnt lgkmcnt(0)
	v_add_f32_e32 v12, v14, v12
	v_bitop3_b32 v14, v144, 13, 8 bitop3:0x6c
	v_cndmask_b32_e32 v16, v50, v103, vcc
	v_cmp_eq_u32_e64 s[0:1], 1, v14
	v_add_f32_e32 v16, v16, v25
	s_nop 0
	v_cndmask_b32_e64 v25, v0, v23, s[0:1]
	v_cmp_eq_u32_e64 s[0:1], 2, v14
	s_nop 1
	v_cndmask_b32_e64 v25, v25, v22, s[0:1]
	v_cmp_eq_u32_e64 s[0:1], 3, v14
	s_nop 1
	v_cndmask_b32_e64 v25, v25, v21, s[0:1]
	v_cmp_eq_u32_e64 s[0:1], 4, v14
	s_nop 1
	v_cndmask_b32_e64 v25, v25, v12, s[0:1]
	v_cmp_eq_u32_e64 s[0:1], 5, v14
	s_nop 1
	v_cndmask_b32_e64 v25, v25, v17, s[0:1]
	v_cmp_eq_u32_e64 s[0:1], 6, v14
	s_nop 1
	v_cndmask_b32_e64 v25, v25, v10, s[0:1]
	v_cmp_eq_u32_e64 s[0:1], 7, v14
	s_nop 1
	v_cndmask_b32_e64 v25, v25, v11, s[0:1]
	v_cmp_eq_u32_e64 s[0:1], 8, v14
	s_nop 1
	v_cndmask_b32_e64 v25, v25, v8, s[0:1]
	v_cmp_eq_u32_e64 s[0:1], 9, v14
	s_nop 1
	v_cndmask_b32_e64 v25, v25, v9, s[0:1]
	v_cmp_eq_u32_e64 s[0:1], 10, v14
	s_nop 1
	v_cndmask_b32_e64 v25, v25, v6, s[0:1]
	v_cmp_eq_u32_e64 s[0:1], 11, v14
	s_nop 1
	v_cndmask_b32_e64 v25, v25, v7, s[0:1]
	v_cmp_eq_u32_e64 s[0:1], 12, v14
	s_nop 1
	v_cndmask_b32_e64 v25, v25, v4, s[0:1]
	v_cmp_eq_u32_e64 s[0:1], 13, v14
	s_nop 1
	v_cndmask_b32_e64 v25, v25, v5, s[0:1]
	v_cmp_eq_u32_e64 s[0:1], 14, v14
	s_nop 1
	v_cndmask_b32_e64 v25, v25, v2, s[0:1]
	v_cmp_eq_u32_e64 s[0:1], 15, v14
	s_nop 1
	v_cndmask_b32_e64 v14, v25, v3, s[0:1]
	v_or_b32_e32 v25, 5, v100
	v_cmp_eq_u32_e64 s[0:1], 1, v25
	ds_bpermute_b32 v14, v24, v14
	s_nop 0
	v_cndmask_b32_e64 v26, v0, v23, s[0:1]
	v_cmp_eq_u32_e64 s[0:1], 2, v25
	s_nop 1
	v_cndmask_b32_e64 v26, v26, v22, s[0:1]
	v_cmp_eq_u32_e64 s[0:1], 3, v25
	s_nop 1
	v_cndmask_b32_e64 v26, v26, v21, s[0:1]
	v_cmp_eq_u32_e64 s[0:1], 4, v25
	s_nop 1
	v_cndmask_b32_e64 v26, v26, v12, s[0:1]
	v_cmp_eq_u32_e64 s[0:1], 5, v25
	s_nop 1
	v_cndmask_b32_e64 v17, v26, v17, s[0:1]
	v_cmp_eq_u32_e64 s[0:1], 6, v25
	v_cndmask_b32_e32 v26, v102, v43, vcc
	ds_bpermute_b32 v26, v24, v26
	v_cndmask_b32_e64 v17, v17, v10, s[0:1]
	v_cmp_eq_u32_e64 s[0:1], 7, v25
	s_nop 1
	v_cndmask_b32_e64 v17, v17, v11, s[0:1]
	v_cmp_eq_u32_e64 s[0:1], 8, v25
	s_nop 1
	v_cndmask_b32_e64 v17, v17, v8, s[0:1]
	v_cmp_eq_u32_e64 s[0:1], 9, v25
	s_nop 1
	v_cndmask_b32_e64 v17, v17, v9, s[0:1]
	v_cmp_eq_u32_e64 s[0:1], 10, v25
	s_nop 1
	v_cndmask_b32_e64 v17, v17, v6, s[0:1]
	v_cmp_eq_u32_e64 s[0:1], 11, v25
	s_nop 1
	v_cndmask_b32_e64 v17, v17, v7, s[0:1]
	v_cmp_eq_u32_e64 s[0:1], 12, v25
	s_nop 1
	v_cndmask_b32_e64 v17, v17, v4, s[0:1]
	v_cmp_eq_u32_e64 s[0:1], 13, v25
	s_nop 1
	v_cndmask_b32_e64 v17, v17, v5, s[0:1]
	v_cmp_eq_u32_e64 s[0:1], 14, v25
	s_nop 1
	v_cndmask_b32_e64 v17, v17, v2, s[0:1]
	v_cmp_eq_u32_e64 s[0:1], 15, v25
	v_cndmask_b32_e32 v25, v43, v102, vcc
	s_nop 0
	v_cndmask_b32_e64 v17, v17, v3, s[0:1]
	s_waitcnt lgkmcnt(0)
	v_add_f32_e32 v14, v17, v14
	v_add_f32_e32 v17, v25, v26
	v_bitop3_b32 v25, v144, 14, 8 bitop3:0x6c
	v_cmp_eq_u32_e64 s[0:1], 1, v25
	s_nop 1
	v_cndmask_b32_e64 v26, v0, v23, s[0:1]
	v_cmp_eq_u32_e64 s[0:1], 2, v25
	s_nop 1
	v_cndmask_b32_e64 v26, v26, v22, s[0:1]
	v_cmp_eq_u32_e64 s[0:1], 3, v25
	s_nop 1
	v_cndmask_b32_e64 v26, v26, v21, s[0:1]
	v_cmp_eq_u32_e64 s[0:1], 4, v25
	s_nop 1
	v_cndmask_b32_e64 v26, v26, v12, s[0:1]
	v_cmp_eq_u32_e64 s[0:1], 5, v25
	s_nop 1
	v_cndmask_b32_e64 v26, v26, v14, s[0:1]
	v_cmp_eq_u32_e64 s[0:1], 6, v25
	s_nop 1
	v_cndmask_b32_e64 v26, v26, v10, s[0:1]
	v_cmp_eq_u32_e64 s[0:1], 7, v25
	s_nop 1
	v_cndmask_b32_e64 v26, v26, v11, s[0:1]
	v_cmp_eq_u32_e64 s[0:1], 8, v25
	s_nop 1
	v_cndmask_b32_e64 v26, v26, v8, s[0:1]
	v_cmp_eq_u32_e64 s[0:1], 9, v25
	s_nop 1
	v_cndmask_b32_e64 v26, v26, v9, s[0:1]
	v_cmp_eq_u32_e64 s[0:1], 10, v25
	s_nop 1
	v_cndmask_b32_e64 v26, v26, v6, s[0:1]
	v_cmp_eq_u32_e64 s[0:1], 11, v25
	s_nop 1
	v_cndmask_b32_e64 v26, v26, v7, s[0:1]
	v_cmp_eq_u32_e64 s[0:1], 12, v25
	s_nop 1
	v_cndmask_b32_e64 v26, v26, v4, s[0:1]
	v_cmp_eq_u32_e64 s[0:1], 13, v25
	s_nop 1
	v_cndmask_b32_e64 v26, v26, v5, s[0:1]
	v_cmp_eq_u32_e64 s[0:1], 14, v25
	s_nop 1
	v_cndmask_b32_e64 v26, v26, v2, s[0:1]
	v_cmp_eq_u32_e64 s[0:1], 15, v25
	s_nop 1
	v_cndmask_b32_e64 v25, v26, v3, s[0:1]
	v_or_b32_e32 v26, 6, v100
	v_cmp_eq_u32_e64 s[0:1], 1, v26
	ds_bpermute_b32 v25, v24, v25
	s_nop 0
	v_cndmask_b32_e64 v27, v0, v23, s[0:1]
	v_cmp_eq_u32_e64 s[0:1], 2, v26
	s_nop 1
	v_cndmask_b32_e64 v27, v27, v22, s[0:1]
	v_cmp_eq_u32_e64 s[0:1], 3, v26
	s_nop 1
	v_cndmask_b32_e64 v27, v27, v21, s[0:1]
	v_cmp_eq_u32_e64 s[0:1], 4, v26
	s_nop 1
	v_cndmask_b32_e64 v27, v27, v12, s[0:1]
	v_cmp_eq_u32_e64 s[0:1], 5, v26
	s_nop 1
	v_cndmask_b32_e64 v27, v27, v14, s[0:1]
	v_cmp_eq_u32_e64 s[0:1], 6, v26
	s_nop 1
	v_cndmask_b32_e64 v10, v27, v10, s[0:1]
	v_cmp_eq_u32_e64 s[0:1], 7, v26
	v_cndmask_b32_e32 v27, v101, v35, vcc
	ds_bpermute_b32 v27, v24, v27
	v_cndmask_b32_e64 v10, v10, v11, s[0:1]
	v_cmp_eq_u32_e64 s[0:1], 8, v26
	s_nop 1
	v_cndmask_b32_e64 v10, v10, v8, s[0:1]
	v_cmp_eq_u32_e64 s[0:1], 9, v26
	s_nop 1
	v_cndmask_b32_e64 v10, v10, v9, s[0:1]
	v_cmp_eq_u32_e64 s[0:1], 10, v26
	s_nop 1
	v_cndmask_b32_e64 v10, v10, v6, s[0:1]
	v_cmp_eq_u32_e64 s[0:1], 11, v26
	s_nop 1
	v_cndmask_b32_e64 v10, v10, v7, s[0:1]
	v_cmp_eq_u32_e64 s[0:1], 12, v26
	s_nop 1
	v_cndmask_b32_e64 v10, v10, v4, s[0:1]
	v_cmp_eq_u32_e64 s[0:1], 13, v26
	s_nop 1
	v_cndmask_b32_e64 v10, v10, v5, s[0:1]
	v_cmp_eq_u32_e64 s[0:1], 14, v26
	s_nop 1
	v_cndmask_b32_e64 v10, v10, v2, s[0:1]
	v_cmp_eq_u32_e64 s[0:1], 15, v26
	v_cndmask_b32_e32 v26, v35, v101, vcc
	s_nop 0
	v_cndmask_b32_e64 v10, v10, v3, s[0:1]
	s_waitcnt lgkmcnt(0)
	v_add_f32_e32 v10, v10, v25
	v_add_f32_e32 v25, v26, v27
	v_bitop3_b32 v26, v144, 15, 8 bitop3:0x6c
	v_cmp_eq_u32_e64 s[0:1], 1, v26
	s_nop 1
	v_cndmask_b32_e64 v27, v0, v23, s[0:1]
	v_cmp_eq_u32_e64 s[0:1], 2, v26
	s_nop 1
	v_cndmask_b32_e64 v27, v27, v22, s[0:1]
	v_cmp_eq_u32_e64 s[0:1], 3, v26
	s_nop 1
	v_cndmask_b32_e64 v27, v27, v21, s[0:1]
	v_cmp_eq_u32_e64 s[0:1], 4, v26
	s_nop 1
	v_cndmask_b32_e64 v27, v27, v12, s[0:1]
	v_cmp_eq_u32_e64 s[0:1], 5, v26
	s_nop 1
	v_cndmask_b32_e64 v27, v27, v14, s[0:1]
	v_cmp_eq_u32_e64 s[0:1], 6, v26
	s_nop 1
	v_cndmask_b32_e64 v27, v27, v10, s[0:1]
	v_cmp_eq_u32_e64 s[0:1], 7, v26
	s_nop 1
	v_cndmask_b32_e64 v27, v27, v11, s[0:1]
	v_cmp_eq_u32_e64 s[0:1], 8, v26
	s_nop 1
	v_cndmask_b32_e64 v27, v27, v8, s[0:1]
	v_cmp_eq_u32_e64 s[0:1], 9, v26
	s_nop 1
	v_cndmask_b32_e64 v27, v27, v9, s[0:1]
	v_cmp_eq_u32_e64 s[0:1], 10, v26
	s_nop 1
	v_cndmask_b32_e64 v27, v27, v6, s[0:1]
	v_cmp_eq_u32_e64 s[0:1], 11, v26
	s_nop 1
	v_cndmask_b32_e64 v27, v27, v7, s[0:1]
	v_cmp_eq_u32_e64 s[0:1], 12, v26
	s_nop 1
	v_cndmask_b32_e64 v27, v27, v4, s[0:1]
	v_cmp_eq_u32_e64 s[0:1], 13, v26
	s_nop 1
	v_cndmask_b32_e64 v27, v27, v5, s[0:1]
	v_cmp_eq_u32_e64 s[0:1], 14, v26
	s_nop 1
	v_cndmask_b32_e64 v27, v27, v2, s[0:1]
	v_cmp_eq_u32_e64 s[0:1], 15, v26
	s_nop 1
	v_cndmask_b32_e64 v26, v27, v3, s[0:1]
	v_or_b32_e32 v27, 7, v100
	v_cmp_eq_u32_e64 s[0:1], 1, v27
	ds_bpermute_b32 v26, v24, v26
	s_nop 0
	v_cndmask_b32_e64 v28, v0, v23, s[0:1]
	v_cmp_eq_u32_e64 s[0:1], 2, v27
	s_nop 1
	v_cndmask_b32_e64 v28, v28, v22, s[0:1]
	v_cmp_eq_u32_e64 s[0:1], 3, v27
	s_nop 1
	v_cndmask_b32_e64 v28, v28, v21, s[0:1]
	v_cmp_eq_u32_e64 s[0:1], 4, v27
	s_nop 1
	v_cndmask_b32_e64 v28, v28, v12, s[0:1]
	v_cmp_eq_u32_e64 s[0:1], 5, v27
	s_nop 1
	v_cndmask_b32_e64 v28, v28, v14, s[0:1]
	v_cmp_eq_u32_e64 s[0:1], 6, v27
	s_nop 1
	v_cndmask_b32_e64 v28, v28, v10, s[0:1]
	v_cmp_eq_u32_e64 s[0:1], 7, v27
	s_nop 1
	v_cndmask_b32_e64 v11, v28, v11, s[0:1]
	v_cmp_eq_u32_e64 s[0:1], 8, v27
	v_cndmask_b32_e32 v28, v13, v34, vcc
	ds_bpermute_b32 v24, v24, v28
	v_cndmask_b32_e64 v11, v11, v8, s[0:1]
	v_cmp_eq_u32_e64 s[0:1], 9, v27
	v_cndmask_b32_e32 v13, v34, v13, vcc
	v_xor_b32_e32 v28, 4, v199
	v_cndmask_b32_e64 v11, v11, v9, s[0:1]
	v_cmp_eq_u32_e64 s[0:1], 10, v27
	s_nop 1
	v_cndmask_b32_e64 v11, v11, v6, s[0:1]
	v_cmp_eq_u32_e64 s[0:1], 11, v27
	s_nop 1
	v_cndmask_b32_e64 v11, v11, v7, s[0:1]
	v_cmp_eq_u32_e64 s[0:1], 12, v27
	s_nop 1
	v_cndmask_b32_e64 v11, v11, v4, s[0:1]
	v_cmp_eq_u32_e64 s[0:1], 13, v27
	s_nop 1
	v_cndmask_b32_e64 v11, v11, v5, s[0:1]
	v_cmp_eq_u32_e64 s[0:1], 14, v27
	s_nop 1
	v_cndmask_b32_e64 v11, v11, v2, s[0:1]
	v_cmp_eq_u32_e64 s[0:1], 15, v27
	s_nop 1
	v_cndmask_b32_e64 v11, v11, v3, s[0:1]
	s_waitcnt lgkmcnt(0)
	v_add_f32_e32 v26, v11, v26
	v_add_f32_e32 v11, v13, v24
	v_bitop3_b32 v24, v144, 4, v144 bitop3:0xc
	v_cmp_eq_u32_e32 vcc, 1, v24
	v_and_b32_e32 v13, 4, v144
	v_cmp_lt_i32_e64 s[0:1], v28, v1
	v_cndmask_b32_e32 v27, v0, v23, vcc
	v_cmp_eq_u32_e32 vcc, 2, v24
	v_cndmask_b32_e64 v28, v199, v28, s[0:1]
	v_lshlrev_b32_e32 v28, 2, v28
	v_cndmask_b32_e32 v27, v27, v22, vcc
	v_cmp_eq_u32_e32 vcc, 3, v24
	v_cmp_eq_u32_e64 s[0:1], 15, v13
	s_nop 0
	v_cndmask_b32_e32 v27, v27, v21, vcc
	v_cmp_eq_u32_e32 vcc, 4, v24
	s_nop 1
	v_cndmask_b32_e32 v27, v27, v12, vcc
	v_cmp_eq_u32_e32 vcc, 5, v24
	s_nop 1
	v_cndmask_b32_e32 v27, v27, v14, vcc
	v_cmp_eq_u32_e32 vcc, 6, v24
	s_nop 1
	v_cndmask_b32_e32 v27, v27, v10, vcc
	v_cmp_eq_u32_e32 vcc, 7, v24
	s_nop 1
	v_cndmask_b32_e32 v27, v27, v26, vcc
	v_cmp_eq_u32_e32 vcc, 8, v24
	s_nop 1
	v_cndmask_b32_e32 v27, v27, v8, vcc
	v_cmp_eq_u32_e32 vcc, 9, v24
	s_nop 1
	v_cndmask_b32_e32 v27, v27, v9, vcc
	v_cmp_eq_u32_e32 vcc, 10, v24
	s_nop 1
	v_cndmask_b32_e32 v27, v27, v6, vcc
	v_cmp_eq_u32_e32 vcc, 11, v24
	s_nop 1
	v_cndmask_b32_e32 v27, v27, v7, vcc
	v_cmp_eq_u32_e32 vcc, 12, v24
	s_nop 1
	v_cndmask_b32_e32 v27, v27, v4, vcc
	v_cmp_eq_u32_e32 vcc, 13, v24
	s_nop 1
	v_cndmask_b32_e32 v27, v27, v5, vcc
	v_cmp_eq_u32_e32 vcc, 14, v24
	s_nop 1
	v_cndmask_b32_e32 v27, v27, v2, vcc
	v_cmp_eq_u32_e32 vcc, 15, v24
	s_nop 1
	v_cndmask_b32_e32 v24, v27, v3, vcc
	v_cmp_eq_u32_e32 vcc, 1, v13
	ds_bpermute_b32 v24, v28, v24
	s_nop 0
	v_cndmask_b32_e32 v0, v0, v23, vcc
	v_cmp_eq_u32_e32 vcc, 2, v13
	s_nop 1
	v_cndmask_b32_e32 v0, v0, v22, vcc
	v_cmp_eq_u32_e32 vcc, 3, v13
	s_nop 1
	v_cndmask_b32_e32 v0, v0, v21, vcc
	v_cmp_ne_u32_e32 vcc, 0, v13
	s_nop 1
	v_cndmask_b32_e32 v0, v0, v12, vcc
	v_cmp_eq_u32_e32 vcc, 5, v13
	s_nop 1
	v_cndmask_b32_e32 v0, v0, v14, vcc
	v_cmp_eq_u32_e32 vcc, 6, v13
	s_nop 1
	v_cndmask_b32_e32 v0, v0, v10, vcc
	v_cmp_eq_u32_e32 vcc, 7, v13
	s_nop 1
	v_cndmask_b32_e32 v0, v0, v26, vcc
	v_cmp_eq_u32_e32 vcc, 8, v13
	s_nop 1
	v_cndmask_b32_e32 v0, v0, v8, vcc
	v_cmp_eq_u32_e32 vcc, 9, v13
	s_nop 1
	v_cndmask_b32_e32 v0, v0, v9, vcc
	v_cmp_eq_u32_e32 vcc, 10, v13
	s_nop 1
	v_cndmask_b32_e32 v0, v0, v6, vcc
	v_cmp_eq_u32_e32 vcc, 11, v13
	s_nop 1
	v_cndmask_b32_e32 v0, v0, v7, vcc
	v_cmp_eq_u32_e32 vcc, 12, v13
	s_nop 1
	v_cndmask_b32_e32 v0, v0, v4, vcc
	v_cmp_eq_u32_e32 vcc, 13, v13
	s_nop 1
	v_cndmask_b32_e32 v0, v0, v5, vcc
	v_cmp_eq_u32_e32 vcc, 14, v13
	s_nop 1
	v_cndmask_b32_e32 v0, v0, v2, vcc
	v_cmp_eq_u32_e32 vcc, 0, v13
	v_cndmask_b32_e64 v0, v0, v3, s[0:1]
	s_waitcnt lgkmcnt(0)
	v_add_f32_e32 v0, v0, v24
	v_cndmask_b32_e32 v27, v15, v16, vcc
	v_cndmask_b32_e32 v15, v16, v15, vcc
	v_bitop3_b32 v16, v144, 5, 4 bitop3:0x6c
	v_cmp_eq_u32_e64 s[0:1], 1, v16
	ds_bpermute_b32 v27, v28, v27
	s_waitcnt lgkmcnt(0)
	v_add_f32_e32 v15, v15, v27
	v_cndmask_b32_e64 v24, v0, v23, s[0:1]
	v_cmp_eq_u32_e64 s[0:1], 2, v16
	v_cndmask_b32_e32 v27, v20, v17, vcc
	v_cndmask_b32_e32 v17, v17, v20, vcc
	v_cndmask_b32_e64 v24, v24, v22, s[0:1]
	v_cmp_eq_u32_e64 s[0:1], 3, v16
	v_bitop3_b32 v20, v144, 6, 4 bitop3:0x6c
	ds_bpermute_b32 v27, v28, v27
	v_cndmask_b32_e64 v24, v24, v21, s[0:1]
	v_cmp_eq_u32_e64 s[0:1], 4, v16
	s_waitcnt lgkmcnt(0)
	v_add_f32_e32 v17, v17, v27
	v_cndmask_b32_e64 v24, v24, v12, s[0:1]
	v_cmp_eq_u32_e64 s[0:1], 5, v16
	s_nop 1
	v_cndmask_b32_e64 v24, v24, v14, s[0:1]
	v_cmp_eq_u32_e64 s[0:1], 6, v16
	s_nop 1
	v_cndmask_b32_e64 v24, v24, v10, s[0:1]
	v_cmp_eq_u32_e64 s[0:1], 7, v16
	s_nop 1
	v_cndmask_b32_e64 v24, v24, v26, s[0:1]
	v_cmp_eq_u32_e64 s[0:1], 8, v16
	s_nop 1
	v_cndmask_b32_e64 v24, v24, v8, s[0:1]
	v_cmp_eq_u32_e64 s[0:1], 9, v16
	s_nop 1
	v_cndmask_b32_e64 v24, v24, v9, s[0:1]
	v_cmp_eq_u32_e64 s[0:1], 10, v16
	s_nop 1
	v_cndmask_b32_e64 v24, v24, v6, s[0:1]
	v_cmp_eq_u32_e64 s[0:1], 11, v16
	s_nop 1
	v_cndmask_b32_e64 v24, v24, v7, s[0:1]
	v_cmp_eq_u32_e64 s[0:1], 12, v16
	s_nop 1
	v_cndmask_b32_e64 v24, v24, v4, s[0:1]
	v_cmp_eq_u32_e64 s[0:1], 13, v16
	s_nop 1
	v_cndmask_b32_e64 v24, v24, v5, s[0:1]
	v_cmp_eq_u32_e64 s[0:1], 14, v16
	s_nop 1
	v_cndmask_b32_e64 v24, v24, v2, s[0:1]
	v_cmp_eq_u32_e64 s[0:1], 15, v16
	s_nop 1
	v_cndmask_b32_e64 v16, v24, v3, s[0:1]
	v_or_b32_e32 v24, 1, v13
	v_cmp_eq_u32_e64 s[0:1], 1, v24
	ds_bpermute_b32 v16, v28, v16
	s_nop 0
	v_cndmask_b32_e64 v23, v0, v23, s[0:1]
	v_cmp_eq_u32_e64 s[0:1], 2, v24
	s_nop 1
	v_cndmask_b32_e64 v23, v23, v22, s[0:1]
	v_cmp_eq_u32_e64 s[0:1], 3, v24
	s_nop 1
	v_cndmask_b32_e64 v23, v23, v21, s[0:1]
	v_cmp_eq_u32_e64 s[0:1], 4, v24
	s_nop 1
	v_cndmask_b32_e64 v23, v23, v12, s[0:1]
	v_cmp_eq_u32_e64 s[0:1], 5, v24
	s_nop 1
	v_cndmask_b32_e64 v23, v23, v14, s[0:1]
	v_cmp_eq_u32_e64 s[0:1], 6, v24
	s_nop 1
	v_cndmask_b32_e64 v23, v23, v10, s[0:1]
	v_cmp_eq_u32_e64 s[0:1], 7, v24
	s_nop 1
	v_cndmask_b32_e64 v23, v23, v26, s[0:1]
	v_cmp_eq_u32_e64 s[0:1], 8, v24
	s_nop 1
	v_cndmask_b32_e64 v23, v23, v8, s[0:1]
	v_cmp_eq_u32_e64 s[0:1], 9, v24
	s_nop 1
	v_cndmask_b32_e64 v23, v23, v9, s[0:1]
	v_cmp_eq_u32_e64 s[0:1], 10, v24
	s_nop 1
	v_cndmask_b32_e64 v23, v23, v6, s[0:1]
	v_cmp_eq_u32_e64 s[0:1], 11, v24
	s_nop 1
	v_cndmask_b32_e64 v23, v23, v7, s[0:1]
	v_cmp_eq_u32_e64 s[0:1], 12, v24
	s_nop 1
	v_cndmask_b32_e64 v23, v23, v4, s[0:1]
	v_cmp_eq_u32_e64 s[0:1], 13, v24
	s_nop 1
	v_cndmask_b32_e64 v23, v23, v5, s[0:1]
	v_cmp_eq_u32_e64 s[0:1], 14, v24
	s_nop 1
	v_cndmask_b32_e64 v23, v23, v2, s[0:1]
	v_cmp_eq_u32_e64 s[0:1], 15, v24
	s_nop 1
	v_cndmask_b32_e64 v23, v23, v3, s[0:1]
	s_waitcnt lgkmcnt(0)
	v_add_f32_e32 v16, v23, v16
	v_cmp_eq_u32_e64 s[0:1], 1, v20
	s_nop 1
	v_cndmask_b32_e64 v23, v0, v16, s[0:1]
	v_cmp_eq_u32_e64 s[0:1], 2, v20
	s_nop 1
	v_cndmask_b32_e64 v23, v23, v22, s[0:1]
	v_cmp_eq_u32_e64 s[0:1], 3, v20
	s_nop 1
	v_cndmask_b32_e64 v23, v23, v21, s[0:1]
	v_cmp_eq_u32_e64 s[0:1], 4, v20
	s_nop 1
	v_cndmask_b32_e64 v23, v23, v12, s[0:1]
	v_cmp_eq_u32_e64 s[0:1], 5, v20
	s_nop 1
	v_cndmask_b32_e64 v23, v23, v14, s[0:1]
	v_cmp_eq_u32_e64 s[0:1], 6, v20
	s_nop 1
	v_cndmask_b32_e64 v23, v23, v10, s[0:1]
	v_cmp_eq_u32_e64 s[0:1], 7, v20
	s_nop 1
	v_cndmask_b32_e64 v23, v23, v26, s[0:1]
	v_cmp_eq_u32_e64 s[0:1], 8, v20
	s_nop 1
	v_cndmask_b32_e64 v23, v23, v8, s[0:1]
	v_cmp_eq_u32_e64 s[0:1], 9, v20
	s_nop 1
	v_cndmask_b32_e64 v23, v23, v9, s[0:1]
	v_cmp_eq_u32_e64 s[0:1], 10, v20
	s_nop 1
	v_cndmask_b32_e64 v23, v23, v6, s[0:1]
	v_cmp_eq_u32_e64 s[0:1], 11, v20
	s_nop 1
	v_cndmask_b32_e64 v23, v23, v7, s[0:1]
	v_cmp_eq_u32_e64 s[0:1], 12, v20
	s_nop 1
	v_cndmask_b32_e64 v23, v23, v4, s[0:1]
	v_cmp_eq_u32_e64 s[0:1], 13, v20
	s_nop 1
	v_cndmask_b32_e64 v23, v23, v5, s[0:1]
	v_cmp_eq_u32_e64 s[0:1], 14, v20
	s_nop 1
	v_cndmask_b32_e64 v23, v23, v2, s[0:1]
	v_cmp_eq_u32_e64 s[0:1], 15, v20
	s_nop 1
	v_cndmask_b32_e64 v20, v23, v3, s[0:1]
	v_or_b32_e32 v23, 2, v13
	v_cmp_eq_u32_e64 s[0:1], 1, v23
	ds_bpermute_b32 v20, v28, v20
	v_or_b32_e32 v13, 3, v13
	v_cndmask_b32_e64 v24, v0, v16, s[0:1]
	v_cmp_eq_u32_e64 s[0:1], 2, v23
	s_nop 1
	v_cndmask_b32_e64 v22, v24, v22, s[0:1]
	v_cmp_eq_u32_e64 s[0:1], 3, v23
	v_cndmask_b32_e32 v24, v18, v25, vcc
	v_cndmask_b32_e32 v18, v25, v18, vcc
	v_cndmask_b32_e64 v22, v22, v21, s[0:1]
	v_cmp_eq_u32_e64 s[0:1], 4, v23
	ds_bpermute_b32 v24, v28, v24
	s_waitcnt lgkmcnt(0)
	v_add_f32_e32 v18, v18, v24
	v_cndmask_b32_e64 v22, v22, v12, s[0:1]
	v_cmp_eq_u32_e64 s[0:1], 5, v23
	s_nop 1
	v_cndmask_b32_e64 v22, v22, v14, s[0:1]
	v_cmp_eq_u32_e64 s[0:1], 6, v23
	s_nop 1
	v_cndmask_b32_e64 v22, v22, v10, s[0:1]
	v_cmp_eq_u32_e64 s[0:1], 7, v23
	s_nop 1
	v_cndmask_b32_e64 v22, v22, v26, s[0:1]
	v_cmp_eq_u32_e64 s[0:1], 8, v23
	s_nop 1
	v_cndmask_b32_e64 v22, v22, v8, s[0:1]
	v_cmp_eq_u32_e64 s[0:1], 9, v23
	s_nop 1
	v_cndmask_b32_e64 v22, v22, v9, s[0:1]
	v_cmp_eq_u32_e64 s[0:1], 10, v23
	s_nop 1
	v_cndmask_b32_e64 v22, v22, v6, s[0:1]
	v_cmp_eq_u32_e64 s[0:1], 11, v23
	s_nop 1
	v_cndmask_b32_e64 v22, v22, v7, s[0:1]
	v_cmp_eq_u32_e64 s[0:1], 12, v23
	s_nop 1
	v_cndmask_b32_e64 v22, v22, v4, s[0:1]
	v_cmp_eq_u32_e64 s[0:1], 13, v23
	s_nop 1
	v_cndmask_b32_e64 v22, v22, v5, s[0:1]
	v_cmp_eq_u32_e64 s[0:1], 14, v23
	s_nop 1
	v_cndmask_b32_e64 v22, v22, v2, s[0:1]
	v_cmp_eq_u32_e64 s[0:1], 15, v23
	s_nop 1
	v_cndmask_b32_e64 v22, v22, v3, s[0:1]
	v_add_f32_e32 v20, v22, v20
	v_bitop3_b32 v22, v144, 7, 4 bitop3:0x6c
	v_cmp_eq_u32_e64 s[0:1], 1, v22
	s_nop 1
	v_cndmask_b32_e64 v23, v0, v16, s[0:1]
	v_cmp_eq_u32_e64 s[0:1], 2, v22
	s_nop 1
	v_cndmask_b32_e64 v23, v23, v20, s[0:1]
	v_cmp_eq_u32_e64 s[0:1], 3, v22
	s_nop 1
	v_cndmask_b32_e64 v23, v23, v21, s[0:1]
	v_cmp_eq_u32_e64 s[0:1], 4, v22
	s_nop 1
	v_cndmask_b32_e64 v23, v23, v12, s[0:1]
	v_cmp_eq_u32_e64 s[0:1], 5, v22
	s_nop 1
	v_cndmask_b32_e64 v23, v23, v14, s[0:1]
	v_cmp_eq_u32_e64 s[0:1], 6, v22
	s_nop 1
	v_cndmask_b32_e64 v23, v23, v10, s[0:1]
	v_cmp_eq_u32_e64 s[0:1], 7, v22
	s_nop 1
	v_cndmask_b32_e64 v23, v23, v26, s[0:1]
	v_cmp_eq_u32_e64 s[0:1], 8, v22
	s_nop 1
	v_cndmask_b32_e64 v23, v23, v8, s[0:1]
	v_cmp_eq_u32_e64 s[0:1], 9, v22
	s_nop 1
	v_cndmask_b32_e64 v23, v23, v9, s[0:1]
	v_cmp_eq_u32_e64 s[0:1], 10, v22
	s_nop 1
	v_cndmask_b32_e64 v23, v23, v6, s[0:1]
	v_cmp_eq_u32_e64 s[0:1], 11, v22
	s_nop 1
	v_cndmask_b32_e64 v23, v23, v7, s[0:1]
	v_cmp_eq_u32_e64 s[0:1], 12, v22
	s_nop 1
	v_cndmask_b32_e64 v23, v23, v4, s[0:1]
	v_cmp_eq_u32_e64 s[0:1], 13, v22
	s_nop 1
	v_cndmask_b32_e64 v23, v23, v5, s[0:1]
	v_cmp_eq_u32_e64 s[0:1], 14, v22
	s_nop 1
	v_cndmask_b32_e64 v23, v23, v2, s[0:1]
	v_cmp_eq_u32_e64 s[0:1], 15, v22
	s_nop 1
	v_cndmask_b32_e64 v22, v23, v3, s[0:1]
	v_cmp_eq_u32_e64 s[0:1], 1, v13
	ds_bpermute_b32 v22, v28, v22
	s_nop 0
	v_cndmask_b32_e64 v23, v0, v16, s[0:1]
	v_cmp_eq_u32_e64 s[0:1], 2, v13
	s_nop 1
	v_cndmask_b32_e64 v23, v23, v20, s[0:1]
	v_cmp_eq_u32_e64 s[0:1], 3, v13
	s_nop 1
	v_cndmask_b32_e64 v21, v23, v21, s[0:1]
	v_cmp_eq_u32_e64 s[0:1], 4, v13
	v_cndmask_b32_e32 v23, v19, v11, vcc
	v_cndmask_b32_e32 v11, v11, v19, vcc
	v_cndmask_b32_e64 v21, v21, v12, s[0:1]
	v_cmp_eq_u32_e64 s[0:1], 5, v13
	v_and_b32_e32 v19, 2, v144
	ds_bpermute_b32 v23, v28, v23
	v_cndmask_b32_e64 v21, v21, v14, s[0:1]
	v_cmp_eq_u32_e64 s[0:1], 6, v13
	s_waitcnt lgkmcnt(0)
	v_add_f32_e32 v11, v11, v23
	v_cndmask_b32_e64 v21, v21, v10, s[0:1]
	v_cmp_eq_u32_e64 s[0:1], 7, v13
	v_xor_b32_e32 v23, 2, v199
	s_nop 0
	v_cndmask_b32_e64 v21, v21, v26, s[0:1]
	v_cmp_eq_u32_e64 s[0:1], 8, v13
	s_nop 1
	v_cndmask_b32_e64 v21, v21, v8, s[0:1]
	v_cmp_eq_u32_e64 s[0:1], 9, v13
	s_nop 1
	v_cndmask_b32_e64 v21, v21, v9, s[0:1]
	v_cmp_eq_u32_e64 s[0:1], 10, v13
	s_nop 1
	v_cndmask_b32_e64 v21, v21, v6, s[0:1]
	v_cmp_eq_u32_e64 s[0:1], 11, v13
	s_nop 1
	v_cndmask_b32_e64 v21, v21, v7, s[0:1]
	v_cmp_eq_u32_e64 s[0:1], 12, v13
	s_nop 1
	v_cndmask_b32_e64 v21, v21, v4, s[0:1]
	v_cmp_eq_u32_e64 s[0:1], 13, v13
	s_nop 1
	v_cndmask_b32_e64 v21, v21, v5, s[0:1]
	v_cmp_eq_u32_e64 s[0:1], 14, v13
	s_nop 1
	v_cndmask_b32_e64 v21, v21, v2, s[0:1]
	v_cmp_eq_u32_e64 s[0:1], 15, v13
	s_nop 1
	v_cndmask_b32_e64 v13, v21, v3, s[0:1]
	v_bitop3_b32 v21, v144, 2, v144 bitop3:0xc
	v_cmp_eq_u32_e32 vcc, 1, v21
	v_add_f32_e32 v13, v13, v22
	v_cmp_lt_i32_e64 s[0:1], v23, v1
	v_cndmask_b32_e32 v22, v0, v16, vcc
	v_cmp_eq_u32_e32 vcc, 2, v21
	v_cndmask_b32_e64 v23, v199, v23, s[0:1]
	v_lshlrev_b32_e32 v23, 2, v23
	v_cndmask_b32_e32 v22, v22, v20, vcc
	v_cmp_eq_u32_e32 vcc, 3, v21
	v_cmp_eq_u32_e64 s[0:1], 15, v19
	s_nop 0
	v_cndmask_b32_e32 v22, v22, v13, vcc
	v_cmp_eq_u32_e32 vcc, 4, v21
	s_nop 1
	v_cndmask_b32_e32 v22, v22, v12, vcc
	v_cmp_eq_u32_e32 vcc, 5, v21
	s_nop 1
	v_cndmask_b32_e32 v22, v22, v14, vcc
	v_cmp_eq_u32_e32 vcc, 6, v21
	s_nop 1
	v_cndmask_b32_e32 v22, v22, v10, vcc
	v_cmp_eq_u32_e32 vcc, 7, v21
	s_nop 1
	v_cndmask_b32_e32 v22, v22, v26, vcc
	v_cmp_eq_u32_e32 vcc, 8, v21
	s_nop 1
	v_cndmask_b32_e32 v22, v22, v8, vcc
	v_cmp_eq_u32_e32 vcc, 9, v21
	s_nop 1
	v_cndmask_b32_e32 v22, v22, v9, vcc
	v_cmp_eq_u32_e32 vcc, 10, v21
	s_nop 1
	v_cndmask_b32_e32 v22, v22, v6, vcc
	v_cmp_eq_u32_e32 vcc, 11, v21
	s_nop 1
	v_cndmask_b32_e32 v22, v22, v7, vcc
	v_cmp_eq_u32_e32 vcc, 12, v21
	s_nop 1
	v_cndmask_b32_e32 v22, v22, v4, vcc
	v_cmp_eq_u32_e32 vcc, 13, v21
	s_nop 1
	v_cndmask_b32_e32 v22, v22, v5, vcc
	v_cmp_eq_u32_e32 vcc, 14, v21
	s_nop 1
	v_cndmask_b32_e32 v22, v22, v2, vcc
	v_cmp_eq_u32_e32 vcc, 15, v21
	s_nop 1
	v_cndmask_b32_e32 v21, v22, v3, vcc
	v_cmp_eq_u32_e32 vcc, 1, v19
	ds_bpermute_b32 v21, v23, v21
	s_nop 0
	v_cndmask_b32_e32 v0, v0, v16, vcc
	v_cmp_ne_u32_e32 vcc, 0, v19
	s_nop 1
	v_cndmask_b32_e32 v0, v0, v20, vcc
	v_cmp_eq_u32_e32 vcc, 3, v19
	s_nop 1
	v_cndmask_b32_e32 v0, v0, v13, vcc
	v_cmp_eq_u32_e32 vcc, 4, v19
	s_nop 1
	v_cndmask_b32_e32 v0, v0, v12, vcc
	v_cmp_eq_u32_e32 vcc, 5, v19
	s_nop 1
	v_cndmask_b32_e32 v0, v0, v14, vcc
	v_cmp_eq_u32_e32 vcc, 6, v19
	s_nop 1
	v_cndmask_b32_e32 v0, v0, v10, vcc
	v_cmp_eq_u32_e32 vcc, 7, v19
	s_nop 1
	v_cndmask_b32_e32 v0, v0, v26, vcc
	v_cmp_eq_u32_e32 vcc, 8, v19
	s_nop 1
	v_cndmask_b32_e32 v0, v0, v8, vcc
	v_cmp_eq_u32_e32 vcc, 9, v19
	s_nop 1
	v_cndmask_b32_e32 v0, v0, v9, vcc
	v_cmp_eq_u32_e32 vcc, 10, v19
	s_nop 1
	v_cndmask_b32_e32 v0, v0, v6, vcc
	v_cmp_eq_u32_e32 vcc, 11, v19
	s_nop 1
	v_cndmask_b32_e32 v0, v0, v7, vcc
	v_cmp_eq_u32_e32 vcc, 12, v19
	s_nop 1
	v_cndmask_b32_e32 v0, v0, v4, vcc
	v_cmp_eq_u32_e32 vcc, 13, v19
	s_nop 1
	v_cndmask_b32_e32 v0, v0, v5, vcc
	v_cmp_eq_u32_e32 vcc, 14, v19
	s_nop 1
	v_cndmask_b32_e32 v0, v0, v2, vcc
	v_cmp_eq_u32_e32 vcc, 0, v19
	v_cndmask_b32_e64 v0, v0, v3, s[0:1]
	v_or_b32_e32 v19, 1, v19
	v_cndmask_b32_e32 v22, v15, v18, vcc
	v_cndmask_b32_e32 v15, v18, v15, vcc
	s_waitcnt lgkmcnt(0)
	v_add_f32_e32 v18, v0, v21
	v_bitop3_b32 v0, v144, 3, 2 bitop3:0x6c
	v_cmp_eq_u32_e64 s[0:1], 1, v0
	ds_bpermute_b32 v22, v23, v22
	s_waitcnt lgkmcnt(0)
	v_add_f32_e32 v15, v15, v22
	v_cndmask_b32_e64 v21, v18, v16, s[0:1]
	v_cmp_eq_u32_e64 s[0:1], 2, v0
	s_nop 1
	v_cndmask_b32_e64 v21, v21, v20, s[0:1]
	v_cmp_eq_u32_e64 s[0:1], 3, v0
	s_nop 1
	v_cndmask_b32_e64 v21, v21, v13, s[0:1]
	v_cmp_eq_u32_e64 s[0:1], 4, v0
	s_nop 1
	v_cndmask_b32_e64 v21, v21, v12, s[0:1]
	v_cmp_eq_u32_e64 s[0:1], 5, v0
	s_nop 1
	v_cndmask_b32_e64 v21, v21, v14, s[0:1]
	v_cmp_eq_u32_e64 s[0:1], 6, v0
	s_nop 1
	v_cndmask_b32_e64 v21, v21, v10, s[0:1]
	v_cmp_eq_u32_e64 s[0:1], 7, v0
	s_nop 1
	v_cndmask_b32_e64 v21, v21, v26, s[0:1]
	v_cmp_eq_u32_e64 s[0:1], 8, v0
	s_nop 1
	v_cndmask_b32_e64 v21, v21, v8, s[0:1]
	v_cmp_eq_u32_e64 s[0:1], 9, v0
	s_nop 1
	v_cndmask_b32_e64 v21, v21, v9, s[0:1]
	v_cmp_eq_u32_e64 s[0:1], 10, v0
	s_nop 1
	v_cndmask_b32_e64 v21, v21, v6, s[0:1]
	v_cmp_eq_u32_e64 s[0:1], 11, v0
	s_nop 1
	v_cndmask_b32_e64 v21, v21, v7, s[0:1]
	v_cmp_eq_u32_e64 s[0:1], 12, v0
	s_nop 1
	v_cndmask_b32_e64 v21, v21, v4, s[0:1]
	v_cmp_eq_u32_e64 s[0:1], 13, v0
	s_nop 1
	v_cndmask_b32_e64 v21, v21, v5, s[0:1]
	v_cmp_eq_u32_e64 s[0:1], 14, v0
	s_nop 1
	v_cndmask_b32_e64 v21, v21, v2, s[0:1]
	v_cmp_eq_u32_e64 s[0:1], 15, v0
	s_nop 1
	v_cndmask_b32_e64 v0, v21, v3, s[0:1]
	v_cmp_eq_u32_e64 s[0:1], 1, v19
	ds_bpermute_b32 v0, v23, v0
	v_cndmask_b32_e32 v21, v17, v11, vcc
	v_cndmask_b32_e64 v16, v18, v16, s[0:1]
	v_cmp_eq_u32_e64 s[0:1], 2, v19
	v_cndmask_b32_e32 v11, v11, v17, vcc
	v_and_b32_e32 v17, 1, v144
	v_cndmask_b32_e64 v16, v16, v20, s[0:1]
	v_cmp_eq_u32_e64 s[0:1], 3, v19
	v_cmp_eq_u32_e32 vcc, 1, v17
	ds_bpermute_b32 v21, v23, v21
	v_cndmask_b32_e64 v16, v16, v13, s[0:1]
	v_cmp_eq_u32_e64 s[0:1], 4, v19
	s_waitcnt lgkmcnt(0)
	v_add_f32_e32 v11, v11, v21
	v_cndmask_b32_e64 v16, v16, v12, s[0:1]
	v_cmp_eq_u32_e64 s[0:1], 5, v19
	v_xor_b32_e32 v21, 1, v199
	v_cmp_lt_i32_e64 s[4:5], v21, v1
	v_cndmask_b32_e64 v16, v16, v14, s[0:1]
	v_cmp_eq_u32_e64 s[0:1], 6, v19
	v_cndmask_b32_e64 v1, v199, v21, s[4:5]
	v_lshlrev_b32_e32 v1, 2, v1
	v_cndmask_b32_e64 v16, v16, v10, s[0:1]
	v_cmp_eq_u32_e64 s[0:1], 7, v19
	s_mov_b64 s[4:5], s[22:23]
	s_nop 0
	v_cndmask_b32_e64 v16, v16, v26, s[0:1]
	v_cmp_eq_u32_e64 s[0:1], 8, v19
	s_nop 1
	v_cndmask_b32_e64 v16, v16, v8, s[0:1]
	v_cmp_eq_u32_e64 s[0:1], 9, v19
	s_nop 1
	v_cndmask_b32_e64 v16, v16, v9, s[0:1]
	v_cmp_eq_u32_e64 s[0:1], 10, v19
	s_nop 1
	v_cndmask_b32_e64 v16, v16, v6, s[0:1]
	v_cmp_eq_u32_e64 s[0:1], 11, v19
	s_nop 1
	v_cndmask_b32_e64 v16, v16, v7, s[0:1]
	v_cmp_eq_u32_e64 s[0:1], 12, v19
	s_nop 1
	v_cndmask_b32_e64 v16, v16, v4, s[0:1]
	v_cmp_eq_u32_e64 s[0:1], 13, v19
	s_nop 1
	v_cndmask_b32_e64 v16, v16, v5, s[0:1]
	v_cmp_eq_u32_e64 s[0:1], 14, v19
	s_nop 1
	v_cndmask_b32_e64 v16, v16, v2, s[0:1]
	v_cmp_eq_u32_e64 s[0:1], 15, v19
	s_nop 1
	v_cndmask_b32_e64 v16, v16, v3, s[0:1]
	v_add_f32_e32 v16, v16, v0
	v_bitop3_b32 v0, v144, 1, v144 bitop3:0xc
	v_cndmask_b32_e32 v19, v16, v18, vcc
	v_cmp_eq_u32_e64 s[0:1], 2, v0
	s_nop 1
	v_cndmask_b32_e64 v19, v19, v20, s[0:1]
	v_cmp_eq_u32_e64 s[0:1], 3, v0
	s_nop 1
	v_cndmask_b32_e64 v19, v19, v13, s[0:1]
	v_cmp_eq_u32_e64 s[0:1], 4, v0
	s_nop 1
	v_cndmask_b32_e64 v19, v19, v12, s[0:1]
	v_cmp_eq_u32_e64 s[0:1], 5, v0
	s_nop 1
	v_cndmask_b32_e64 v19, v19, v14, s[0:1]
	v_cmp_eq_u32_e64 s[0:1], 6, v0
	s_nop 1
	v_cndmask_b32_e64 v19, v19, v10, s[0:1]
	v_cmp_eq_u32_e64 s[0:1], 7, v0
	s_nop 1
	v_cndmask_b32_e64 v19, v19, v26, s[0:1]
	v_cmp_eq_u32_e64 s[0:1], 8, v0
	s_nop 1
	v_cndmask_b32_e64 v19, v19, v8, s[0:1]
	v_cmp_eq_u32_e64 s[0:1], 9, v0
	s_nop 1
	v_cndmask_b32_e64 v19, v19, v9, s[0:1]
	v_cmp_eq_u32_e64 s[0:1], 10, v0
	s_nop 1
	v_cndmask_b32_e64 v19, v19, v6, s[0:1]
	v_cmp_eq_u32_e64 s[0:1], 11, v0
	s_nop 1
	v_cndmask_b32_e64 v19, v19, v7, s[0:1]
	v_cmp_eq_u32_e64 s[0:1], 12, v0
	s_nop 1
	v_cndmask_b32_e64 v19, v19, v4, s[0:1]
	v_cmp_eq_u32_e64 s[0:1], 13, v0
	s_nop 1
	v_cndmask_b32_e64 v19, v19, v5, s[0:1]
	v_cmp_eq_u32_e64 s[0:1], 14, v0
	s_nop 1
	v_cndmask_b32_e64 v19, v19, v2, s[0:1]
	v_cmp_eq_u32_e64 s[0:1], 15, v0
	s_nop 1
	v_cndmask_b32_e64 v0, v19, v3, s[0:1]
	v_cmp_eq_u32_e64 s[0:1], 0, v17
	ds_bpermute_b32 v0, v1, v0
	s_nop 0
	v_cndmask_b32_e64 v19, v15, v11, s[0:1]
	v_cndmask_b32_e64 v11, v11, v15, s[0:1]
	v_cndmask_b32_e32 v15, v18, v16, vcc
	v_cmp_eq_u32_e32 vcc, 2, v17
	ds_bpermute_b32 v1, v1, v19
	s_lshl_b32 s0, s2, 1
	v_cndmask_b32_e32 v15, v15, v20, vcc
	v_cmp_eq_u32_e32 vcc, 3, v17
	s_ashr_i32 s1, s0, 31
	s_add_u32 s0, s0, s34
	v_cndmask_b32_e32 v13, v15, v13, vcc
	v_cmp_eq_u32_e32 vcc, 4, v17
	s_addc_u32 s1, s1, s43
	s_mov_b32 s2, s16
	v_cndmask_b32_e32 v12, v13, v12, vcc
	v_cmp_eq_u32_e32 vcc, 5, v17
	s_nop 1
	v_cndmask_b32_e32 v12, v12, v14, vcc
	v_cmp_eq_u32_e32 vcc, 6, v17
	s_nop 1
	v_cndmask_b32_e32 v10, v12, v10, vcc
	v_cmp_eq_u32_e32 vcc, 7, v17
	s_nop 1
	v_cndmask_b32_e32 v10, v10, v26, vcc
	v_cmp_eq_u32_e32 vcc, 8, v17
	s_nop 1
	v_cndmask_b32_e32 v8, v10, v8, vcc
	v_cmp_eq_u32_e32 vcc, 9, v17
	s_nop 1
	v_cndmask_b32_e32 v8, v8, v9, vcc
	v_cmp_eq_u32_e32 vcc, 10, v17
	s_nop 1
	v_cndmask_b32_e32 v6, v8, v6, vcc
	v_cmp_eq_u32_e32 vcc, 11, v17
	s_nop 1
	v_cndmask_b32_e32 v6, v6, v7, vcc
	v_cmp_eq_u32_e32 vcc, 12, v17
	s_nop 1
	v_cndmask_b32_e32 v4, v6, v4, vcc
	v_cmp_eq_u32_e32 vcc, 13, v17
	s_nop 1
	v_cndmask_b32_e32 v4, v4, v5, vcc
	v_cmp_eq_u32_e32 vcc, 14, v17
	s_nop 1
	v_cndmask_b32_e32 v2, v4, v2, vcc
	v_cmp_eq_u32_e32 vcc, 15, v17
	s_nop 1
	v_cndmask_b32_e32 v10, v2, v3, vcc
	v_lshlrev_b32_e32 v2, 4, v144
	v_and_b32_e32 v2, 0xffffff80, v2
	v_add_u32_e32 v2, v138, v2
	v_and_or_b32 v2, v144, 7, v2
	v_ashrrev_i32_e32 v3, 31, v2
	v_lshlrev_b64 v[2:3], 8, v[2:3]
	v_lshl_add_u64 v[2:3], s[12:13], 0, v[2:3]
	s_waitcnt lgkmcnt(0)
	v_pk_add_f32 v[0:1], v[10:11], v[0:1]
	v_lshl_add_u64 v[2:3], s[0:1], 3, v[2:3]
	s_and_b64 vcc, exec, s[14:15]
	s_mov_b64 s[0:1], s[20:21]
	global_store_dwordx2 v[2:3], v[0:1], off
	s_cbranch_vccz .LBB0_327
	s_waitcnt vmcnt(0)
	s_cmpk_gt_u32 s30, 0xff
	s_cbranch_scc1 .LBB0_338
	s_barrier
